# GEMM units: accumulator zero-fill removed (first K iteration peeled with SrcC=0; no-loop fill moved to cold path)
# speedup vs baseline: 1.0472x; 1.0227x over previous
; #define PG8_BAR __builtin_amdgcn_s_barrier()
; template <class Epi, class Sched, bool ALIGN_EPI = false, bool SP2 = false>
; __device__ __forceinline__ void gemm_phase(PG8_LAS unsigned char* lds, const Gemm g, const Sched& S, const Epi& E) {
;     ...
;     f32x4 acc[2][2][4][2];
; #pragma unroll
;     for (int a = 0; a < 2; ++a)
; #pragma unroll
;         for (int b = 0; b < 2; ++b)
; #pragma unroll
;             for (int m = 0; m < 4; ++m)
; #pragma unroll
;                 for (int n = 0; n < 2; ++n) acc[a][b][m][n] = (f32x4){0.f, 0.f, 0.f, 0.f};
;     ...
;         if constexpr (ALIGN_EPI) { if (wr == 0) PG8_BAR; }
;         if constexpr (!Epi::AFTER_DRAIN) { E(acc, cur, wr, wc, fr, fq); S.done(cur); }
.Lcoldz_0:
	v_mov_b32_e32 v123, 0
	v_mov_b32_e32 v122, v123
	v_mov_b32_e32 v121, v123
	v_mov_b32_e32 v120, v123
	v_mov_b32_e32 v119, v123
	v_mov_b32_e32 v118, v123
	v_mov_b32_e32 v117, v123
	v_mov_b32_e32 v116, v123
	v_mov_b32_e32 v111, v123
	v_mov_b32_e32 v110, v123
	v_mov_b32_e32 v109, v123
	v_mov_b32_e32 v108, v123
	v_mov_b32_e32 v103, v123
	v_mov_b32_e32 v102, v123
	v_mov_b32_e32 v101, v123
	v_mov_b32_e32 v100, v123
	v_mov_b32_e32 v95, v123
	v_mov_b32_e32 v94, v123
	v_mov_b32_e32 v93, v123
	v_mov_b32_e32 v92, v123
	v_mov_b32_e32 v87, v123
	v_mov_b32_e32 v86, v123
	v_mov_b32_e32 v85, v123
	v_mov_b32_e32 v84, v123
	v_mov_b32_e32 v79, v123
	v_mov_b32_e32 v78, v123
	v_mov_b32_e32 v77, v123
	v_mov_b32_e32 v76, v123
	v_mov_b32_e32 v71, v123
	v_mov_b32_e32 v70, v123
	v_mov_b32_e32 v69, v123
	v_mov_b32_e32 v68, v123
	v_mov_b32_e32 v127, v123
	v_mov_b32_e32 v126, v123
	v_mov_b32_e32 v125, v123
	v_mov_b32_e32 v124, v123
	v_mov_b32_e32 v115, v123
	v_mov_b32_e32 v114, v123
	v_mov_b32_e32 v113, v123
	v_mov_b32_e32 v112, v123
	v_mov_b32_e32 v107, v123
	v_mov_b32_e32 v106, v123
	v_mov_b32_e32 v105, v123
	v_mov_b32_e32 v104, v123
	v_mov_b32_e32 v99, v123
	v_mov_b32_e32 v98, v123
	v_mov_b32_e32 v97, v123
	v_mov_b32_e32 v96, v123
	v_mov_b32_e32 v91, v123
	v_mov_b32_e32 v90, v123
	v_mov_b32_e32 v89, v123
	v_mov_b32_e32 v88, v123
	v_mov_b32_e32 v83, v123
	v_mov_b32_e32 v82, v123
	v_mov_b32_e32 v81, v123
	v_mov_b32_e32 v80, v123
	v_mov_b32_e32 v75, v123
	v_mov_b32_e32 v74, v123
	v_mov_b32_e32 v73, v123
	v_mov_b32_e32 v72, v123
	v_mov_b32_e32 v67, v123
	v_mov_b32_e32 v66, v123
	v_mov_b32_e32 v65, v123
	v_mov_b32_e32 v64, v123
	v_mov_b32_e32 v63, v123
	v_mov_b32_e32 v62, v123
	v_mov_b32_e32 v61, v123
	v_mov_b32_e32 v60, v123
	v_mov_b32_e32 v55, v123
	v_mov_b32_e32 v54, v123
	v_mov_b32_e32 v53, v123
	v_mov_b32_e32 v52, v123
	v_mov_b32_e32 v47, v123
	v_mov_b32_e32 v46, v123
	v_mov_b32_e32 v45, v123
	v_mov_b32_e32 v44, v123
	v_mov_b32_e32 v39, v123
	v_mov_b32_e32 v38, v123
	v_mov_b32_e32 v37, v123
	v_mov_b32_e32 v36, v123
	v_mov_b32_e32 v31, v123
	v_mov_b32_e32 v30, v123
	v_mov_b32_e32 v29, v123
	v_mov_b32_e32 v28, v123
	v_mov_b32_e32 v23, v123
	v_mov_b32_e32 v22, v123
	v_mov_b32_e32 v21, v123
	v_mov_b32_e32 v20, v123
	v_mov_b32_e32 v15, v123
	v_mov_b32_e32 v14, v123
	v_mov_b32_e32 v13, v123
	v_mov_b32_e32 v12, v123
	v_mov_b32_e32 v7, v123
	v_mov_b32_e32 v6, v123
	v_mov_b32_e32 v5, v123
	v_mov_b32_e32 v4, v123
	v_mov_b32_e32 v59, v123
	v_mov_b32_e32 v58, v123
	v_mov_b32_e32 v57, v123
	v_mov_b32_e32 v56, v123
	v_mov_b32_e32 v51, v123
	v_mov_b32_e32 v50, v123
	v_mov_b32_e32 v49, v123
	v_mov_b32_e32 v48, v123
	v_mov_b32_e32 v43, v123
	v_mov_b32_e32 v42, v123
	v_mov_b32_e32 v41, v123
	v_mov_b32_e32 v40, v123
	v_mov_b32_e32 v35, v123
	v_mov_b32_e32 v34, v123
	v_mov_b32_e32 v33, v123
	v_mov_b32_e32 v32, v123
	v_mov_b32_e32 v27, v123
	v_mov_b32_e32 v26, v123
	v_mov_b32_e32 v25, v123
	v_mov_b32_e32 v24, v123
	v_mov_b32_e32 v19, v123
	v_mov_b32_e32 v18, v123
	v_mov_b32_e32 v17, v123
	v_mov_b32_e32 v16, v123
	v_mov_b32_e32 v11, v123
	v_mov_b32_e32 v10, v123
	v_mov_b32_e32 v9, v123
	v_mov_b32_e32 v8, v123
	v_mov_b32_e32 v3, v123
	v_mov_b32_e32 v2, v123
	v_mov_b32_e32 v1, v123
	v_mov_b32_e32 v0, v123
	s_branch .LBB0_350

; #define PG8_STAGE(bufoff, gbase, voff) do { _Pragma("unroll") for (int _i = 0; _i < 2; ++_i) \
;         __builtin_amdgcn_global_load_lds((const unsigned*)((const char*)(gbase) + (voff)[_i]), (PG8_LAS unsigned*)(lds + (bufoff) + ldsw + _i * 8192), 16, 0, 0); } while (0)
; #define PG8_LDA(dst, b, h) do { _Pragma("unroll") for (int m = 0; m < 4; ++m) _Pragma("unroll") for (int k = 0; k < 2; ++k) dst[m][k] = *(const PG8_LAS bf16x8*)(lds + PG8_SA(b, h) + aoff + m * 2048 + k * 1024); } while (0)
; #define PG8_LDB(dst, b, h) do { _Pragma("unroll") for (int n = 0; n < 2; ++n) _Pragma("unroll") for (int k = 0; k < 2; ++k) dst[n][k] = *(const PG8_LAS bf16x8*)(lds + PG8_SB(b, h) + boff + n * 2048 + k * 1024); } while (0)
; #define PG8_MMA(ai, bj, At, Bt) do { __builtin_amdgcn_s_setprio(1); _Pragma("unroll") for (int m = 0; m < 4; ++m) _Pragma("unroll") for (int n = 0; n < 2; ++n) _Pragma("unroll") for (int k = 0; k < 2; ++k) \
;         acc[ai][bj][m][n] = __builtin_amdgcn_mfma_f32_16x16x32_bf16(Bt[n][k], At[m][k], acc[ai][bj][m][n], 0, 0, 0); __builtin_amdgcn_s_setprio(0); } while (0)
; #define PG8_WAIT_V(n) asm volatile("s_waitcnt vmcnt(" #n ")" ::: "memory")
; #define PG8_BAR __builtin_amdgcn_s_barrier()
; template <class Epi, class Sched, bool ALIGN_EPI = false, bool SP2 = false>
; __device__ __forceinline__ void gemm_phase(PG8_LAS unsigned char* lds, const Gemm g, const Sched& S, const Epi& E) {
;     ...
;         for (int t = 0; t < nt; t += 2) {
;             const bool last = (t == nt - 2);
;             const char* a1 = cA + (size_t)(t + 1) * kstep;
;             const char* a2 = last ? nA : cA + (size_t)(t + 2) * kstep; const char* b2 = last ? nB : cB + (size_t)(t + 2) * kstep;
;             const char* a3 = a2 + kstep; const char* b3 = b2 + kstep;
;             if (last && has_next) S.a_ready(nxt);
;             if constexpr (SP2) {
;             PG8_LDB(B0, 0, 0); PG8_LDB(B1, 0, 1); PG8_SCHED; PG8_LDA(At, 0, 0); PG8_STAGE(PG8_SA(1, 1), a1 + hstep, voffA);
;             PG8_WAIT_V(8); PG8_WAIT_L(0); PG8_BAR; PG8_MMA(0, 0, At, B0); PG8_MMA(0, 1, At, B1); PG8_BAR; PG8_SCHED;
;             PG8_LDA(At, 0, 1); PG8_STAGE(PG8_SB(0, 0), b2, voffB); PG8_STAGE(PG8_SB(0, 1), b2 + hstep, voffB); PG8_STAGE(PG8_SA(0, 0), a2, voffA);
;             PG8_WAIT_V(8); PG8_WAIT_L(0); PG8_BAR; PG8_MMA(1, 0, At, B0); PG8_MMA(1, 1, At, B1); PG8_BAR; PG8_SCHED;
.LBB0_347:
	s_and_b64 vcc, exec, s[6:7]
	s_cbranch_vccnz .Lcoldz_0
	s_add_u32 s38, s38, 0x80
	s_addc_u32 s39, s39, 0
	s_add_u32 s24, s40, 0x100
	s_addc_u32 s25, s41, 0
	s_mov_b32 s40, 0
	ds_read_b128 v[152:155], v148
	ds_read_b128 v[156:159], v148 offset:1024
	ds_read_b128 v[160:163], v148 offset:2048
	ds_read_b128 v[164:167], v148 offset:3072
	ds_read_b128 v[168:171], v149
	ds_read_b128 v[172:175], v149 offset:1024
	ds_read_b128 v[176:179], v149 offset:2048
	ds_read_b128 v[180:183], v149 offset:3072
	s_add_i32 s54, s40, 2
	s_add_u32 s55, s38, 0x80
	s_addc_u32 s41, s39, 0
	s_cmp_eq_u32 s43, s40
	s_cselect_b32 s40, s10, s55
	s_cselect_b32 s41, s11, s41
	s_cselect_b32 s57, s37, s25
	s_cselect_b32 s56, s36, s24
	s_mov_b32 m0, s47
	v_lshl_add_u64 v[216:217], s[38:39], 0, v[136:137]
	ds_read_b128 v[184:187], v150
	ds_read_b128 v[188:191], v150 offset:1024
	ds_read_b128 v[192:195], v150 offset:2048
	ds_read_b128 v[196:199], v150 offset:3072
	ds_read_b128 v[200:203], v150 offset:4096
	ds_read_b128 v[204:207], v150 offset:5120
	ds_read_b128 v[208:211], v150 offset:6144
	ds_read_b128 v[212:215], v150 offset:7168
	global_load_lds_dwordx4 v[216:217], off
	v_lshl_add_u64 v[216:217], s[38:39], 0, v[138:139]
	s_mov_b32 m0, s48
	s_nop 0
	global_load_lds_dwordx4 v[216:217], off
	s_waitcnt vmcnt(8)
	s_waitcnt lgkmcnt(0)
	s_barrier
	s_setprio 1
	s_waitcnt lgkmcnt(0)
	v_mfma_f32_16x16x32_bf16 v[120:123], v[152:155], v[184:187], 0
	v_mfma_f32_16x16x32_bf16 v[116:119], v[160:163], v[184:187], 0
	v_mfma_f32_16x16x32_bf16 v[108:111], v[152:155], v[192:195], 0
	v_mfma_f32_16x16x32_bf16 v[100:103], v[160:163], v[192:195], 0
	v_mfma_f32_16x16x32_bf16 v[92:95], v[152:155], v[200:203], 0
	v_mfma_f32_16x16x32_bf16 v[84:87], v[160:163], v[200:203], 0
	v_mfma_f32_16x16x32_bf16 v[76:79], v[152:155], v[208:211], 0
	v_mfma_f32_16x16x32_bf16 v[68:71], v[160:163], v[208:211], 0
	v_mfma_f32_16x16x32_bf16 v[120:123], v[156:159], v[188:191], v[120:123]
	v_mfma_f32_16x16x32_bf16 v[116:119], v[164:167], v[188:191], v[116:119]
	v_mfma_f32_16x16x32_bf16 v[108:111], v[156:159], v[196:199], v[108:111]
	v_mfma_f32_16x16x32_bf16 v[100:103], v[164:167], v[196:199], v[100:103]
	v_mfma_f32_16x16x32_bf16 v[92:95], v[156:159], v[204:207], v[92:95]
	v_mfma_f32_16x16x32_bf16 v[84:87], v[164:167], v[204:207], v[84:87]
	v_mfma_f32_16x16x32_bf16 v[76:79], v[156:159], v[212:215], v[76:79]
	v_mfma_f32_16x16x32_bf16 v[68:71], v[164:167], v[212:215], v[68:71]
	s_setprio 0
	s_setprio 1
	v_mfma_f32_16x16x32_bf16 v[124:127], v[168:171], v[184:187], 0
	v_mfma_f32_16x16x32_bf16 v[112:115], v[176:179], v[184:187], 0
	v_mfma_f32_16x16x32_bf16 v[104:107], v[168:171], v[192:195], 0
	v_mfma_f32_16x16x32_bf16 v[96:99], v[176:179], v[192:195], 0
	v_mfma_f32_16x16x32_bf16 v[88:91], v[168:171], v[200:203], 0
	v_mfma_f32_16x16x32_bf16 v[80:83], v[176:179], v[200:203], 0
	v_mfma_f32_16x16x32_bf16 v[72:75], v[168:171], v[208:211], 0
	v_mfma_f32_16x16x32_bf16 v[64:67], v[176:179], v[208:211], 0
	v_mfma_f32_16x16x32_bf16 v[124:127], v[172:175], v[188:191], v[124:127]
	v_mfma_f32_16x16x32_bf16 v[112:115], v[180:183], v[188:191], v[112:115]
	v_mfma_f32_16x16x32_bf16 v[104:107], v[172:175], v[196:199], v[104:107]
	v_mfma_f32_16x16x32_bf16 v[96:99], v[180:183], v[196:199], v[96:99]
	v_mfma_f32_16x16x32_bf16 v[88:91], v[172:175], v[204:207], v[88:91]
	v_mfma_f32_16x16x32_bf16 v[80:83], v[180:183], v[204:207], v[80:83]
	v_mfma_f32_16x16x32_bf16 v[72:75], v[172:175], v[212:215], v[72:75]
	v_mfma_f32_16x16x32_bf16 v[64:67], v[180:183], v[212:215], v[64:67]
	s_setprio 0
	s_barrier
	s_add_i32 s55, s44, s3
	v_lshl_add_u64 v[216:217], s[56:57], 0, v[132:133]
	s_mov_b32 m0, s55
	ds_read_b128 v[184:187], v150 offset:16384
	ds_read_b128 v[188:191], v150 offset:17408
	ds_read_b128 v[192:195], v150 offset:18432
	ds_read_b128 v[196:199], v150 offset:19456
	ds_read_b128 v[200:203], v150 offset:20480
	ds_read_b128 v[204:207], v150 offset:21504
	ds_read_b128 v[208:211], v150 offset:22528
	ds_read_b128 v[212:215], v150 offset:23552
	global_load_lds_dwordx4 v[216:217], off
	s_add_i32 m0, s55, 0x2000
	v_lshl_add_u64 v[218:219], s[56:57], 0, v[128:129]
	s_add_u32 s56, s56, s12
	s_addc_u32 s57, s57, s13
	s_add_i32 s55, s45, s3
	global_load_lds_dwordx4 v[218:219], off
	v_lshl_add_u64 v[220:221], s[56:57], 0, v[132:133]
	s_mov_b32 m0, s55
	v_lshl_add_u64 v[222:223], s[56:57], 0, v[128:129]
	global_load_lds_dwordx4 v[220:221], off
	s_add_i32 m0, s55, 0x2000
	v_lshl_add_u64 v[224:225], s[40:41], 0, v[134:135]
	global_load_lds_dwordx4 v[222:223], off
	s_mov_b32 m0, s17
	v_lshl_add_u64 v[226:227], s[40:41], 0, v[130:131]
	global_load_lds_dwordx4 v[224:225], off
	s_mov_b32 m0, s18
	s_nop 0
	global_load_lds_dwordx4 v[226:227], off
	s_waitcnt vmcnt(8)
	s_waitcnt lgkmcnt(0)
	s_barrier
; #define PG8_STAGE(bufoff, gbase, voff) do { _Pragma("unroll") for (int _i = 0; _i < 2; ++_i) \
;         __builtin_amdgcn_global_load_lds((const unsigned*)((const char*)(gbase) + (voff)[_i]), (PG8_LAS unsigned*)(lds + (bufoff) + ldsw + _i * 8192), 16, 0, 0); } while (0)
; #define PG8_LDA(dst, b, h) do { _Pragma("unroll") for (int m = 0; m < 4; ++m) _Pragma("unroll") for (int k = 0; k < 2; ++k) dst[m][k] = *(const PG8_LAS bf16x8*)(lds + PG8_SA(b, h) + aoff + m * 2048 + k * 1024); } while (0)
; #define PG8_LDB(dst, b, h) do { _Pragma("unroll") for (int n = 0; n < 2; ++n) _Pragma("unroll") for (int k = 0; k < 2; ++k) dst[n][k] = *(const PG8_LAS bf16x8*)(lds + PG8_SB(b, h) + boff + n * 2048 + k * 1024); } while (0)
; #define PG8_MMA(ai, bj, At, Bt) do { __builtin_amdgcn_s_setprio(1); _Pragma("unroll") for (int m = 0; m < 4; ++m) _Pragma("unroll") for (int n = 0; n < 2; ++n) _Pragma("unroll") for (int k = 0; k < 2; ++k) \
;         acc[ai][bj][m][n] = __builtin_amdgcn_mfma_f32_16x16x32_bf16(Bt[n][k], At[m][k], acc[ai][bj][m][n], 0, 0, 0); __builtin_amdgcn_s_setprio(0); } while (0)
; #define PG8_WAIT_V(n) asm volatile("s_waitcnt vmcnt(" #n ")" ::: "memory")
; #define PG8_WAIT_L(n) asm volatile("s_waitcnt lgkmcnt(" #n ")" ::: "memory")
; #define PG8_BAR __builtin_amdgcn_s_barrier()
; #define PG8_SCHED __builtin_amdgcn_sched_barrier(0)
; template <class Epi, class Sched, bool ALIGN_EPI = false, bool SP2 = false>
; __device__ __forceinline__ void gemm_phase(PG8_LAS unsigned char* lds, const Gemm g, const Sched& S, const Epi& E) {
;     ...
;             PG8_WAIT_V(8); PG8_WAIT_L(0); PG8_BAR; PG8_MMA(1, 0, At, B0); PG8_MMA(1, 1, At, B1); PG8_BAR; PG8_SCHED;
;             PG8_LDB(B0, 1, 0); PG8_LDB(B1, 1, 1); PG8_SCHED; PG8_LDA(At, 1, 0); PG8_STAGE(PG8_SA(0, 1), a2 + hstep, voffA);
;             PG8_WAIT_V(8); PG8_WAIT_L(0); PG8_BAR; PG8_MMA(0, 0, At, B0); PG8_MMA(0, 1, At, B1); PG8_BAR; PG8_SCHED;
;             PG8_LDA(At, 1, 1); PG8_STAGE(PG8_SB(1, 0), b3, voffB); PG8_STAGE(PG8_SB(1, 1), b3 + hstep, voffB); PG8_STAGE(PG8_SA(1, 0), a3, voffA);
	s_setprio 1
	s_waitcnt lgkmcnt(0)
	v_mfma_f32_16x16x32_bf16 v[60:63], v[152:155], v[184:187], 0
	v_mfma_f32_16x16x32_bf16 v[52:55], v[160:163], v[184:187], 0
	v_mfma_f32_16x16x32_bf16 v[44:47], v[152:155], v[192:195], 0
	v_mfma_f32_16x16x32_bf16 v[36:39], v[160:163], v[192:195], 0
	v_mfma_f32_16x16x32_bf16 v[28:31], v[152:155], v[200:203], 0
	v_mfma_f32_16x16x32_bf16 v[20:23], v[160:163], v[200:203], 0
	v_mfma_f32_16x16x32_bf16 v[12:15], v[152:155], v[208:211], 0
	v_mfma_f32_16x16x32_bf16 v[4:7], v[160:163], v[208:211], 0
	v_mfma_f32_16x16x32_bf16 v[60:63], v[156:159], v[188:191], v[60:63]
	v_mfma_f32_16x16x32_bf16 v[52:55], v[164:167], v[188:191], v[52:55]
	v_mfma_f32_16x16x32_bf16 v[44:47], v[156:159], v[196:199], v[44:47]
	v_mfma_f32_16x16x32_bf16 v[36:39], v[164:167], v[196:199], v[36:39]
	v_mfma_f32_16x16x32_bf16 v[28:31], v[156:159], v[204:207], v[28:31]
	v_mfma_f32_16x16x32_bf16 v[20:23], v[164:167], v[204:207], v[20:23]
	v_mfma_f32_16x16x32_bf16 v[12:15], v[156:159], v[212:215], v[12:15]
	v_mfma_f32_16x16x32_bf16 v[4:7], v[164:167], v[212:215], v[4:7]
	s_setprio 0
	s_setprio 1
	v_mfma_f32_16x16x32_bf16 v[56:59], v[168:171], v[184:187], 0
	v_mfma_f32_16x16x32_bf16 v[48:51], v[176:179], v[184:187], 0
	v_mfma_f32_16x16x32_bf16 v[40:43], v[168:171], v[192:195], 0
	v_mfma_f32_16x16x32_bf16 v[32:35], v[176:179], v[192:195], 0
	v_mfma_f32_16x16x32_bf16 v[24:27], v[168:171], v[200:203], 0
	v_mfma_f32_16x16x32_bf16 v[16:19], v[176:179], v[200:203], 0
	v_mfma_f32_16x16x32_bf16 v[8:11], v[168:171], v[208:211], 0
	v_mfma_f32_16x16x32_bf16 v[0:3], v[176:179], v[208:211], 0
	v_mfma_f32_16x16x32_bf16 v[56:59], v[172:175], v[188:191], v[56:59]
	v_mfma_f32_16x16x32_bf16 v[48:51], v[180:183], v[188:191], v[48:51]
	v_mfma_f32_16x16x32_bf16 v[40:43], v[172:175], v[196:199], v[40:43]
	v_mfma_f32_16x16x32_bf16 v[32:35], v[180:183], v[196:199], v[32:35]
	v_mfma_f32_16x16x32_bf16 v[24:27], v[172:175], v[204:207], v[24:27]
	v_mfma_f32_16x16x32_bf16 v[16:19], v[180:183], v[204:207], v[16:19]
	v_mfma_f32_16x16x32_bf16 v[8:11], v[172:175], v[212:215], v[8:11]
	v_mfma_f32_16x16x32_bf16 v[0:3], v[180:183], v[212:215], v[0:3]
	s_setprio 0
	s_barrier
	s_add_i32 s55, 0, 0x18000
	v_add_u32_e32 v151, s55, v145
	s_add_i32 s56, 0, 0x1c000
	ds_read_b128 v[152:155], v151
	ds_read_b128 v[156:159], v151 offset:1024
	ds_read_b128 v[160:163], v151 offset:2048
	ds_read_b128 v[164:167], v151 offset:3072
	v_add_u32_e32 v151, s56, v145
	ds_read_b128 v[168:171], v151
	ds_read_b128 v[172:175], v151 offset:1024
	ds_read_b128 v[176:179], v151 offset:2048
	ds_read_b128 v[180:183], v151 offset:3072
	s_add_u32 s40, s40, s12
	s_addc_u32 s41, s41, s13
	s_mov_b32 m0, s19
	v_lshl_add_u64 v[228:229], s[40:41], 0, v[134:135]
	ds_read_b128 v[184:187], v150 offset:32768
	ds_read_b128 v[188:191], v150 offset:33792
	ds_read_b128 v[192:195], v150 offset:34816
	ds_read_b128 v[196:199], v150 offset:35840
	ds_read_b128 v[200:203], v150 offset:36864
	ds_read_b128 v[204:207], v150 offset:37888
	ds_read_b128 v[208:211], v150 offset:38912
	ds_read_b128 v[212:215], v150 offset:39936
	global_load_lds_dwordx4 v[228:229], off
	v_lshl_add_u64 v[228:229], s[40:41], 0, v[130:131]
	s_mov_b32 m0, s26
	s_nop 0
	global_load_lds_dwordx4 v[228:229], off
	s_waitcnt vmcnt(8)
	s_waitcnt lgkmcnt(0)
	s_barrier
	s_setprio 1
	s_waitcnt lgkmcnt(0)
	v_mfma_f32_16x16x32_bf16 v[120:123], v[152:155], v[184:187], v[120:123]
	v_mfma_f32_16x16x32_bf16 v[116:119], v[160:163], v[184:187], v[116:119]
	v_mfma_f32_16x16x32_bf16 v[108:111], v[152:155], v[192:195], v[108:111]
	v_mfma_f32_16x16x32_bf16 v[100:103], v[160:163], v[192:195], v[100:103]
	v_mfma_f32_16x16x32_bf16 v[92:95], v[152:155], v[200:203], v[92:95]
	v_mfma_f32_16x16x32_bf16 v[84:87], v[160:163], v[200:203], v[84:87]
	v_mfma_f32_16x16x32_bf16 v[76:79], v[152:155], v[208:211], v[76:79]
	v_mfma_f32_16x16x32_bf16 v[68:71], v[160:163], v[208:211], v[68:71]
	v_mfma_f32_16x16x32_bf16 v[120:123], v[156:159], v[188:191], v[120:123]
	v_mfma_f32_16x16x32_bf16 v[116:119], v[164:167], v[188:191], v[116:119]
	v_mfma_f32_16x16x32_bf16 v[108:111], v[156:159], v[196:199], v[108:111]
	v_mfma_f32_16x16x32_bf16 v[100:103], v[164:167], v[196:199], v[100:103]
	v_mfma_f32_16x16x32_bf16 v[92:95], v[156:159], v[204:207], v[92:95]
	v_mfma_f32_16x16x32_bf16 v[84:87], v[164:167], v[204:207], v[84:87]
	v_mfma_f32_16x16x32_bf16 v[76:79], v[156:159], v[212:215], v[76:79]
	v_mfma_f32_16x16x32_bf16 v[68:71], v[164:167], v[212:215], v[68:71]
	s_setprio 0
	s_setprio 1
	v_mfma_f32_16x16x32_bf16 v[124:127], v[168:171], v[184:187], v[124:127]
	v_mfma_f32_16x16x32_bf16 v[112:115], v[176:179], v[184:187], v[112:115]
	v_mfma_f32_16x16x32_bf16 v[104:107], v[168:171], v[192:195], v[104:107]
	v_mfma_f32_16x16x32_bf16 v[96:99], v[176:179], v[192:195], v[96:99]
	v_mfma_f32_16x16x32_bf16 v[88:91], v[168:171], v[200:203], v[88:91]
	v_mfma_f32_16x16x32_bf16 v[80:83], v[176:179], v[200:203], v[80:83]
	v_mfma_f32_16x16x32_bf16 v[72:75], v[168:171], v[208:211], v[72:75]
	v_mfma_f32_16x16x32_bf16 v[64:67], v[176:179], v[208:211], v[64:67]
	v_mfma_f32_16x16x32_bf16 v[124:127], v[172:175], v[188:191], v[124:127]
	v_mfma_f32_16x16x32_bf16 v[112:115], v[180:183], v[188:191], v[112:115]
	v_mfma_f32_16x16x32_bf16 v[104:107], v[172:175], v[196:199], v[104:107]
	v_mfma_f32_16x16x32_bf16 v[96:99], v[180:183], v[196:199], v[96:99]
	v_mfma_f32_16x16x32_bf16 v[88:91], v[172:175], v[204:207], v[88:91]
	v_mfma_f32_16x16x32_bf16 v[80:83], v[180:183], v[204:207], v[80:83]
	v_mfma_f32_16x16x32_bf16 v[72:75], v[172:175], v[212:215], v[72:75]
	v_mfma_f32_16x16x32_bf16 v[64:67], v[180:183], v[212:215], v[64:67]
	s_setprio 0
	s_barrier
; #define PG8_STAGE(bufoff, gbase, voff) do { _Pragma("unroll") for (int _i = 0; _i < 2; ++_i) \
;         __builtin_amdgcn_global_load_lds((const unsigned*)((const char*)(gbase) + (voff)[_i]), (PG8_LAS unsigned*)(lds + (bufoff) + ldsw + _i * 8192), 16, 0, 0); } while (0)
; #define PG8_LDA(dst, b, h) do { _Pragma("unroll") for (int m = 0; m < 4; ++m) _Pragma("unroll") for (int k = 0; k < 2; ++k) dst[m][k] = *(const PG8_LAS bf16x8*)(lds + PG8_SA(b, h) + aoff + m * 2048 + k * 1024); } while (0)
; #define PG8_MMA(ai, bj, At, Bt) do { __builtin_amdgcn_s_setprio(1); _Pragma("unroll") for (int m = 0; m < 4; ++m) _Pragma("unroll") for (int n = 0; n < 2; ++n) _Pragma("unroll") for (int k = 0; k < 2; ++k) \
;         acc[ai][bj][m][n] = __builtin_amdgcn_mfma_f32_16x16x32_bf16(Bt[n][k], At[m][k], acc[ai][bj][m][n], 0, 0, 0); __builtin_amdgcn_s_setprio(0); } while (0)
; #define PG8_WAIT_V(n) asm volatile("s_waitcnt vmcnt(" #n ")" ::: "memory")
; #define PG8_WAIT_L(n) asm volatile("s_waitcnt lgkmcnt(" #n ")" ::: "memory")
; #define PG8_BAR __builtin_amdgcn_s_barrier()
; #define PG8_SCHED __builtin_amdgcn_sched_barrier(0)
; template <class Epi, class Sched, bool ALIGN_EPI = false, bool SP2 = false>
; __device__ __forceinline__ void gemm_phase(PG8_LAS unsigned char* lds, const Gemm g, const Sched& S, const Epi& E) {
;     ...
;         for (int t = 0; t < nt; t += 2) {
;             const bool last = (t == nt - 2);
;             const char* a1 = cA + (size_t)(t + 1) * kstep;
;             const char* a2 = last ? nA : cA + (size_t)(t + 2) * kstep; const char* b2 = last ? nB : cB + (size_t)(t + 2) * kstep;
;     ...
;             PG8_LDA(At, 1, 1); PG8_STAGE(PG8_SB(1, 0), b3, voffB); PG8_STAGE(PG8_SB(1, 1), b3 + hstep, voffB); PG8_STAGE(PG8_SA(1, 0), a3, voffA);
;             PG8_WAIT_V(8); PG8_WAIT_L(0); PG8_BAR; PG8_MMA(1, 0, At, B0); PG8_MMA(1, 1, At, B1); PG8_BAR; PG8_SCHED;
	s_add_i32 s40, s55, s3
	v_lshl_add_u64 v[216:217], v[216:217], 0, s[30:31]
	s_mov_b32 m0, s40
	ds_read_b128 v[184:187], v150 offset:49152
	ds_read_b128 v[188:191], v150 offset:50176
	ds_read_b128 v[192:195], v150 offset:51200
	ds_read_b128 v[196:199], v150 offset:52224
	ds_read_b128 v[200:203], v150 offset:53248
	ds_read_b128 v[204:207], v150 offset:54272
	ds_read_b128 v[208:211], v150 offset:55296
	ds_read_b128 v[212:215], v150 offset:56320
	global_load_lds_dwordx4 v[216:217], off
	v_lshl_add_u64 v[216:217], v[218:219], 0, s[30:31]
	s_add_i32 m0, s40, 0x2000
	s_add_i32 s40, s56, s3
	global_load_lds_dwordx4 v[216:217], off
	v_lshl_add_u64 v[216:217], v[220:221], 0, s[30:31]
	s_mov_b32 m0, s40
	s_nop 0
	global_load_lds_dwordx4 v[216:217], off
	v_lshl_add_u64 v[216:217], v[222:223], 0, s[30:31]
	s_add_i32 m0, s40, 0x2000
	s_nop 0
	global_load_lds_dwordx4 v[216:217], off
	v_lshl_add_u64 v[216:217], v[224:225], 0, s[30:31]
	s_mov_b32 m0, s27
	s_nop 0
	global_load_lds_dwordx4 v[216:217], off
	v_lshl_add_u64 v[216:217], v[226:227], 0, s[30:31]
	s_mov_b32 m0, s33
	s_nop 0
	global_load_lds_dwordx4 v[216:217], off
	s_waitcnt vmcnt(8)
	s_waitcnt lgkmcnt(0)
	s_barrier
	s_setprio 1
	s_waitcnt lgkmcnt(0)
	v_mfma_f32_16x16x32_bf16 v[60:63], v[152:155], v[184:187], v[60:63]
	v_mfma_f32_16x16x32_bf16 v[52:55], v[160:163], v[184:187], v[52:55]
	v_mfma_f32_16x16x32_bf16 v[44:47], v[152:155], v[192:195], v[44:47]
	v_mfma_f32_16x16x32_bf16 v[36:39], v[160:163], v[192:195], v[36:39]
	v_mfma_f32_16x16x32_bf16 v[28:31], v[152:155], v[200:203], v[28:31]
	v_mfma_f32_16x16x32_bf16 v[20:23], v[160:163], v[200:203], v[20:23]
	v_mfma_f32_16x16x32_bf16 v[12:15], v[152:155], v[208:211], v[12:15]
	v_mfma_f32_16x16x32_bf16 v[4:7], v[160:163], v[208:211], v[4:7]
	v_mfma_f32_16x16x32_bf16 v[60:63], v[156:159], v[188:191], v[60:63]
	v_mfma_f32_16x16x32_bf16 v[52:55], v[164:167], v[188:191], v[52:55]
	v_mfma_f32_16x16x32_bf16 v[44:47], v[156:159], v[196:199], v[44:47]
	v_mfma_f32_16x16x32_bf16 v[36:39], v[164:167], v[196:199], v[36:39]
	v_mfma_f32_16x16x32_bf16 v[28:31], v[156:159], v[204:207], v[28:31]
	v_mfma_f32_16x16x32_bf16 v[20:23], v[164:167], v[204:207], v[20:23]
	v_mfma_f32_16x16x32_bf16 v[12:15], v[156:159], v[212:215], v[12:15]
	v_mfma_f32_16x16x32_bf16 v[4:7], v[164:167], v[212:215], v[4:7]
	s_setprio 0
	s_setprio 1
	v_mfma_f32_16x16x32_bf16 v[56:59], v[168:171], v[184:187], v[56:59]
	v_mfma_f32_16x16x32_bf16 v[48:51], v[176:179], v[184:187], v[48:51]
	v_mfma_f32_16x16x32_bf16 v[40:43], v[168:171], v[192:195], v[40:43]
	v_mfma_f32_16x16x32_bf16 v[32:35], v[176:179], v[192:195], v[32:35]
	v_mfma_f32_16x16x32_bf16 v[24:27], v[168:171], v[200:203], v[24:27]
	v_mfma_f32_16x16x32_bf16 v[16:19], v[176:179], v[200:203], v[16:19]
	v_mfma_f32_16x16x32_bf16 v[8:11], v[168:171], v[208:211], v[8:11]
	v_mfma_f32_16x16x32_bf16 v[0:3], v[176:179], v[208:211], v[0:3]
	v_mfma_f32_16x16x32_bf16 v[56:59], v[172:175], v[188:191], v[56:59]
	v_mfma_f32_16x16x32_bf16 v[48:51], v[180:183], v[188:191], v[48:51]
	v_mfma_f32_16x16x32_bf16 v[40:43], v[172:175], v[196:199], v[40:43]
	v_mfma_f32_16x16x32_bf16 v[32:35], v[180:183], v[196:199], v[32:35]
	v_mfma_f32_16x16x32_bf16 v[24:27], v[172:175], v[204:207], v[24:27]
	v_mfma_f32_16x16x32_bf16 v[16:19], v[180:183], v[204:207], v[16:19]
	v_mfma_f32_16x16x32_bf16 v[8:11], v[172:175], v[212:215], v[8:11]
	v_mfma_f32_16x16x32_bf16 v[0:3], v[180:183], v[212:215], v[0:3]
	s_setprio 0
	s_barrier
	s_add_u32 s38, s38, 0x100
	s_addc_u32 s39, s39, 0
	s_add_u32 s24, s24, 0x100
	s_addc_u32 s25, s25, 0
	s_cmp_ge_i32 s54, s42
	s_mov_b32 s40, s54
	s_cbranch_scc1 .Lpeelx_0

; #define PG8_BAR __builtin_amdgcn_s_barrier()
; template <class Epi, class Sched, bool ALIGN_EPI = false, bool SP2 = false>
; __device__ __forceinline__ void gemm_phase(PG8_LAS unsigned char* lds, const Gemm g, const Sched& S, const Epi& E) {
;     ...
;         if constexpr (ALIGN_EPI) { if (wr == 0) PG8_BAR; }
;         if constexpr (!Epi::AFTER_DRAIN) { E(acc, cur, wr, wc, fr, fq); S.done(cur); }
.Lpeelx_0:
.LBB0_350:
	s_and_b64 vcc, exec, s[34:35]
	s_cbranch_vccz .LBB0_352
	s_barrier

; #define PG8_BAR __builtin_amdgcn_s_barrier()
; template <class Epi, class Sched, bool ALIGN_EPI = false, bool SP2 = false>
; __device__ __forceinline__ void gemm_phase(PG8_LAS unsigned char* lds, const Gemm g, const Sched& S, const Epi& E) {
;     ...
;         if constexpr (ALIGN_EPI) { if (wr == 0) PG8_BAR; }
;         if constexpr (!Epi::AFTER_DRAIN) { E(acc, cur, wr, wc, fr, fq); S.done(cur); }
;     ...
; #pragma unroll
;         for (int a = 0; a < 2; ++a)
; #pragma unroll
;             for (int b = 0; b < 2; ++b)
; #pragma unroll
;                 for (int m = 0; m < 4; ++m)
; #pragma unroll
;                     for (int n = 0; n < 2; ++n) acc[a][b][m][n] = (f32x4){0.f, 0.f, 0.f, 0.f};
.Lcoldz_1:
	v_mov_b32_e32 v223, 0
	v_mov_b32_e32 v222, 0
	v_mov_b32_e32 v221, 0
	v_mov_b32_e32 v220, 0
	v_mov_b32_e32 v219, 0
	v_mov_b32_e32 v218, 0
	v_mov_b32_e32 v217, 0
	v_mov_b32_e32 v216, 0
	v_mov_b32_e32 v203, 0
	v_mov_b32_e32 v202, 0
	v_mov_b32_e32 v201, 0
	v_mov_b32_e32 v200, 0
	v_mov_b32_e32 v199, 0
	v_mov_b32_e32 v198, 0
	v_mov_b32_e32 v197, 0
	v_mov_b32_e32 v196, 0
	v_mov_b32_e32 v183, 0
	v_mov_b32_e32 v182, 0
	v_mov_b32_e32 v181, 0
	v_mov_b32_e32 v180, 0
	v_mov_b32_e32 v179, 0
	v_mov_b32_e32 v178, 0
	v_mov_b32_e32 v177, 0
	v_mov_b32_e32 v176, 0
	v_mov_b32_e32 v163, 0
	v_mov_b32_e32 v162, 0
	v_mov_b32_e32 v161, 0
	v_mov_b32_e32 v160, 0
	v_mov_b32_e32 v159, 0
	v_mov_b32_e32 v158, 0
	v_mov_b32_e32 v157, 0
	v_mov_b32_e32 v156, 0
	v_mov_b32_e32 v215, 0
	v_mov_b32_e32 v214, 0
	v_mov_b32_e32 v213, 0
	v_mov_b32_e32 v212, 0
	v_mov_b32_e32 v211, 0
	v_mov_b32_e32 v210, 0
	v_mov_b32_e32 v209, 0
	v_mov_b32_e32 v208, 0
	v_mov_b32_e32 v195, 0
	v_mov_b32_e32 v194, 0
	v_mov_b32_e32 v193, 0
	v_mov_b32_e32 v192, 0
	v_mov_b32_e32 v191, 0
	v_mov_b32_e32 v190, 0
	v_mov_b32_e32 v189, 0
	v_mov_b32_e32 v188, 0
	v_mov_b32_e32 v175, 0
	v_mov_b32_e32 v174, 0
	v_mov_b32_e32 v173, 0
	v_mov_b32_e32 v172, 0
	v_mov_b32_e32 v171, 0
	v_mov_b32_e32 v170, 0
	v_mov_b32_e32 v169, 0
	v_mov_b32_e32 v168, 0
	v_mov_b32_e32 v155, 0
	v_mov_b32_e32 v154, 0
	v_mov_b32_e32 v153, 0
	v_mov_b32_e32 v152, 0
	v_mov_b32_e32 v151, 0
	v_mov_b32_e32 v150, 0
	v_mov_b32_e32 v149, 0
	v_mov_b32_e32 v148, 0
	v_mov_b32_e32 v143, 0
	v_mov_b32_e32 v142, 0
	v_mov_b32_e32 v127, 0
	v_mov_b32_e32 v126, 0
	v_mov_b32_e32 v125, 0
	v_mov_b32_e32 v124, 0
	v_mov_b32_e32 v123, 0
	v_mov_b32_e32 v122, 0
	v_mov_b32_e32 v111, 0
	v_mov_b32_e32 v110, 0
	v_mov_b32_e32 v109, 0
	v_mov_b32_e32 v108, 0
	v_mov_b32_e32 v107, 0
	v_mov_b32_e32 v106, 0
	v_mov_b32_e32 v105, 0
	v_mov_b32_e32 v104, 0
	v_mov_b32_e32 v95, 0
	v_mov_b32_e32 v94, 0
	v_mov_b32_e32 v93, 0
	v_mov_b32_e32 v92, 0
	v_mov_b32_e32 v91, 0
	v_mov_b32_e32 v90, 0
	v_mov_b32_e32 v89, 0
	v_mov_b32_e32 v88, 0
	v_mov_b32_e32 v79, 0
	v_mov_b32_e32 v78, 0
	v_mov_b32_e32 v77, 0
	v_mov_b32_e32 v76, 0
	v_mov_b32_e32 v75, 0
	v_mov_b32_e32 v74, 0
	v_mov_b32_e32 v73, 0
	v_mov_b32_e32 v72, 0
	v_mov_b32_e32 v121, 0
	v_mov_b32_e32 v120, 0
	v_mov_b32_e32 v119, 0
	v_mov_b32_e32 v118, 0
	v_mov_b32_e32 v117, 0
	v_mov_b32_e32 v116, 0
	v_mov_b32_e32 v115, 0
	v_mov_b32_e32 v114, 0
	v_mov_b32_e32 v103, 0
	v_mov_b32_e32 v102, 0
	v_mov_b32_e32 v101, 0
	v_mov_b32_e32 v100, 0
	v_mov_b32_e32 v99, 0
	v_mov_b32_e32 v98, 0
	v_mov_b32_e32 v97, 0
	v_mov_b32_e32 v96, 0
	v_mov_b32_e32 v87, 0
	v_mov_b32_e32 v86, 0
	v_mov_b32_e32 v85, 0
	v_mov_b32_e32 v84, 0
	v_mov_b32_e32 v83, 0
	v_mov_b32_e32 v82, 0
	v_mov_b32_e32 v81, 0
	v_mov_b32_e32 v80, 0
	v_mov_b32_e32 v71, 0
	v_mov_b32_e32 v70, 0
	v_mov_b32_e32 v69, 0
	v_mov_b32_e32 v68, 0
	v_mov_b32_e32 v67, 0
	v_mov_b32_e32 v66, 0
	v_mov_b32_e32 v65, 0
	v_mov_b32_e32 v64, 0
	s_branch .LBB0_434

; #define PG8_STAGE(bufoff, gbase, voff) do { _Pragma("unroll") for (int _i = 0; _i < 2; ++_i) \
;         __builtin_amdgcn_global_load_lds((const unsigned*)((const char*)(gbase) + (voff)[_i]), (PG8_LAS unsigned*)(lds + (bufoff) + ldsw + _i * 8192), 16, 0, 0); } while (0)
; #define PG8_LDA(dst, b, h) do { _Pragma("unroll") for (int m = 0; m < 4; ++m) _Pragma("unroll") for (int k = 0; k < 2; ++k) dst[m][k] = *(const PG8_LAS bf16x8*)(lds + PG8_SA(b, h) + aoff + m * 2048 + k * 1024); } while (0)
; #define PG8_LDB(dst, b, h) do { _Pragma("unroll") for (int n = 0; n < 2; ++n) _Pragma("unroll") for (int k = 0; k < 2; ++k) dst[n][k] = *(const PG8_LAS bf16x8*)(lds + PG8_SB(b, h) + boff + n * 2048 + k * 1024); } while (0)
; #define PG8_MMA(ai, bj, At, Bt) do { __builtin_amdgcn_s_setprio(1); _Pragma("unroll") for (int m = 0; m < 4; ++m) _Pragma("unroll") for (int n = 0; n < 2; ++n) _Pragma("unroll") for (int k = 0; k < 2; ++k) \
;         acc[ai][bj][m][n] = __builtin_amdgcn_mfma_f32_16x16x32_bf16(Bt[n][k], At[m][k], acc[ai][bj][m][n], 0, 0, 0); __builtin_amdgcn_s_setprio(0); } while (0)
; #define PG8_WAIT_V(n) asm volatile("s_waitcnt vmcnt(" #n ")" ::: "memory")
; #define PG8_BAR __builtin_amdgcn_s_barrier()
; template <class Epi, class Sched, bool ALIGN_EPI = false, bool SP2 = false>
; __device__ __forceinline__ void gemm_phase(PG8_LAS unsigned char* lds, const Gemm g, const Sched& S, const Epi& E) {
;     ...
;         for (int t = 0; t < nt; t += 2) {
;             const bool last = (t == nt - 2);
;             const char* a1 = cA + (size_t)(t + 1) * kstep;
;             const char* a2 = last ? nA : cA + (size_t)(t + 2) * kstep; const char* b2 = last ? nB : cB + (size_t)(t + 2) * kstep;
;             const char* a3 = a2 + kstep; const char* b3 = b2 + kstep;
;             if (last && has_next) S.a_ready(nxt);
;             if constexpr (SP2) {
;             PG8_LDB(B0, 0, 0); PG8_LDB(B1, 0, 1); PG8_SCHED; PG8_LDA(At, 0, 0); PG8_STAGE(PG8_SA(1, 1), a1 + hstep, voffA);
;             PG8_WAIT_V(8); PG8_WAIT_L(0); PG8_BAR; PG8_MMA(0, 0, At, B0); PG8_MMA(0, 1, At, B1); PG8_BAR; PG8_SCHED;
;             PG8_LDA(At, 0, 1); PG8_STAGE(PG8_SB(0, 0), b2, voffB); PG8_STAGE(PG8_SB(0, 1), b2 + hstep, voffB); PG8_STAGE(PG8_SA(0, 0), a2, voffA);
;             PG8_WAIT_V(8); PG8_WAIT_L(0); PG8_BAR; PG8_MMA(1, 0, At, B0); PG8_MMA(1, 1, At, B1); PG8_BAR; PG8_SCHED;
.LBB0_430:
	s_and_b64 vcc, exec, s[10:11]
	s_cbranch_vccnz .Lcoldz_1
	s_add_u32 s46, s46, 0x80
	s_addc_u32 s47, s47, 0
	s_add_u32 s2, s48, 0x100
	s_addc_u32 s24, s49, 0
	s_mov_b32 s25, 0
	ds_read_b128 v[142:145], v246
	ds_read_b128 v[146:149], v246 offset:1024
	ds_read_b128 v[150:153], v246 offset:2048
	ds_read_b128 v[154:157], v246 offset:3072
	ds_read_b128 v[158:161], v247
	ds_read_b128 v[162:165], v247 offset:1024
	ds_read_b128 v[166:169], v247 offset:2048
	ds_read_b128 v[170:173], v247 offset:3072
	s_add_i32 s56, s25, 2
	s_add_u32 s48, s46, 0x80
	s_addc_u32 s49, s47, 0
	s_cmp_eq_u32 s50, s25
	s_cselect_b32 s49, s15, s49
	s_cselect_b32 s48, s14, s48
	s_cselect_b32 s61, s45, s24
	s_cselect_b32 s60, s44, s2
	v_lshl_add_u64 v[206:207], s[46:47], 0, v[136:137]
	s_add_i32 m0, s7, 0xc000
	ds_read_b128 v[174:177], v248
	ds_read_b128 v[178:181], v248 offset:1024
	ds_read_b128 v[182:185], v248 offset:2048
	ds_read_b128 v[186:189], v248 offset:3072
	ds_read_b128 v[190:193], v248 offset:4096
	ds_read_b128 v[194:197], v248 offset:5120
	ds_read_b128 v[198:201], v248 offset:6144
	ds_read_b128 v[202:205], v248 offset:7168
	global_load_lds_dwordx4 v[206:207], off
	v_lshl_add_u64 v[206:207], s[46:47], 0, v[138:139]
	s_add_i32 m0, s7, 0xe000
	s_nop 0
	global_load_lds_dwordx4 v[206:207], off
	s_waitcnt vmcnt(8)
	s_waitcnt lgkmcnt(0)
	s_barrier
	s_setprio 1
	s_waitcnt lgkmcnt(0)
	v_mfma_f32_16x16x32_bf16 v[124:127], v[142:145], v[174:177], 0
	v_mfma_f32_16x16x32_bf16 v[120:123], v[150:153], v[174:177], 0
	v_mfma_f32_16x16x32_bf16 v[116:119], v[142:145], v[182:185], 0
	v_mfma_f32_16x16x32_bf16 v[112:115], v[150:153], v[182:185], 0
	v_mfma_f32_16x16x32_bf16 v[104:107], v[142:145], v[190:193], 0
	v_mfma_f32_16x16x32_bf16 v[96:99], v[150:153], v[190:193], 0
	v_mfma_f32_16x16x32_bf16 v[88:91], v[142:145], v[198:201], 0
	v_mfma_f32_16x16x32_bf16 v[80:83], v[150:153], v[198:201], 0
	v_mfma_f32_16x16x32_bf16 v[124:127], v[146:149], v[178:181], v[124:127]
	v_mfma_f32_16x16x32_bf16 v[120:123], v[154:157], v[178:181], v[120:123]
	v_mfma_f32_16x16x32_bf16 v[116:119], v[146:149], v[186:189], v[116:119]
	v_mfma_f32_16x16x32_bf16 v[112:115], v[154:157], v[186:189], v[112:115]
	v_mfma_f32_16x16x32_bf16 v[104:107], v[146:149], v[194:197], v[104:107]
	v_mfma_f32_16x16x32_bf16 v[96:99], v[154:157], v[194:197], v[96:99]
	v_mfma_f32_16x16x32_bf16 v[88:91], v[146:149], v[202:205], v[88:91]
	v_mfma_f32_16x16x32_bf16 v[80:83], v[154:157], v[202:205], v[80:83]
	s_setprio 0
	s_setprio 1
	v_mfma_f32_16x16x32_bf16 v[108:111], v[158:161], v[174:177], 0
	v_mfma_f32_16x16x32_bf16 v[100:103], v[166:169], v[174:177], 0
	v_mfma_f32_16x16x32_bf16 v[92:95], v[158:161], v[182:185], 0
	v_mfma_f32_16x16x32_bf16 v[84:87], v[166:169], v[182:185], 0
	v_mfma_f32_16x16x32_bf16 v[76:79], v[158:161], v[190:193], 0
	v_mfma_f32_16x16x32_bf16 v[72:75], v[166:169], v[190:193], 0
	v_mfma_f32_16x16x32_bf16 v[68:71], v[158:161], v[198:201], 0
	v_mfma_f32_16x16x32_bf16 v[64:67], v[166:169], v[198:201], 0
	v_mfma_f32_16x16x32_bf16 v[108:111], v[162:165], v[178:181], v[108:111]
	v_mfma_f32_16x16x32_bf16 v[100:103], v[170:173], v[178:181], v[100:103]
	v_mfma_f32_16x16x32_bf16 v[92:95], v[162:165], v[186:189], v[92:95]
	v_mfma_f32_16x16x32_bf16 v[84:87], v[170:173], v[186:189], v[84:87]
	v_mfma_f32_16x16x32_bf16 v[76:79], v[162:165], v[194:197], v[76:79]
	v_mfma_f32_16x16x32_bf16 v[72:75], v[170:173], v[194:197], v[72:75]
	v_mfma_f32_16x16x32_bf16 v[68:71], v[162:165], v[202:205], v[68:71]
	v_mfma_f32_16x16x32_bf16 v[64:67], v[170:173], v[202:205], v[64:67]
	s_setprio 0
	s_barrier
	s_add_i32 s25, s51, s6
	v_lshl_add_u64 v[206:207], s[60:61], 0, v[130:131]
	s_mov_b32 m0, s25
	ds_read_b128 v[174:177], v248 offset:16384
	ds_read_b128 v[178:181], v248 offset:17408
	ds_read_b128 v[182:185], v248 offset:18432
	ds_read_b128 v[186:189], v248 offset:19456
	ds_read_b128 v[190:193], v248 offset:20480
	ds_read_b128 v[194:197], v248 offset:21504
	ds_read_b128 v[198:201], v248 offset:22528
	ds_read_b128 v[202:205], v248 offset:23552
	global_load_lds_dwordx4 v[206:207], off
	s_add_i32 m0, s25, 0x2000
	v_lshl_add_u64 v[208:209], s[60:61], 0, v[134:135]
	s_add_u32 s60, s60, s30
	s_addc_u32 s61, s61, s31
	s_add_i32 s25, s52, s6
	global_load_lds_dwordx4 v[208:209], off
	v_lshl_add_u64 v[210:211], s[60:61], 0, v[130:131]
	s_mov_b32 m0, s25
	v_lshl_add_u64 v[212:213], s[60:61], 0, v[134:135]
	global_load_lds_dwordx4 v[210:211], off
	s_add_i32 m0, s25, 0x2000
	v_lshl_add_u64 v[214:215], s[48:49], 0, v[128:129]
	global_load_lds_dwordx4 v[212:213], off
	s_mov_b32 m0, s7
	v_lshl_add_u64 v[216:217], s[48:49], 0, v[132:133]
	global_load_lds_dwordx4 v[214:215], off
	s_mov_b32 m0, s16
	s_nop 0
	global_load_lds_dwordx4 v[216:217], off
	s_waitcnt vmcnt(8)
	s_waitcnt lgkmcnt(0)
	s_barrier
; #define PG8_STAGE(bufoff, gbase, voff) do { _Pragma("unroll") for (int _i = 0; _i < 2; ++_i) \
;         __builtin_amdgcn_global_load_lds((const unsigned*)((const char*)(gbase) + (voff)[_i]), (PG8_LAS unsigned*)(lds + (bufoff) + ldsw + _i * 8192), 16, 0, 0); } while (0)
; #define PG8_LDA(dst, b, h) do { _Pragma("unroll") for (int m = 0; m < 4; ++m) _Pragma("unroll") for (int k = 0; k < 2; ++k) dst[m][k] = *(const PG8_LAS bf16x8*)(lds + PG8_SA(b, h) + aoff + m * 2048 + k * 1024); } while (0)
; #define PG8_LDB(dst, b, h) do { _Pragma("unroll") for (int n = 0; n < 2; ++n) _Pragma("unroll") for (int k = 0; k < 2; ++k) dst[n][k] = *(const PG8_LAS bf16x8*)(lds + PG8_SB(b, h) + boff + n * 2048 + k * 1024); } while (0)
; #define PG8_MMA(ai, bj, At, Bt) do { __builtin_amdgcn_s_setprio(1); _Pragma("unroll") for (int m = 0; m < 4; ++m) _Pragma("unroll") for (int n = 0; n < 2; ++n) _Pragma("unroll") for (int k = 0; k < 2; ++k) \
;         acc[ai][bj][m][n] = __builtin_amdgcn_mfma_f32_16x16x32_bf16(Bt[n][k], At[m][k], acc[ai][bj][m][n], 0, 0, 0); __builtin_amdgcn_s_setprio(0); } while (0)
; #define PG8_WAIT_V(n) asm volatile("s_waitcnt vmcnt(" #n ")" ::: "memory")
; #define PG8_WAIT_L(n) asm volatile("s_waitcnt lgkmcnt(" #n ")" ::: "memory")
; #define PG8_BAR __builtin_amdgcn_s_barrier()
; #define PG8_SCHED __builtin_amdgcn_sched_barrier(0)
; template <class Epi, class Sched, bool ALIGN_EPI = false, bool SP2 = false>
; __device__ __forceinline__ void gemm_phase(PG8_LAS unsigned char* lds, const Gemm g, const Sched& S, const Epi& E) {
;     ...
;             PG8_WAIT_V(8); PG8_WAIT_L(0); PG8_BAR; PG8_MMA(1, 0, At, B0); PG8_MMA(1, 1, At, B1); PG8_BAR; PG8_SCHED;
;             PG8_LDB(B0, 1, 0); PG8_LDB(B1, 1, 1); PG8_SCHED; PG8_LDA(At, 1, 0); PG8_STAGE(PG8_SA(0, 1), a2 + hstep, voffA);
;             PG8_WAIT_V(8); PG8_WAIT_L(0); PG8_BAR; PG8_MMA(0, 0, At, B0); PG8_MMA(0, 1, At, B1); PG8_BAR; PG8_SCHED;
;             PG8_LDA(At, 1, 1); PG8_STAGE(PG8_SB(1, 0), b3, voffB); PG8_STAGE(PG8_SB(1, 1), b3 + hstep, voffB); PG8_STAGE(PG8_SA(1, 0), a3, voffA);
	s_setprio 1
	s_waitcnt lgkmcnt(0)
	v_mfma_f32_16x16x32_bf16 v[60:63], v[142:145], v[174:177], 0
	v_mfma_f32_16x16x32_bf16 v[56:59], v[150:153], v[174:177], 0
	v_mfma_f32_16x16x32_bf16 v[52:55], v[142:145], v[182:185], 0
	v_mfma_f32_16x16x32_bf16 v[48:51], v[150:153], v[182:185], 0
	v_mfma_f32_16x16x32_bf16 v[40:43], v[142:145], v[190:193], 0
	v_mfma_f32_16x16x32_bf16 v[32:35], v[150:153], v[190:193], 0
	v_mfma_f32_16x16x32_bf16 v[24:27], v[142:145], v[198:201], 0
	v_mfma_f32_16x16x32_bf16 v[16:19], v[150:153], v[198:201], 0
	v_mfma_f32_16x16x32_bf16 v[60:63], v[146:149], v[178:181], v[60:63]
	v_mfma_f32_16x16x32_bf16 v[56:59], v[154:157], v[178:181], v[56:59]
	v_mfma_f32_16x16x32_bf16 v[52:55], v[146:149], v[186:189], v[52:55]
	v_mfma_f32_16x16x32_bf16 v[48:51], v[154:157], v[186:189], v[48:51]
	v_mfma_f32_16x16x32_bf16 v[40:43], v[146:149], v[194:197], v[40:43]
	v_mfma_f32_16x16x32_bf16 v[32:35], v[154:157], v[194:197], v[32:35]
	v_mfma_f32_16x16x32_bf16 v[24:27], v[146:149], v[202:205], v[24:27]
	v_mfma_f32_16x16x32_bf16 v[16:19], v[154:157], v[202:205], v[16:19]
	s_setprio 0
	s_setprio 1
	v_mfma_f32_16x16x32_bf16 v[44:47], v[158:161], v[174:177], 0
	v_mfma_f32_16x16x32_bf16 v[36:39], v[166:169], v[174:177], 0
	v_mfma_f32_16x16x32_bf16 v[28:31], v[158:161], v[182:185], 0
	v_mfma_f32_16x16x32_bf16 v[20:23], v[166:169], v[182:185], 0
	v_mfma_f32_16x16x32_bf16 v[12:15], v[158:161], v[190:193], 0
	v_mfma_f32_16x16x32_bf16 v[8:11], v[166:169], v[190:193], 0
	v_mfma_f32_16x16x32_bf16 v[4:7], v[158:161], v[198:201], 0
	v_mfma_f32_16x16x32_bf16 v[0:3], v[166:169], v[198:201], 0
	v_mfma_f32_16x16x32_bf16 v[44:47], v[162:165], v[178:181], v[44:47]
	v_mfma_f32_16x16x32_bf16 v[36:39], v[170:173], v[178:181], v[36:39]
	v_mfma_f32_16x16x32_bf16 v[28:31], v[162:165], v[186:189], v[28:31]
	v_mfma_f32_16x16x32_bf16 v[20:23], v[170:173], v[186:189], v[20:23]
	v_mfma_f32_16x16x32_bf16 v[12:15], v[162:165], v[194:197], v[12:15]
	v_mfma_f32_16x16x32_bf16 v[8:11], v[170:173], v[194:197], v[8:11]
	v_mfma_f32_16x16x32_bf16 v[4:7], v[162:165], v[202:205], v[4:7]
	v_mfma_f32_16x16x32_bf16 v[0:3], v[170:173], v[202:205], v[0:3]
	s_setprio 0
	s_barrier
	s_add_i32 s25, 0, 0x18000
	s_add_i32 s57, 0, 0x1c000
	v_add_u32_e32 v154, s25, v244
	v_add_u32_e32 v170, s57, v244
	ds_read_b128 v[142:145], v154
	ds_read_b128 v[146:149], v154 offset:1024
	ds_read_b128 v[150:153], v154 offset:2048
	ds_read_b128 v[154:157], v154 offset:3072
	ds_read_b128 v[158:161], v170
	ds_read_b128 v[162:165], v170 offset:1024
	ds_read_b128 v[166:169], v170 offset:2048
	ds_read_b128 v[170:173], v170 offset:3072
	s_add_u32 s48, s48, s30
	s_addc_u32 s49, s49, s31
	s_mov_b32 m0, s17
	v_lshl_add_u64 v[218:219], s[48:49], 0, v[128:129]
	ds_read_b128 v[174:177], v248 offset:32768
	ds_read_b128 v[178:181], v248 offset:33792
	ds_read_b128 v[182:185], v248 offset:34816
	ds_read_b128 v[186:189], v248 offset:35840
	ds_read_b128 v[190:193], v248 offset:36864
	ds_read_b128 v[194:197], v248 offset:37888
	ds_read_b128 v[198:201], v248 offset:38912
	ds_read_b128 v[202:205], v248 offset:39936
	global_load_lds_dwordx4 v[218:219], off
	v_lshl_add_u64 v[218:219], s[48:49], 0, v[132:133]
	s_mov_b32 m0, s18
	s_nop 0
	global_load_lds_dwordx4 v[218:219], off
	s_waitcnt vmcnt(8)
	s_waitcnt lgkmcnt(0)
	s_barrier
	s_setprio 1
	s_waitcnt lgkmcnt(0)
	v_mfma_f32_16x16x32_bf16 v[124:127], v[142:145], v[174:177], v[124:127]
	v_mfma_f32_16x16x32_bf16 v[120:123], v[150:153], v[174:177], v[120:123]
	v_mfma_f32_16x16x32_bf16 v[116:119], v[142:145], v[182:185], v[116:119]
	v_mfma_f32_16x16x32_bf16 v[112:115], v[150:153], v[182:185], v[112:115]
	v_mfma_f32_16x16x32_bf16 v[104:107], v[142:145], v[190:193], v[104:107]
	v_mfma_f32_16x16x32_bf16 v[96:99], v[150:153], v[190:193], v[96:99]
	v_mfma_f32_16x16x32_bf16 v[88:91], v[142:145], v[198:201], v[88:91]
	v_mfma_f32_16x16x32_bf16 v[80:83], v[150:153], v[198:201], v[80:83]
	v_mfma_f32_16x16x32_bf16 v[124:127], v[146:149], v[178:181], v[124:127]
	v_mfma_f32_16x16x32_bf16 v[120:123], v[154:157], v[178:181], v[120:123]
	v_mfma_f32_16x16x32_bf16 v[116:119], v[146:149], v[186:189], v[116:119]
	v_mfma_f32_16x16x32_bf16 v[112:115], v[154:157], v[186:189], v[112:115]
	v_mfma_f32_16x16x32_bf16 v[104:107], v[146:149], v[194:197], v[104:107]
	v_mfma_f32_16x16x32_bf16 v[96:99], v[154:157], v[194:197], v[96:99]
	v_mfma_f32_16x16x32_bf16 v[88:91], v[146:149], v[202:205], v[88:91]
	v_mfma_f32_16x16x32_bf16 v[80:83], v[154:157], v[202:205], v[80:83]
	s_setprio 0
	s_setprio 1
	v_mfma_f32_16x16x32_bf16 v[108:111], v[158:161], v[174:177], v[108:111]
	v_mfma_f32_16x16x32_bf16 v[100:103], v[166:169], v[174:177], v[100:103]
	v_mfma_f32_16x16x32_bf16 v[92:95], v[158:161], v[182:185], v[92:95]
	v_mfma_f32_16x16x32_bf16 v[84:87], v[166:169], v[182:185], v[84:87]
	v_mfma_f32_16x16x32_bf16 v[76:79], v[158:161], v[190:193], v[76:79]
	v_mfma_f32_16x16x32_bf16 v[72:75], v[166:169], v[190:193], v[72:75]
	v_mfma_f32_16x16x32_bf16 v[68:71], v[158:161], v[198:201], v[68:71]
	v_mfma_f32_16x16x32_bf16 v[64:67], v[166:169], v[198:201], v[64:67]
	v_mfma_f32_16x16x32_bf16 v[108:111], v[162:165], v[178:181], v[108:111]
	v_mfma_f32_16x16x32_bf16 v[100:103], v[170:173], v[178:181], v[100:103]
	v_mfma_f32_16x16x32_bf16 v[92:95], v[162:165], v[186:189], v[92:95]
	v_mfma_f32_16x16x32_bf16 v[84:87], v[170:173], v[186:189], v[84:87]
	v_mfma_f32_16x16x32_bf16 v[76:79], v[162:165], v[194:197], v[76:79]
	v_mfma_f32_16x16x32_bf16 v[72:75], v[170:173], v[194:197], v[72:75]
	v_mfma_f32_16x16x32_bf16 v[68:71], v[162:165], v[202:205], v[68:71]
	v_mfma_f32_16x16x32_bf16 v[64:67], v[170:173], v[202:205], v[64:67]
	s_setprio 0
	s_barrier
; #define PG8_STAGE(bufoff, gbase, voff) do { _Pragma("unroll") for (int _i = 0; _i < 2; ++_i) \
;         __builtin_amdgcn_global_load_lds((const unsigned*)((const char*)(gbase) + (voff)[_i]), (PG8_LAS unsigned*)(lds + (bufoff) + ldsw + _i * 8192), 16, 0, 0); } while (0)
; #define PG8_LDA(dst, b, h) do { _Pragma("unroll") for (int m = 0; m < 4; ++m) _Pragma("unroll") for (int k = 0; k < 2; ++k) dst[m][k] = *(const PG8_LAS bf16x8*)(lds + PG8_SA(b, h) + aoff + m * 2048 + k * 1024); } while (0)
; #define PG8_MMA(ai, bj, At, Bt) do { __builtin_amdgcn_s_setprio(1); _Pragma("unroll") for (int m = 0; m < 4; ++m) _Pragma("unroll") for (int n = 0; n < 2; ++n) _Pragma("unroll") for (int k = 0; k < 2; ++k) \
;         acc[ai][bj][m][n] = __builtin_amdgcn_mfma_f32_16x16x32_bf16(Bt[n][k], At[m][k], acc[ai][bj][m][n], 0, 0, 0); __builtin_amdgcn_s_setprio(0); } while (0)
; #define PG8_WAIT_V(n) asm volatile("s_waitcnt vmcnt(" #n ")" ::: "memory")
; #define PG8_WAIT_L(n) asm volatile("s_waitcnt lgkmcnt(" #n ")" ::: "memory")
; #define PG8_BAR __builtin_amdgcn_s_barrier()
; #define PG8_SCHED __builtin_amdgcn_sched_barrier(0)
; template <class Epi, class Sched, bool ALIGN_EPI = false, bool SP2 = false>
; __device__ __forceinline__ void gemm_phase(PG8_LAS unsigned char* lds, const Gemm g, const Sched& S, const Epi& E) {
;     ...
;         for (int t = 0; t < nt; t += 2) {
;             const bool last = (t == nt - 2);
;             const char* a1 = cA + (size_t)(t + 1) * kstep;
;             const char* a2 = last ? nA : cA + (size_t)(t + 2) * kstep; const char* b2 = last ? nB : cB + (size_t)(t + 2) * kstep;
;     ...
;             PG8_LDA(At, 1, 1); PG8_STAGE(PG8_SB(1, 0), b3, voffB); PG8_STAGE(PG8_SB(1, 1), b3 + hstep, voffB); PG8_STAGE(PG8_SA(1, 0), a3, voffA);
;             PG8_WAIT_V(8); PG8_WAIT_L(0); PG8_BAR; PG8_MMA(1, 0, At, B0); PG8_MMA(1, 1, At, B1); PG8_BAR; PG8_SCHED;
	s_add_i32 s25, s25, s6
	v_lshl_add_u64 v[206:207], v[206:207], 0, s[40:41]
	s_mov_b32 m0, s25
	ds_read_b128 v[174:177], v248 offset:49152
	ds_read_b128 v[178:181], v248 offset:50176
	ds_read_b128 v[182:185], v248 offset:51200
	ds_read_b128 v[186:189], v248 offset:52224
	ds_read_b128 v[190:193], v248 offset:53248
	ds_read_b128 v[194:197], v248 offset:54272
	ds_read_b128 v[198:201], v248 offset:55296
	ds_read_b128 v[202:205], v248 offset:56320
	global_load_lds_dwordx4 v[206:207], off
	v_lshl_add_u64 v[206:207], v[208:209], 0, s[40:41]
	s_add_i32 m0, s25, 0x2000
	s_add_i32 s25, s57, s6
	global_load_lds_dwordx4 v[206:207], off
	v_lshl_add_u64 v[206:207], v[210:211], 0, s[40:41]
	s_mov_b32 m0, s25
	s_nop 0
	global_load_lds_dwordx4 v[206:207], off
	v_lshl_add_u64 v[206:207], v[212:213], 0, s[40:41]
	s_add_i32 m0, s25, 0x2000
	s_nop 0
	global_load_lds_dwordx4 v[206:207], off
	v_lshl_add_u64 v[206:207], v[214:215], 0, s[40:41]
	s_mov_b32 m0, s19
	s_nop 0
	global_load_lds_dwordx4 v[206:207], off
	v_lshl_add_u64 v[206:207], v[216:217], 0, s[40:41]
	s_mov_b32 m0, s26
	s_nop 0
	global_load_lds_dwordx4 v[206:207], off
	s_waitcnt vmcnt(8)
	s_waitcnt lgkmcnt(0)
	s_barrier
	s_setprio 1
	s_waitcnt lgkmcnt(0)
	v_mfma_f32_16x16x32_bf16 v[60:63], v[142:145], v[174:177], v[60:63]
	v_mfma_f32_16x16x32_bf16 v[56:59], v[150:153], v[174:177], v[56:59]
	v_mfma_f32_16x16x32_bf16 v[52:55], v[142:145], v[182:185], v[52:55]
	v_mfma_f32_16x16x32_bf16 v[48:51], v[150:153], v[182:185], v[48:51]
	v_mfma_f32_16x16x32_bf16 v[40:43], v[142:145], v[190:193], v[40:43]
	v_mfma_f32_16x16x32_bf16 v[32:35], v[150:153], v[190:193], v[32:35]
	v_mfma_f32_16x16x32_bf16 v[24:27], v[142:145], v[198:201], v[24:27]
	v_mfma_f32_16x16x32_bf16 v[16:19], v[150:153], v[198:201], v[16:19]
	v_mfma_f32_16x16x32_bf16 v[60:63], v[146:149], v[178:181], v[60:63]
	v_mfma_f32_16x16x32_bf16 v[56:59], v[154:157], v[178:181], v[56:59]
	v_mfma_f32_16x16x32_bf16 v[52:55], v[146:149], v[186:189], v[52:55]
	v_mfma_f32_16x16x32_bf16 v[48:51], v[154:157], v[186:189], v[48:51]
	v_mfma_f32_16x16x32_bf16 v[40:43], v[146:149], v[194:197], v[40:43]
	v_mfma_f32_16x16x32_bf16 v[32:35], v[154:157], v[194:197], v[32:35]
	v_mfma_f32_16x16x32_bf16 v[24:27], v[146:149], v[202:205], v[24:27]
	v_mfma_f32_16x16x32_bf16 v[16:19], v[154:157], v[202:205], v[16:19]
	s_setprio 0
	s_setprio 1
	v_mfma_f32_16x16x32_bf16 v[44:47], v[158:161], v[174:177], v[44:47]
	v_mfma_f32_16x16x32_bf16 v[36:39], v[166:169], v[174:177], v[36:39]
	v_mfma_f32_16x16x32_bf16 v[28:31], v[158:161], v[182:185], v[28:31]
	v_mfma_f32_16x16x32_bf16 v[20:23], v[166:169], v[182:185], v[20:23]
	v_mfma_f32_16x16x32_bf16 v[12:15], v[158:161], v[190:193], v[12:15]
	v_mfma_f32_16x16x32_bf16 v[8:11], v[166:169], v[190:193], v[8:11]
	v_mfma_f32_16x16x32_bf16 v[4:7], v[158:161], v[198:201], v[4:7]
	v_mfma_f32_16x16x32_bf16 v[0:3], v[166:169], v[198:201], v[0:3]
	v_mfma_f32_16x16x32_bf16 v[44:47], v[162:165], v[178:181], v[44:47]
	v_mfma_f32_16x16x32_bf16 v[36:39], v[170:173], v[178:181], v[36:39]
	v_mfma_f32_16x16x32_bf16 v[28:31], v[162:165], v[186:189], v[28:31]
	v_mfma_f32_16x16x32_bf16 v[20:23], v[170:173], v[186:189], v[20:23]
	v_mfma_f32_16x16x32_bf16 v[12:15], v[162:165], v[194:197], v[12:15]
	v_mfma_f32_16x16x32_bf16 v[8:11], v[170:173], v[194:197], v[8:11]
	v_mfma_f32_16x16x32_bf16 v[4:7], v[162:165], v[202:205], v[4:7]
	v_mfma_f32_16x16x32_bf16 v[0:3], v[170:173], v[202:205], v[0:3]
	s_setprio 0
	s_barrier
	s_add_u32 s46, s46, 0x100
	s_addc_u32 s47, s47, 0
	s_add_u32 s2, s2, 0x100
	s_addc_u32 s24, s24, 0
	s_cmp_ge_i32 s56, s33
	s_mov_b32 s25, s56
	s_cbranch_scc1 .Lpeelx_1

;     __device__ __forceinline__ void operator()(const f32x4 (&acc)[2][2][4][2], const Unit& u, int wr, int wc, int fr, int fq) const {
;     ...
;                 for (int bj = 0; bj < 2; ++bj) { const u32x4 x4 = xw[ai][m][bj]; f32x4 v0, v1;
;                     v0[0] = __uint_as_float(x4.x << 16); v0[1] = __uint_as_float(x4.x & 0xffff0000u); v0[2] = __uint_as_float(x4.y << 16); v0[3] = __uint_as_float(x4.y & 0xffff0000u);
;                     v1[0] = __uint_as_float(x4.z << 16); v1[1] = __uint_as_float(x4.z & 0xffff0000u); v1[2] = __uint_as_float(x4.w << 16); v1[3] = __uint_as_float(x4.w & 0xffff0000u);
;                     v0 = v0 + acc[ai][bj][m][0] * scale; v1 = v1 + acc[ai][bj][m][1] * scale;
.Lpeelx_1:
	v_pk_mul_f32 v[222:223], v[126:127], 0.5 op_sel_hi:[1,0]
	v_pk_mul_f32 v[220:221], v[124:125], 0.5 op_sel_hi:[1,0]
	v_pk_mul_f32 v[218:219], v[122:123], 0.5 op_sel_hi:[1,0]
	v_pk_mul_f32 v[216:217], v[120:121], 0.5 op_sel_hi:[1,0]
	v_pk_mul_f32 v[214:215], v[110:111], 0.5 op_sel_hi:[1,0]
	v_pk_mul_f32 v[212:213], v[108:109], 0.5 op_sel_hi:[1,0]
	v_pk_mul_f32 v[210:211], v[102:103], 0.5 op_sel_hi:[1,0]
	v_pk_mul_f32 v[208:209], v[100:101], 0.5 op_sel_hi:[1,0]
	v_pk_mul_f32 v[202:203], v[118:119], 0.5 op_sel_hi:[1,0]
	v_pk_mul_f32 v[200:201], v[116:117], 0.5 op_sel_hi:[1,0]
	v_pk_mul_f32 v[198:199], v[114:115], 0.5 op_sel_hi:[1,0]
	v_pk_mul_f32 v[196:197], v[112:113], 0.5 op_sel_hi:[1,0]
	v_pk_mul_f32 v[194:195], v[94:95], 0.5 op_sel_hi:[1,0]
	v_pk_mul_f32 v[192:193], v[92:93], 0.5 op_sel_hi:[1,0]
	v_pk_mul_f32 v[190:191], v[86:87], 0.5 op_sel_hi:[1,0]
	v_pk_mul_f32 v[188:189], v[84:85], 0.5 op_sel_hi:[1,0]
	v_pk_mul_f32 v[182:183], v[106:107], 0.5 op_sel_hi:[1,0]
	v_pk_mul_f32 v[180:181], v[104:105], 0.5 op_sel_hi:[1,0]
	v_pk_mul_f32 v[178:179], v[98:99], 0.5 op_sel_hi:[1,0]
	v_pk_mul_f32 v[176:177], v[96:97], 0.5 op_sel_hi:[1,0]
	v_pk_mul_f32 v[174:175], v[78:79], 0.5 op_sel_hi:[1,0]
	v_pk_mul_f32 v[172:173], v[76:77], 0.5 op_sel_hi:[1,0]
	v_pk_mul_f32 v[170:171], v[74:75], 0.5 op_sel_hi:[1,0]
	v_pk_mul_f32 v[168:169], v[72:73], 0.5 op_sel_hi:[1,0]
	v_pk_mul_f32 v[162:163], v[90:91], 0.5 op_sel_hi:[1,0]
	v_pk_mul_f32 v[160:161], v[88:89], 0.5 op_sel_hi:[1,0]
	v_pk_mul_f32 v[158:159], v[82:83], 0.5 op_sel_hi:[1,0]
	v_pk_mul_f32 v[156:157], v[80:81], 0.5 op_sel_hi:[1,0]
	v_pk_mul_f32 v[154:155], v[70:71], 0.5 op_sel_hi:[1,0]
	v_pk_mul_f32 v[152:153], v[68:69], 0.5 op_sel_hi:[1,0]
	v_pk_mul_f32 v[150:151], v[66:67], 0.5 op_sel_hi:[1,0]
	v_pk_mul_f32 v[148:149], v[64:65], 0.5 op_sel_hi:[1,0]
	v_pk_mul_f32 v[142:143], v[62:63], 0.5 op_sel_hi:[1,0]
	v_pk_mul_f32 v[126:127], v[60:61], 0.5 op_sel_hi:[1,0]
	v_pk_mul_f32 v[124:125], v[58:59], 0.5 op_sel_hi:[1,0]
	v_pk_mul_f32 v[122:123], v[56:57], 0.5 op_sel_hi:[1,0]
	v_pk_mul_f32 v[120:121], v[46:47], 0.5 op_sel_hi:[1,0]
	v_pk_mul_f32 v[118:119], v[44:45], 0.5 op_sel_hi:[1,0]
	v_pk_mul_f32 v[116:117], v[38:39], 0.5 op_sel_hi:[1,0]
	v_pk_mul_f32 v[114:115], v[36:37], 0.5 op_sel_hi:[1,0]
	v_pk_mul_f32 v[110:111], v[54:55], 0.5 op_sel_hi:[1,0]
	v_pk_mul_f32 v[108:109], v[52:53], 0.5 op_sel_hi:[1,0]
	v_pk_mul_f32 v[106:107], v[50:51], 0.5 op_sel_hi:[1,0]
	v_pk_mul_f32 v[104:105], v[48:49], 0.5 op_sel_hi:[1,0]
	v_pk_mul_f32 v[102:103], v[30:31], 0.5 op_sel_hi:[1,0]
	v_pk_mul_f32 v[100:101], v[28:29], 0.5 op_sel_hi:[1,0]
	v_pk_mul_f32 v[98:99], v[22:23], 0.5 op_sel_hi:[1,0]
	v_pk_mul_f32 v[96:97], v[20:21], 0.5 op_sel_hi:[1,0]
	v_pk_mul_f32 v[94:95], v[42:43], 0.5 op_sel_hi:[1,0]
	v_pk_mul_f32 v[92:93], v[40:41], 0.5 op_sel_hi:[1,0]
	v_pk_mul_f32 v[90:91], v[34:35], 0.5 op_sel_hi:[1,0]
	v_pk_mul_f32 v[88:89], v[32:33], 0.5 op_sel_hi:[1,0]
	v_pk_mul_f32 v[86:87], v[14:15], 0.5 op_sel_hi:[1,0]
	v_pk_mul_f32 v[84:85], v[12:13], 0.5 op_sel_hi:[1,0]
	v_pk_mul_f32 v[82:83], v[10:11], 0.5 op_sel_hi:[1,0]
	v_pk_mul_f32 v[80:81], v[8:9], 0.5 op_sel_hi:[1,0]
	v_pk_mul_f32 v[78:79], v[26:27], 0.5 op_sel_hi:[1,0]
	v_pk_mul_f32 v[76:77], v[24:25], 0.5 op_sel_hi:[1,0]
	v_pk_mul_f32 v[74:75], v[18:19], 0.5 op_sel_hi:[1,0]
	v_pk_mul_f32 v[72:73], v[16:17], 0.5 op_sel_hi:[1,0]
	v_pk_mul_f32 v[70:71], v[6:7], 0.5 op_sel_hi:[1,0]
	v_pk_mul_f32 v[68:69], v[4:5], 0.5 op_sel_hi:[1,0]
	v_pk_mul_f32 v[66:67], v[2:3], 0.5 op_sel_hi:[1,0]
	v_pk_mul_f32 v[64:65], v[0:1], 0.5 op_sel_hi:[1,0]

; #define PG8_BAR __builtin_amdgcn_s_barrier()
; template <class Epi, class Sched, bool ALIGN_EPI = false, bool SP2 = false>
; __device__ __forceinline__ void gemm_phase(PG8_LAS unsigned char* lds, const Gemm g, const Sched& S, const Epi& E) {
;     ...
;     f32x4 acc[2][2][4][2];
; #pragma unroll
;     for (int a = 0; a < 2; ++a)
; #pragma unroll
;         for (int b = 0; b < 2; ++b)
; #pragma unroll
;             for (int m = 0; m < 4; ++m)
; #pragma unroll
;                 for (int n = 0; n < 2; ++n) acc[a][b][m][n] = (f32x4){0.f, 0.f, 0.f, 0.f};
;     ...
;         if constexpr (ALIGN_EPI) { if (wr == 0) PG8_BAR; }
;         if constexpr (!Epi::AFTER_DRAIN) { E(acc, cur, wr, wc, fr, fq); S.done(cur); }
.Lcoldz_2:
	v_mov_b32_e32 v127, 0
	v_mov_b32_e32 v126, v127
	v_mov_b32_e32 v125, v127
	v_mov_b32_e32 v124, v127
	v_mov_b32_e32 v123, v127
	v_mov_b32_e32 v122, v127
	v_mov_b32_e32 v121, v127
	v_mov_b32_e32 v120, v127
	v_mov_b32_e32 v111, v127
	v_mov_b32_e32 v110, v127
	v_mov_b32_e32 v109, v127
	v_mov_b32_e32 v108, v127
	v_mov_b32_e32 v107, v127
	v_mov_b32_e32 v106, v127
	v_mov_b32_e32 v105, v127
	v_mov_b32_e32 v104, v127
	v_mov_b32_e32 v95, v127
	v_mov_b32_e32 v94, v127
	v_mov_b32_e32 v93, v127
	v_mov_b32_e32 v92, v127
	v_mov_b32_e32 v91, v127
	v_mov_b32_e32 v90, v127
	v_mov_b32_e32 v89, v127
	v_mov_b32_e32 v88, v127
	v_mov_b32_e32 v79, v127
	v_mov_b32_e32 v78, v127
	v_mov_b32_e32 v77, v127
	v_mov_b32_e32 v76, v127
	v_mov_b32_e32 v75, v127
	v_mov_b32_e32 v74, v127
	v_mov_b32_e32 v73, v127
	v_mov_b32_e32 v72, v127
	v_mov_b32_e32 v119, v127
	v_mov_b32_e32 v118, v127
	v_mov_b32_e32 v117, v127
	v_mov_b32_e32 v116, v127
	v_mov_b32_e32 v115, v127
	v_mov_b32_e32 v114, v127
	v_mov_b32_e32 v113, v127
	v_mov_b32_e32 v112, v127
	v_mov_b32_e32 v103, v127
	v_mov_b32_e32 v102, v127
	v_mov_b32_e32 v101, v127
	v_mov_b32_e32 v100, v127
	v_mov_b32_e32 v99, v127
	v_mov_b32_e32 v98, v127
	v_mov_b32_e32 v97, v127
	v_mov_b32_e32 v96, v127
	v_mov_b32_e32 v87, v127
	v_mov_b32_e32 v86, v127
	v_mov_b32_e32 v85, v127
	v_mov_b32_e32 v84, v127
	v_mov_b32_e32 v83, v127
	v_mov_b32_e32 v82, v127
	v_mov_b32_e32 v81, v127
	v_mov_b32_e32 v80, v127
	v_mov_b32_e32 v71, v127
	v_mov_b32_e32 v70, v127
	v_mov_b32_e32 v69, v127
	v_mov_b32_e32 v68, v127
	v_mov_b32_e32 v67, v127
	v_mov_b32_e32 v66, v127
	v_mov_b32_e32 v65, v127
	v_mov_b32_e32 v64, v127
	v_mov_b32_e32 v63, v127
	v_mov_b32_e32 v62, v127
	v_mov_b32_e32 v61, v127
	v_mov_b32_e32 v60, v127
	v_mov_b32_e32 v59, v127
	v_mov_b32_e32 v58, v127
	v_mov_b32_e32 v57, v127
	v_mov_b32_e32 v56, v127
	v_mov_b32_e32 v47, v127
	v_mov_b32_e32 v46, v127
	v_mov_b32_e32 v45, v127
	v_mov_b32_e32 v44, v127
	v_mov_b32_e32 v43, v127
	v_mov_b32_e32 v42, v127
	v_mov_b32_e32 v41, v127
	v_mov_b32_e32 v40, v127
	v_mov_b32_e32 v31, v127
	v_mov_b32_e32 v30, v127
	v_mov_b32_e32 v29, v127
	v_mov_b32_e32 v28, v127
	v_mov_b32_e32 v27, v127
	v_mov_b32_e32 v26, v127
	v_mov_b32_e32 v25, v127
	v_mov_b32_e32 v24, v127
	v_mov_b32_e32 v15, v127
	v_mov_b32_e32 v14, v127
	v_mov_b32_e32 v13, v127
	v_mov_b32_e32 v12, v127
	v_mov_b32_e32 v11, v127
	v_mov_b32_e32 v10, v127
	v_mov_b32_e32 v9, v127
	v_mov_b32_e32 v8, v127
	v_mov_b32_e32 v55, v127
	v_mov_b32_e32 v54, v127
	v_mov_b32_e32 v53, v127
	v_mov_b32_e32 v52, v127
	v_mov_b32_e32 v51, v127
	v_mov_b32_e32 v50, v127
	v_mov_b32_e32 v49, v127
	v_mov_b32_e32 v48, v127
	v_mov_b32_e32 v39, v127
	v_mov_b32_e32 v38, v127
	v_mov_b32_e32 v37, v127
	v_mov_b32_e32 v36, v127
	v_mov_b32_e32 v35, v127
	v_mov_b32_e32 v34, v127
	v_mov_b32_e32 v33, v127
	v_mov_b32_e32 v32, v127
	v_mov_b32_e32 v23, v127
	v_mov_b32_e32 v22, v127
	v_mov_b32_e32 v21, v127
	v_mov_b32_e32 v20, v127
	v_mov_b32_e32 v19, v127
	v_mov_b32_e32 v18, v127
	v_mov_b32_e32 v17, v127
	v_mov_b32_e32 v16, v127
	v_mov_b32_e32 v7, v127
	v_mov_b32_e32 v6, v127
	v_mov_b32_e32 v5, v127
	v_mov_b32_e32 v4, v127
	v_mov_b32_e32 v3, v127
	v_mov_b32_e32 v2, v127
	v_mov_b32_e32 v1, v127
	v_mov_b32_e32 v0, v127
	s_branch .LBB0_535

; #define PG8_STAGE(bufoff, gbase, voff) do { _Pragma("unroll") for (int _i = 0; _i < 2; ++_i) \
;         __builtin_amdgcn_global_load_lds((const unsigned*)((const char*)(gbase) + (voff)[_i]), (PG8_LAS unsigned*)(lds + (bufoff) + ldsw + _i * 8192), 16, 0, 0); } while (0)
; #define PG8_LDA(dst, b, h) do { _Pragma("unroll") for (int m = 0; m < 4; ++m) _Pragma("unroll") for (int k = 0; k < 2; ++k) dst[m][k] = *(const PG8_LAS bf16x8*)(lds + PG8_SA(b, h) + aoff + m * 2048 + k * 1024); } while (0)
; #define PG8_LDB(dst, b, h) do { _Pragma("unroll") for (int n = 0; n < 2; ++n) _Pragma("unroll") for (int k = 0; k < 2; ++k) dst[n][k] = *(const PG8_LAS bf16x8*)(lds + PG8_SB(b, h) + boff + n * 2048 + k * 1024); } while (0)
; #define PG8_MMA(ai, bj, At, Bt) do { __builtin_amdgcn_s_setprio(1); _Pragma("unroll") for (int m = 0; m < 4; ++m) _Pragma("unroll") for (int n = 0; n < 2; ++n) _Pragma("unroll") for (int k = 0; k < 2; ++k) \
;         acc[ai][bj][m][n] = __builtin_amdgcn_mfma_f32_16x16x32_bf16(Bt[n][k], At[m][k], acc[ai][bj][m][n], 0, 0, 0); __builtin_amdgcn_s_setprio(0); } while (0)
; #define PG8_WAIT_V(n) asm volatile("s_waitcnt vmcnt(" #n ")" ::: "memory")
; #define PG8_BAR __builtin_amdgcn_s_barrier()
; template <class Epi, class Sched, bool ALIGN_EPI = false, bool SP2 = false>
; __device__ __forceinline__ void gemm_phase(PG8_LAS unsigned char* lds, const Gemm g, const Sched& S, const Epi& E) {
;     ...
;         for (int t = 0; t < nt; t += 2) {
;             const bool last = (t == nt - 2);
;             const char* a1 = cA + (size_t)(t + 1) * kstep;
;             const char* a2 = last ? nA : cA + (size_t)(t + 2) * kstep; const char* b2 = last ? nB : cB + (size_t)(t + 2) * kstep;
;             const char* a3 = a2 + kstep; const char* b3 = b2 + kstep;
;             if (last && has_next) S.a_ready(nxt);
;             if constexpr (SP2) {
;             PG8_LDB(B0, 0, 0); PG8_LDB(B1, 0, 1); PG8_SCHED; PG8_LDA(At, 0, 0); PG8_STAGE(PG8_SA(1, 1), a1 + hstep, voffA);
;             PG8_WAIT_V(8); PG8_WAIT_L(0); PG8_BAR; PG8_MMA(0, 0, At, B0); PG8_MMA(0, 1, At, B1); PG8_BAR; PG8_SCHED;
;             PG8_LDA(At, 0, 1); PG8_STAGE(PG8_SB(0, 0), b2, voffB); PG8_STAGE(PG8_SB(0, 1), b2 + hstep, voffB); PG8_STAGE(PG8_SA(0, 0), a2, voffA);
;             PG8_WAIT_V(8); PG8_WAIT_L(0); PG8_BAR; PG8_MMA(1, 0, At, B0); PG8_MMA(1, 1, At, B1); PG8_BAR; PG8_SCHED;
.LBB0_532:
	s_and_b64 vcc, exec, s[8:9]
	s_cbranch_vccnz .Lcoldz_2
	s_add_u32 s54, s54, 0x80
	s_addc_u32 s55, s55, 0
	s_add_u32 s2, s56, 0x100
	s_addc_u32 s24, s57, 0
	s_mov_b32 s25, 0
	ds_read_b128 v[128:131], v209
	ds_read_b128 v[132:135], v209 offset:1024
	ds_read_b128 v[136:139], v209 offset:2048
	ds_read_b128 v[140:143], v209 offset:3072
	ds_read_b128 v[144:147], v210
	ds_read_b128 v[148:151], v210 offset:1024
	ds_read_b128 v[152:155], v210 offset:2048
	ds_read_b128 v[156:159], v210 offset:3072
	s_add_i32 s65, s25, 2
	s_add_u32 s56, s54, 0x80
	s_addc_u32 s57, s55, 0
	s_cmp_eq_u32 s34, s25
	s_cselect_b32 s57, s13, s57
	s_cselect_b32 s56, s12, s56
	s_cselect_b32 s67, s53, s24
	s_cselect_b32 s66, s52, s2
	v_lshl_add_u64 v[202:203], s[54:55], 0, v[186:187]
	s_add_i32 m0, s16, 0xc000
	ds_read_b128 v[160:163], v211
	ds_read_b128 v[164:167], v211 offset:1024
	ds_read_b128 v[168:171], v211 offset:2048
	ds_read_b128 v[172:175], v211 offset:3072
	ds_read_b128 v[194:197], v211 offset:4096
	ds_read_b128 v[198:201], v211 offset:5120
	ds_read_b128 v[214:217], v211 offset:6144
	ds_read_b128 v[218:221], v211 offset:7168
	global_load_lds_dwordx4 v[202:203], off
	v_lshl_add_u64 v[202:203], s[54:55], 0, v[188:189]
	s_add_i32 m0, s16, 0xe000
	s_nop 0
	global_load_lds_dwordx4 v[202:203], off
	s_waitcnt vmcnt(8)
	s_waitcnt lgkmcnt(0)
	s_barrier
	s_setprio 1
	s_waitcnt lgkmcnt(0)
	v_mfma_f32_16x16x32_bf16 v[124:127], v[128:131], v[160:163], 0
	v_mfma_f32_16x16x32_bf16 v[120:123], v[136:139], v[160:163], 0
	v_mfma_f32_16x16x32_bf16 v[108:111], v[128:131], v[168:171], 0
	v_mfma_f32_16x16x32_bf16 v[104:107], v[136:139], v[168:171], 0
	v_mfma_f32_16x16x32_bf16 v[92:95], v[128:131], v[194:197], 0
	v_mfma_f32_16x16x32_bf16 v[88:91], v[136:139], v[194:197], 0
	v_mfma_f32_16x16x32_bf16 v[76:79], v[128:131], v[214:217], 0
	v_mfma_f32_16x16x32_bf16 v[72:75], v[136:139], v[214:217], 0
	v_mfma_f32_16x16x32_bf16 v[124:127], v[132:135], v[164:167], v[124:127]
	v_mfma_f32_16x16x32_bf16 v[120:123], v[140:143], v[164:167], v[120:123]
	v_mfma_f32_16x16x32_bf16 v[108:111], v[132:135], v[172:175], v[108:111]
	v_mfma_f32_16x16x32_bf16 v[104:107], v[140:143], v[172:175], v[104:107]
	v_mfma_f32_16x16x32_bf16 v[92:95], v[132:135], v[198:201], v[92:95]
	v_mfma_f32_16x16x32_bf16 v[88:91], v[140:143], v[198:201], v[88:91]
	v_mfma_f32_16x16x32_bf16 v[76:79], v[132:135], v[218:221], v[76:79]
	v_mfma_f32_16x16x32_bf16 v[72:75], v[140:143], v[218:221], v[72:75]
	s_setprio 0
	s_setprio 1
	v_mfma_f32_16x16x32_bf16 v[116:119], v[144:147], v[160:163], 0
	v_mfma_f32_16x16x32_bf16 v[112:115], v[152:155], v[160:163], 0
	v_mfma_f32_16x16x32_bf16 v[100:103], v[144:147], v[168:171], 0
	v_mfma_f32_16x16x32_bf16 v[96:99], v[152:155], v[168:171], 0
	v_mfma_f32_16x16x32_bf16 v[84:87], v[144:147], v[194:197], 0
	v_mfma_f32_16x16x32_bf16 v[80:83], v[152:155], v[194:197], 0
	v_mfma_f32_16x16x32_bf16 v[68:71], v[144:147], v[214:217], 0
	v_mfma_f32_16x16x32_bf16 v[64:67], v[152:155], v[214:217], 0
	v_mfma_f32_16x16x32_bf16 v[116:119], v[148:151], v[164:167], v[116:119]
	v_mfma_f32_16x16x32_bf16 v[112:115], v[156:159], v[164:167], v[112:115]
	v_mfma_f32_16x16x32_bf16 v[100:103], v[148:151], v[172:175], v[100:103]
	v_mfma_f32_16x16x32_bf16 v[96:99], v[156:159], v[172:175], v[96:99]
	v_mfma_f32_16x16x32_bf16 v[84:87], v[148:151], v[198:201], v[84:87]
	v_mfma_f32_16x16x32_bf16 v[80:83], v[156:159], v[198:201], v[80:83]
	v_mfma_f32_16x16x32_bf16 v[68:71], v[148:151], v[218:221], v[68:71]
	v_mfma_f32_16x16x32_bf16 v[64:67], v[156:159], v[218:221], v[64:67]
	s_setprio 0
	s_barrier
	s_add_i32 s25, s3, s4
	v_lshl_add_u64 v[202:203], s[66:67], 0, v[180:181]
	s_mov_b32 m0, s25
	ds_read_b128 v[160:163], v211 offset:16384
	ds_read_b128 v[164:167], v211 offset:17408
	ds_read_b128 v[168:171], v211 offset:18432
	ds_read_b128 v[172:175], v211 offset:19456
	ds_read_b128 v[194:197], v211 offset:20480
	ds_read_b128 v[198:201], v211 offset:21504
	ds_read_b128 v[214:217], v211 offset:22528
	ds_read_b128 v[218:221], v211 offset:23552
	global_load_lds_dwordx4 v[202:203], off
	s_add_i32 m0, s25, 0x2000
	v_lshl_add_u64 v[222:223], s[66:67], 0, v[176:177]
	s_add_u32 s66, s66, s14
	s_addc_u32 s67, s67, s15
	s_add_i32 s25, s35, s4
	global_load_lds_dwordx4 v[222:223], off
	v_lshl_add_u64 v[224:225], s[66:67], 0, v[180:181]
	s_mov_b32 m0, s25
	v_lshl_add_u64 v[226:227], s[66:67], 0, v[176:177]
	global_load_lds_dwordx4 v[224:225], off
	s_add_i32 m0, s25, 0x2000
	v_lshl_add_u64 v[228:229], s[56:57], 0, v[182:183]
	global_load_lds_dwordx4 v[226:227], off
	s_mov_b32 m0, s16
	v_lshl_add_u64 v[230:231], s[56:57], 0, v[178:179]
	global_load_lds_dwordx4 v[228:229], off
	s_mov_b32 m0, s17
	s_nop 0
	global_load_lds_dwordx4 v[230:231], off
	s_waitcnt vmcnt(8)
	s_waitcnt lgkmcnt(0)
	s_barrier
; #define PG8_STAGE(bufoff, gbase, voff) do { _Pragma("unroll") for (int _i = 0; _i < 2; ++_i) \
;         __builtin_amdgcn_global_load_lds((const unsigned*)((const char*)(gbase) + (voff)[_i]), (PG8_LAS unsigned*)(lds + (bufoff) + ldsw + _i * 8192), 16, 0, 0); } while (0)
; #define PG8_LDA(dst, b, h) do { _Pragma("unroll") for (int m = 0; m < 4; ++m) _Pragma("unroll") for (int k = 0; k < 2; ++k) dst[m][k] = *(const PG8_LAS bf16x8*)(lds + PG8_SA(b, h) + aoff + m * 2048 + k * 1024); } while (0)
; #define PG8_LDB(dst, b, h) do { _Pragma("unroll") for (int n = 0; n < 2; ++n) _Pragma("unroll") for (int k = 0; k < 2; ++k) dst[n][k] = *(const PG8_LAS bf16x8*)(lds + PG8_SB(b, h) + boff + n * 2048 + k * 1024); } while (0)
; #define PG8_MMA(ai, bj, At, Bt) do { __builtin_amdgcn_s_setprio(1); _Pragma("unroll") for (int m = 0; m < 4; ++m) _Pragma("unroll") for (int n = 0; n < 2; ++n) _Pragma("unroll") for (int k = 0; k < 2; ++k) \
;         acc[ai][bj][m][n] = __builtin_amdgcn_mfma_f32_16x16x32_bf16(Bt[n][k], At[m][k], acc[ai][bj][m][n], 0, 0, 0); __builtin_amdgcn_s_setprio(0); } while (0)
; #define PG8_WAIT_V(n) asm volatile("s_waitcnt vmcnt(" #n ")" ::: "memory")
; #define PG8_WAIT_L(n) asm volatile("s_waitcnt lgkmcnt(" #n ")" ::: "memory")
; #define PG8_BAR __builtin_amdgcn_s_barrier()
; #define PG8_SCHED __builtin_amdgcn_sched_barrier(0)
; template <class Epi, class Sched, bool ALIGN_EPI = false, bool SP2 = false>
; __device__ __forceinline__ void gemm_phase(PG8_LAS unsigned char* lds, const Gemm g, const Sched& S, const Epi& E) {
;     ...
;             PG8_WAIT_V(8); PG8_WAIT_L(0); PG8_BAR; PG8_MMA(1, 0, At, B0); PG8_MMA(1, 1, At, B1); PG8_BAR; PG8_SCHED;
;             PG8_LDB(B0, 1, 0); PG8_LDB(B1, 1, 1); PG8_SCHED; PG8_LDA(At, 1, 0); PG8_STAGE(PG8_SA(0, 1), a2 + hstep, voffA);
;             PG8_WAIT_V(8); PG8_WAIT_L(0); PG8_BAR; PG8_MMA(0, 0, At, B0); PG8_MMA(0, 1, At, B1); PG8_BAR; PG8_SCHED;
;             PG8_LDA(At, 1, 1); PG8_STAGE(PG8_SB(1, 0), b3, voffB); PG8_STAGE(PG8_SB(1, 1), b3 + hstep, voffB); PG8_STAGE(PG8_SA(1, 0), a3, voffA);
	s_setprio 1
	s_waitcnt lgkmcnt(0)
	v_mfma_f32_16x16x32_bf16 v[60:63], v[128:131], v[160:163], 0
	v_mfma_f32_16x16x32_bf16 v[56:59], v[136:139], v[160:163], 0
	v_mfma_f32_16x16x32_bf16 v[44:47], v[128:131], v[168:171], 0
	v_mfma_f32_16x16x32_bf16 v[40:43], v[136:139], v[168:171], 0
	v_mfma_f32_16x16x32_bf16 v[28:31], v[128:131], v[194:197], 0
	v_mfma_f32_16x16x32_bf16 v[24:27], v[136:139], v[194:197], 0
	v_mfma_f32_16x16x32_bf16 v[12:15], v[128:131], v[214:217], 0
	v_mfma_f32_16x16x32_bf16 v[8:11], v[136:139], v[214:217], 0
	v_mfma_f32_16x16x32_bf16 v[60:63], v[132:135], v[164:167], v[60:63]
	v_mfma_f32_16x16x32_bf16 v[56:59], v[140:143], v[164:167], v[56:59]
	v_mfma_f32_16x16x32_bf16 v[44:47], v[132:135], v[172:175], v[44:47]
	v_mfma_f32_16x16x32_bf16 v[40:43], v[140:143], v[172:175], v[40:43]
	v_mfma_f32_16x16x32_bf16 v[28:31], v[132:135], v[198:201], v[28:31]
	v_mfma_f32_16x16x32_bf16 v[24:27], v[140:143], v[198:201], v[24:27]
	v_mfma_f32_16x16x32_bf16 v[12:15], v[132:135], v[218:221], v[12:15]
	v_mfma_f32_16x16x32_bf16 v[8:11], v[140:143], v[218:221], v[8:11]
	s_setprio 0
	s_setprio 1
	v_mfma_f32_16x16x32_bf16 v[52:55], v[144:147], v[160:163], 0
	v_mfma_f32_16x16x32_bf16 v[48:51], v[152:155], v[160:163], 0
	v_mfma_f32_16x16x32_bf16 v[36:39], v[144:147], v[168:171], 0
	v_mfma_f32_16x16x32_bf16 v[32:35], v[152:155], v[168:171], 0
	v_mfma_f32_16x16x32_bf16 v[20:23], v[144:147], v[194:197], 0
	v_mfma_f32_16x16x32_bf16 v[16:19], v[152:155], v[194:197], 0
	v_mfma_f32_16x16x32_bf16 v[4:7], v[144:147], v[214:217], 0
	v_mfma_f32_16x16x32_bf16 v[0:3], v[152:155], v[214:217], 0
	v_mfma_f32_16x16x32_bf16 v[52:55], v[148:151], v[164:167], v[52:55]
	v_mfma_f32_16x16x32_bf16 v[48:51], v[156:159], v[164:167], v[48:51]
	v_mfma_f32_16x16x32_bf16 v[36:39], v[148:151], v[172:175], v[36:39]
	v_mfma_f32_16x16x32_bf16 v[32:35], v[156:159], v[172:175], v[32:35]
	v_mfma_f32_16x16x32_bf16 v[20:23], v[148:151], v[198:201], v[20:23]
	v_mfma_f32_16x16x32_bf16 v[16:19], v[156:159], v[198:201], v[16:19]
	v_mfma_f32_16x16x32_bf16 v[4:7], v[148:151], v[218:221], v[4:7]
	v_mfma_f32_16x16x32_bf16 v[0:3], v[156:159], v[218:221], v[0:3]
	s_setprio 0
	s_barrier
	s_add_i32 s25, 0, 0x18000
	s_add_i32 s66, 0, 0x1c000
	v_add_u32_e32 v140, s25, v205
	v_add_u32_e32 v156, s66, v205
	ds_read_b128 v[128:131], v140
	ds_read_b128 v[132:135], v140 offset:1024
	ds_read_b128 v[136:139], v140 offset:2048
	ds_read_b128 v[140:143], v140 offset:3072
	ds_read_b128 v[144:147], v156
	ds_read_b128 v[148:151], v156 offset:1024
	ds_read_b128 v[152:155], v156 offset:2048
	ds_read_b128 v[156:159], v156 offset:3072
	s_add_u32 s56, s56, s14
	s_addc_u32 s57, s57, s15
	s_mov_b32 m0, s18
	v_lshl_add_u64 v[232:233], s[56:57], 0, v[182:183]
	ds_read_b128 v[160:163], v211 offset:32768
	ds_read_b128 v[164:167], v211 offset:33792
	ds_read_b128 v[168:171], v211 offset:34816
	ds_read_b128 v[172:175], v211 offset:35840
	ds_read_b128 v[194:197], v211 offset:36864
	ds_read_b128 v[198:201], v211 offset:37888
	ds_read_b128 v[214:217], v211 offset:38912
	ds_read_b128 v[218:221], v211 offset:39936
	global_load_lds_dwordx4 v[232:233], off
	v_lshl_add_u64 v[232:233], s[56:57], 0, v[178:179]
	s_mov_b32 m0, s19
	s_nop 0
	global_load_lds_dwordx4 v[232:233], off
	s_waitcnt vmcnt(8)
	s_waitcnt lgkmcnt(0)
	s_barrier
	s_setprio 1
	s_waitcnt lgkmcnt(0)
	v_mfma_f32_16x16x32_bf16 v[124:127], v[128:131], v[160:163], v[124:127]
	v_mfma_f32_16x16x32_bf16 v[120:123], v[136:139], v[160:163], v[120:123]
	v_mfma_f32_16x16x32_bf16 v[108:111], v[128:131], v[168:171], v[108:111]
	v_mfma_f32_16x16x32_bf16 v[104:107], v[136:139], v[168:171], v[104:107]
	v_mfma_f32_16x16x32_bf16 v[92:95], v[128:131], v[194:197], v[92:95]
	v_mfma_f32_16x16x32_bf16 v[88:91], v[136:139], v[194:197], v[88:91]
	v_mfma_f32_16x16x32_bf16 v[76:79], v[128:131], v[214:217], v[76:79]
	v_mfma_f32_16x16x32_bf16 v[72:75], v[136:139], v[214:217], v[72:75]
	v_mfma_f32_16x16x32_bf16 v[124:127], v[132:135], v[164:167], v[124:127]
	v_mfma_f32_16x16x32_bf16 v[120:123], v[140:143], v[164:167], v[120:123]
	v_mfma_f32_16x16x32_bf16 v[108:111], v[132:135], v[172:175], v[108:111]
	v_mfma_f32_16x16x32_bf16 v[104:107], v[140:143], v[172:175], v[104:107]
	v_mfma_f32_16x16x32_bf16 v[92:95], v[132:135], v[198:201], v[92:95]
	v_mfma_f32_16x16x32_bf16 v[88:91], v[140:143], v[198:201], v[88:91]
	v_mfma_f32_16x16x32_bf16 v[76:79], v[132:135], v[218:221], v[76:79]
	v_mfma_f32_16x16x32_bf16 v[72:75], v[140:143], v[218:221], v[72:75]
	s_setprio 0
	s_setprio 1
	v_mfma_f32_16x16x32_bf16 v[116:119], v[144:147], v[160:163], v[116:119]
	v_mfma_f32_16x16x32_bf16 v[112:115], v[152:155], v[160:163], v[112:115]
	v_mfma_f32_16x16x32_bf16 v[100:103], v[144:147], v[168:171], v[100:103]
	v_mfma_f32_16x16x32_bf16 v[96:99], v[152:155], v[168:171], v[96:99]
	v_mfma_f32_16x16x32_bf16 v[84:87], v[144:147], v[194:197], v[84:87]
	v_mfma_f32_16x16x32_bf16 v[80:83], v[152:155], v[194:197], v[80:83]
	v_mfma_f32_16x16x32_bf16 v[68:71], v[144:147], v[214:217], v[68:71]
	v_mfma_f32_16x16x32_bf16 v[64:67], v[152:155], v[214:217], v[64:67]
	v_mfma_f32_16x16x32_bf16 v[116:119], v[148:151], v[164:167], v[116:119]
	v_mfma_f32_16x16x32_bf16 v[112:115], v[156:159], v[164:167], v[112:115]
	v_mfma_f32_16x16x32_bf16 v[100:103], v[148:151], v[172:175], v[100:103]
	v_mfma_f32_16x16x32_bf16 v[96:99], v[156:159], v[172:175], v[96:99]
	v_mfma_f32_16x16x32_bf16 v[84:87], v[148:151], v[198:201], v[84:87]
	v_mfma_f32_16x16x32_bf16 v[80:83], v[156:159], v[198:201], v[80:83]
	v_mfma_f32_16x16x32_bf16 v[68:71], v[148:151], v[218:221], v[68:71]
	v_mfma_f32_16x16x32_bf16 v[64:67], v[156:159], v[218:221], v[64:67]
	s_setprio 0
	s_barrier
; #define PG8_STAGE(bufoff, gbase, voff) do { _Pragma("unroll") for (int _i = 0; _i < 2; ++_i) \
;         __builtin_amdgcn_global_load_lds((const unsigned*)((const char*)(gbase) + (voff)[_i]), (PG8_LAS unsigned*)(lds + (bufoff) + ldsw + _i * 8192), 16, 0, 0); } while (0)
; #define PG8_LDA(dst, b, h) do { _Pragma("unroll") for (int m = 0; m < 4; ++m) _Pragma("unroll") for (int k = 0; k < 2; ++k) dst[m][k] = *(const PG8_LAS bf16x8*)(lds + PG8_SA(b, h) + aoff + m * 2048 + k * 1024); } while (0)
; #define PG8_MMA(ai, bj, At, Bt) do { __builtin_amdgcn_s_setprio(1); _Pragma("unroll") for (int m = 0; m < 4; ++m) _Pragma("unroll") for (int n = 0; n < 2; ++n) _Pragma("unroll") for (int k = 0; k < 2; ++k) \
;         acc[ai][bj][m][n] = __builtin_amdgcn_mfma_f32_16x16x32_bf16(Bt[n][k], At[m][k], acc[ai][bj][m][n], 0, 0, 0); __builtin_amdgcn_s_setprio(0); } while (0)
; #define PG8_WAIT_V(n) asm volatile("s_waitcnt vmcnt(" #n ")" ::: "memory")
; #define PG8_WAIT_L(n) asm volatile("s_waitcnt lgkmcnt(" #n ")" ::: "memory")
; #define PG8_BAR __builtin_amdgcn_s_barrier()
; #define PG8_SCHED __builtin_amdgcn_sched_barrier(0)
; template <class Epi, class Sched, bool ALIGN_EPI = false, bool SP2 = false>
; __device__ __forceinline__ void gemm_phase(PG8_LAS unsigned char* lds, const Gemm g, const Sched& S, const Epi& E) {
;     ...
;         for (int t = 0; t < nt; t += 2) {
;             const bool last = (t == nt - 2);
;             const char* a1 = cA + (size_t)(t + 1) * kstep;
;             const char* a2 = last ? nA : cA + (size_t)(t + 2) * kstep; const char* b2 = last ? nB : cB + (size_t)(t + 2) * kstep;
;     ...
;             PG8_LDA(At, 1, 1); PG8_STAGE(PG8_SB(1, 0), b3, voffB); PG8_STAGE(PG8_SB(1, 1), b3 + hstep, voffB); PG8_STAGE(PG8_SA(1, 0), a3, voffA);
;             PG8_WAIT_V(8); PG8_WAIT_L(0); PG8_BAR; PG8_MMA(1, 0, At, B0); PG8_MMA(1, 1, At, B1); PG8_BAR; PG8_SCHED;
	s_add_i32 s25, s25, s4
	v_lshl_add_u64 v[202:203], v[202:203], 0, s[38:39]
	s_mov_b32 m0, s25
	ds_read_b128 v[160:163], v211 offset:49152
	ds_read_b128 v[164:167], v211 offset:50176
	ds_read_b128 v[168:171], v211 offset:51200
	ds_read_b128 v[172:175], v211 offset:52224
	ds_read_b128 v[194:197], v211 offset:53248
	ds_read_b128 v[198:201], v211 offset:54272
	ds_read_b128 v[214:217], v211 offset:55296
	ds_read_b128 v[218:221], v211 offset:56320
	global_load_lds_dwordx4 v[202:203], off
	v_lshl_add_u64 v[202:203], v[222:223], 0, s[38:39]
	s_add_i32 m0, s25, 0x2000
	s_add_i32 s25, s66, s4
	global_load_lds_dwordx4 v[202:203], off
	v_lshl_add_u64 v[202:203], v[224:225], 0, s[38:39]
	s_mov_b32 m0, s25
	s_nop 0
	global_load_lds_dwordx4 v[202:203], off
	v_lshl_add_u64 v[202:203], v[226:227], 0, s[38:39]
	s_add_i32 m0, s25, 0x2000
	s_nop 0
	global_load_lds_dwordx4 v[202:203], off
	v_lshl_add_u64 v[202:203], v[228:229], 0, s[38:39]
	s_mov_b32 m0, s26
	s_nop 0
	global_load_lds_dwordx4 v[202:203], off
	v_lshl_add_u64 v[202:203], v[230:231], 0, s[38:39]
	s_mov_b32 m0, s27
	s_nop 0
	global_load_lds_dwordx4 v[202:203], off
	s_waitcnt vmcnt(8)
	s_waitcnt lgkmcnt(0)
	s_barrier
	s_setprio 1
	s_waitcnt lgkmcnt(0)
	v_mfma_f32_16x16x32_bf16 v[60:63], v[128:131], v[160:163], v[60:63]
	v_mfma_f32_16x16x32_bf16 v[56:59], v[136:139], v[160:163], v[56:59]
	v_mfma_f32_16x16x32_bf16 v[44:47], v[128:131], v[168:171], v[44:47]
	v_mfma_f32_16x16x32_bf16 v[40:43], v[136:139], v[168:171], v[40:43]
	v_mfma_f32_16x16x32_bf16 v[28:31], v[128:131], v[194:197], v[28:31]
	v_mfma_f32_16x16x32_bf16 v[24:27], v[136:139], v[194:197], v[24:27]
	v_mfma_f32_16x16x32_bf16 v[12:15], v[128:131], v[214:217], v[12:15]
	v_mfma_f32_16x16x32_bf16 v[8:11], v[136:139], v[214:217], v[8:11]
	v_mfma_f32_16x16x32_bf16 v[60:63], v[132:135], v[164:167], v[60:63]
	v_mfma_f32_16x16x32_bf16 v[56:59], v[140:143], v[164:167], v[56:59]
	v_mfma_f32_16x16x32_bf16 v[44:47], v[132:135], v[172:175], v[44:47]
	v_mfma_f32_16x16x32_bf16 v[40:43], v[140:143], v[172:175], v[40:43]
	v_mfma_f32_16x16x32_bf16 v[28:31], v[132:135], v[198:201], v[28:31]
	v_mfma_f32_16x16x32_bf16 v[24:27], v[140:143], v[198:201], v[24:27]
	v_mfma_f32_16x16x32_bf16 v[12:15], v[132:135], v[218:221], v[12:15]
	v_mfma_f32_16x16x32_bf16 v[8:11], v[140:143], v[218:221], v[8:11]
	s_setprio 0
	s_setprio 1
	v_mfma_f32_16x16x32_bf16 v[52:55], v[144:147], v[160:163], v[52:55]
	v_mfma_f32_16x16x32_bf16 v[48:51], v[152:155], v[160:163], v[48:51]
	v_mfma_f32_16x16x32_bf16 v[36:39], v[144:147], v[168:171], v[36:39]
	v_mfma_f32_16x16x32_bf16 v[32:35], v[152:155], v[168:171], v[32:35]
	v_mfma_f32_16x16x32_bf16 v[20:23], v[144:147], v[194:197], v[20:23]
	v_mfma_f32_16x16x32_bf16 v[16:19], v[152:155], v[194:197], v[16:19]
	v_mfma_f32_16x16x32_bf16 v[4:7], v[144:147], v[214:217], v[4:7]
	v_mfma_f32_16x16x32_bf16 v[0:3], v[152:155], v[214:217], v[0:3]
	v_mfma_f32_16x16x32_bf16 v[52:55], v[148:151], v[164:167], v[52:55]
	v_mfma_f32_16x16x32_bf16 v[48:51], v[156:159], v[164:167], v[48:51]
	v_mfma_f32_16x16x32_bf16 v[36:39], v[148:151], v[172:175], v[36:39]
	v_mfma_f32_16x16x32_bf16 v[32:35], v[156:159], v[172:175], v[32:35]
	v_mfma_f32_16x16x32_bf16 v[20:23], v[148:151], v[198:201], v[20:23]
	v_mfma_f32_16x16x32_bf16 v[16:19], v[156:159], v[198:201], v[16:19]
	v_mfma_f32_16x16x32_bf16 v[4:7], v[148:151], v[218:221], v[4:7]
	v_mfma_f32_16x16x32_bf16 v[0:3], v[156:159], v[218:221], v[0:3]
	s_setprio 0
	s_barrier
	s_add_u32 s54, s54, 0x100
	s_addc_u32 s55, s55, 0
	s_add_u32 s2, s2, 0x100
	s_addc_u32 s24, s24, 0
	s_cmp_ge_i32 s65, s33
	s_mov_b32 s25, s65
	s_cbranch_scc1 .Lpeelx_2

; #define PG8_BAR __builtin_amdgcn_s_barrier()
; template <class Epi, class Sched, bool ALIGN_EPI = false, bool SP2 = false>
; __device__ __forceinline__ void gemm_phase(PG8_LAS unsigned char* lds, const Gemm g, const Sched& S, const Epi& E) {
;     ...
;         if constexpr (ALIGN_EPI) { if (wr == 0) PG8_BAR; }
;         if constexpr (!Epi::AFTER_DRAIN) { E(acc, cur, wr, wc, fr, fq); S.done(cur); }
.Lpeelx_2:
.LBB0_535:
	s_and_b64 vcc, exec, s[42:43]
	s_cbranch_vccz .LBB0_537
	s_barrier

; #define PG8_BAR __builtin_amdgcn_s_barrier()
; template <class Epi, class Sched, bool ALIGN_EPI = false, bool SP2 = false>
; __device__ __forceinline__ void gemm_phase(PG8_LAS unsigned char* lds, const Gemm g, const Sched& S, const Epi& E) {
;     ...
;     f32x4 acc[2][2][4][2];
; #pragma unroll
;     for (int a = 0; a < 2; ++a)
; #pragma unroll
;         for (int b = 0; b < 2; ++b)
; #pragma unroll
;             for (int m = 0; m < 4; ++m)
; #pragma unroll
;                 for (int n = 0; n < 2; ++n) acc[a][b][m][n] = (f32x4){0.f, 0.f, 0.f, 0.f};
;     ...
;         if constexpr (ALIGN_EPI) { if (wr == 0) PG8_BAR; }
;         if constexpr (!Epi::AFTER_DRAIN) { E(acc, cur, wr, wc, fr, fq); S.done(cur); }
.Lcoldz_3:
	v_mov_b32_e32 v131, 0
	v_mov_b32_e32 v130, v131
	v_mov_b32_e32 v129, v131
	v_mov_b32_e32 v128, v131
	v_mov_b32_e32 v127, v131
	v_mov_b32_e32 v126, v131
	v_mov_b32_e32 v125, v131
	v_mov_b32_e32 v124, v131
	v_mov_b32_e32 v111, v131
	v_mov_b32_e32 v110, v131
	v_mov_b32_e32 v109, v131
	v_mov_b32_e32 v108, v131
	v_mov_b32_e32 v107, v131
	v_mov_b32_e32 v106, v131
	v_mov_b32_e32 v105, v131
	v_mov_b32_e32 v104, v131
	v_mov_b32_e32 v95, v131
	v_mov_b32_e32 v94, v131
	v_mov_b32_e32 v93, v131
	v_mov_b32_e32 v92, v131
	v_mov_b32_e32 v91, v131
	v_mov_b32_e32 v90, v131
	v_mov_b32_e32 v89, v131
	v_mov_b32_e32 v88, v131
	v_mov_b32_e32 v79, v131
	v_mov_b32_e32 v78, v131
	v_mov_b32_e32 v77, v131
	v_mov_b32_e32 v76, v131
	v_mov_b32_e32 v75, v131
	v_mov_b32_e32 v74, v131
	v_mov_b32_e32 v73, v131
	v_mov_b32_e32 v72, v131
	v_mov_b32_e32 v119, v131
	v_mov_b32_e32 v118, v131
	v_mov_b32_e32 v117, v131
	v_mov_b32_e32 v116, v131
	v_mov_b32_e32 v115, v131
	v_mov_b32_e32 v114, v131
	v_mov_b32_e32 v113, v131
	v_mov_b32_e32 v112, v131
	v_mov_b32_e32 v103, v131
	v_mov_b32_e32 v102, v131
	v_mov_b32_e32 v101, v131
	v_mov_b32_e32 v100, v131
	v_mov_b32_e32 v99, v131
	v_mov_b32_e32 v98, v131
	v_mov_b32_e32 v97, v131
	v_mov_b32_e32 v96, v131
	v_mov_b32_e32 v87, v131
	v_mov_b32_e32 v86, v131
	v_mov_b32_e32 v85, v131
	v_mov_b32_e32 v84, v131
	v_mov_b32_e32 v83, v131
	v_mov_b32_e32 v82, v131
	v_mov_b32_e32 v81, v131
	v_mov_b32_e32 v80, v131
	v_mov_b32_e32 v71, v131
	v_mov_b32_e32 v70, v131
	v_mov_b32_e32 v69, v131
	v_mov_b32_e32 v68, v131
	v_mov_b32_e32 v67, v131
	v_mov_b32_e32 v66, v131
	v_mov_b32_e32 v65, v131
	v_mov_b32_e32 v64, v131
	v_mov_b32_e32 v63, v131
	v_mov_b32_e32 v62, v131
	v_mov_b32_e32 v61, v131
	v_mov_b32_e32 v60, v131
	v_mov_b32_e32 v59, v131
	v_mov_b32_e32 v58, v131
	v_mov_b32_e32 v57, v131
	v_mov_b32_e32 v56, v131
	v_mov_b32_e32 v47, v131
	v_mov_b32_e32 v46, v131
	v_mov_b32_e32 v45, v131
	v_mov_b32_e32 v44, v131
	v_mov_b32_e32 v43, v131
	v_mov_b32_e32 v42, v131
	v_mov_b32_e32 v41, v131
	v_mov_b32_e32 v40, v131
	v_mov_b32_e32 v31, v131
	v_mov_b32_e32 v30, v131
	v_mov_b32_e32 v29, v131
	v_mov_b32_e32 v28, v131
	v_mov_b32_e32 v27, v131
	v_mov_b32_e32 v26, v131
	v_mov_b32_e32 v25, v131
	v_mov_b32_e32 v24, v131
	v_mov_b32_e32 v15, v131
	v_mov_b32_e32 v14, v131
	v_mov_b32_e32 v13, v131
	v_mov_b32_e32 v12, v131
	v_mov_b32_e32 v11, v131
	v_mov_b32_e32 v10, v131
	v_mov_b32_e32 v9, v131
	v_mov_b32_e32 v8, v131
	v_mov_b32_e32 v55, v131
	v_mov_b32_e32 v54, v131
	v_mov_b32_e32 v53, v131
	v_mov_b32_e32 v52, v131
	v_mov_b32_e32 v51, v131
	v_mov_b32_e32 v50, v131
	v_mov_b32_e32 v49, v131
	v_mov_b32_e32 v48, v131
	v_mov_b32_e32 v39, v131
	v_mov_b32_e32 v38, v131
	v_mov_b32_e32 v37, v131
	v_mov_b32_e32 v36, v131
	v_mov_b32_e32 v35, v131
	v_mov_b32_e32 v34, v131
	v_mov_b32_e32 v33, v131
	v_mov_b32_e32 v32, v131
	v_mov_b32_e32 v23, v131
	v_mov_b32_e32 v22, v131
	v_mov_b32_e32 v21, v131
	v_mov_b32_e32 v20, v131
	v_mov_b32_e32 v19, v131
	v_mov_b32_e32 v18, v131
	v_mov_b32_e32 v17, v131
	v_mov_b32_e32 v16, v131
	v_mov_b32_e32 v7, v131
	v_mov_b32_e32 v6, v131
	v_mov_b32_e32 v5, v131
	v_mov_b32_e32 v4, v131
	v_mov_b32_e32 v3, v131
	v_mov_b32_e32 v2, v131
	v_mov_b32_e32 v1, v131
	v_mov_b32_e32 v0, v131
	s_branch .LBB0_1223

; #define PG8_STAGE(bufoff, gbase, voff) do { _Pragma("unroll") for (int _i = 0; _i < 2; ++_i) \
;         __builtin_amdgcn_global_load_lds((const unsigned*)((const char*)(gbase) + (voff)[_i]), (PG8_LAS unsigned*)(lds + (bufoff) + ldsw + _i * 8192), 16, 0, 0); } while (0)
; #define PG8_LDA(dst, b, h) do { _Pragma("unroll") for (int m = 0; m < 4; ++m) _Pragma("unroll") for (int k = 0; k < 2; ++k) dst[m][k] = *(const PG8_LAS bf16x8*)(lds + PG8_SA(b, h) + aoff + m * 2048 + k * 1024); } while (0)
; #define PG8_LDB(dst, b, h) do { _Pragma("unroll") for (int n = 0; n < 2; ++n) _Pragma("unroll") for (int k = 0; k < 2; ++k) dst[n][k] = *(const PG8_LAS bf16x8*)(lds + PG8_SB(b, h) + boff + n * 2048 + k * 1024); } while (0)
; #define PG8_MMA(ai, bj, At, Bt) do { __builtin_amdgcn_s_setprio(1); _Pragma("unroll") for (int m = 0; m < 4; ++m) _Pragma("unroll") for (int n = 0; n < 2; ++n) _Pragma("unroll") for (int k = 0; k < 2; ++k) \
;         acc[ai][bj][m][n] = __builtin_amdgcn_mfma_f32_16x16x32_bf16(Bt[n][k], At[m][k], acc[ai][bj][m][n], 0, 0, 0); __builtin_amdgcn_s_setprio(0); } while (0)
; #define PG8_WAIT_V(n) asm volatile("s_waitcnt vmcnt(" #n ")" ::: "memory")
; #define PG8_BAR __builtin_amdgcn_s_barrier()
; template <class Epi, class Sched, bool ALIGN_EPI = false, bool SP2 = false>
; __device__ __forceinline__ void gemm_phase(PG8_LAS unsigned char* lds, const Gemm g, const Sched& S, const Epi& E) {
;     ...
;         for (int t = 0; t < nt; t += 2) {
;             const bool last = (t == nt - 2);
;             const char* a1 = cA + (size_t)(t + 1) * kstep;
;             const char* a2 = last ? nA : cA + (size_t)(t + 2) * kstep; const char* b2 = last ? nB : cB + (size_t)(t + 2) * kstep;
;             const char* a3 = a2 + kstep; const char* b3 = b2 + kstep;
;             if (last && has_next) S.a_ready(nxt);
;             if constexpr (SP2) {
;             PG8_LDB(B0, 0, 0); PG8_LDB(B1, 0, 1); PG8_SCHED; PG8_LDA(At, 0, 0); PG8_STAGE(PG8_SA(1, 1), a1 + hstep, voffA);
;             PG8_WAIT_V(8); PG8_WAIT_L(0); PG8_BAR; PG8_MMA(0, 0, At, B0); PG8_MMA(0, 1, At, B1); PG8_BAR; PG8_SCHED;
;             PG8_LDA(At, 0, 1); PG8_STAGE(PG8_SB(0, 0), b2, voffB); PG8_STAGE(PG8_SB(0, 1), b2 + hstep, voffB); PG8_STAGE(PG8_SA(0, 0), a2, voffA);
;             PG8_WAIT_V(8); PG8_WAIT_L(0); PG8_BAR; PG8_MMA(1, 0, At, B0); PG8_MMA(1, 1, At, B1); PG8_BAR; PG8_SCHED;
.LBB0_1220:
	s_and_b64 vcc, exec, s[10:11]
	s_cbranch_vccnz .Lcoldz_3
	s_add_u32 s56, s56, 0x80
	s_addc_u32 s57, s57, 0
	s_add_u32 s2, s58, 0x100
	s_addc_u32 s24, s59, 0
	s_mov_b32 s25, 0
	ds_read_b128 v[120:123], v246
	ds_read_b128 v[132:135], v246 offset:1024
	ds_read_b128 v[136:139], v246 offset:2048
	ds_read_b128 v[140:143], v246 offset:3072
	ds_read_b128 v[144:147], v247
	ds_read_b128 v[148:151], v247 offset:1024
	ds_read_b128 v[152:155], v247 offset:2048
	ds_read_b128 v[156:159], v247 offset:3072
	s_add_i32 s39, s25, 2
	s_add_u32 s46, s56, 0x80
	s_addc_u32 s58, s57, 0
	s_cmp_eq_u32 s31, s25
	s_cselect_b32 s59, s15, s58
	s_cselect_b32 s58, s14, s46
	s_cselect_b32 s61, s55, s24
	s_cselect_b32 s60, s54, s2
	v_lshl_add_u64 v[206:207], s[56:57], 0, v[200:201]
	s_add_i32 m0, s7, 0xc000
	ds_read_b128 v[160:163], v248
	ds_read_b128 v[164:167], v248 offset:1024
	ds_read_b128 v[168:171], v248 offset:2048
	ds_read_b128 v[172:175], v248 offset:3072
	ds_read_b128 v[176:179], v248 offset:4096
	ds_read_b128 v[180:183], v248 offset:5120
	ds_read_b128 v[184:187], v248 offset:6144
	ds_read_b128 v[188:191], v248 offset:7168
	global_load_lds_dwordx4 v[206:207], off
	v_lshl_add_u64 v[206:207], s[56:57], 0, v[202:203]
	s_add_i32 m0, s7, 0xe000
	s_nop 0
	global_load_lds_dwordx4 v[206:207], off
	s_waitcnt vmcnt(8)
	s_waitcnt lgkmcnt(0)
	s_barrier
	s_setprio 1
	s_waitcnt lgkmcnt(0)
	v_mfma_f32_16x16x32_bf16 v[128:131], v[120:123], v[160:163], 0
	v_mfma_f32_16x16x32_bf16 v[124:127], v[136:139], v[160:163], 0
	v_mfma_f32_16x16x32_bf16 v[108:111], v[120:123], v[168:171], 0
	v_mfma_f32_16x16x32_bf16 v[104:107], v[136:139], v[168:171], 0
	v_mfma_f32_16x16x32_bf16 v[92:95], v[120:123], v[176:179], 0
	v_mfma_f32_16x16x32_bf16 v[88:91], v[136:139], v[176:179], 0
	v_mfma_f32_16x16x32_bf16 v[76:79], v[120:123], v[184:187], 0
	v_mfma_f32_16x16x32_bf16 v[72:75], v[136:139], v[184:187], 0
	v_mfma_f32_16x16x32_bf16 v[128:131], v[132:135], v[164:167], v[128:131]
	v_mfma_f32_16x16x32_bf16 v[124:127], v[140:143], v[164:167], v[124:127]
	v_mfma_f32_16x16x32_bf16 v[108:111], v[132:135], v[172:175], v[108:111]
	v_mfma_f32_16x16x32_bf16 v[104:107], v[140:143], v[172:175], v[104:107]
	v_mfma_f32_16x16x32_bf16 v[92:95], v[132:135], v[180:183], v[92:95]
	v_mfma_f32_16x16x32_bf16 v[88:91], v[140:143], v[180:183], v[88:91]
	v_mfma_f32_16x16x32_bf16 v[76:79], v[132:135], v[188:191], v[76:79]
	v_mfma_f32_16x16x32_bf16 v[72:75], v[140:143], v[188:191], v[72:75]
	s_setprio 0
	s_setprio 1
	v_mfma_f32_16x16x32_bf16 v[116:119], v[144:147], v[160:163], 0
	v_mfma_f32_16x16x32_bf16 v[112:115], v[152:155], v[160:163], 0
	v_mfma_f32_16x16x32_bf16 v[100:103], v[144:147], v[168:171], 0
	v_mfma_f32_16x16x32_bf16 v[96:99], v[152:155], v[168:171], 0
	v_mfma_f32_16x16x32_bf16 v[84:87], v[144:147], v[176:179], 0
	v_mfma_f32_16x16x32_bf16 v[80:83], v[152:155], v[176:179], 0
	v_mfma_f32_16x16x32_bf16 v[68:71], v[144:147], v[184:187], 0
	v_mfma_f32_16x16x32_bf16 v[64:67], v[152:155], v[184:187], 0
	v_mfma_f32_16x16x32_bf16 v[116:119], v[148:151], v[164:167], v[116:119]
	v_mfma_f32_16x16x32_bf16 v[112:115], v[156:159], v[164:167], v[112:115]
	v_mfma_f32_16x16x32_bf16 v[100:103], v[148:151], v[172:175], v[100:103]
	v_mfma_f32_16x16x32_bf16 v[96:99], v[156:159], v[172:175], v[96:99]
	v_mfma_f32_16x16x32_bf16 v[84:87], v[148:151], v[180:183], v[84:87]
	v_mfma_f32_16x16x32_bf16 v[80:83], v[156:159], v[180:183], v[80:83]
	v_mfma_f32_16x16x32_bf16 v[68:71], v[148:151], v[188:191], v[68:71]
	v_mfma_f32_16x16x32_bf16 v[64:67], v[156:159], v[188:191], v[64:67]
	s_setprio 0
	s_barrier
	s_add_i32 s25, s33, s6
	v_lshl_add_u64 v[206:207], s[60:61], 0, v[194:195]
	s_mov_b32 m0, s25
	ds_read_b128 v[160:163], v248 offset:16384
	ds_read_b128 v[164:167], v248 offset:17408
	ds_read_b128 v[168:171], v248 offset:18432
	ds_read_b128 v[172:175], v248 offset:19456
	ds_read_b128 v[176:179], v248 offset:20480
	ds_read_b128 v[180:183], v248 offset:21504
	ds_read_b128 v[184:187], v248 offset:22528
	ds_read_b128 v[188:191], v248 offset:23552
	global_load_lds_dwordx4 v[206:207], off
	s_add_i32 m0, s25, 0x2000
	v_lshl_add_u64 v[208:209], s[60:61], 0, v[198:199]
	s_add_u32 s60, s60, s42
	s_addc_u32 s61, s61, s43
	s_add_i32 s25, s34, s6
	global_load_lds_dwordx4 v[208:209], off
	v_lshl_add_u64 v[210:211], s[60:61], 0, v[194:195]
	s_mov_b32 m0, s25
	v_lshl_add_u64 v[212:213], s[60:61], 0, v[198:199]
	global_load_lds_dwordx4 v[210:211], off
	s_add_i32 m0, s25, 0x2000
	v_lshl_add_u64 v[214:215], s[58:59], 0, v[192:193]
	global_load_lds_dwordx4 v[212:213], off
	s_mov_b32 m0, s7
	v_lshl_add_u64 v[216:217], s[58:59], 0, v[196:197]
	global_load_lds_dwordx4 v[214:215], off
	s_mov_b32 m0, s16
	s_nop 0
	global_load_lds_dwordx4 v[216:217], off
	s_waitcnt vmcnt(8)
	s_waitcnt lgkmcnt(0)
	s_barrier
; #define PG8_STAGE(bufoff, gbase, voff) do { _Pragma("unroll") for (int _i = 0; _i < 2; ++_i) \
;         __builtin_amdgcn_global_load_lds((const unsigned*)((const char*)(gbase) + (voff)[_i]), (PG8_LAS unsigned*)(lds + (bufoff) + ldsw + _i * 8192), 16, 0, 0); } while (0)
; #define PG8_LDA(dst, b, h) do { _Pragma("unroll") for (int m = 0; m < 4; ++m) _Pragma("unroll") for (int k = 0; k < 2; ++k) dst[m][k] = *(const PG8_LAS bf16x8*)(lds + PG8_SA(b, h) + aoff + m * 2048 + k * 1024); } while (0)
; #define PG8_LDB(dst, b, h) do { _Pragma("unroll") for (int n = 0; n < 2; ++n) _Pragma("unroll") for (int k = 0; k < 2; ++k) dst[n][k] = *(const PG8_LAS bf16x8*)(lds + PG8_SB(b, h) + boff + n * 2048 + k * 1024); } while (0)
; #define PG8_MMA(ai, bj, At, Bt) do { __builtin_amdgcn_s_setprio(1); _Pragma("unroll") for (int m = 0; m < 4; ++m) _Pragma("unroll") for (int n = 0; n < 2; ++n) _Pragma("unroll") for (int k = 0; k < 2; ++k) \
;         acc[ai][bj][m][n] = __builtin_amdgcn_mfma_f32_16x16x32_bf16(Bt[n][k], At[m][k], acc[ai][bj][m][n], 0, 0, 0); __builtin_amdgcn_s_setprio(0); } while (0)
; #define PG8_WAIT_V(n) asm volatile("s_waitcnt vmcnt(" #n ")" ::: "memory")
; #define PG8_WAIT_L(n) asm volatile("s_waitcnt lgkmcnt(" #n ")" ::: "memory")
; #define PG8_BAR __builtin_amdgcn_s_barrier()
; #define PG8_SCHED __builtin_amdgcn_sched_barrier(0)
; template <class Epi, class Sched, bool ALIGN_EPI = false, bool SP2 = false>
; __device__ __forceinline__ void gemm_phase(PG8_LAS unsigned char* lds, const Gemm g, const Sched& S, const Epi& E) {
;     ...
;             PG8_WAIT_V(8); PG8_WAIT_L(0); PG8_BAR; PG8_MMA(1, 0, At, B0); PG8_MMA(1, 1, At, B1); PG8_BAR; PG8_SCHED;
;             PG8_LDB(B0, 1, 0); PG8_LDB(B1, 1, 1); PG8_SCHED; PG8_LDA(At, 1, 0); PG8_STAGE(PG8_SA(0, 1), a2 + hstep, voffA);
;             PG8_WAIT_V(8); PG8_WAIT_L(0); PG8_BAR; PG8_MMA(0, 0, At, B0); PG8_MMA(0, 1, At, B1); PG8_BAR; PG8_SCHED;
;             PG8_LDA(At, 1, 1); PG8_STAGE(PG8_SB(1, 0), b3, voffB); PG8_STAGE(PG8_SB(1, 1), b3 + hstep, voffB); PG8_STAGE(PG8_SA(1, 0), a3, voffA);
	s_setprio 1
	s_waitcnt lgkmcnt(0)
	v_mfma_f32_16x16x32_bf16 v[60:63], v[120:123], v[160:163], 0
	v_mfma_f32_16x16x32_bf16 v[56:59], v[136:139], v[160:163], 0
	v_mfma_f32_16x16x32_bf16 v[44:47], v[120:123], v[168:171], 0
	v_mfma_f32_16x16x32_bf16 v[40:43], v[136:139], v[168:171], 0
	v_mfma_f32_16x16x32_bf16 v[28:31], v[120:123], v[176:179], 0
	v_mfma_f32_16x16x32_bf16 v[24:27], v[136:139], v[176:179], 0
	v_mfma_f32_16x16x32_bf16 v[12:15], v[120:123], v[184:187], 0
	v_mfma_f32_16x16x32_bf16 v[8:11], v[136:139], v[184:187], 0
	v_mfma_f32_16x16x32_bf16 v[60:63], v[132:135], v[164:167], v[60:63]
	v_mfma_f32_16x16x32_bf16 v[56:59], v[140:143], v[164:167], v[56:59]
	v_mfma_f32_16x16x32_bf16 v[44:47], v[132:135], v[172:175], v[44:47]
	v_mfma_f32_16x16x32_bf16 v[40:43], v[140:143], v[172:175], v[40:43]
	v_mfma_f32_16x16x32_bf16 v[28:31], v[132:135], v[180:183], v[28:31]
	v_mfma_f32_16x16x32_bf16 v[24:27], v[140:143], v[180:183], v[24:27]
	v_mfma_f32_16x16x32_bf16 v[12:15], v[132:135], v[188:191], v[12:15]
	v_mfma_f32_16x16x32_bf16 v[8:11], v[140:143], v[188:191], v[8:11]
	s_setprio 0
	s_setprio 1
	v_mfma_f32_16x16x32_bf16 v[52:55], v[144:147], v[160:163], 0
	v_mfma_f32_16x16x32_bf16 v[48:51], v[152:155], v[160:163], 0
	v_mfma_f32_16x16x32_bf16 v[36:39], v[144:147], v[168:171], 0
	v_mfma_f32_16x16x32_bf16 v[32:35], v[152:155], v[168:171], 0
	v_mfma_f32_16x16x32_bf16 v[20:23], v[144:147], v[176:179], 0
	v_mfma_f32_16x16x32_bf16 v[16:19], v[152:155], v[176:179], 0
	v_mfma_f32_16x16x32_bf16 v[4:7], v[144:147], v[184:187], 0
	v_mfma_f32_16x16x32_bf16 v[0:3], v[152:155], v[184:187], 0
	v_mfma_f32_16x16x32_bf16 v[52:55], v[148:151], v[164:167], v[52:55]
	v_mfma_f32_16x16x32_bf16 v[48:51], v[156:159], v[164:167], v[48:51]
	v_mfma_f32_16x16x32_bf16 v[36:39], v[148:151], v[172:175], v[36:39]
	v_mfma_f32_16x16x32_bf16 v[32:35], v[156:159], v[172:175], v[32:35]
	v_mfma_f32_16x16x32_bf16 v[20:23], v[148:151], v[180:183], v[20:23]
	v_mfma_f32_16x16x32_bf16 v[16:19], v[156:159], v[180:183], v[16:19]
	v_mfma_f32_16x16x32_bf16 v[4:7], v[148:151], v[188:191], v[4:7]
	v_mfma_f32_16x16x32_bf16 v[0:3], v[156:159], v[188:191], v[0:3]
	s_setprio 0
	s_barrier
	s_add_i32 s25, 0, 0x18000
	s_add_i32 s46, 0, 0x1c000
	v_add_u32_e32 v140, s25, v244
	v_add_u32_e32 v156, s46, v244
	ds_read_b128 v[120:123], v140
	ds_read_b128 v[132:135], v140 offset:1024
	ds_read_b128 v[136:139], v140 offset:2048
	ds_read_b128 v[140:143], v140 offset:3072
	ds_read_b128 v[144:147], v156
	ds_read_b128 v[148:151], v156 offset:1024
	ds_read_b128 v[152:155], v156 offset:2048
	ds_read_b128 v[156:159], v156 offset:3072
	s_add_u32 s58, s58, s42
	s_addc_u32 s59, s59, s43
	s_mov_b32 m0, s17
	v_lshl_add_u64 v[218:219], s[58:59], 0, v[192:193]
	ds_read_b128 v[160:163], v248 offset:32768
	ds_read_b128 v[164:167], v248 offset:33792
	ds_read_b128 v[168:171], v248 offset:34816
	ds_read_b128 v[172:175], v248 offset:35840
	ds_read_b128 v[176:179], v248 offset:36864
	ds_read_b128 v[180:183], v248 offset:37888
	ds_read_b128 v[184:187], v248 offset:38912
	ds_read_b128 v[188:191], v248 offset:39936
	global_load_lds_dwordx4 v[218:219], off
	v_lshl_add_u64 v[218:219], s[58:59], 0, v[196:197]
	s_mov_b32 m0, s18
	s_nop 0
	global_load_lds_dwordx4 v[218:219], off
	s_waitcnt vmcnt(8)
	s_waitcnt lgkmcnt(0)
	s_barrier
	s_setprio 1
	s_waitcnt lgkmcnt(0)
	v_mfma_f32_16x16x32_bf16 v[128:131], v[120:123], v[160:163], v[128:131]
	v_mfma_f32_16x16x32_bf16 v[124:127], v[136:139], v[160:163], v[124:127]
	v_mfma_f32_16x16x32_bf16 v[108:111], v[120:123], v[168:171], v[108:111]
	v_mfma_f32_16x16x32_bf16 v[104:107], v[136:139], v[168:171], v[104:107]
	v_mfma_f32_16x16x32_bf16 v[92:95], v[120:123], v[176:179], v[92:95]
	v_mfma_f32_16x16x32_bf16 v[88:91], v[136:139], v[176:179], v[88:91]
	v_mfma_f32_16x16x32_bf16 v[76:79], v[120:123], v[184:187], v[76:79]
	v_mfma_f32_16x16x32_bf16 v[72:75], v[136:139], v[184:187], v[72:75]
	v_mfma_f32_16x16x32_bf16 v[128:131], v[132:135], v[164:167], v[128:131]
	v_mfma_f32_16x16x32_bf16 v[124:127], v[140:143], v[164:167], v[124:127]
	v_mfma_f32_16x16x32_bf16 v[108:111], v[132:135], v[172:175], v[108:111]
	v_mfma_f32_16x16x32_bf16 v[104:107], v[140:143], v[172:175], v[104:107]
	v_mfma_f32_16x16x32_bf16 v[92:95], v[132:135], v[180:183], v[92:95]
	v_mfma_f32_16x16x32_bf16 v[88:91], v[140:143], v[180:183], v[88:91]
	v_mfma_f32_16x16x32_bf16 v[76:79], v[132:135], v[188:191], v[76:79]
	v_mfma_f32_16x16x32_bf16 v[72:75], v[140:143], v[188:191], v[72:75]
	s_setprio 0
	s_setprio 1
	v_mfma_f32_16x16x32_bf16 v[116:119], v[144:147], v[160:163], v[116:119]
	v_mfma_f32_16x16x32_bf16 v[112:115], v[152:155], v[160:163], v[112:115]
	v_mfma_f32_16x16x32_bf16 v[100:103], v[144:147], v[168:171], v[100:103]
	v_mfma_f32_16x16x32_bf16 v[96:99], v[152:155], v[168:171], v[96:99]
	v_mfma_f32_16x16x32_bf16 v[84:87], v[144:147], v[176:179], v[84:87]
	v_mfma_f32_16x16x32_bf16 v[80:83], v[152:155], v[176:179], v[80:83]
	v_mfma_f32_16x16x32_bf16 v[68:71], v[144:147], v[184:187], v[68:71]
	v_mfma_f32_16x16x32_bf16 v[64:67], v[152:155], v[184:187], v[64:67]
	v_mfma_f32_16x16x32_bf16 v[116:119], v[148:151], v[164:167], v[116:119]
	v_mfma_f32_16x16x32_bf16 v[112:115], v[156:159], v[164:167], v[112:115]
	v_mfma_f32_16x16x32_bf16 v[100:103], v[148:151], v[172:175], v[100:103]
	v_mfma_f32_16x16x32_bf16 v[96:99], v[156:159], v[172:175], v[96:99]
	v_mfma_f32_16x16x32_bf16 v[84:87], v[148:151], v[180:183], v[84:87]
	v_mfma_f32_16x16x32_bf16 v[80:83], v[156:159], v[180:183], v[80:83]
	v_mfma_f32_16x16x32_bf16 v[68:71], v[148:151], v[188:191], v[68:71]
	v_mfma_f32_16x16x32_bf16 v[64:67], v[156:159], v[188:191], v[64:67]
	s_setprio 0
	s_barrier
; #define PG8_STAGE(bufoff, gbase, voff) do { _Pragma("unroll") for (int _i = 0; _i < 2; ++_i) \
;         __builtin_amdgcn_global_load_lds((const unsigned*)((const char*)(gbase) + (voff)[_i]), (PG8_LAS unsigned*)(lds + (bufoff) + ldsw + _i * 8192), 16, 0, 0); } while (0)
; #define PG8_LDA(dst, b, h) do { _Pragma("unroll") for (int m = 0; m < 4; ++m) _Pragma("unroll") for (int k = 0; k < 2; ++k) dst[m][k] = *(const PG8_LAS bf16x8*)(lds + PG8_SA(b, h) + aoff + m * 2048 + k * 1024); } while (0)
; #define PG8_MMA(ai, bj, At, Bt) do { __builtin_amdgcn_s_setprio(1); _Pragma("unroll") for (int m = 0; m < 4; ++m) _Pragma("unroll") for (int n = 0; n < 2; ++n) _Pragma("unroll") for (int k = 0; k < 2; ++k) \
;         acc[ai][bj][m][n] = __builtin_amdgcn_mfma_f32_16x16x32_bf16(Bt[n][k], At[m][k], acc[ai][bj][m][n], 0, 0, 0); __builtin_amdgcn_s_setprio(0); } while (0)
; #define PG8_WAIT_V(n) asm volatile("s_waitcnt vmcnt(" #n ")" ::: "memory")
; #define PG8_WAIT_L(n) asm volatile("s_waitcnt lgkmcnt(" #n ")" ::: "memory")
; #define PG8_BAR __builtin_amdgcn_s_barrier()
; #define PG8_SCHED __builtin_amdgcn_sched_barrier(0)
; template <class Epi, class Sched, bool ALIGN_EPI = false, bool SP2 = false>
; __device__ __forceinline__ void gemm_phase(PG8_LAS unsigned char* lds, const Gemm g, const Sched& S, const Epi& E) {
;     ...
;         for (int t = 0; t < nt; t += 2) {
;             const bool last = (t == nt - 2);
;             const char* a1 = cA + (size_t)(t + 1) * kstep;
;             const char* a2 = last ? nA : cA + (size_t)(t + 2) * kstep; const char* b2 = last ? nB : cB + (size_t)(t + 2) * kstep;
;     ...
;             PG8_LDA(At, 1, 1); PG8_STAGE(PG8_SB(1, 0), b3, voffB); PG8_STAGE(PG8_SB(1, 1), b3 + hstep, voffB); PG8_STAGE(PG8_SA(1, 0), a3, voffA);
;             PG8_WAIT_V(8); PG8_WAIT_L(0); PG8_BAR; PG8_MMA(1, 0, At, B0); PG8_MMA(1, 1, At, B1); PG8_BAR; PG8_SCHED;
	s_add_i32 s25, s25, s6
	v_lshl_add_u64 v[206:207], v[206:207], 0, s[50:51]
	s_mov_b32 m0, s25
	ds_read_b128 v[160:163], v248 offset:49152
	ds_read_b128 v[164:167], v248 offset:50176
	ds_read_b128 v[168:171], v248 offset:51200
	ds_read_b128 v[172:175], v248 offset:52224
	ds_read_b128 v[176:179], v248 offset:53248
	ds_read_b128 v[180:183], v248 offset:54272
	ds_read_b128 v[184:187], v248 offset:55296
	ds_read_b128 v[188:191], v248 offset:56320
	global_load_lds_dwordx4 v[206:207], off
	v_lshl_add_u64 v[206:207], v[208:209], 0, s[50:51]
	s_add_i32 m0, s25, 0x2000
	s_add_i32 s25, s46, s6
	global_load_lds_dwordx4 v[206:207], off
	v_lshl_add_u64 v[206:207], v[210:211], 0, s[50:51]
	s_mov_b32 m0, s25
	s_nop 0
	global_load_lds_dwordx4 v[206:207], off
	v_lshl_add_u64 v[206:207], v[212:213], 0, s[50:51]
	s_add_i32 m0, s25, 0x2000
	s_nop 0
	global_load_lds_dwordx4 v[206:207], off
	v_lshl_add_u64 v[206:207], v[214:215], 0, s[50:51]
	s_mov_b32 m0, s19
	s_nop 0
	global_load_lds_dwordx4 v[206:207], off
	v_lshl_add_u64 v[206:207], v[216:217], 0, s[50:51]
	s_mov_b32 m0, s26
	s_nop 0
	global_load_lds_dwordx4 v[206:207], off
	s_waitcnt vmcnt(8)
	s_waitcnt lgkmcnt(0)
	s_barrier
	s_setprio 1
	s_waitcnt lgkmcnt(0)
	v_mfma_f32_16x16x32_bf16 v[60:63], v[120:123], v[160:163], v[60:63]
	v_mfma_f32_16x16x32_bf16 v[56:59], v[136:139], v[160:163], v[56:59]
	v_mfma_f32_16x16x32_bf16 v[44:47], v[120:123], v[168:171], v[44:47]
	v_mfma_f32_16x16x32_bf16 v[40:43], v[136:139], v[168:171], v[40:43]
	v_mfma_f32_16x16x32_bf16 v[28:31], v[120:123], v[176:179], v[28:31]
	v_mfma_f32_16x16x32_bf16 v[24:27], v[136:139], v[176:179], v[24:27]
	v_mfma_f32_16x16x32_bf16 v[12:15], v[120:123], v[184:187], v[12:15]
	v_mfma_f32_16x16x32_bf16 v[8:11], v[136:139], v[184:187], v[8:11]
	v_mfma_f32_16x16x32_bf16 v[60:63], v[132:135], v[164:167], v[60:63]
	v_mfma_f32_16x16x32_bf16 v[56:59], v[140:143], v[164:167], v[56:59]
	v_mfma_f32_16x16x32_bf16 v[44:47], v[132:135], v[172:175], v[44:47]
	v_mfma_f32_16x16x32_bf16 v[40:43], v[140:143], v[172:175], v[40:43]
	v_mfma_f32_16x16x32_bf16 v[28:31], v[132:135], v[180:183], v[28:31]
	v_mfma_f32_16x16x32_bf16 v[24:27], v[140:143], v[180:183], v[24:27]
	v_mfma_f32_16x16x32_bf16 v[12:15], v[132:135], v[188:191], v[12:15]
	v_mfma_f32_16x16x32_bf16 v[8:11], v[140:143], v[188:191], v[8:11]
	s_setprio 0
	s_setprio 1
	v_mfma_f32_16x16x32_bf16 v[52:55], v[144:147], v[160:163], v[52:55]
	v_mfma_f32_16x16x32_bf16 v[48:51], v[152:155], v[160:163], v[48:51]
	v_mfma_f32_16x16x32_bf16 v[36:39], v[144:147], v[168:171], v[36:39]
	v_mfma_f32_16x16x32_bf16 v[32:35], v[152:155], v[168:171], v[32:35]
	v_mfma_f32_16x16x32_bf16 v[20:23], v[144:147], v[176:179], v[20:23]
	v_mfma_f32_16x16x32_bf16 v[16:19], v[152:155], v[176:179], v[16:19]
	v_mfma_f32_16x16x32_bf16 v[4:7], v[144:147], v[184:187], v[4:7]
	v_mfma_f32_16x16x32_bf16 v[0:3], v[152:155], v[184:187], v[0:3]
	v_mfma_f32_16x16x32_bf16 v[52:55], v[148:151], v[164:167], v[52:55]
	v_mfma_f32_16x16x32_bf16 v[48:51], v[156:159], v[164:167], v[48:51]
	v_mfma_f32_16x16x32_bf16 v[36:39], v[148:151], v[172:175], v[36:39]
	v_mfma_f32_16x16x32_bf16 v[32:35], v[156:159], v[172:175], v[32:35]
	v_mfma_f32_16x16x32_bf16 v[20:23], v[148:151], v[180:183], v[20:23]
	v_mfma_f32_16x16x32_bf16 v[16:19], v[156:159], v[180:183], v[16:19]
	v_mfma_f32_16x16x32_bf16 v[4:7], v[148:151], v[188:191], v[4:7]
	v_mfma_f32_16x16x32_bf16 v[0:3], v[156:159], v[188:191], v[0:3]
	s_setprio 0
	s_barrier
	s_add_u32 s56, s56, 0x100
	s_addc_u32 s57, s57, 0
	s_add_u32 s2, s2, 0x100
	s_addc_u32 s24, s24, 0
	s_cmp_ge_i32 s39, s30
	s_mov_b32 s25, s39
	s_cbranch_scc1 .Lpeelx_3

; #define PG8_BAR __builtin_amdgcn_s_barrier()
; template <class Epi, class Sched, bool ALIGN_EPI = false, bool SP2 = false>
; __device__ __forceinline__ void gemm_phase(PG8_LAS unsigned char* lds, const Gemm g, const Sched& S, const Epi& E) {
;     ...
;         if constexpr (ALIGN_EPI) { if (wr == 0) PG8_BAR; }
;         if constexpr (!Epi::AFTER_DRAIN) { E(acc, cur, wr, wc, fr, fq); S.done(cur); }
.Lpeelx_3:
.LBB0_1223:
	s_and_b64 vcc, exec, s[52:53]
	s_cbranch_vccz .LBB0_1225
	s_barrier

; #define PG8_STAGE(bufoff, gbase, voff) do { _Pragma("unroll") for (int _i = 0; _i < 2; ++_i) \
;         __builtin_amdgcn_global_load_lds((const unsigned*)((const char*)(gbase) + (voff)[_i]), (PG8_LAS unsigned*)(lds + (bufoff) + ldsw + _i * 8192), 16, 0, 0); } while (0)
; #define PG8_LDA(dst, b, h) do { _Pragma("unroll") for (int m = 0; m < 4; ++m) _Pragma("unroll") for (int k = 0; k < 2; ++k) dst[m][k] = *(const PG8_LAS bf16x8*)(lds + PG8_SA(b, h) + aoff + m * 2048 + k * 1024); } while (0)
; #define PG8_LDB(dst, b, h) do { _Pragma("unroll") for (int n = 0; n < 2; ++n) _Pragma("unroll") for (int k = 0; k < 2; ++k) dst[n][k] = *(const PG8_LAS bf16x8*)(lds + PG8_SB(b, h) + boff + n * 2048 + k * 1024); } while (0)
; #define PG8_MMA(ai, bj, At, Bt) do { __builtin_amdgcn_s_setprio(1); _Pragma("unroll") for (int m = 0; m < 4; ++m) _Pragma("unroll") for (int n = 0; n < 2; ++n) _Pragma("unroll") for (int k = 0; k < 2; ++k) \
;         acc[ai][bj][m][n] = __builtin_amdgcn_mfma_f32_16x16x32_bf16(Bt[n][k], At[m][k], acc[ai][bj][m][n], 0, 0, 0); __builtin_amdgcn_s_setprio(0); } while (0)
; #define PG8_WAIT_V(n) asm volatile("s_waitcnt vmcnt(" #n ")" ::: "memory")
; #define PG8_BAR __builtin_amdgcn_s_barrier()
; template <class Epi, class Sched, bool ALIGN_EPI = false, bool SP2 = false>
; __device__ __forceinline__ void gemm_phase(PG8_LAS unsigned char* lds, const Gemm g, const Sched& S, const Epi& E) {
;     ...
;         for (int t = 0; t < nt; t += 2) {
;             const bool last = (t == nt - 2);
;             const char* a1 = cA + (size_t)(t + 1) * kstep;
;             const char* a2 = last ? nA : cA + (size_t)(t + 2) * kstep; const char* b2 = last ? nB : cB + (size_t)(t + 2) * kstep;
;             const char* a3 = a2 + kstep; const char* b3 = b2 + kstep;
;             if (last && has_next) S.a_ready(nxt);
;             if constexpr (SP2) {
;             PG8_LDB(B0, 0, 0); PG8_LDB(B1, 0, 1); PG8_SCHED; PG8_LDA(At, 0, 0); PG8_STAGE(PG8_SA(1, 1), a1 + hstep, voffA);
;             PG8_WAIT_V(8); PG8_WAIT_L(0); PG8_BAR; PG8_MMA(0, 0, At, B0); PG8_MMA(0, 1, At, B1); PG8_BAR; PG8_SCHED;
;             PG8_LDA(At, 0, 1); PG8_STAGE(PG8_SB(0, 0), b2, voffB); PG8_STAGE(PG8_SB(0, 1), b2 + hstep, voffB); PG8_STAGE(PG8_SA(0, 0), a2, voffA);
;             PG8_WAIT_V(8); PG8_WAIT_L(0); PG8_BAR; PG8_MMA(1, 0, At, B0); PG8_MMA(1, 1, At, B1); PG8_BAR; PG8_SCHED;
.LBB0_1321:
	s_and_b64 vcc, exec, s[10:11]
	s_cbranch_vccnz .Lcoldz_4
	s_add_u32 s50, s50, 0x80
	s_addc_u32 s51, s51, 0
	s_add_u32 s24, s52, 0x100
	s_addc_u32 s25, s53, 0
	s_mov_b32 s52, 0
	ds_read_b128 v[152:155], v148
	ds_read_b128 v[156:159], v148 offset:1024
	ds_read_b128 v[160:163], v148 offset:2048
	ds_read_b128 v[164:167], v148 offset:3072
	ds_read_b128 v[168:171], v149
	ds_read_b128 v[172:175], v149 offset:1024
	ds_read_b128 v[176:179], v149 offset:2048
	ds_read_b128 v[180:183], v149 offset:3072
	s_add_i32 s58, s52, 2
	s_add_u32 s59, s50, 0x80
	s_addc_u32 s53, s51, 0
	s_cmp_eq_u32 s33, s52
	s_cselect_b32 s52, s14, s59
	s_cselect_b32 s53, s15, s53
	s_cselect_b32 s61, s49, s25
	s_cselect_b32 s60, s48, s24
	s_mov_b32 m0, s37
	v_lshl_add_u64 v[216:217], s[50:51], 0, v[136:137]
	ds_read_b128 v[184:187], v150
	ds_read_b128 v[188:191], v150 offset:1024
	ds_read_b128 v[192:195], v150 offset:2048
	ds_read_b128 v[196:199], v150 offset:3072
	ds_read_b128 v[200:203], v150 offset:4096
	ds_read_b128 v[204:207], v150 offset:5120
	ds_read_b128 v[208:211], v150 offset:6144
	ds_read_b128 v[212:215], v150 offset:7168
	global_load_lds_dwordx4 v[216:217], off
	v_lshl_add_u64 v[216:217], s[50:51], 0, v[138:139]
	s_mov_b32 m0, s38
	s_nop 0
	global_load_lds_dwordx4 v[216:217], off
	s_waitcnt vmcnt(8)
	s_waitcnt lgkmcnt(0)
	s_barrier
	s_setprio 1
	s_waitcnt lgkmcnt(0)
	v_mfma_f32_16x16x32_bf16 v[120:123], v[152:155], v[184:187], 0
	v_mfma_f32_16x16x32_bf16 v[116:119], v[160:163], v[184:187], 0
	v_mfma_f32_16x16x32_bf16 v[108:111], v[152:155], v[192:195], 0
	v_mfma_f32_16x16x32_bf16 v[100:103], v[160:163], v[192:195], 0
	v_mfma_f32_16x16x32_bf16 v[92:95], v[152:155], v[200:203], 0
	v_mfma_f32_16x16x32_bf16 v[84:87], v[160:163], v[200:203], 0
	v_mfma_f32_16x16x32_bf16 v[76:79], v[152:155], v[208:211], 0
	v_mfma_f32_16x16x32_bf16 v[68:71], v[160:163], v[208:211], 0
	v_mfma_f32_16x16x32_bf16 v[120:123], v[156:159], v[188:191], v[120:123]
	v_mfma_f32_16x16x32_bf16 v[116:119], v[164:167], v[188:191], v[116:119]
	v_mfma_f32_16x16x32_bf16 v[108:111], v[156:159], v[196:199], v[108:111]
	v_mfma_f32_16x16x32_bf16 v[100:103], v[164:167], v[196:199], v[100:103]
	v_mfma_f32_16x16x32_bf16 v[92:95], v[156:159], v[204:207], v[92:95]
	v_mfma_f32_16x16x32_bf16 v[84:87], v[164:167], v[204:207], v[84:87]
	v_mfma_f32_16x16x32_bf16 v[76:79], v[156:159], v[212:215], v[76:79]
	v_mfma_f32_16x16x32_bf16 v[68:71], v[164:167], v[212:215], v[68:71]
	s_setprio 0
	s_setprio 1
	v_mfma_f32_16x16x32_bf16 v[124:127], v[168:171], v[184:187], 0
	v_mfma_f32_16x16x32_bf16 v[112:115], v[176:179], v[184:187], 0
	v_mfma_f32_16x16x32_bf16 v[104:107], v[168:171], v[192:195], 0
	v_mfma_f32_16x16x32_bf16 v[96:99], v[176:179], v[192:195], 0
	v_mfma_f32_16x16x32_bf16 v[88:91], v[168:171], v[200:203], 0
	v_mfma_f32_16x16x32_bf16 v[80:83], v[176:179], v[200:203], 0
	v_mfma_f32_16x16x32_bf16 v[72:75], v[168:171], v[208:211], 0
	v_mfma_f32_16x16x32_bf16 v[64:67], v[176:179], v[208:211], 0
	v_mfma_f32_16x16x32_bf16 v[124:127], v[172:175], v[188:191], v[124:127]
	v_mfma_f32_16x16x32_bf16 v[112:115], v[180:183], v[188:191], v[112:115]
	v_mfma_f32_16x16x32_bf16 v[104:107], v[172:175], v[196:199], v[104:107]
	v_mfma_f32_16x16x32_bf16 v[96:99], v[180:183], v[196:199], v[96:99]
	v_mfma_f32_16x16x32_bf16 v[88:91], v[172:175], v[204:207], v[88:91]
	v_mfma_f32_16x16x32_bf16 v[80:83], v[180:183], v[204:207], v[80:83]
	v_mfma_f32_16x16x32_bf16 v[72:75], v[172:175], v[212:215], v[72:75]
	v_mfma_f32_16x16x32_bf16 v[64:67], v[180:183], v[212:215], v[64:67]
	s_setprio 0
	s_barrier
	s_add_i32 s59, s34, s3
	v_lshl_add_u64 v[216:217], s[60:61], 0, v[132:133]
	s_mov_b32 m0, s59
	ds_read_b128 v[184:187], v150 offset:16384
	ds_read_b128 v[188:191], v150 offset:17408
	ds_read_b128 v[192:195], v150 offset:18432
	ds_read_b128 v[196:199], v150 offset:19456
	ds_read_b128 v[200:203], v150 offset:20480
	ds_read_b128 v[204:207], v150 offset:21504
	ds_read_b128 v[208:211], v150 offset:22528
	ds_read_b128 v[212:215], v150 offset:23552
	global_load_lds_dwordx4 v[216:217], off
	s_add_i32 m0, s59, 0x2000
	v_lshl_add_u64 v[218:219], s[60:61], 0, v[128:129]
	s_add_u32 s60, s60, s16
	s_addc_u32 s61, s61, s17
	s_add_i32 s59, s35, s3
	global_load_lds_dwordx4 v[218:219], off
	v_lshl_add_u64 v[220:221], s[60:61], 0, v[132:133]
	s_mov_b32 m0, s59
	v_lshl_add_u64 v[222:223], s[60:61], 0, v[128:129]
	global_load_lds_dwordx4 v[220:221], off
	s_add_i32 m0, s59, 0x2000
	v_lshl_add_u64 v[224:225], s[52:53], 0, v[134:135]
	global_load_lds_dwordx4 v[222:223], off
	s_mov_b32 m0, s7
	v_lshl_add_u64 v[226:227], s[52:53], 0, v[130:131]
	global_load_lds_dwordx4 v[224:225], off
	s_mov_b32 m0, s18
	s_nop 0
	global_load_lds_dwordx4 v[226:227], off
	s_waitcnt vmcnt(8)
	s_waitcnt lgkmcnt(0)
	s_barrier
; #define PG8_STAGE(bufoff, gbase, voff) do { _Pragma("unroll") for (int _i = 0; _i < 2; ++_i) \
;         __builtin_amdgcn_global_load_lds((const unsigned*)((const char*)(gbase) + (voff)[_i]), (PG8_LAS unsigned*)(lds + (bufoff) + ldsw + _i * 8192), 16, 0, 0); } while (0)
; #define PG8_LDA(dst, b, h) do { _Pragma("unroll") for (int m = 0; m < 4; ++m) _Pragma("unroll") for (int k = 0; k < 2; ++k) dst[m][k] = *(const PG8_LAS bf16x8*)(lds + PG8_SA(b, h) + aoff + m * 2048 + k * 1024); } while (0)
; #define PG8_LDB(dst, b, h) do { _Pragma("unroll") for (int n = 0; n < 2; ++n) _Pragma("unroll") for (int k = 0; k < 2; ++k) dst[n][k] = *(const PG8_LAS bf16x8*)(lds + PG8_SB(b, h) + boff + n * 2048 + k * 1024); } while (0)
; #define PG8_MMA(ai, bj, At, Bt) do { __builtin_amdgcn_s_setprio(1); _Pragma("unroll") for (int m = 0; m < 4; ++m) _Pragma("unroll") for (int n = 0; n < 2; ++n) _Pragma("unroll") for (int k = 0; k < 2; ++k) \
;         acc[ai][bj][m][n] = __builtin_amdgcn_mfma_f32_16x16x32_bf16(Bt[n][k], At[m][k], acc[ai][bj][m][n], 0, 0, 0); __builtin_amdgcn_s_setprio(0); } while (0)
; #define PG8_WAIT_V(n) asm volatile("s_waitcnt vmcnt(" #n ")" ::: "memory")
; #define PG8_WAIT_L(n) asm volatile("s_waitcnt lgkmcnt(" #n ")" ::: "memory")
; #define PG8_BAR __builtin_amdgcn_s_barrier()
; #define PG8_SCHED __builtin_amdgcn_sched_barrier(0)
; template <class Epi, class Sched, bool ALIGN_EPI = false, bool SP2 = false>
; __device__ __forceinline__ void gemm_phase(PG8_LAS unsigned char* lds, const Gemm g, const Sched& S, const Epi& E) {
;     ...
;             PG8_WAIT_V(8); PG8_WAIT_L(0); PG8_BAR; PG8_MMA(1, 0, At, B0); PG8_MMA(1, 1, At, B1); PG8_BAR; PG8_SCHED;
;             PG8_LDB(B0, 1, 0); PG8_LDB(B1, 1, 1); PG8_SCHED; PG8_LDA(At, 1, 0); PG8_STAGE(PG8_SA(0, 1), a2 + hstep, voffA);
;             PG8_WAIT_V(8); PG8_WAIT_L(0); PG8_BAR; PG8_MMA(0, 0, At, B0); PG8_MMA(0, 1, At, B1); PG8_BAR; PG8_SCHED;
;             PG8_LDA(At, 1, 1); PG8_STAGE(PG8_SB(1, 0), b3, voffB); PG8_STAGE(PG8_SB(1, 1), b3 + hstep, voffB); PG8_STAGE(PG8_SA(1, 0), a3, voffA);
	s_setprio 1
	s_waitcnt lgkmcnt(0)
	v_mfma_f32_16x16x32_bf16 v[60:63], v[152:155], v[184:187], 0
	v_mfma_f32_16x16x32_bf16 v[52:55], v[160:163], v[184:187], 0
	v_mfma_f32_16x16x32_bf16 v[44:47], v[152:155], v[192:195], 0
	v_mfma_f32_16x16x32_bf16 v[36:39], v[160:163], v[192:195], 0
	v_mfma_f32_16x16x32_bf16 v[28:31], v[152:155], v[200:203], 0
	v_mfma_f32_16x16x32_bf16 v[20:23], v[160:163], v[200:203], 0
	v_mfma_f32_16x16x32_bf16 v[12:15], v[152:155], v[208:211], 0
	v_mfma_f32_16x16x32_bf16 v[4:7], v[160:163], v[208:211], 0
	v_mfma_f32_16x16x32_bf16 v[60:63], v[156:159], v[188:191], v[60:63]
	v_mfma_f32_16x16x32_bf16 v[52:55], v[164:167], v[188:191], v[52:55]
	v_mfma_f32_16x16x32_bf16 v[44:47], v[156:159], v[196:199], v[44:47]
	v_mfma_f32_16x16x32_bf16 v[36:39], v[164:167], v[196:199], v[36:39]
	v_mfma_f32_16x16x32_bf16 v[28:31], v[156:159], v[204:207], v[28:31]
	v_mfma_f32_16x16x32_bf16 v[20:23], v[164:167], v[204:207], v[20:23]
	v_mfma_f32_16x16x32_bf16 v[12:15], v[156:159], v[212:215], v[12:15]
	v_mfma_f32_16x16x32_bf16 v[4:7], v[164:167], v[212:215], v[4:7]
	s_setprio 0
	s_setprio 1
	v_mfma_f32_16x16x32_bf16 v[56:59], v[168:171], v[184:187], 0
	v_mfma_f32_16x16x32_bf16 v[48:51], v[176:179], v[184:187], 0
	v_mfma_f32_16x16x32_bf16 v[40:43], v[168:171], v[192:195], 0
	v_mfma_f32_16x16x32_bf16 v[32:35], v[176:179], v[192:195], 0
	v_mfma_f32_16x16x32_bf16 v[24:27], v[168:171], v[200:203], 0
	v_mfma_f32_16x16x32_bf16 v[16:19], v[176:179], v[200:203], 0
	v_mfma_f32_16x16x32_bf16 v[8:11], v[168:171], v[208:211], 0
	v_mfma_f32_16x16x32_bf16 v[0:3], v[176:179], v[208:211], 0
	v_mfma_f32_16x16x32_bf16 v[56:59], v[172:175], v[188:191], v[56:59]
	v_mfma_f32_16x16x32_bf16 v[48:51], v[180:183], v[188:191], v[48:51]
	v_mfma_f32_16x16x32_bf16 v[40:43], v[172:175], v[196:199], v[40:43]
	v_mfma_f32_16x16x32_bf16 v[32:35], v[180:183], v[196:199], v[32:35]
	v_mfma_f32_16x16x32_bf16 v[24:27], v[172:175], v[204:207], v[24:27]
	v_mfma_f32_16x16x32_bf16 v[16:19], v[180:183], v[204:207], v[16:19]
	v_mfma_f32_16x16x32_bf16 v[8:11], v[172:175], v[212:215], v[8:11]
	v_mfma_f32_16x16x32_bf16 v[0:3], v[180:183], v[212:215], v[0:3]
	s_setprio 0
	s_barrier
	s_add_i32 s59, 0, 0x18000
	v_add_u32_e32 v151, s59, v145
	s_add_i32 s60, 0, 0x1c000
	ds_read_b128 v[152:155], v151
	ds_read_b128 v[156:159], v151 offset:1024
	ds_read_b128 v[160:163], v151 offset:2048
	ds_read_b128 v[164:167], v151 offset:3072
	v_add_u32_e32 v151, s60, v145
	ds_read_b128 v[168:171], v151
	ds_read_b128 v[172:175], v151 offset:1024
	ds_read_b128 v[176:179], v151 offset:2048
	ds_read_b128 v[180:183], v151 offset:3072
	s_add_u32 s52, s52, s16
	s_addc_u32 s53, s53, s17
	s_mov_b32 m0, s19
	v_lshl_add_u64 v[228:229], s[52:53], 0, v[134:135]
	ds_read_b128 v[184:187], v150 offset:32768
	ds_read_b128 v[188:191], v150 offset:33792
	ds_read_b128 v[192:195], v150 offset:34816
	ds_read_b128 v[196:199], v150 offset:35840
	ds_read_b128 v[200:203], v150 offset:36864
	ds_read_b128 v[204:207], v150 offset:37888
	ds_read_b128 v[208:211], v150 offset:38912
	ds_read_b128 v[212:215], v150 offset:39936
	global_load_lds_dwordx4 v[228:229], off
	v_lshl_add_u64 v[228:229], s[52:53], 0, v[130:131]
	s_mov_b32 m0, s26
	s_nop 0
	global_load_lds_dwordx4 v[228:229], off
	s_waitcnt vmcnt(8)
	s_waitcnt lgkmcnt(0)
	s_barrier
	s_setprio 1
	s_waitcnt lgkmcnt(0)
	v_mfma_f32_16x16x32_bf16 v[120:123], v[152:155], v[184:187], v[120:123]
	v_mfma_f32_16x16x32_bf16 v[116:119], v[160:163], v[184:187], v[116:119]
	v_mfma_f32_16x16x32_bf16 v[108:111], v[152:155], v[192:195], v[108:111]
	v_mfma_f32_16x16x32_bf16 v[100:103], v[160:163], v[192:195], v[100:103]
	v_mfma_f32_16x16x32_bf16 v[92:95], v[152:155], v[200:203], v[92:95]
	v_mfma_f32_16x16x32_bf16 v[84:87], v[160:163], v[200:203], v[84:87]
	v_mfma_f32_16x16x32_bf16 v[76:79], v[152:155], v[208:211], v[76:79]
	v_mfma_f32_16x16x32_bf16 v[68:71], v[160:163], v[208:211], v[68:71]
	v_mfma_f32_16x16x32_bf16 v[120:123], v[156:159], v[188:191], v[120:123]
	v_mfma_f32_16x16x32_bf16 v[116:119], v[164:167], v[188:191], v[116:119]
	v_mfma_f32_16x16x32_bf16 v[108:111], v[156:159], v[196:199], v[108:111]
	v_mfma_f32_16x16x32_bf16 v[100:103], v[164:167], v[196:199], v[100:103]
	v_mfma_f32_16x16x32_bf16 v[92:95], v[156:159], v[204:207], v[92:95]
	v_mfma_f32_16x16x32_bf16 v[84:87], v[164:167], v[204:207], v[84:87]
	v_mfma_f32_16x16x32_bf16 v[76:79], v[156:159], v[212:215], v[76:79]
	v_mfma_f32_16x16x32_bf16 v[68:71], v[164:167], v[212:215], v[68:71]
	s_setprio 0
	s_setprio 1
	v_mfma_f32_16x16x32_bf16 v[124:127], v[168:171], v[184:187], v[124:127]
	v_mfma_f32_16x16x32_bf16 v[112:115], v[176:179], v[184:187], v[112:115]
	v_mfma_f32_16x16x32_bf16 v[104:107], v[168:171], v[192:195], v[104:107]
	v_mfma_f32_16x16x32_bf16 v[96:99], v[176:179], v[192:195], v[96:99]
	v_mfma_f32_16x16x32_bf16 v[88:91], v[168:171], v[200:203], v[88:91]
	v_mfma_f32_16x16x32_bf16 v[80:83], v[176:179], v[200:203], v[80:83]
	v_mfma_f32_16x16x32_bf16 v[72:75], v[168:171], v[208:211], v[72:75]
	v_mfma_f32_16x16x32_bf16 v[64:67], v[176:179], v[208:211], v[64:67]
	v_mfma_f32_16x16x32_bf16 v[124:127], v[172:175], v[188:191], v[124:127]
	v_mfma_f32_16x16x32_bf16 v[112:115], v[180:183], v[188:191], v[112:115]
	v_mfma_f32_16x16x32_bf16 v[104:107], v[172:175], v[196:199], v[104:107]
	v_mfma_f32_16x16x32_bf16 v[96:99], v[180:183], v[196:199], v[96:99]
	v_mfma_f32_16x16x32_bf16 v[88:91], v[172:175], v[204:207], v[88:91]
	v_mfma_f32_16x16x32_bf16 v[80:83], v[180:183], v[204:207], v[80:83]
	v_mfma_f32_16x16x32_bf16 v[72:75], v[172:175], v[212:215], v[72:75]
	v_mfma_f32_16x16x32_bf16 v[64:67], v[180:183], v[212:215], v[64:67]
	s_setprio 0
	s_barrier
; #define PG8_STAGE(bufoff, gbase, voff) do { _Pragma("unroll") for (int _i = 0; _i < 2; ++_i) \
;         __builtin_amdgcn_global_load_lds((const unsigned*)((const char*)(gbase) + (voff)[_i]), (PG8_LAS unsigned*)(lds + (bufoff) + ldsw + _i * 8192), 16, 0, 0); } while (0)
; #define PG8_LDA(dst, b, h) do { _Pragma("unroll") for (int m = 0; m < 4; ++m) _Pragma("unroll") for (int k = 0; k < 2; ++k) dst[m][k] = *(const PG8_LAS bf16x8*)(lds + PG8_SA(b, h) + aoff + m * 2048 + k * 1024); } while (0)
; #define PG8_MMA(ai, bj, At, Bt) do { __builtin_amdgcn_s_setprio(1); _Pragma("unroll") for (int m = 0; m < 4; ++m) _Pragma("unroll") for (int n = 0; n < 2; ++n) _Pragma("unroll") for (int k = 0; k < 2; ++k) \
;         acc[ai][bj][m][n] = __builtin_amdgcn_mfma_f32_16x16x32_bf16(Bt[n][k], At[m][k], acc[ai][bj][m][n], 0, 0, 0); __builtin_amdgcn_s_setprio(0); } while (0)
; #define PG8_WAIT_V(n) asm volatile("s_waitcnt vmcnt(" #n ")" ::: "memory")
; #define PG8_WAIT_L(n) asm volatile("s_waitcnt lgkmcnt(" #n ")" ::: "memory")
; #define PG8_BAR __builtin_amdgcn_s_barrier()
; #define PG8_SCHED __builtin_amdgcn_sched_barrier(0)
; template <class Epi, class Sched, bool ALIGN_EPI = false, bool SP2 = false>
; __device__ __forceinline__ void gemm_phase(PG8_LAS unsigned char* lds, const Gemm g, const Sched& S, const Epi& E) {
;     ...
;         for (int t = 0; t < nt; t += 2) {
;             const bool last = (t == nt - 2);
;             const char* a1 = cA + (size_t)(t + 1) * kstep;
;             const char* a2 = last ? nA : cA + (size_t)(t + 2) * kstep; const char* b2 = last ? nB : cB + (size_t)(t + 2) * kstep;
;     ...
;             PG8_LDA(At, 1, 1); PG8_STAGE(PG8_SB(1, 0), b3, voffB); PG8_STAGE(PG8_SB(1, 1), b3 + hstep, voffB); PG8_STAGE(PG8_SA(1, 0), a3, voffA);
;             PG8_WAIT_V(8); PG8_WAIT_L(0); PG8_BAR; PG8_MMA(1, 0, At, B0); PG8_MMA(1, 1, At, B1); PG8_BAR; PG8_SCHED;
	s_add_i32 s52, s59, s3
	v_lshl_add_u64 v[216:217], v[216:217], 0, s[44:45]
	s_mov_b32 m0, s52
	ds_read_b128 v[184:187], v150 offset:49152
	ds_read_b128 v[188:191], v150 offset:50176
	ds_read_b128 v[192:195], v150 offset:51200
	ds_read_b128 v[196:199], v150 offset:52224
	ds_read_b128 v[200:203], v150 offset:53248
	ds_read_b128 v[204:207], v150 offset:54272
	ds_read_b128 v[208:211], v150 offset:55296
	ds_read_b128 v[212:215], v150 offset:56320
	global_load_lds_dwordx4 v[216:217], off
	v_lshl_add_u64 v[216:217], v[218:219], 0, s[44:45]
	s_add_i32 m0, s52, 0x2000
	s_add_i32 s52, s60, s3
	global_load_lds_dwordx4 v[216:217], off
	v_lshl_add_u64 v[216:217], v[220:221], 0, s[44:45]
	s_mov_b32 m0, s52
	s_nop 0
	global_load_lds_dwordx4 v[216:217], off
	v_lshl_add_u64 v[216:217], v[222:223], 0, s[44:45]
	s_add_i32 m0, s52, 0x2000
	s_nop 0
	global_load_lds_dwordx4 v[216:217], off
	v_lshl_add_u64 v[216:217], v[224:225], 0, s[44:45]
	s_mov_b32 m0, s27
	s_nop 0
	global_load_lds_dwordx4 v[216:217], off
	v_lshl_add_u64 v[216:217], v[226:227], 0, s[44:45]
	s_mov_b32 m0, s30
	s_nop 0
	global_load_lds_dwordx4 v[216:217], off
	s_waitcnt vmcnt(8)
	s_waitcnt lgkmcnt(0)
	s_barrier
	s_setprio 1
	s_waitcnt lgkmcnt(0)
	v_mfma_f32_16x16x32_bf16 v[60:63], v[152:155], v[184:187], v[60:63]
	v_mfma_f32_16x16x32_bf16 v[52:55], v[160:163], v[184:187], v[52:55]
	v_mfma_f32_16x16x32_bf16 v[44:47], v[152:155], v[192:195], v[44:47]
	v_mfma_f32_16x16x32_bf16 v[36:39], v[160:163], v[192:195], v[36:39]
	v_mfma_f32_16x16x32_bf16 v[28:31], v[152:155], v[200:203], v[28:31]
	v_mfma_f32_16x16x32_bf16 v[20:23], v[160:163], v[200:203], v[20:23]
	v_mfma_f32_16x16x32_bf16 v[12:15], v[152:155], v[208:211], v[12:15]
	v_mfma_f32_16x16x32_bf16 v[4:7], v[160:163], v[208:211], v[4:7]
	v_mfma_f32_16x16x32_bf16 v[60:63], v[156:159], v[188:191], v[60:63]
	v_mfma_f32_16x16x32_bf16 v[52:55], v[164:167], v[188:191], v[52:55]
	v_mfma_f32_16x16x32_bf16 v[44:47], v[156:159], v[196:199], v[44:47]
	v_mfma_f32_16x16x32_bf16 v[36:39], v[164:167], v[196:199], v[36:39]
	v_mfma_f32_16x16x32_bf16 v[28:31], v[156:159], v[204:207], v[28:31]
	v_mfma_f32_16x16x32_bf16 v[20:23], v[164:167], v[204:207], v[20:23]
	v_mfma_f32_16x16x32_bf16 v[12:15], v[156:159], v[212:215], v[12:15]
	v_mfma_f32_16x16x32_bf16 v[4:7], v[164:167], v[212:215], v[4:7]
	s_setprio 0
	s_setprio 1
	v_mfma_f32_16x16x32_bf16 v[56:59], v[168:171], v[184:187], v[56:59]
	v_mfma_f32_16x16x32_bf16 v[48:51], v[176:179], v[184:187], v[48:51]
	v_mfma_f32_16x16x32_bf16 v[40:43], v[168:171], v[192:195], v[40:43]
	v_mfma_f32_16x16x32_bf16 v[32:35], v[176:179], v[192:195], v[32:35]
	v_mfma_f32_16x16x32_bf16 v[24:27], v[168:171], v[200:203], v[24:27]
	v_mfma_f32_16x16x32_bf16 v[16:19], v[176:179], v[200:203], v[16:19]
	v_mfma_f32_16x16x32_bf16 v[8:11], v[168:171], v[208:211], v[8:11]
	v_mfma_f32_16x16x32_bf16 v[0:3], v[176:179], v[208:211], v[0:3]
	v_mfma_f32_16x16x32_bf16 v[56:59], v[172:175], v[188:191], v[56:59]
	v_mfma_f32_16x16x32_bf16 v[48:51], v[180:183], v[188:191], v[48:51]
	v_mfma_f32_16x16x32_bf16 v[40:43], v[172:175], v[196:199], v[40:43]
	v_mfma_f32_16x16x32_bf16 v[32:35], v[180:183], v[196:199], v[32:35]
	v_mfma_f32_16x16x32_bf16 v[24:27], v[172:175], v[204:207], v[24:27]
	v_mfma_f32_16x16x32_bf16 v[16:19], v[180:183], v[204:207], v[16:19]
	v_mfma_f32_16x16x32_bf16 v[8:11], v[172:175], v[212:215], v[8:11]
	v_mfma_f32_16x16x32_bf16 v[0:3], v[180:183], v[212:215], v[0:3]
	s_setprio 0
	s_barrier
	s_add_u32 s50, s50, 0x100
	s_addc_u32 s51, s51, 0
	s_add_u32 s24, s24, 0x100
	s_addc_u32 s25, s25, 0
	s_cmp_ge_i32 s58, s31
	s_mov_b32 s52, s58
	s_cbranch_scc1 .Lpeelx_4

; #define PG8_BAR __builtin_amdgcn_s_barrier()
; template <class Epi, class Sched, bool ALIGN_EPI = false, bool SP2 = false>
; __device__ __forceinline__ void gemm_phase(PG8_LAS unsigned char* lds, const Gemm g, const Sched& S, const Epi& E) {
;     ...
;         if constexpr (ALIGN_EPI) { if (wr == 0) PG8_BAR; }
;         if constexpr (!Epi::AFTER_DRAIN) { E(acc, cur, wr, wc, fr, fq); S.done(cur); }
.Lpeelx_4:
.LBB0_1324:
	s_and_b64 vcc, exec, s[46:47]
	s_cbranch_vccz .LBB0_1326
	s_barrier

; #define PG8_STAGE(bufoff, gbase, voff) do { _Pragma("unroll") for (int _i = 0; _i < 2; ++_i) \
;         __builtin_amdgcn_global_load_lds((const unsigned*)((const char*)(gbase) + (voff)[_i]), (PG8_LAS unsigned*)(lds + (bufoff) + ldsw + _i * 8192), 16, 0, 0); } while (0)
; #define PG8_LDA(dst, b, h) do { _Pragma("unroll") for (int m = 0; m < 4; ++m) _Pragma("unroll") for (int k = 0; k < 2; ++k) dst[m][k] = *(const PG8_LAS bf16x8*)(lds + PG8_SA(b, h) + aoff + m * 2048 + k * 1024); } while (0)
; #define PG8_LDB(dst, b, h) do { _Pragma("unroll") for (int n = 0; n < 2; ++n) _Pragma("unroll") for (int k = 0; k < 2; ++k) dst[n][k] = *(const PG8_LAS bf16x8*)(lds + PG8_SB(b, h) + boff + n * 2048 + k * 1024); } while (0)
; #define PG8_WAIT_V(n) asm volatile("s_waitcnt vmcnt(" #n ")" ::: "memory")
; #define PG8_WAIT_L(n) asm volatile("s_waitcnt lgkmcnt(" #n ")" ::: "memory")
; #define PG8_BAR __builtin_amdgcn_s_barrier()
; #define PG8_SCHED __builtin_amdgcn_sched_barrier(0)
; template <class Epi, class Sched, bool ALIGN_EPI = false, bool SP2 = false>
; __device__ __forceinline__ void gemm_phase(PG8_LAS unsigned char* lds, const Gemm g, const Sched& S, const Epi& E) {
;     ...
;     f32x4 acc[2][2][4][2];
; #pragma unroll
;     for (int a = 0; a < 2; ++a)
; #pragma unroll
;         for (int b = 0; b < 2; ++b)
; #pragma unroll
;             for (int m = 0; m < 4; ++m)
; #pragma unroll
;                 for (int n = 0; n < 2; ++n) acc[a][b][m][n] = (f32x4){0.f, 0.f, 0.f, 0.f};
;     ...
;         for (int t = 0; t < nt; t += 2) {
;             const bool last = (t == nt - 2);
;             const char* a1 = cA + (size_t)(t + 1) * kstep;
;             const char* a2 = last ? nA : cA + (size_t)(t + 2) * kstep; const char* b2 = last ? nB : cB + (size_t)(t + 2) * kstep;
;             const char* a3 = a2 + kstep; const char* b3 = b2 + kstep;
;             if (last && has_next) S.a_ready(nxt);
;             if constexpr (SP2) {
;             PG8_LDB(B0, 0, 0); PG8_LDB(B1, 0, 1); PG8_SCHED; PG8_LDA(At, 0, 0); PG8_STAGE(PG8_SA(1, 1), a1 + hstep, voffA);
;             PG8_WAIT_V(8); PG8_WAIT_L(0); PG8_BAR; PG8_MMA(0, 0, At, B0); PG8_MMA(0, 1, At, B1); PG8_BAR; PG8_SCHED;
;             PG8_LDA(At, 0, 1); PG8_STAGE(PG8_SB(0, 0), b2, voffB); PG8_STAGE(PG8_SB(0, 1), b2 + hstep, voffB); PG8_STAGE(PG8_SA(0, 0), a2, voffA);
.LBB0_1404:
	s_and_b64 vcc, exec, s[12:13]
	s_cbranch_vccnz .Lcoldz_5
	s_add_u32 s56, s56, 0x80
	s_addc_u32 s57, s57, 0
	s_add_u32 s2, s58, 0x100
	s_addc_u32 s24, s59, 0
	s_mov_b32 s25, 0
	ds_read_b128 v[142:145], v246
	ds_read_b128 v[146:149], v246 offset:1024
	ds_read_b128 v[150:153], v246 offset:2048
	ds_read_b128 v[154:157], v246 offset:3072
	ds_read_b128 v[158:161], v247
	ds_read_b128 v[162:165], v247 offset:1024
	ds_read_b128 v[166:169], v247 offset:2048
	ds_read_b128 v[170:173], v247 offset:3072
	s_add_i32 s60, s25, 2
	s_add_u32 s58, s56, 0x80
	s_addc_u32 s59, s57, 0
	s_cmp_eq_u32 s34, s25
	s_cselect_b32 s59, s17, s59
	s_cselect_b32 s58, s16, s58
	s_cselect_b32 s63, s55, s24
	s_cselect_b32 s62, s54, s2
	v_lshl_add_u64 v[206:207], s[56:57], 0, v[136:137]
	s_add_i32 m0, s7, 0xc000
	ds_read_b128 v[174:177], v248
	ds_read_b128 v[178:181], v248 offset:1024
	ds_read_b128 v[182:185], v248 offset:2048
	ds_read_b128 v[186:189], v248 offset:3072
	ds_read_b128 v[190:193], v248 offset:4096
	ds_read_b128 v[194:197], v248 offset:5120
	ds_read_b128 v[198:201], v248 offset:6144
	ds_read_b128 v[202:205], v248 offset:7168
	global_load_lds_dwordx4 v[206:207], off
	v_lshl_add_u64 v[206:207], s[56:57], 0, v[138:139]
	s_add_i32 m0, s7, 0xe000
	s_nop 0
	global_load_lds_dwordx4 v[206:207], off
	s_waitcnt vmcnt(8)
	s_waitcnt lgkmcnt(0)
	s_barrier
	s_setprio 1
	s_waitcnt lgkmcnt(0)
	v_mfma_f32_16x16x32_bf16 v[124:127], v[142:145], v[174:177], 0
	v_mfma_f32_16x16x32_bf16 v[120:123], v[150:153], v[174:177], 0
	v_mfma_f32_16x16x32_bf16 v[116:119], v[142:145], v[182:185], 0
	v_mfma_f32_16x16x32_bf16 v[112:115], v[150:153], v[182:185], 0
	v_mfma_f32_16x16x32_bf16 v[104:107], v[142:145], v[190:193], 0
	v_mfma_f32_16x16x32_bf16 v[96:99], v[150:153], v[190:193], 0
	v_mfma_f32_16x16x32_bf16 v[88:91], v[142:145], v[198:201], 0
	v_mfma_f32_16x16x32_bf16 v[80:83], v[150:153], v[198:201], 0
	v_mfma_f32_16x16x32_bf16 v[124:127], v[146:149], v[178:181], v[124:127]
	v_mfma_f32_16x16x32_bf16 v[120:123], v[154:157], v[178:181], v[120:123]
	v_mfma_f32_16x16x32_bf16 v[116:119], v[146:149], v[186:189], v[116:119]
	v_mfma_f32_16x16x32_bf16 v[112:115], v[154:157], v[186:189], v[112:115]
	v_mfma_f32_16x16x32_bf16 v[104:107], v[146:149], v[194:197], v[104:107]
	v_mfma_f32_16x16x32_bf16 v[96:99], v[154:157], v[194:197], v[96:99]
	v_mfma_f32_16x16x32_bf16 v[88:91], v[146:149], v[202:205], v[88:91]
	v_mfma_f32_16x16x32_bf16 v[80:83], v[154:157], v[202:205], v[80:83]
	s_setprio 0
	s_setprio 1
	v_mfma_f32_16x16x32_bf16 v[108:111], v[158:161], v[174:177], 0
	v_mfma_f32_16x16x32_bf16 v[100:103], v[166:169], v[174:177], 0
	v_mfma_f32_16x16x32_bf16 v[92:95], v[158:161], v[182:185], 0
	v_mfma_f32_16x16x32_bf16 v[84:87], v[166:169], v[182:185], 0
	v_mfma_f32_16x16x32_bf16 v[76:79], v[158:161], v[190:193], 0
	v_mfma_f32_16x16x32_bf16 v[72:75], v[166:169], v[190:193], 0
	v_mfma_f32_16x16x32_bf16 v[68:71], v[158:161], v[198:201], 0
	v_mfma_f32_16x16x32_bf16 v[64:67], v[166:169], v[198:201], 0
	v_mfma_f32_16x16x32_bf16 v[108:111], v[162:165], v[178:181], v[108:111]
	v_mfma_f32_16x16x32_bf16 v[100:103], v[170:173], v[178:181], v[100:103]
	v_mfma_f32_16x16x32_bf16 v[92:95], v[162:165], v[186:189], v[92:95]
	v_mfma_f32_16x16x32_bf16 v[84:87], v[170:173], v[186:189], v[84:87]
	v_mfma_f32_16x16x32_bf16 v[76:79], v[162:165], v[194:197], v[76:79]
	v_mfma_f32_16x16x32_bf16 v[72:75], v[170:173], v[194:197], v[72:75]
	v_mfma_f32_16x16x32_bf16 v[68:71], v[162:165], v[202:205], v[68:71]
	v_mfma_f32_16x16x32_bf16 v[64:67], v[170:173], v[202:205], v[64:67]
	s_setprio 0
	s_barrier
	s_add_i32 s25, s35, s6
	v_lshl_add_u64 v[206:207], s[62:63], 0, v[130:131]
	s_mov_b32 m0, s25
	ds_read_b128 v[174:177], v248 offset:16384
	ds_read_b128 v[178:181], v248 offset:17408
	ds_read_b128 v[182:185], v248 offset:18432
	ds_read_b128 v[186:189], v248 offset:19456
	ds_read_b128 v[190:193], v248 offset:20480
	ds_read_b128 v[194:197], v248 offset:21504
	ds_read_b128 v[198:201], v248 offset:22528
	ds_read_b128 v[202:205], v248 offset:23552
	global_load_lds_dwordx4 v[206:207], off
	s_add_i32 m0, s25, 0x2000
	v_lshl_add_u64 v[208:209], s[62:63], 0, v[134:135]
	s_add_u32 s62, s62, s42
	s_addc_u32 s63, s63, s43
	s_add_i32 s25, s36, s6
	global_load_lds_dwordx4 v[208:209], off
	v_lshl_add_u64 v[210:211], s[62:63], 0, v[130:131]
	s_mov_b32 m0, s25
	v_lshl_add_u64 v[212:213], s[62:63], 0, v[134:135]
	global_load_lds_dwordx4 v[210:211], off
	s_add_i32 m0, s25, 0x2000
	v_lshl_add_u64 v[214:215], s[58:59], 0, v[128:129]
	global_load_lds_dwordx4 v[212:213], off
	s_mov_b32 m0, s7
	v_lshl_add_u64 v[216:217], s[58:59], 0, v[132:133]
	global_load_lds_dwordx4 v[214:215], off
	s_mov_b32 m0, s18
	s_nop 0
	global_load_lds_dwordx4 v[216:217], off
	s_waitcnt vmcnt(8)
	s_waitcnt lgkmcnt(0)
	s_barrier
; #define PG8_STAGE(bufoff, gbase, voff) do { _Pragma("unroll") for (int _i = 0; _i < 2; ++_i) \
;         __builtin_amdgcn_global_load_lds((const unsigned*)((const char*)(gbase) + (voff)[_i]), (PG8_LAS unsigned*)(lds + (bufoff) + ldsw + _i * 8192), 16, 0, 0); } while (0)
; #define PG8_LDA(dst, b, h) do { _Pragma("unroll") for (int m = 0; m < 4; ++m) _Pragma("unroll") for (int k = 0; k < 2; ++k) dst[m][k] = *(const PG8_LAS bf16x8*)(lds + PG8_SA(b, h) + aoff + m * 2048 + k * 1024); } while (0)
; #define PG8_LDB(dst, b, h) do { _Pragma("unroll") for (int n = 0; n < 2; ++n) _Pragma("unroll") for (int k = 0; k < 2; ++k) dst[n][k] = *(const PG8_LAS bf16x8*)(lds + PG8_SB(b, h) + boff + n * 2048 + k * 1024); } while (0)
; #define PG8_MMA(ai, bj, At, Bt) do { __builtin_amdgcn_s_setprio(1); _Pragma("unroll") for (int m = 0; m < 4; ++m) _Pragma("unroll") for (int n = 0; n < 2; ++n) _Pragma("unroll") for (int k = 0; k < 2; ++k) \
;         acc[ai][bj][m][n] = __builtin_amdgcn_mfma_f32_16x16x32_bf16(Bt[n][k], At[m][k], acc[ai][bj][m][n], 0, 0, 0); __builtin_amdgcn_s_setprio(0); } while (0)
; #define PG8_WAIT_V(n) asm volatile("s_waitcnt vmcnt(" #n ")" ::: "memory")
; #define PG8_WAIT_L(n) asm volatile("s_waitcnt lgkmcnt(" #n ")" ::: "memory")
; #define PG8_BAR __builtin_amdgcn_s_barrier()
; #define PG8_SCHED __builtin_amdgcn_sched_barrier(0)
; template <class Epi, class Sched, bool ALIGN_EPI = false, bool SP2 = false>
; __device__ __forceinline__ void gemm_phase(PG8_LAS unsigned char* lds, const Gemm g, const Sched& S, const Epi& E) {
;     ...
;             PG8_WAIT_V(8); PG8_WAIT_L(0); PG8_BAR; PG8_MMA(1, 0, At, B0); PG8_MMA(1, 1, At, B1); PG8_BAR; PG8_SCHED;
;             PG8_LDB(B0, 1, 0); PG8_LDB(B1, 1, 1); PG8_SCHED; PG8_LDA(At, 1, 0); PG8_STAGE(PG8_SA(0, 1), a2 + hstep, voffA);
;             PG8_WAIT_V(8); PG8_WAIT_L(0); PG8_BAR; PG8_MMA(0, 0, At, B0); PG8_MMA(0, 1, At, B1); PG8_BAR; PG8_SCHED;
	s_setprio 1
	s_waitcnt lgkmcnt(0)
	v_mfma_f32_16x16x32_bf16 v[60:63], v[142:145], v[174:177], 0
	v_mfma_f32_16x16x32_bf16 v[56:59], v[150:153], v[174:177], 0
	v_mfma_f32_16x16x32_bf16 v[52:55], v[142:145], v[182:185], 0
	v_mfma_f32_16x16x32_bf16 v[48:51], v[150:153], v[182:185], 0
	v_mfma_f32_16x16x32_bf16 v[40:43], v[142:145], v[190:193], 0
	v_mfma_f32_16x16x32_bf16 v[32:35], v[150:153], v[190:193], 0
	v_mfma_f32_16x16x32_bf16 v[24:27], v[142:145], v[198:201], 0
	v_mfma_f32_16x16x32_bf16 v[16:19], v[150:153], v[198:201], 0
	v_mfma_f32_16x16x32_bf16 v[60:63], v[146:149], v[178:181], v[60:63]
	v_mfma_f32_16x16x32_bf16 v[56:59], v[154:157], v[178:181], v[56:59]
	v_mfma_f32_16x16x32_bf16 v[52:55], v[146:149], v[186:189], v[52:55]
	v_mfma_f32_16x16x32_bf16 v[48:51], v[154:157], v[186:189], v[48:51]
	v_mfma_f32_16x16x32_bf16 v[40:43], v[146:149], v[194:197], v[40:43]
	v_mfma_f32_16x16x32_bf16 v[32:35], v[154:157], v[194:197], v[32:35]
	v_mfma_f32_16x16x32_bf16 v[24:27], v[146:149], v[202:205], v[24:27]
	v_mfma_f32_16x16x32_bf16 v[16:19], v[154:157], v[202:205], v[16:19]
	s_setprio 0
	s_setprio 1
	v_mfma_f32_16x16x32_bf16 v[44:47], v[158:161], v[174:177], 0
	v_mfma_f32_16x16x32_bf16 v[36:39], v[166:169], v[174:177], 0
	v_mfma_f32_16x16x32_bf16 v[28:31], v[158:161], v[182:185], 0
	v_mfma_f32_16x16x32_bf16 v[20:23], v[166:169], v[182:185], 0
	v_mfma_f32_16x16x32_bf16 v[12:15], v[158:161], v[190:193], 0
	v_mfma_f32_16x16x32_bf16 v[8:11], v[166:169], v[190:193], 0
	v_mfma_f32_16x16x32_bf16 v[4:7], v[158:161], v[198:201], 0
	v_mfma_f32_16x16x32_bf16 v[0:3], v[166:169], v[198:201], 0
	v_mfma_f32_16x16x32_bf16 v[44:47], v[162:165], v[178:181], v[44:47]
	v_mfma_f32_16x16x32_bf16 v[36:39], v[170:173], v[178:181], v[36:39]
	v_mfma_f32_16x16x32_bf16 v[28:31], v[162:165], v[186:189], v[28:31]
	v_mfma_f32_16x16x32_bf16 v[20:23], v[170:173], v[186:189], v[20:23]
	v_mfma_f32_16x16x32_bf16 v[12:15], v[162:165], v[194:197], v[12:15]
	v_mfma_f32_16x16x32_bf16 v[8:11], v[170:173], v[194:197], v[8:11]
	v_mfma_f32_16x16x32_bf16 v[4:7], v[162:165], v[202:205], v[4:7]
	v_mfma_f32_16x16x32_bf16 v[0:3], v[170:173], v[202:205], v[0:3]
	s_setprio 0
	s_barrier
	s_add_i32 s25, 0, 0x18000
	s_add_i32 s61, 0, 0x1c000
	v_add_u32_e32 v154, s25, v244
	v_add_u32_e32 v170, s61, v244
	ds_read_b128 v[142:145], v154
	ds_read_b128 v[146:149], v154 offset:1024
	ds_read_b128 v[150:153], v154 offset:2048
	ds_read_b128 v[154:157], v154 offset:3072
	ds_read_b128 v[158:161], v170
	ds_read_b128 v[162:165], v170 offset:1024
	ds_read_b128 v[166:169], v170 offset:2048
	ds_read_b128 v[170:173], v170 offset:3072
	s_add_u32 s58, s58, s42
	s_addc_u32 s59, s59, s43
	s_mov_b32 m0, s19
	v_lshl_add_u64 v[218:219], s[58:59], 0, v[128:129]
	ds_read_b128 v[174:177], v248 offset:32768
	ds_read_b128 v[178:181], v248 offset:33792
	ds_read_b128 v[182:185], v248 offset:34816
	ds_read_b128 v[186:189], v248 offset:35840
	ds_read_b128 v[190:193], v248 offset:36864
	ds_read_b128 v[194:197], v248 offset:37888
	ds_read_b128 v[198:201], v248 offset:38912
	ds_read_b128 v[202:205], v248 offset:39936
	global_load_lds_dwordx4 v[218:219], off
	v_lshl_add_u64 v[218:219], s[58:59], 0, v[132:133]
	s_mov_b32 m0, s26
	s_nop 0
	global_load_lds_dwordx4 v[218:219], off
	s_waitcnt vmcnt(8)
	s_waitcnt lgkmcnt(0)
	s_barrier
	s_setprio 1
	s_waitcnt lgkmcnt(0)
	v_mfma_f32_16x16x32_bf16 v[124:127], v[142:145], v[174:177], v[124:127]
	v_mfma_f32_16x16x32_bf16 v[120:123], v[150:153], v[174:177], v[120:123]
	v_mfma_f32_16x16x32_bf16 v[116:119], v[142:145], v[182:185], v[116:119]
	v_mfma_f32_16x16x32_bf16 v[112:115], v[150:153], v[182:185], v[112:115]
	v_mfma_f32_16x16x32_bf16 v[104:107], v[142:145], v[190:193], v[104:107]
	v_mfma_f32_16x16x32_bf16 v[96:99], v[150:153], v[190:193], v[96:99]
	v_mfma_f32_16x16x32_bf16 v[88:91], v[142:145], v[198:201], v[88:91]
	v_mfma_f32_16x16x32_bf16 v[80:83], v[150:153], v[198:201], v[80:83]
	v_mfma_f32_16x16x32_bf16 v[124:127], v[146:149], v[178:181], v[124:127]
	v_mfma_f32_16x16x32_bf16 v[120:123], v[154:157], v[178:181], v[120:123]
	v_mfma_f32_16x16x32_bf16 v[116:119], v[146:149], v[186:189], v[116:119]
	v_mfma_f32_16x16x32_bf16 v[112:115], v[154:157], v[186:189], v[112:115]
	v_mfma_f32_16x16x32_bf16 v[104:107], v[146:149], v[194:197], v[104:107]
	v_mfma_f32_16x16x32_bf16 v[96:99], v[154:157], v[194:197], v[96:99]
	v_mfma_f32_16x16x32_bf16 v[88:91], v[146:149], v[202:205], v[88:91]
	v_mfma_f32_16x16x32_bf16 v[80:83], v[154:157], v[202:205], v[80:83]
	s_setprio 0
	s_setprio 1
	v_mfma_f32_16x16x32_bf16 v[108:111], v[158:161], v[174:177], v[108:111]
	v_mfma_f32_16x16x32_bf16 v[100:103], v[166:169], v[174:177], v[100:103]
	v_mfma_f32_16x16x32_bf16 v[92:95], v[158:161], v[182:185], v[92:95]
	v_mfma_f32_16x16x32_bf16 v[84:87], v[166:169], v[182:185], v[84:87]
	v_mfma_f32_16x16x32_bf16 v[76:79], v[158:161], v[190:193], v[76:79]
	v_mfma_f32_16x16x32_bf16 v[72:75], v[166:169], v[190:193], v[72:75]
	v_mfma_f32_16x16x32_bf16 v[68:71], v[158:161], v[198:201], v[68:71]
	v_mfma_f32_16x16x32_bf16 v[64:67], v[166:169], v[198:201], v[64:67]
	v_mfma_f32_16x16x32_bf16 v[108:111], v[162:165], v[178:181], v[108:111]
	v_mfma_f32_16x16x32_bf16 v[100:103], v[170:173], v[178:181], v[100:103]
	v_mfma_f32_16x16x32_bf16 v[92:95], v[162:165], v[186:189], v[92:95]
	v_mfma_f32_16x16x32_bf16 v[84:87], v[170:173], v[186:189], v[84:87]
	v_mfma_f32_16x16x32_bf16 v[76:79], v[162:165], v[194:197], v[76:79]
	v_mfma_f32_16x16x32_bf16 v[72:75], v[170:173], v[194:197], v[72:75]
	v_mfma_f32_16x16x32_bf16 v[68:71], v[162:165], v[202:205], v[68:71]
	v_mfma_f32_16x16x32_bf16 v[64:67], v[170:173], v[202:205], v[64:67]
	s_setprio 0
	s_barrier
; #define PG8_STAGE(bufoff, gbase, voff) do { _Pragma("unroll") for (int _i = 0; _i < 2; ++_i) \
;         __builtin_amdgcn_global_load_lds((const unsigned*)((const char*)(gbase) + (voff)[_i]), (PG8_LAS unsigned*)(lds + (bufoff) + ldsw + _i * 8192), 16, 0, 0); } while (0)
; #define PG8_LDA(dst, b, h) do { _Pragma("unroll") for (int m = 0; m < 4; ++m) _Pragma("unroll") for (int k = 0; k < 2; ++k) dst[m][k] = *(const PG8_LAS bf16x8*)(lds + PG8_SA(b, h) + aoff + m * 2048 + k * 1024); } while (0)
; #define PG8_MMA(ai, bj, At, Bt) do { __builtin_amdgcn_s_setprio(1); _Pragma("unroll") for (int m = 0; m < 4; ++m) _Pragma("unroll") for (int n = 0; n < 2; ++n) _Pragma("unroll") for (int k = 0; k < 2; ++k) \
;         acc[ai][bj][m][n] = __builtin_amdgcn_mfma_f32_16x16x32_bf16(Bt[n][k], At[m][k], acc[ai][bj][m][n], 0, 0, 0); __builtin_amdgcn_s_setprio(0); } while (0)
; #define PG8_WAIT_V(n) asm volatile("s_waitcnt vmcnt(" #n ")" ::: "memory")
; #define PG8_WAIT_L(n) asm volatile("s_waitcnt lgkmcnt(" #n ")" ::: "memory")
; #define PG8_BAR __builtin_amdgcn_s_barrier()
; #define PG8_SCHED __builtin_amdgcn_sched_barrier(0)
; template <class Epi, class Sched, bool ALIGN_EPI = false, bool SP2 = false>
; __device__ __forceinline__ void gemm_phase(PG8_LAS unsigned char* lds, const Gemm g, const Sched& S, const Epi& E) {
;     ...
;         for (int t = 0; t < nt; t += 2) {
;             const bool last = (t == nt - 2);
;             const char* a1 = cA + (size_t)(t + 1) * kstep;
;             const char* a2 = last ? nA : cA + (size_t)(t + 2) * kstep; const char* b2 = last ? nB : cB + (size_t)(t + 2) * kstep;
;     ...
;             PG8_LDA(At, 1, 1); PG8_STAGE(PG8_SB(1, 0), b3, voffB); PG8_STAGE(PG8_SB(1, 1), b3 + hstep, voffB); PG8_STAGE(PG8_SA(1, 0), a3, voffA);
;             PG8_WAIT_V(8); PG8_WAIT_L(0); PG8_BAR; PG8_MMA(1, 0, At, B0); PG8_MMA(1, 1, At, B1); PG8_BAR; PG8_SCHED;
	s_add_i32 s25, s25, s6
	v_lshl_add_u64 v[206:207], v[206:207], 0, s[50:51]
	s_mov_b32 m0, s25
	ds_read_b128 v[174:177], v248 offset:49152
	ds_read_b128 v[178:181], v248 offset:50176
	ds_read_b128 v[182:185], v248 offset:51200
	ds_read_b128 v[186:189], v248 offset:52224
	ds_read_b128 v[190:193], v248 offset:53248
	ds_read_b128 v[194:197], v248 offset:54272
	ds_read_b128 v[198:201], v248 offset:55296
	ds_read_b128 v[202:205], v248 offset:56320
	global_load_lds_dwordx4 v[206:207], off
	v_lshl_add_u64 v[206:207], v[208:209], 0, s[50:51]
	s_add_i32 m0, s25, 0x2000
	s_add_i32 s25, s61, s6
	global_load_lds_dwordx4 v[206:207], off
	v_lshl_add_u64 v[206:207], v[210:211], 0, s[50:51]
	s_mov_b32 m0, s25
	s_nop 0
	global_load_lds_dwordx4 v[206:207], off
	v_lshl_add_u64 v[206:207], v[212:213], 0, s[50:51]
	s_add_i32 m0, s25, 0x2000
	s_nop 0
	global_load_lds_dwordx4 v[206:207], off
	v_lshl_add_u64 v[206:207], v[214:215], 0, s[50:51]
	s_mov_b32 m0, s27
	s_nop 0
	global_load_lds_dwordx4 v[206:207], off
	v_lshl_add_u64 v[206:207], v[216:217], 0, s[50:51]
	s_mov_b32 m0, s30
	s_nop 0
	global_load_lds_dwordx4 v[206:207], off
	s_waitcnt vmcnt(8)
	s_waitcnt lgkmcnt(0)
	s_barrier
	s_setprio 1
	s_waitcnt lgkmcnt(0)
	v_mfma_f32_16x16x32_bf16 v[60:63], v[142:145], v[174:177], v[60:63]
	v_mfma_f32_16x16x32_bf16 v[56:59], v[150:153], v[174:177], v[56:59]
	v_mfma_f32_16x16x32_bf16 v[52:55], v[142:145], v[182:185], v[52:55]
	v_mfma_f32_16x16x32_bf16 v[48:51], v[150:153], v[182:185], v[48:51]
	v_mfma_f32_16x16x32_bf16 v[40:43], v[142:145], v[190:193], v[40:43]
	v_mfma_f32_16x16x32_bf16 v[32:35], v[150:153], v[190:193], v[32:35]
	v_mfma_f32_16x16x32_bf16 v[24:27], v[142:145], v[198:201], v[24:27]
	v_mfma_f32_16x16x32_bf16 v[16:19], v[150:153], v[198:201], v[16:19]
	v_mfma_f32_16x16x32_bf16 v[60:63], v[146:149], v[178:181], v[60:63]
	v_mfma_f32_16x16x32_bf16 v[56:59], v[154:157], v[178:181], v[56:59]
	v_mfma_f32_16x16x32_bf16 v[52:55], v[146:149], v[186:189], v[52:55]
	v_mfma_f32_16x16x32_bf16 v[48:51], v[154:157], v[186:189], v[48:51]
	v_mfma_f32_16x16x32_bf16 v[40:43], v[146:149], v[194:197], v[40:43]
	v_mfma_f32_16x16x32_bf16 v[32:35], v[154:157], v[194:197], v[32:35]
	v_mfma_f32_16x16x32_bf16 v[24:27], v[146:149], v[202:205], v[24:27]
	v_mfma_f32_16x16x32_bf16 v[16:19], v[154:157], v[202:205], v[16:19]
	s_setprio 0
	s_setprio 1
	v_mfma_f32_16x16x32_bf16 v[44:47], v[158:161], v[174:177], v[44:47]
	v_mfma_f32_16x16x32_bf16 v[36:39], v[166:169], v[174:177], v[36:39]
	v_mfma_f32_16x16x32_bf16 v[28:31], v[158:161], v[182:185], v[28:31]
	v_mfma_f32_16x16x32_bf16 v[20:23], v[166:169], v[182:185], v[20:23]
	v_mfma_f32_16x16x32_bf16 v[12:15], v[158:161], v[190:193], v[12:15]
	v_mfma_f32_16x16x32_bf16 v[8:11], v[166:169], v[190:193], v[8:11]
	v_mfma_f32_16x16x32_bf16 v[4:7], v[158:161], v[198:201], v[4:7]
	v_mfma_f32_16x16x32_bf16 v[0:3], v[166:169], v[198:201], v[0:3]
	v_mfma_f32_16x16x32_bf16 v[44:47], v[162:165], v[178:181], v[44:47]
	v_mfma_f32_16x16x32_bf16 v[36:39], v[170:173], v[178:181], v[36:39]
	v_mfma_f32_16x16x32_bf16 v[28:31], v[162:165], v[186:189], v[28:31]
	v_mfma_f32_16x16x32_bf16 v[20:23], v[170:173], v[186:189], v[20:23]
	v_mfma_f32_16x16x32_bf16 v[12:15], v[162:165], v[194:197], v[12:15]
	v_mfma_f32_16x16x32_bf16 v[8:11], v[170:173], v[194:197], v[8:11]
	v_mfma_f32_16x16x32_bf16 v[4:7], v[162:165], v[202:205], v[4:7]
	v_mfma_f32_16x16x32_bf16 v[0:3], v[170:173], v[202:205], v[0:3]
	s_setprio 0
	s_barrier
	s_add_u32 s56, s56, 0x100
	s_addc_u32 s57, s57, 0
	s_add_u32 s2, s2, 0x100
	s_addc_u32 s24, s24, 0
	s_cmp_ge_i32 s60, s33
	s_mov_b32 s25, s60
	s_cbranch_scc1 .Lpeelx_5

; #define PG8_STAGE(bufoff, gbase, voff) do { _Pragma("unroll") for (int _i = 0; _i < 2; ++_i) \
;         __builtin_amdgcn_global_load_lds((const unsigned*)((const char*)(gbase) + (voff)[_i]), (PG8_LAS unsigned*)(lds + (bufoff) + ldsw + _i * 8192), 16, 0, 0); } while (0)
; #define PG8_LDA(dst, b, h) do { _Pragma("unroll") for (int m = 0; m < 4; ++m) _Pragma("unroll") for (int k = 0; k < 2; ++k) dst[m][k] = *(const PG8_LAS bf16x8*)(lds + PG8_SA(b, h) + aoff + m * 2048 + k * 1024); } while (0)
; #define PG8_LDB(dst, b, h) do { _Pragma("unroll") for (int n = 0; n < 2; ++n) _Pragma("unroll") for (int k = 0; k < 2; ++k) dst[n][k] = *(const PG8_LAS bf16x8*)(lds + PG8_SB(b, h) + boff + n * 2048 + k * 1024); } while (0)
; #define PG8_WAIT_V(n) asm volatile("s_waitcnt vmcnt(" #n ")" ::: "memory")
; #define PG8_WAIT_L(n) asm volatile("s_waitcnt lgkmcnt(" #n ")" ::: "memory")
; #define PG8_BAR __builtin_amdgcn_s_barrier()
; #define PG8_SCHED __builtin_amdgcn_sched_barrier(0)
; template <class Epi, class Sched, bool ALIGN_EPI = false, bool SP2 = false>
; __device__ __forceinline__ void gemm_phase(PG8_LAS unsigned char* lds, const Gemm g, const Sched& S, const Epi& E) {
;     ...
;     f32x4 acc[2][2][4][2];
; #pragma unroll
;     for (int a = 0; a < 2; ++a)
; #pragma unroll
;         for (int b = 0; b < 2; ++b)
; #pragma unroll
;             for (int m = 0; m < 4; ++m)
; #pragma unroll
;                 for (int n = 0; n < 2; ++n) acc[a][b][m][n] = (f32x4){0.f, 0.f, 0.f, 0.f};
;     ...
;         for (int t = 0; t < nt; t += 2) {
;             const bool last = (t == nt - 2);
;             const char* a1 = cA + (size_t)(t + 1) * kstep;
;             const char* a2 = last ? nA : cA + (size_t)(t + 2) * kstep; const char* b2 = last ? nB : cB + (size_t)(t + 2) * kstep;
;             const char* a3 = a2 + kstep; const char* b3 = b2 + kstep;
;             if (last && has_next) S.a_ready(nxt);
;             if constexpr (SP2) {
;             PG8_LDB(B0, 0, 0); PG8_LDB(B1, 0, 1); PG8_SCHED; PG8_LDA(At, 0, 0); PG8_STAGE(PG8_SA(1, 1), a1 + hstep, voffA);
;             PG8_WAIT_V(8); PG8_WAIT_L(0); PG8_BAR; PG8_MMA(0, 0, At, B0); PG8_MMA(0, 1, At, B1); PG8_BAR; PG8_SCHED;
;             PG8_LDA(At, 0, 1); PG8_STAGE(PG8_SB(0, 0), b2, voffB); PG8_STAGE(PG8_SB(0, 1), b2 + hstep, voffB); PG8_STAGE(PG8_SA(0, 0), a2, voffA);
.LBB0_1994:
	s_and_b64 vcc, exec, s[10:11]
	s_cbranch_vccnz .Lcoldz_8
	s_add_u32 s58, s58, 0x80
	s_addc_u32 s59, s59, 0
	s_add_u32 s24, s60, 0x100
	s_addc_u32 s25, s61, 0
	s_mov_b32 s60, 0
	ds_read_b128 v[128:131], v216
	ds_read_b128 v[132:135], v216 offset:1024
	ds_read_b128 v[136:139], v216 offset:2048
	ds_read_b128 v[140:143], v216 offset:3072
	ds_read_b128 v[144:147], v217
	ds_read_b128 v[148:151], v217 offset:1024
	ds_read_b128 v[152:155], v217 offset:2048
	ds_read_b128 v[156:159], v217 offset:3072
	s_add_i32 s65, s60, 2
	s_add_u32 s66, s58, 0x80
	s_addc_u32 s61, s59, 0
	s_cmp_eq_u32 s34, s60
	s_cselect_b32 s60, s14, s66
	s_cselect_b32 s61, s15, s61
	s_cselect_b32 s67, s57, s25
	s_cselect_b32 s66, s56, s24
	v_lshl_add_u64 v[212:213], s[58:59], 0, v[188:189]
	s_add_i32 m0, s18, 0xc000
	ds_read_b128 v[160:163], v218
	ds_read_b128 v[164:167], v218 offset:1024
	ds_read_b128 v[168:171], v218 offset:2048
	ds_read_b128 v[172:175], v218 offset:3072
	ds_read_b128 v[196:199], v218 offset:4096
	ds_read_b128 v[200:203], v218 offset:5120
	ds_read_b128 v[204:207], v218 offset:6144
	ds_read_b128 v[208:211], v218 offset:7168
	global_load_lds_dwordx4 v[212:213], off
	v_lshl_add_u64 v[212:213], s[58:59], 0, v[190:191]
	s_add_i32 m0, s18, 0xe000
	s_nop 0
	global_load_lds_dwordx4 v[212:213], off
	s_waitcnt vmcnt(8)
	s_waitcnt lgkmcnt(0)
	s_barrier
	s_setprio 1
	s_waitcnt lgkmcnt(0)
	v_mfma_f32_16x16x32_bf16 v[124:127], v[128:131], v[160:163], 0
	v_mfma_f32_16x16x32_bf16 v[120:123], v[136:139], v[160:163], 0
	v_mfma_f32_16x16x32_bf16 v[108:111], v[128:131], v[168:171], 0
	v_mfma_f32_16x16x32_bf16 v[104:107], v[136:139], v[168:171], 0
	v_mfma_f32_16x16x32_bf16 v[92:95], v[128:131], v[196:199], 0
	v_mfma_f32_16x16x32_bf16 v[88:91], v[136:139], v[196:199], 0
	v_mfma_f32_16x16x32_bf16 v[76:79], v[128:131], v[204:207], 0
	v_mfma_f32_16x16x32_bf16 v[72:75], v[136:139], v[204:207], 0
	v_mfma_f32_16x16x32_bf16 v[124:127], v[132:135], v[164:167], v[124:127]
	v_mfma_f32_16x16x32_bf16 v[120:123], v[140:143], v[164:167], v[120:123]
	v_mfma_f32_16x16x32_bf16 v[108:111], v[132:135], v[172:175], v[108:111]
	v_mfma_f32_16x16x32_bf16 v[104:107], v[140:143], v[172:175], v[104:107]
	v_mfma_f32_16x16x32_bf16 v[92:95], v[132:135], v[200:203], v[92:95]
	v_mfma_f32_16x16x32_bf16 v[88:91], v[140:143], v[200:203], v[88:91]
	v_mfma_f32_16x16x32_bf16 v[76:79], v[132:135], v[208:211], v[76:79]
	v_mfma_f32_16x16x32_bf16 v[72:75], v[140:143], v[208:211], v[72:75]
	s_setprio 0
	s_setprio 1
	v_mfma_f32_16x16x32_bf16 v[116:119], v[144:147], v[160:163], 0
	v_mfma_f32_16x16x32_bf16 v[112:115], v[152:155], v[160:163], 0
	v_mfma_f32_16x16x32_bf16 v[100:103], v[144:147], v[168:171], 0
	v_mfma_f32_16x16x32_bf16 v[96:99], v[152:155], v[168:171], 0
	v_mfma_f32_16x16x32_bf16 v[84:87], v[144:147], v[196:199], 0
	v_mfma_f32_16x16x32_bf16 v[80:83], v[152:155], v[196:199], 0
	v_mfma_f32_16x16x32_bf16 v[68:71], v[144:147], v[204:207], 0
	v_mfma_f32_16x16x32_bf16 v[64:67], v[152:155], v[204:207], 0
	v_mfma_f32_16x16x32_bf16 v[116:119], v[148:151], v[164:167], v[116:119]
	v_mfma_f32_16x16x32_bf16 v[112:115], v[156:159], v[164:167], v[112:115]
	v_mfma_f32_16x16x32_bf16 v[100:103], v[148:151], v[172:175], v[100:103]
	v_mfma_f32_16x16x32_bf16 v[96:99], v[156:159], v[172:175], v[96:99]
	v_mfma_f32_16x16x32_bf16 v[84:87], v[148:151], v[200:203], v[84:87]
	v_mfma_f32_16x16x32_bf16 v[80:83], v[156:159], v[200:203], v[80:83]
	v_mfma_f32_16x16x32_bf16 v[68:71], v[148:151], v[208:211], v[68:71]
	v_mfma_f32_16x16x32_bf16 v[64:67], v[156:159], v[208:211], v[64:67]
	s_setprio 0
	s_barrier
	s_add_i32 s68, s35, s4
	v_lshl_add_u64 v[212:213], s[66:67], 0, v[180:181]
	s_mov_b32 m0, s68
	ds_read_b128 v[160:163], v218 offset:16384
	ds_read_b128 v[164:167], v218 offset:17408
	ds_read_b128 v[168:171], v218 offset:18432
	ds_read_b128 v[172:175], v218 offset:19456
	ds_read_b128 v[196:199], v218 offset:20480
	ds_read_b128 v[200:203], v218 offset:21504
	ds_read_b128 v[204:207], v218 offset:22528
	ds_read_b128 v[208:211], v218 offset:23552
	global_load_lds_dwordx4 v[212:213], off
	s_add_i32 m0, s68, 0x2000
	v_lshl_add_u64 v[220:221], s[66:67], 0, v[176:177]
	s_add_u32 s66, s66, s44
	s_addc_u32 s67, s67, s45
	s_add_i32 s68, s36, s4
	global_load_lds_dwordx4 v[220:221], off
	v_lshl_add_u64 v[222:223], s[66:67], 0, v[180:181]
	s_mov_b32 m0, s68
	v_lshl_add_u64 v[224:225], s[66:67], 0, v[176:177]
	global_load_lds_dwordx4 v[222:223], off
	s_add_i32 m0, s68, 0x2000
	v_lshl_add_u64 v[226:227], s[60:61], 0, v[182:183]
	global_load_lds_dwordx4 v[224:225], off
	s_mov_b32 m0, s18
	v_lshl_add_u64 v[228:229], s[60:61], 0, v[178:179]
	global_load_lds_dwordx4 v[226:227], off
	s_mov_b32 m0, s19
	s_nop 0
	global_load_lds_dwordx4 v[228:229], off
	s_waitcnt vmcnt(8)
	s_waitcnt lgkmcnt(0)
	s_barrier
; #define PG8_STAGE(bufoff, gbase, voff) do { _Pragma("unroll") for (int _i = 0; _i < 2; ++_i) \
;         __builtin_amdgcn_global_load_lds((const unsigned*)((const char*)(gbase) + (voff)[_i]), (PG8_LAS unsigned*)(lds + (bufoff) + ldsw + _i * 8192), 16, 0, 0); } while (0)
; #define PG8_LDA(dst, b, h) do { _Pragma("unroll") for (int m = 0; m < 4; ++m) _Pragma("unroll") for (int k = 0; k < 2; ++k) dst[m][k] = *(const PG8_LAS bf16x8*)(lds + PG8_SA(b, h) + aoff + m * 2048 + k * 1024); } while (0)
; #define PG8_LDB(dst, b, h) do { _Pragma("unroll") for (int n = 0; n < 2; ++n) _Pragma("unroll") for (int k = 0; k < 2; ++k) dst[n][k] = *(const PG8_LAS bf16x8*)(lds + PG8_SB(b, h) + boff + n * 2048 + k * 1024); } while (0)
; #define PG8_MMA(ai, bj, At, Bt) do { __builtin_amdgcn_s_setprio(1); _Pragma("unroll") for (int m = 0; m < 4; ++m) _Pragma("unroll") for (int n = 0; n < 2; ++n) _Pragma("unroll") for (int k = 0; k < 2; ++k) \
;         acc[ai][bj][m][n] = __builtin_amdgcn_mfma_f32_16x16x32_bf16(Bt[n][k], At[m][k], acc[ai][bj][m][n], 0, 0, 0); __builtin_amdgcn_s_setprio(0); } while (0)
; #define PG8_WAIT_V(n) asm volatile("s_waitcnt vmcnt(" #n ")" ::: "memory")
; #define PG8_WAIT_L(n) asm volatile("s_waitcnt lgkmcnt(" #n ")" ::: "memory")
; #define PG8_BAR __builtin_amdgcn_s_barrier()
; #define PG8_SCHED __builtin_amdgcn_sched_barrier(0)
; template <class Epi, class Sched, bool ALIGN_EPI = false, bool SP2 = false>
; __device__ __forceinline__ void gemm_phase(PG8_LAS unsigned char* lds, const Gemm g, const Sched& S, const Epi& E) {
;     ...
;             PG8_WAIT_V(8); PG8_WAIT_L(0); PG8_BAR; PG8_MMA(1, 0, At, B0); PG8_MMA(1, 1, At, B1); PG8_BAR; PG8_SCHED;
;             PG8_LDB(B0, 1, 0); PG8_LDB(B1, 1, 1); PG8_SCHED; PG8_LDA(At, 1, 0); PG8_STAGE(PG8_SA(0, 1), a2 + hstep, voffA);
;             PG8_WAIT_V(8); PG8_WAIT_L(0); PG8_BAR; PG8_MMA(0, 0, At, B0); PG8_MMA(0, 1, At, B1); PG8_BAR; PG8_SCHED;
	s_setprio 1
	s_waitcnt lgkmcnt(0)
	v_mfma_f32_16x16x32_bf16 v[60:63], v[128:131], v[160:163], 0
	v_mfma_f32_16x16x32_bf16 v[56:59], v[136:139], v[160:163], 0
	v_mfma_f32_16x16x32_bf16 v[44:47], v[128:131], v[168:171], 0
	v_mfma_f32_16x16x32_bf16 v[40:43], v[136:139], v[168:171], 0
	v_mfma_f32_16x16x32_bf16 v[28:31], v[128:131], v[196:199], 0
	v_mfma_f32_16x16x32_bf16 v[24:27], v[136:139], v[196:199], 0
	v_mfma_f32_16x16x32_bf16 v[12:15], v[128:131], v[204:207], 0
	v_mfma_f32_16x16x32_bf16 v[8:11], v[136:139], v[204:207], 0
	v_mfma_f32_16x16x32_bf16 v[60:63], v[132:135], v[164:167], v[60:63]
	v_mfma_f32_16x16x32_bf16 v[56:59], v[140:143], v[164:167], v[56:59]
	v_mfma_f32_16x16x32_bf16 v[44:47], v[132:135], v[172:175], v[44:47]
	v_mfma_f32_16x16x32_bf16 v[40:43], v[140:143], v[172:175], v[40:43]
	v_mfma_f32_16x16x32_bf16 v[28:31], v[132:135], v[200:203], v[28:31]
	v_mfma_f32_16x16x32_bf16 v[24:27], v[140:143], v[200:203], v[24:27]
	v_mfma_f32_16x16x32_bf16 v[12:15], v[132:135], v[208:211], v[12:15]
	v_mfma_f32_16x16x32_bf16 v[8:11], v[140:143], v[208:211], v[8:11]
	s_setprio 0
	s_setprio 1
	v_mfma_f32_16x16x32_bf16 v[52:55], v[144:147], v[160:163], 0
	v_mfma_f32_16x16x32_bf16 v[48:51], v[152:155], v[160:163], 0
	v_mfma_f32_16x16x32_bf16 v[36:39], v[144:147], v[168:171], 0
	v_mfma_f32_16x16x32_bf16 v[32:35], v[152:155], v[168:171], 0
	v_mfma_f32_16x16x32_bf16 v[20:23], v[144:147], v[196:199], 0
	v_mfma_f32_16x16x32_bf16 v[16:19], v[152:155], v[196:199], 0
	v_mfma_f32_16x16x32_bf16 v[4:7], v[144:147], v[204:207], 0
	v_mfma_f32_16x16x32_bf16 v[0:3], v[152:155], v[204:207], 0
	v_mfma_f32_16x16x32_bf16 v[52:55], v[148:151], v[164:167], v[52:55]
	v_mfma_f32_16x16x32_bf16 v[48:51], v[156:159], v[164:167], v[48:51]
	v_mfma_f32_16x16x32_bf16 v[36:39], v[148:151], v[172:175], v[36:39]
	v_mfma_f32_16x16x32_bf16 v[32:35], v[156:159], v[172:175], v[32:35]
	v_mfma_f32_16x16x32_bf16 v[20:23], v[148:151], v[200:203], v[20:23]
	v_mfma_f32_16x16x32_bf16 v[16:19], v[156:159], v[200:203], v[16:19]
	v_mfma_f32_16x16x32_bf16 v[4:7], v[148:151], v[208:211], v[4:7]
	v_mfma_f32_16x16x32_bf16 v[0:3], v[156:159], v[208:211], v[0:3]
	s_setprio 0
	s_barrier
	s_add_i32 s66, 0, 0x18000
	s_add_i32 s67, 0, 0x1c000
	v_add_u32_e32 v140, s66, v214
	v_add_u32_e32 v156, s67, v214
	ds_read_b128 v[128:131], v140
	ds_read_b128 v[132:135], v140 offset:1024
	ds_read_b128 v[136:139], v140 offset:2048
	ds_read_b128 v[140:143], v140 offset:3072
	ds_read_b128 v[144:147], v156
	ds_read_b128 v[148:151], v156 offset:1024
	ds_read_b128 v[152:155], v156 offset:2048
	ds_read_b128 v[156:159], v156 offset:3072
	s_add_u32 s60, s60, s44
	s_addc_u32 s61, s61, s45
	s_mov_b32 m0, s26
	v_lshl_add_u64 v[230:231], s[60:61], 0, v[182:183]
	ds_read_b128 v[160:163], v218 offset:32768
	ds_read_b128 v[164:167], v218 offset:33792
	ds_read_b128 v[168:171], v218 offset:34816
	ds_read_b128 v[172:175], v218 offset:35840
	ds_read_b128 v[196:199], v218 offset:36864
	ds_read_b128 v[200:203], v218 offset:37888
	ds_read_b128 v[204:207], v218 offset:38912
	ds_read_b128 v[208:211], v218 offset:39936
	global_load_lds_dwordx4 v[230:231], off
	v_lshl_add_u64 v[230:231], s[60:61], 0, v[178:179]
	s_mov_b32 m0, s27
	s_nop 0
	global_load_lds_dwordx4 v[230:231], off
	s_waitcnt vmcnt(8)
	s_waitcnt lgkmcnt(0)
	s_barrier
	s_setprio 1
	s_waitcnt lgkmcnt(0)
	v_mfma_f32_16x16x32_bf16 v[124:127], v[128:131], v[160:163], v[124:127]
	v_mfma_f32_16x16x32_bf16 v[120:123], v[136:139], v[160:163], v[120:123]
	v_mfma_f32_16x16x32_bf16 v[108:111], v[128:131], v[168:171], v[108:111]
	v_mfma_f32_16x16x32_bf16 v[104:107], v[136:139], v[168:171], v[104:107]
	v_mfma_f32_16x16x32_bf16 v[92:95], v[128:131], v[196:199], v[92:95]
	v_mfma_f32_16x16x32_bf16 v[88:91], v[136:139], v[196:199], v[88:91]
	v_mfma_f32_16x16x32_bf16 v[76:79], v[128:131], v[204:207], v[76:79]
	v_mfma_f32_16x16x32_bf16 v[72:75], v[136:139], v[204:207], v[72:75]
	v_mfma_f32_16x16x32_bf16 v[124:127], v[132:135], v[164:167], v[124:127]
	v_mfma_f32_16x16x32_bf16 v[120:123], v[140:143], v[164:167], v[120:123]
	v_mfma_f32_16x16x32_bf16 v[108:111], v[132:135], v[172:175], v[108:111]
	v_mfma_f32_16x16x32_bf16 v[104:107], v[140:143], v[172:175], v[104:107]
	v_mfma_f32_16x16x32_bf16 v[92:95], v[132:135], v[200:203], v[92:95]
	v_mfma_f32_16x16x32_bf16 v[88:91], v[140:143], v[200:203], v[88:91]
	v_mfma_f32_16x16x32_bf16 v[76:79], v[132:135], v[208:211], v[76:79]
	v_mfma_f32_16x16x32_bf16 v[72:75], v[140:143], v[208:211], v[72:75]
	s_setprio 0
	s_setprio 1
	v_mfma_f32_16x16x32_bf16 v[116:119], v[144:147], v[160:163], v[116:119]
	v_mfma_f32_16x16x32_bf16 v[112:115], v[152:155], v[160:163], v[112:115]
	v_mfma_f32_16x16x32_bf16 v[100:103], v[144:147], v[168:171], v[100:103]
	v_mfma_f32_16x16x32_bf16 v[96:99], v[152:155], v[168:171], v[96:99]
	v_mfma_f32_16x16x32_bf16 v[84:87], v[144:147], v[196:199], v[84:87]
	v_mfma_f32_16x16x32_bf16 v[80:83], v[152:155], v[196:199], v[80:83]
	v_mfma_f32_16x16x32_bf16 v[68:71], v[144:147], v[204:207], v[68:71]
	v_mfma_f32_16x16x32_bf16 v[64:67], v[152:155], v[204:207], v[64:67]
	v_mfma_f32_16x16x32_bf16 v[116:119], v[148:151], v[164:167], v[116:119]
	v_mfma_f32_16x16x32_bf16 v[112:115], v[156:159], v[164:167], v[112:115]
	v_mfma_f32_16x16x32_bf16 v[100:103], v[148:151], v[172:175], v[100:103]
	v_mfma_f32_16x16x32_bf16 v[96:99], v[156:159], v[172:175], v[96:99]
	v_mfma_f32_16x16x32_bf16 v[84:87], v[148:151], v[200:203], v[84:87]
	v_mfma_f32_16x16x32_bf16 v[80:83], v[156:159], v[200:203], v[80:83]
	v_mfma_f32_16x16x32_bf16 v[68:71], v[148:151], v[208:211], v[68:71]
	v_mfma_f32_16x16x32_bf16 v[64:67], v[156:159], v[208:211], v[64:67]
	s_setprio 0
	s_barrier
; #define PG8_STAGE(bufoff, gbase, voff) do { _Pragma("unroll") for (int _i = 0; _i < 2; ++_i) \
;         __builtin_amdgcn_global_load_lds((const unsigned*)((const char*)(gbase) + (voff)[_i]), (PG8_LAS unsigned*)(lds + (bufoff) + ldsw + _i * 8192), 16, 0, 0); } while (0)
; #define PG8_LDA(dst, b, h) do { _Pragma("unroll") for (int m = 0; m < 4; ++m) _Pragma("unroll") for (int k = 0; k < 2; ++k) dst[m][k] = *(const PG8_LAS bf16x8*)(lds + PG8_SA(b, h) + aoff + m * 2048 + k * 1024); } while (0)
; #define PG8_MMA(ai, bj, At, Bt) do { __builtin_amdgcn_s_setprio(1); _Pragma("unroll") for (int m = 0; m < 4; ++m) _Pragma("unroll") for (int n = 0; n < 2; ++n) _Pragma("unroll") for (int k = 0; k < 2; ++k) \
;         acc[ai][bj][m][n] = __builtin_amdgcn_mfma_f32_16x16x32_bf16(Bt[n][k], At[m][k], acc[ai][bj][m][n], 0, 0, 0); __builtin_amdgcn_s_setprio(0); } while (0)
; #define PG8_WAIT_V(n) asm volatile("s_waitcnt vmcnt(" #n ")" ::: "memory")
; #define PG8_WAIT_L(n) asm volatile("s_waitcnt lgkmcnt(" #n ")" ::: "memory")
; #define PG8_BAR __builtin_amdgcn_s_barrier()
; #define PG8_SCHED __builtin_amdgcn_sched_barrier(0)
; template <class Epi, class Sched, bool ALIGN_EPI = false, bool SP2 = false>
; __device__ __forceinline__ void gemm_phase(PG8_LAS unsigned char* lds, const Gemm g, const Sched& S, const Epi& E) {
;     ...
;         for (int t = 0; t < nt; t += 2) {
;             const bool last = (t == nt - 2);
;             const char* a1 = cA + (size_t)(t + 1) * kstep;
;             const char* a2 = last ? nA : cA + (size_t)(t + 2) * kstep; const char* b2 = last ? nB : cB + (size_t)(t + 2) * kstep;
;     ...
;             PG8_LDA(At, 1, 1); PG8_STAGE(PG8_SB(1, 0), b3, voffB); PG8_STAGE(PG8_SB(1, 1), b3 + hstep, voffB); PG8_STAGE(PG8_SA(1, 0), a3, voffA);
;             PG8_WAIT_V(8); PG8_WAIT_L(0); PG8_BAR; PG8_MMA(1, 0, At, B0); PG8_MMA(1, 1, At, B1); PG8_BAR; PG8_SCHED;
	s_add_i32 s60, s66, s4
	v_lshl_add_u64 v[212:213], v[212:213], 0, s[52:53]
	s_mov_b32 m0, s60
	ds_read_b128 v[160:163], v218 offset:49152
	ds_read_b128 v[164:167], v218 offset:50176
	ds_read_b128 v[168:171], v218 offset:51200
	ds_read_b128 v[172:175], v218 offset:52224
	ds_read_b128 v[196:199], v218 offset:53248
	ds_read_b128 v[200:203], v218 offset:54272
	ds_read_b128 v[204:207], v218 offset:55296
	ds_read_b128 v[208:211], v218 offset:56320
	global_load_lds_dwordx4 v[212:213], off
	v_lshl_add_u64 v[212:213], v[220:221], 0, s[52:53]
	s_add_i32 m0, s60, 0x2000
	s_add_i32 s60, s67, s4
	global_load_lds_dwordx4 v[212:213], off
	v_lshl_add_u64 v[212:213], v[222:223], 0, s[52:53]
	s_mov_b32 m0, s60
	s_nop 0
	global_load_lds_dwordx4 v[212:213], off
	v_lshl_add_u64 v[212:213], v[224:225], 0, s[52:53]
	s_add_i32 m0, s60, 0x2000
	s_nop 0
	global_load_lds_dwordx4 v[212:213], off
	v_lshl_add_u64 v[212:213], v[226:227], 0, s[52:53]
	s_mov_b32 m0, s3
	s_nop 0
	global_load_lds_dwordx4 v[212:213], off
	v_lshl_add_u64 v[212:213], v[228:229], 0, s[52:53]
	s_mov_b32 m0, s30
	s_nop 0
	global_load_lds_dwordx4 v[212:213], off
	s_waitcnt vmcnt(8)
	s_waitcnt lgkmcnt(0)
	s_barrier
	s_setprio 1
	s_waitcnt lgkmcnt(0)
	v_mfma_f32_16x16x32_bf16 v[60:63], v[128:131], v[160:163], v[60:63]
	v_mfma_f32_16x16x32_bf16 v[56:59], v[136:139], v[160:163], v[56:59]
	v_mfma_f32_16x16x32_bf16 v[44:47], v[128:131], v[168:171], v[44:47]
	v_mfma_f32_16x16x32_bf16 v[40:43], v[136:139], v[168:171], v[40:43]
	v_mfma_f32_16x16x32_bf16 v[28:31], v[128:131], v[196:199], v[28:31]
	v_mfma_f32_16x16x32_bf16 v[24:27], v[136:139], v[196:199], v[24:27]
	v_mfma_f32_16x16x32_bf16 v[12:15], v[128:131], v[204:207], v[12:15]
	v_mfma_f32_16x16x32_bf16 v[8:11], v[136:139], v[204:207], v[8:11]
	v_mfma_f32_16x16x32_bf16 v[60:63], v[132:135], v[164:167], v[60:63]
	v_mfma_f32_16x16x32_bf16 v[56:59], v[140:143], v[164:167], v[56:59]
	v_mfma_f32_16x16x32_bf16 v[44:47], v[132:135], v[172:175], v[44:47]
	v_mfma_f32_16x16x32_bf16 v[40:43], v[140:143], v[172:175], v[40:43]
	v_mfma_f32_16x16x32_bf16 v[28:31], v[132:135], v[200:203], v[28:31]
	v_mfma_f32_16x16x32_bf16 v[24:27], v[140:143], v[200:203], v[24:27]
	v_mfma_f32_16x16x32_bf16 v[12:15], v[132:135], v[208:211], v[12:15]
	v_mfma_f32_16x16x32_bf16 v[8:11], v[140:143], v[208:211], v[8:11]
	s_setprio 0
	s_setprio 1
	v_mfma_f32_16x16x32_bf16 v[52:55], v[144:147], v[160:163], v[52:55]
	v_mfma_f32_16x16x32_bf16 v[48:51], v[152:155], v[160:163], v[48:51]
	v_mfma_f32_16x16x32_bf16 v[36:39], v[144:147], v[168:171], v[36:39]
	v_mfma_f32_16x16x32_bf16 v[32:35], v[152:155], v[168:171], v[32:35]
	v_mfma_f32_16x16x32_bf16 v[20:23], v[144:147], v[196:199], v[20:23]
	v_mfma_f32_16x16x32_bf16 v[16:19], v[152:155], v[196:199], v[16:19]
	v_mfma_f32_16x16x32_bf16 v[4:7], v[144:147], v[204:207], v[4:7]
	v_mfma_f32_16x16x32_bf16 v[0:3], v[152:155], v[204:207], v[0:3]
	v_mfma_f32_16x16x32_bf16 v[52:55], v[148:151], v[164:167], v[52:55]
	v_mfma_f32_16x16x32_bf16 v[48:51], v[156:159], v[164:167], v[48:51]
	v_mfma_f32_16x16x32_bf16 v[36:39], v[148:151], v[172:175], v[36:39]
	v_mfma_f32_16x16x32_bf16 v[32:35], v[156:159], v[172:175], v[32:35]
	v_mfma_f32_16x16x32_bf16 v[20:23], v[148:151], v[200:203], v[20:23]
	v_mfma_f32_16x16x32_bf16 v[16:19], v[156:159], v[200:203], v[16:19]
	v_mfma_f32_16x16x32_bf16 v[4:7], v[148:151], v[208:211], v[4:7]
	v_mfma_f32_16x16x32_bf16 v[0:3], v[156:159], v[208:211], v[0:3]
	s_setprio 0
	s_barrier
	s_add_u32 s58, s58, 0x100
	s_addc_u32 s59, s59, 0
	s_add_u32 s24, s24, 0x100
	s_addc_u32 s25, s25, 0
	s_cmp_ge_i32 s65, s31
	s_mov_b32 s60, s65
	s_cbranch_scc1 .Lpeelx_8

; #define PG8_BAR __builtin_amdgcn_s_barrier()
; template <class Epi, class Sched, bool ALIGN_EPI = false, bool SP2 = false>
; __device__ __forceinline__ void gemm_phase(PG8_LAS unsigned char* lds, const Gemm g, const Sched& S, const Epi& E) {
;     ...
;         if constexpr (ALIGN_EPI) { if (wr == 0) PG8_BAR; }
;         if constexpr (!Epi::AFTER_DRAIN) { E(acc, cur, wr, wc, fr, fq); S.done(cur); }
.Lpeelx_8:
.LBB0_1997:
	s_and_b64 vcc, exec, s[54:55]
	s_cbranch_vccz .LBB0_1999
	s_barrier

; #define PG8_STAGE(bufoff, gbase, voff) do { _Pragma("unroll") for (int _i = 0; _i < 2; ++_i) \
;         __builtin_amdgcn_global_load_lds((const unsigned*)((const char*)(gbase) + (voff)[_i]), (PG8_LAS unsigned*)(lds + (bufoff) + ldsw + _i * 8192), 16, 0, 0); } while (0)
; #define PG8_LDA(dst, b, h) do { _Pragma("unroll") for (int m = 0; m < 4; ++m) _Pragma("unroll") for (int k = 0; k < 2; ++k) dst[m][k] = *(const PG8_LAS bf16x8*)(lds + PG8_SA(b, h) + aoff + m * 2048 + k * 1024); } while (0)
; #define PG8_LDB(dst, b, h) do { _Pragma("unroll") for (int n = 0; n < 2; ++n) _Pragma("unroll") for (int k = 0; k < 2; ++k) dst[n][k] = *(const PG8_LAS bf16x8*)(lds + PG8_SB(b, h) + boff + n * 2048 + k * 1024); } while (0)
; #define PG8_WAIT_V(n) asm volatile("s_waitcnt vmcnt(" #n ")" ::: "memory")
; #define PG8_WAIT_L(n) asm volatile("s_waitcnt lgkmcnt(" #n ")" ::: "memory")
; #define PG8_BAR __builtin_amdgcn_s_barrier()
; #define PG8_SCHED __builtin_amdgcn_sched_barrier(0)
; template <class Epi, class Sched, bool ALIGN_EPI = false, bool SP2 = false>
; __device__ __forceinline__ void gemm_phase(PG8_LAS unsigned char* lds, const Gemm g, const Sched& S, const Epi& E) {
;     ...
;     f32x4 acc[2][2][4][2];
; #pragma unroll
;     for (int a = 0; a < 2; ++a)
; #pragma unroll
;         for (int b = 0; b < 2; ++b)
; #pragma unroll
;             for (int m = 0; m < 4; ++m)
; #pragma unroll
;                 for (int n = 0; n < 2; ++n) acc[a][b][m][n] = (f32x4){0.f, 0.f, 0.f, 0.f};
;     ...
;         for (int t = 0; t < nt; t += 2) {
;             const bool last = (t == nt - 2);
;             const char* a1 = cA + (size_t)(t + 1) * kstep;
;             const char* a2 = last ? nA : cA + (size_t)(t + 2) * kstep; const char* b2 = last ? nB : cB + (size_t)(t + 2) * kstep;
;             const char* a3 = a2 + kstep; const char* b3 = b2 + kstep;
;             if (last && has_next) S.a_ready(nxt);
;             if constexpr (SP2) {
;             PG8_LDB(B0, 0, 0); PG8_LDB(B1, 0, 1); PG8_SCHED; PG8_LDA(At, 0, 0); PG8_STAGE(PG8_SA(1, 1), a1 + hstep, voffA);
;             PG8_WAIT_V(8); PG8_WAIT_L(0); PG8_BAR; PG8_MMA(0, 0, At, B0); PG8_MMA(0, 1, At, B1); PG8_BAR; PG8_SCHED;
;             PG8_LDA(At, 0, 1); PG8_STAGE(PG8_SB(0, 0), b2, voffB); PG8_STAGE(PG8_SB(0, 1), b2 + hstep, voffB); PG8_STAGE(PG8_SA(0, 0), a2, voffA);
.LBB0_2069:
	s_and_b64 vcc, exec, s[10:11]
	s_cbranch_vccnz .Lcoldz_9
	s_add_u32 s50, s50, 0x80
	s_addc_u32 s51, s51, 0
	s_add_u32 s2, s52, 0x100
	s_addc_u32 s24, s53, 0
	s_mov_b32 s25, 0
	ds_read_b128 v[154:157], v151
	ds_read_b128 v[158:161], v151 offset:1024
	ds_read_b128 v[162:165], v151 offset:2048
	ds_read_b128 v[166:169], v151 offset:3072
	ds_read_b128 v[170:173], v152
	ds_read_b128 v[174:177], v152 offset:1024
	ds_read_b128 v[178:181], v152 offset:2048
	ds_read_b128 v[182:185], v152 offset:3072
	s_add_i32 s60, s25, 2
	s_add_u32 s52, s50, 0x80
	s_addc_u32 s53, s51, 0
	s_cmp_eq_u32 s31, s25
	s_cselect_b32 s53, s15, s53
	s_cselect_b32 s52, s14, s52
	s_cselect_b32 s63, s49, s24
	s_cselect_b32 s62, s48, s2
	v_lshl_add_u64 v[146:147], s[50:51], 0, v[138:139]
	s_add_i32 m0, s6, 0xc000
	ds_read_b128 v[186:189], v153
	ds_read_b128 v[190:193], v153 offset:1024
	ds_read_b128 v[194:197], v153 offset:2048
	ds_read_b128 v[198:201], v153 offset:3072
	ds_read_b128 v[202:205], v153 offset:4096
	ds_read_b128 v[206:209], v153 offset:5120
	ds_read_b128 v[210:213], v153 offset:6144
	ds_read_b128 v[214:217], v153 offset:7168
	global_load_lds_dwordx4 v[146:147], off
	v_lshl_add_u64 v[146:147], s[50:51], 0, v[140:141]
	s_add_i32 m0, s6, 0xe000
	s_nop 0
	global_load_lds_dwordx4 v[146:147], off
	s_waitcnt vmcnt(8)
	s_waitcnt lgkmcnt(0)
	s_barrier
	s_setprio 1
	s_waitcnt lgkmcnt(0)
	v_mfma_f32_16x16x32_bf16 v[124:127], v[154:157], v[186:189], 0
	v_mfma_f32_16x16x32_bf16 v[120:123], v[162:165], v[186:189], 0
	v_mfma_f32_16x16x32_bf16 v[108:111], v[154:157], v[194:197], 0
	v_mfma_f32_16x16x32_bf16 v[104:107], v[162:165], v[194:197], 0
	v_mfma_f32_16x16x32_bf16 v[92:95], v[154:157], v[202:205], 0
	v_mfma_f32_16x16x32_bf16 v[88:91], v[162:165], v[202:205], 0
	v_mfma_f32_16x16x32_bf16 v[76:79], v[154:157], v[210:213], 0
	v_mfma_f32_16x16x32_bf16 v[72:75], v[162:165], v[210:213], 0
	v_mfma_f32_16x16x32_bf16 v[124:127], v[158:161], v[190:193], v[124:127]
	v_mfma_f32_16x16x32_bf16 v[120:123], v[166:169], v[190:193], v[120:123]
	v_mfma_f32_16x16x32_bf16 v[108:111], v[158:161], v[198:201], v[108:111]
	v_mfma_f32_16x16x32_bf16 v[104:107], v[166:169], v[198:201], v[104:107]
	v_mfma_f32_16x16x32_bf16 v[92:95], v[158:161], v[206:209], v[92:95]
	v_mfma_f32_16x16x32_bf16 v[88:91], v[166:169], v[206:209], v[88:91]
	v_mfma_f32_16x16x32_bf16 v[76:79], v[158:161], v[214:217], v[76:79]
	v_mfma_f32_16x16x32_bf16 v[72:75], v[166:169], v[214:217], v[72:75]
	s_setprio 0
	s_setprio 1
	v_mfma_f32_16x16x32_bf16 v[116:119], v[170:173], v[186:189], 0
	v_mfma_f32_16x16x32_bf16 v[112:115], v[178:181], v[186:189], 0
	v_mfma_f32_16x16x32_bf16 v[100:103], v[170:173], v[194:197], 0
	v_mfma_f32_16x16x32_bf16 v[96:99], v[178:181], v[194:197], 0
	v_mfma_f32_16x16x32_bf16 v[84:87], v[170:173], v[202:205], 0
	v_mfma_f32_16x16x32_bf16 v[80:83], v[178:181], v[202:205], 0
	v_mfma_f32_16x16x32_bf16 v[68:71], v[170:173], v[210:213], 0
	v_mfma_f32_16x16x32_bf16 v[64:67], v[178:181], v[210:213], 0
	v_mfma_f32_16x16x32_bf16 v[116:119], v[174:177], v[190:193], v[116:119]
	v_mfma_f32_16x16x32_bf16 v[112:115], v[182:185], v[190:193], v[112:115]
	v_mfma_f32_16x16x32_bf16 v[100:103], v[174:177], v[198:201], v[100:103]
	v_mfma_f32_16x16x32_bf16 v[96:99], v[182:185], v[198:201], v[96:99]
	v_mfma_f32_16x16x32_bf16 v[84:87], v[174:177], v[206:209], v[84:87]
	v_mfma_f32_16x16x32_bf16 v[80:83], v[182:185], v[206:209], v[80:83]
	v_mfma_f32_16x16x32_bf16 v[68:71], v[174:177], v[214:217], v[68:71]
	v_mfma_f32_16x16x32_bf16 v[64:67], v[182:185], v[214:217], v[64:67]
	s_setprio 0
	s_barrier
	s_add_i32 s25, s33, s3
	v_lshl_add_u64 v[146:147], s[62:63], 0, v[130:131]
	s_mov_b32 m0, s25
	ds_read_b128 v[186:189], v153 offset:16384
	ds_read_b128 v[190:193], v153 offset:17408
	ds_read_b128 v[194:197], v153 offset:18432
	ds_read_b128 v[198:201], v153 offset:19456
	ds_read_b128 v[202:205], v153 offset:20480
	ds_read_b128 v[206:209], v153 offset:21504
	ds_read_b128 v[210:213], v153 offset:22528
	ds_read_b128 v[214:217], v153 offset:23552
	global_load_lds_dwordx4 v[146:147], off
	s_add_i32 m0, s25, 0x2000
	v_lshl_add_u64 v[218:219], s[62:63], 0, v[134:135]
	s_add_u32 s62, s62, s34
	s_addc_u32 s63, s63, s35
	s_add_i32 s25, s38, s3
	global_load_lds_dwordx4 v[218:219], off
	v_lshl_add_u64 v[220:221], s[62:63], 0, v[130:131]
	s_mov_b32 m0, s25
	v_lshl_add_u64 v[222:223], s[62:63], 0, v[134:135]
	global_load_lds_dwordx4 v[220:221], off
	s_add_i32 m0, s25, 0x2000
	v_lshl_add_u64 v[224:225], s[52:53], 0, v[128:129]
	global_load_lds_dwordx4 v[222:223], off
	s_mov_b32 m0, s6
	v_lshl_add_u64 v[226:227], s[52:53], 0, v[132:133]
	global_load_lds_dwordx4 v[224:225], off
	s_mov_b32 m0, s7
	s_nop 0
	global_load_lds_dwordx4 v[226:227], off
	s_waitcnt vmcnt(8)
	s_waitcnt lgkmcnt(0)
	s_barrier
; #define PG8_STAGE(bufoff, gbase, voff) do { _Pragma("unroll") for (int _i = 0; _i < 2; ++_i) \
;         __builtin_amdgcn_global_load_lds((const unsigned*)((const char*)(gbase) + (voff)[_i]), (PG8_LAS unsigned*)(lds + (bufoff) + ldsw + _i * 8192), 16, 0, 0); } while (0)
; #define PG8_LDA(dst, b, h) do { _Pragma("unroll") for (int m = 0; m < 4; ++m) _Pragma("unroll") for (int k = 0; k < 2; ++k) dst[m][k] = *(const PG8_LAS bf16x8*)(lds + PG8_SA(b, h) + aoff + m * 2048 + k * 1024); } while (0)
; #define PG8_LDB(dst, b, h) do { _Pragma("unroll") for (int n = 0; n < 2; ++n) _Pragma("unroll") for (int k = 0; k < 2; ++k) dst[n][k] = *(const PG8_LAS bf16x8*)(lds + PG8_SB(b, h) + boff + n * 2048 + k * 1024); } while (0)
; #define PG8_MMA(ai, bj, At, Bt) do { __builtin_amdgcn_s_setprio(1); _Pragma("unroll") for (int m = 0; m < 4; ++m) _Pragma("unroll") for (int n = 0; n < 2; ++n) _Pragma("unroll") for (int k = 0; k < 2; ++k) \
;         acc[ai][bj][m][n] = __builtin_amdgcn_mfma_f32_16x16x32_bf16(Bt[n][k], At[m][k], acc[ai][bj][m][n], 0, 0, 0); __builtin_amdgcn_s_setprio(0); } while (0)
; #define PG8_WAIT_V(n) asm volatile("s_waitcnt vmcnt(" #n ")" ::: "memory")
; #define PG8_WAIT_L(n) asm volatile("s_waitcnt lgkmcnt(" #n ")" ::: "memory")
; #define PG8_BAR __builtin_amdgcn_s_barrier()
; #define PG8_SCHED __builtin_amdgcn_sched_barrier(0)
; template <class Epi, class Sched, bool ALIGN_EPI = false, bool SP2 = false>
; __device__ __forceinline__ void gemm_phase(PG8_LAS unsigned char* lds, const Gemm g, const Sched& S, const Epi& E) {
;     ...
;             PG8_WAIT_V(8); PG8_WAIT_L(0); PG8_BAR; PG8_MMA(1, 0, At, B0); PG8_MMA(1, 1, At, B1); PG8_BAR; PG8_SCHED;
;             PG8_LDB(B0, 1, 0); PG8_LDB(B1, 1, 1); PG8_SCHED; PG8_LDA(At, 1, 0); PG8_STAGE(PG8_SA(0, 1), a2 + hstep, voffA);
;             PG8_WAIT_V(8); PG8_WAIT_L(0); PG8_BAR; PG8_MMA(0, 0, At, B0); PG8_MMA(0, 1, At, B1); PG8_BAR; PG8_SCHED;
	s_setprio 1
	s_waitcnt lgkmcnt(0)
	v_mfma_f32_16x16x32_bf16 v[60:63], v[154:157], v[186:189], 0
	v_mfma_f32_16x16x32_bf16 v[56:59], v[162:165], v[186:189], 0
	v_mfma_f32_16x16x32_bf16 v[44:47], v[154:157], v[194:197], 0
	v_mfma_f32_16x16x32_bf16 v[40:43], v[162:165], v[194:197], 0
	v_mfma_f32_16x16x32_bf16 v[28:31], v[154:157], v[202:205], 0
	v_mfma_f32_16x16x32_bf16 v[24:27], v[162:165], v[202:205], 0
	v_mfma_f32_16x16x32_bf16 v[12:15], v[154:157], v[210:213], 0
	v_mfma_f32_16x16x32_bf16 v[8:11], v[162:165], v[210:213], 0
	v_mfma_f32_16x16x32_bf16 v[60:63], v[158:161], v[190:193], v[60:63]
	v_mfma_f32_16x16x32_bf16 v[56:59], v[166:169], v[190:193], v[56:59]
	v_mfma_f32_16x16x32_bf16 v[44:47], v[158:161], v[198:201], v[44:47]
	v_mfma_f32_16x16x32_bf16 v[40:43], v[166:169], v[198:201], v[40:43]
	v_mfma_f32_16x16x32_bf16 v[28:31], v[158:161], v[206:209], v[28:31]
	v_mfma_f32_16x16x32_bf16 v[24:27], v[166:169], v[206:209], v[24:27]
	v_mfma_f32_16x16x32_bf16 v[12:15], v[158:161], v[214:217], v[12:15]
	v_mfma_f32_16x16x32_bf16 v[8:11], v[166:169], v[214:217], v[8:11]
	s_setprio 0
	s_setprio 1
	v_mfma_f32_16x16x32_bf16 v[52:55], v[170:173], v[186:189], 0
	v_mfma_f32_16x16x32_bf16 v[48:51], v[178:181], v[186:189], 0
	v_mfma_f32_16x16x32_bf16 v[36:39], v[170:173], v[194:197], 0
	v_mfma_f32_16x16x32_bf16 v[32:35], v[178:181], v[194:197], 0
	v_mfma_f32_16x16x32_bf16 v[20:23], v[170:173], v[202:205], 0
	v_mfma_f32_16x16x32_bf16 v[16:19], v[178:181], v[202:205], 0
	v_mfma_f32_16x16x32_bf16 v[4:7], v[170:173], v[210:213], 0
	v_mfma_f32_16x16x32_bf16 v[0:3], v[178:181], v[210:213], 0
	v_mfma_f32_16x16x32_bf16 v[52:55], v[174:177], v[190:193], v[52:55]
	v_mfma_f32_16x16x32_bf16 v[48:51], v[182:185], v[190:193], v[48:51]
	v_mfma_f32_16x16x32_bf16 v[36:39], v[174:177], v[198:201], v[36:39]
	v_mfma_f32_16x16x32_bf16 v[32:35], v[182:185], v[198:201], v[32:35]
	v_mfma_f32_16x16x32_bf16 v[20:23], v[174:177], v[206:209], v[20:23]
	v_mfma_f32_16x16x32_bf16 v[16:19], v[182:185], v[206:209], v[16:19]
	v_mfma_f32_16x16x32_bf16 v[4:7], v[174:177], v[214:217], v[4:7]
	v_mfma_f32_16x16x32_bf16 v[0:3], v[182:185], v[214:217], v[0:3]
	s_setprio 0
	s_barrier
	s_add_i32 s25, 0, 0x18000
	s_add_i32 s61, 0, 0x1c000
	v_add_u32_e32 v166, s25, v149
	v_add_u32_e32 v182, s61, v149
	ds_read_b128 v[154:157], v166
	ds_read_b128 v[158:161], v166 offset:1024
	ds_read_b128 v[162:165], v166 offset:2048
	ds_read_b128 v[166:169], v166 offset:3072
	ds_read_b128 v[170:173], v182
	ds_read_b128 v[174:177], v182 offset:1024
	ds_read_b128 v[178:181], v182 offset:2048
	ds_read_b128 v[182:185], v182 offset:3072
	s_add_u32 s52, s52, s34
	s_addc_u32 s53, s53, s35
	s_mov_b32 m0, s18
	v_lshl_add_u64 v[228:229], s[52:53], 0, v[128:129]
	ds_read_b128 v[186:189], v153 offset:32768
	ds_read_b128 v[190:193], v153 offset:33792
	ds_read_b128 v[194:197], v153 offset:34816
	ds_read_b128 v[198:201], v153 offset:35840
	ds_read_b128 v[202:205], v153 offset:36864
	ds_read_b128 v[206:209], v153 offset:37888
	ds_read_b128 v[210:213], v153 offset:38912
	ds_read_b128 v[214:217], v153 offset:39936
	global_load_lds_dwordx4 v[228:229], off
	v_lshl_add_u64 v[228:229], s[52:53], 0, v[132:133]
	s_mov_b32 m0, s19
	s_nop 0
	global_load_lds_dwordx4 v[228:229], off
	s_waitcnt vmcnt(8)
	s_waitcnt lgkmcnt(0)
	s_barrier
	s_setprio 1
	s_waitcnt lgkmcnt(0)
	v_mfma_f32_16x16x32_bf16 v[124:127], v[154:157], v[186:189], v[124:127]
	v_mfma_f32_16x16x32_bf16 v[120:123], v[162:165], v[186:189], v[120:123]
	v_mfma_f32_16x16x32_bf16 v[108:111], v[154:157], v[194:197], v[108:111]
	v_mfma_f32_16x16x32_bf16 v[104:107], v[162:165], v[194:197], v[104:107]
	v_mfma_f32_16x16x32_bf16 v[92:95], v[154:157], v[202:205], v[92:95]
	v_mfma_f32_16x16x32_bf16 v[88:91], v[162:165], v[202:205], v[88:91]
	v_mfma_f32_16x16x32_bf16 v[76:79], v[154:157], v[210:213], v[76:79]
	v_mfma_f32_16x16x32_bf16 v[72:75], v[162:165], v[210:213], v[72:75]
	v_mfma_f32_16x16x32_bf16 v[124:127], v[158:161], v[190:193], v[124:127]
	v_mfma_f32_16x16x32_bf16 v[120:123], v[166:169], v[190:193], v[120:123]
	v_mfma_f32_16x16x32_bf16 v[108:111], v[158:161], v[198:201], v[108:111]
	v_mfma_f32_16x16x32_bf16 v[104:107], v[166:169], v[198:201], v[104:107]
	v_mfma_f32_16x16x32_bf16 v[92:95], v[158:161], v[206:209], v[92:95]
	v_mfma_f32_16x16x32_bf16 v[88:91], v[166:169], v[206:209], v[88:91]
	v_mfma_f32_16x16x32_bf16 v[76:79], v[158:161], v[214:217], v[76:79]
	v_mfma_f32_16x16x32_bf16 v[72:75], v[166:169], v[214:217], v[72:75]
	s_setprio 0
	s_setprio 1
	v_mfma_f32_16x16x32_bf16 v[116:119], v[170:173], v[186:189], v[116:119]
	v_mfma_f32_16x16x32_bf16 v[112:115], v[178:181], v[186:189], v[112:115]
	v_mfma_f32_16x16x32_bf16 v[100:103], v[170:173], v[194:197], v[100:103]
	v_mfma_f32_16x16x32_bf16 v[96:99], v[178:181], v[194:197], v[96:99]
	v_mfma_f32_16x16x32_bf16 v[84:87], v[170:173], v[202:205], v[84:87]
	v_mfma_f32_16x16x32_bf16 v[80:83], v[178:181], v[202:205], v[80:83]
	v_mfma_f32_16x16x32_bf16 v[68:71], v[170:173], v[210:213], v[68:71]
	v_mfma_f32_16x16x32_bf16 v[64:67], v[178:181], v[210:213], v[64:67]
	v_mfma_f32_16x16x32_bf16 v[116:119], v[174:177], v[190:193], v[116:119]
	v_mfma_f32_16x16x32_bf16 v[112:115], v[182:185], v[190:193], v[112:115]
	v_mfma_f32_16x16x32_bf16 v[100:103], v[174:177], v[198:201], v[100:103]
	v_mfma_f32_16x16x32_bf16 v[96:99], v[182:185], v[198:201], v[96:99]
	v_mfma_f32_16x16x32_bf16 v[84:87], v[174:177], v[206:209], v[84:87]
	v_mfma_f32_16x16x32_bf16 v[80:83], v[182:185], v[206:209], v[80:83]
	v_mfma_f32_16x16x32_bf16 v[68:71], v[174:177], v[214:217], v[68:71]
	v_mfma_f32_16x16x32_bf16 v[64:67], v[182:185], v[214:217], v[64:67]
	s_setprio 0
	s_barrier
; #define PG8_STAGE(bufoff, gbase, voff) do { _Pragma("unroll") for (int _i = 0; _i < 2; ++_i) \
;         __builtin_amdgcn_global_load_lds((const unsigned*)((const char*)(gbase) + (voff)[_i]), (PG8_LAS unsigned*)(lds + (bufoff) + ldsw + _i * 8192), 16, 0, 0); } while (0)
; #define PG8_LDA(dst, b, h) do { _Pragma("unroll") for (int m = 0; m < 4; ++m) _Pragma("unroll") for (int k = 0; k < 2; ++k) dst[m][k] = *(const PG8_LAS bf16x8*)(lds + PG8_SA(b, h) + aoff + m * 2048 + k * 1024); } while (0)
; #define PG8_MMA(ai, bj, At, Bt) do { __builtin_amdgcn_s_setprio(1); _Pragma("unroll") for (int m = 0; m < 4; ++m) _Pragma("unroll") for (int n = 0; n < 2; ++n) _Pragma("unroll") for (int k = 0; k < 2; ++k) \
;         acc[ai][bj][m][n] = __builtin_amdgcn_mfma_f32_16x16x32_bf16(Bt[n][k], At[m][k], acc[ai][bj][m][n], 0, 0, 0); __builtin_amdgcn_s_setprio(0); } while (0)
; #define PG8_WAIT_V(n) asm volatile("s_waitcnt vmcnt(" #n ")" ::: "memory")
; #define PG8_WAIT_L(n) asm volatile("s_waitcnt lgkmcnt(" #n ")" ::: "memory")
; #define PG8_BAR __builtin_amdgcn_s_barrier()
; #define PG8_SCHED __builtin_amdgcn_sched_barrier(0)
; template <class Epi, class Sched, bool ALIGN_EPI = false, bool SP2 = false>
; __device__ __forceinline__ void gemm_phase(PG8_LAS unsigned char* lds, const Gemm g, const Sched& S, const Epi& E) {
;     ...
;         for (int t = 0; t < nt; t += 2) {
;             const bool last = (t == nt - 2);
;             const char* a1 = cA + (size_t)(t + 1) * kstep;
;             const char* a2 = last ? nA : cA + (size_t)(t + 2) * kstep; const char* b2 = last ? nB : cB + (size_t)(t + 2) * kstep;
;     ...
;             PG8_LDA(At, 1, 1); PG8_STAGE(PG8_SB(1, 0), b3, voffB); PG8_STAGE(PG8_SB(1, 1), b3 + hstep, voffB); PG8_STAGE(PG8_SA(1, 0), a3, voffA);
;             PG8_WAIT_V(8); PG8_WAIT_L(0); PG8_BAR; PG8_MMA(1, 0, At, B0); PG8_MMA(1, 1, At, B1); PG8_BAR; PG8_SCHED;
	s_add_i32 s25, s25, s3
	v_lshl_add_u64 v[146:147], v[146:147], 0, s[44:45]
	s_mov_b32 m0, s25
	ds_read_b128 v[186:189], v153 offset:49152
	ds_read_b128 v[190:193], v153 offset:50176
	ds_read_b128 v[194:197], v153 offset:51200
	ds_read_b128 v[198:201], v153 offset:52224
	ds_read_b128 v[202:205], v153 offset:53248
	ds_read_b128 v[206:209], v153 offset:54272
	ds_read_b128 v[210:213], v153 offset:55296
	ds_read_b128 v[214:217], v153 offset:56320
	global_load_lds_dwordx4 v[146:147], off
	v_lshl_add_u64 v[146:147], v[218:219], 0, s[44:45]
	s_add_i32 m0, s25, 0x2000
	s_add_i32 s25, s61, s3
	global_load_lds_dwordx4 v[146:147], off
	v_lshl_add_u64 v[146:147], v[220:221], 0, s[44:45]
	s_mov_b32 m0, s25
	s_nop 0
	global_load_lds_dwordx4 v[146:147], off
	v_lshl_add_u64 v[146:147], v[222:223], 0, s[44:45]
	s_add_i32 m0, s25, 0x2000
	s_nop 0
	global_load_lds_dwordx4 v[146:147], off
	v_lshl_add_u64 v[146:147], v[224:225], 0, s[44:45]
	s_mov_b32 m0, s26
	s_nop 0
	global_load_lds_dwordx4 v[146:147], off
	v_lshl_add_u64 v[146:147], v[226:227], 0, s[44:45]
	s_mov_b32 m0, s27
	s_nop 0
	global_load_lds_dwordx4 v[146:147], off
	s_waitcnt vmcnt(8)
	s_waitcnt lgkmcnt(0)
	s_barrier
	s_setprio 1
	s_waitcnt lgkmcnt(0)
	v_mfma_f32_16x16x32_bf16 v[60:63], v[154:157], v[186:189], v[60:63]
	v_mfma_f32_16x16x32_bf16 v[56:59], v[162:165], v[186:189], v[56:59]
	v_mfma_f32_16x16x32_bf16 v[44:47], v[154:157], v[194:197], v[44:47]
	v_mfma_f32_16x16x32_bf16 v[40:43], v[162:165], v[194:197], v[40:43]
	v_mfma_f32_16x16x32_bf16 v[28:31], v[154:157], v[202:205], v[28:31]
	v_mfma_f32_16x16x32_bf16 v[24:27], v[162:165], v[202:205], v[24:27]
	v_mfma_f32_16x16x32_bf16 v[12:15], v[154:157], v[210:213], v[12:15]
	v_mfma_f32_16x16x32_bf16 v[8:11], v[162:165], v[210:213], v[8:11]
	v_mfma_f32_16x16x32_bf16 v[60:63], v[158:161], v[190:193], v[60:63]
	v_mfma_f32_16x16x32_bf16 v[56:59], v[166:169], v[190:193], v[56:59]
	v_mfma_f32_16x16x32_bf16 v[44:47], v[158:161], v[198:201], v[44:47]
	v_mfma_f32_16x16x32_bf16 v[40:43], v[166:169], v[198:201], v[40:43]
	v_mfma_f32_16x16x32_bf16 v[28:31], v[158:161], v[206:209], v[28:31]
	v_mfma_f32_16x16x32_bf16 v[24:27], v[166:169], v[206:209], v[24:27]
	v_mfma_f32_16x16x32_bf16 v[12:15], v[158:161], v[214:217], v[12:15]
	v_mfma_f32_16x16x32_bf16 v[8:11], v[166:169], v[214:217], v[8:11]
	s_setprio 0
	s_setprio 1
	v_mfma_f32_16x16x32_bf16 v[52:55], v[170:173], v[186:189], v[52:55]
	v_mfma_f32_16x16x32_bf16 v[48:51], v[178:181], v[186:189], v[48:51]
	v_mfma_f32_16x16x32_bf16 v[36:39], v[170:173], v[194:197], v[36:39]
	v_mfma_f32_16x16x32_bf16 v[32:35], v[178:181], v[194:197], v[32:35]
	v_mfma_f32_16x16x32_bf16 v[20:23], v[170:173], v[202:205], v[20:23]
	v_mfma_f32_16x16x32_bf16 v[16:19], v[178:181], v[202:205], v[16:19]
	v_mfma_f32_16x16x32_bf16 v[4:7], v[170:173], v[210:213], v[4:7]
	v_mfma_f32_16x16x32_bf16 v[0:3], v[178:181], v[210:213], v[0:3]
	v_mfma_f32_16x16x32_bf16 v[52:55], v[174:177], v[190:193], v[52:55]
	v_mfma_f32_16x16x32_bf16 v[48:51], v[182:185], v[190:193], v[48:51]
	v_mfma_f32_16x16x32_bf16 v[36:39], v[174:177], v[198:201], v[36:39]
	v_mfma_f32_16x16x32_bf16 v[32:35], v[182:185], v[198:201], v[32:35]
	v_mfma_f32_16x16x32_bf16 v[20:23], v[174:177], v[206:209], v[20:23]
	v_mfma_f32_16x16x32_bf16 v[16:19], v[182:185], v[206:209], v[16:19]
	v_mfma_f32_16x16x32_bf16 v[4:7], v[174:177], v[214:217], v[4:7]
	v_mfma_f32_16x16x32_bf16 v[0:3], v[182:185], v[214:217], v[0:3]
	s_setprio 0
	s_barrier
	s_add_u32 s50, s50, 0x100
	s_addc_u32 s51, s51, 0
	s_add_u32 s2, s2, 0x100
	s_addc_u32 s24, s24, 0
	s_cmp_ge_i32 s60, s30
	s_mov_b32 s25, s60
	s_cbranch_scc1 .Lpeelx_9

; #define PG8_STAGE(bufoff, gbase, voff) do { _Pragma("unroll") for (int _i = 0; _i < 2; ++_i) \
;         __builtin_amdgcn_global_load_lds((const unsigned*)((const char*)(gbase) + (voff)[_i]), (PG8_LAS unsigned*)(lds + (bufoff) + ldsw + _i * 8192), 16, 0, 0); } while (0)
; #define PG8_LDA(dst, b, h) do { _Pragma("unroll") for (int m = 0; m < 4; ++m) _Pragma("unroll") for (int k = 0; k < 2; ++k) dst[m][k] = *(const PG8_LAS bf16x8*)(lds + PG8_SA(b, h) + aoff + m * 2048 + k * 1024); } while (0)
; #define PG8_LDB(dst, b, h) do { _Pragma("unroll") for (int n = 0; n < 2; ++n) _Pragma("unroll") for (int k = 0; k < 2; ++k) dst[n][k] = *(const PG8_LAS bf16x8*)(lds + PG8_SB(b, h) + boff + n * 2048 + k * 1024); } while (0)
; #define PG8_WAIT_V(n) asm volatile("s_waitcnt vmcnt(" #n ")" ::: "memory")
; #define PG8_WAIT_L(n) asm volatile("s_waitcnt lgkmcnt(" #n ")" ::: "memory")
; #define PG8_BAR __builtin_amdgcn_s_barrier()
; #define PG8_SCHED __builtin_amdgcn_sched_barrier(0)
; template <class Epi, class Sched, bool ALIGN_EPI = false, bool SP2 = false>
; __device__ __forceinline__ void gemm_phase(PG8_LAS unsigned char* lds, const Gemm g, const Sched& S, const Epi& E) {
;     ...
;     f32x4 acc[2][2][4][2];
; #pragma unroll
;     for (int a = 0; a < 2; ++a)
; #pragma unroll
;         for (int b = 0; b < 2; ++b)
; #pragma unroll
;             for (int m = 0; m < 4; ++m)
; #pragma unroll
;                 for (int n = 0; n < 2; ++n) acc[a][b][m][n] = (f32x4){0.f, 0.f, 0.f, 0.f};
;     ...
;         for (int t = 0; t < nt; t += 2) {
;             const bool last = (t == nt - 2);
;             const char* a1 = cA + (size_t)(t + 1) * kstep;
;             const char* a2 = last ? nA : cA + (size_t)(t + 2) * kstep; const char* b2 = last ? nB : cB + (size_t)(t + 2) * kstep;
;             const char* a3 = a2 + kstep; const char* b3 = b2 + kstep;
;             if (last && has_next) S.a_ready(nxt);
;             if constexpr (SP2) {
;             PG8_LDB(B0, 0, 0); PG8_LDB(B1, 0, 1); PG8_SCHED; PG8_LDA(At, 0, 0); PG8_STAGE(PG8_SA(1, 1), a1 + hstep, voffA);
;             PG8_WAIT_V(8); PG8_WAIT_L(0); PG8_BAR; PG8_MMA(0, 0, At, B0); PG8_MMA(0, 1, At, B1); PG8_BAR; PG8_SCHED;
;             PG8_LDA(At, 0, 1); PG8_STAGE(PG8_SB(0, 0), b2, voffB); PG8_STAGE(PG8_SB(0, 1), b2 + hstep, voffB); PG8_STAGE(PG8_SA(0, 0), a2, voffA);
.LBB0_2283:
	s_and_b64 vcc, exec, s[12:13]
	s_cbranch_vccnz .Lcoldz_10
	s_add_u32 s48, s48, 0x80
	s_addc_u32 s49, s49, 0
	s_add_u32 s2, s50, 0x100
	s_addc_u32 s24, s51, 0
	s_mov_b32 s25, 0
	ds_read_b128 v[120:123], v246
	ds_read_b128 v[132:135], v246 offset:1024
	ds_read_b128 v[136:139], v246 offset:2048
	ds_read_b128 v[140:143], v246 offset:3072
	ds_read_b128 v[144:147], v247
	ds_read_b128 v[148:151], v247 offset:1024
	ds_read_b128 v[152:155], v247 offset:2048
	ds_read_b128 v[156:159], v247 offset:3072
	s_add_i32 s60, s25, 2
	s_add_u32 s50, s48, 0x80
	s_addc_u32 s51, s49, 0
	s_cmp_eq_u32 s54, s25
	s_cselect_b32 s51, s17, s51
	s_cselect_b32 s50, s16, s50
	s_cselect_b32 s63, s47, s24
	s_cselect_b32 s62, s46, s2
	v_lshl_add_u64 v[206:207], s[48:49], 0, v[200:201]
	s_add_i32 m0, s7, 0xc000
	ds_read_b128 v[160:163], v248
	ds_read_b128 v[164:167], v248 offset:1024
	ds_read_b128 v[168:171], v248 offset:2048
	ds_read_b128 v[172:175], v248 offset:3072
	ds_read_b128 v[176:179], v248 offset:4096
	ds_read_b128 v[180:183], v248 offset:5120
	ds_read_b128 v[184:187], v248 offset:6144
	ds_read_b128 v[188:191], v248 offset:7168
	global_load_lds_dwordx4 v[206:207], off
	v_lshl_add_u64 v[206:207], s[48:49], 0, v[202:203]
	s_add_i32 m0, s7, 0xe000
	s_nop 0
	global_load_lds_dwordx4 v[206:207], off
	s_waitcnt vmcnt(8)
	s_waitcnt lgkmcnt(0)
	s_barrier
	s_setprio 1
	s_waitcnt lgkmcnt(0)
	v_mfma_f32_16x16x32_bf16 v[128:131], v[120:123], v[160:163], 0
	v_mfma_f32_16x16x32_bf16 v[124:127], v[136:139], v[160:163], 0
	v_mfma_f32_16x16x32_bf16 v[108:111], v[120:123], v[168:171], 0
	v_mfma_f32_16x16x32_bf16 v[104:107], v[136:139], v[168:171], 0
	v_mfma_f32_16x16x32_bf16 v[92:95], v[120:123], v[176:179], 0
	v_mfma_f32_16x16x32_bf16 v[88:91], v[136:139], v[176:179], 0
	v_mfma_f32_16x16x32_bf16 v[76:79], v[120:123], v[184:187], 0
	v_mfma_f32_16x16x32_bf16 v[72:75], v[136:139], v[184:187], 0
	v_mfma_f32_16x16x32_bf16 v[128:131], v[132:135], v[164:167], v[128:131]
	v_mfma_f32_16x16x32_bf16 v[124:127], v[140:143], v[164:167], v[124:127]
	v_mfma_f32_16x16x32_bf16 v[108:111], v[132:135], v[172:175], v[108:111]
	v_mfma_f32_16x16x32_bf16 v[104:107], v[140:143], v[172:175], v[104:107]
	v_mfma_f32_16x16x32_bf16 v[92:95], v[132:135], v[180:183], v[92:95]
	v_mfma_f32_16x16x32_bf16 v[88:91], v[140:143], v[180:183], v[88:91]
	v_mfma_f32_16x16x32_bf16 v[76:79], v[132:135], v[188:191], v[76:79]
	v_mfma_f32_16x16x32_bf16 v[72:75], v[140:143], v[188:191], v[72:75]
	s_setprio 0
	s_setprio 1
	v_mfma_f32_16x16x32_bf16 v[116:119], v[144:147], v[160:163], 0
	v_mfma_f32_16x16x32_bf16 v[112:115], v[152:155], v[160:163], 0
	v_mfma_f32_16x16x32_bf16 v[100:103], v[144:147], v[168:171], 0
	v_mfma_f32_16x16x32_bf16 v[96:99], v[152:155], v[168:171], 0
	v_mfma_f32_16x16x32_bf16 v[84:87], v[144:147], v[176:179], 0
	v_mfma_f32_16x16x32_bf16 v[80:83], v[152:155], v[176:179], 0
	v_mfma_f32_16x16x32_bf16 v[68:71], v[144:147], v[184:187], 0
	v_mfma_f32_16x16x32_bf16 v[64:67], v[152:155], v[184:187], 0
	v_mfma_f32_16x16x32_bf16 v[116:119], v[148:151], v[164:167], v[116:119]
	v_mfma_f32_16x16x32_bf16 v[112:115], v[156:159], v[164:167], v[112:115]
	v_mfma_f32_16x16x32_bf16 v[100:103], v[148:151], v[172:175], v[100:103]
	v_mfma_f32_16x16x32_bf16 v[96:99], v[156:159], v[172:175], v[96:99]
	v_mfma_f32_16x16x32_bf16 v[84:87], v[148:151], v[180:183], v[84:87]
	v_mfma_f32_16x16x32_bf16 v[80:83], v[156:159], v[180:183], v[80:83]
	v_mfma_f32_16x16x32_bf16 v[68:71], v[148:151], v[188:191], v[68:71]
	v_mfma_f32_16x16x32_bf16 v[64:67], v[156:159], v[188:191], v[64:67]
	s_setprio 0
	s_barrier
	s_add_i32 s25, s55, s6
	v_lshl_add_u64 v[206:207], s[62:63], 0, v[194:195]
	s_mov_b32 m0, s25
	ds_read_b128 v[160:163], v248 offset:16384
	ds_read_b128 v[164:167], v248 offset:17408
	ds_read_b128 v[168:171], v248 offset:18432
	ds_read_b128 v[172:175], v248 offset:19456
	ds_read_b128 v[176:179], v248 offset:20480
	ds_read_b128 v[180:183], v248 offset:21504
	ds_read_b128 v[184:187], v248 offset:22528
	ds_read_b128 v[188:191], v248 offset:23552
	global_load_lds_dwordx4 v[206:207], off
	s_add_i32 m0, s25, 0x2000
	v_lshl_add_u64 v[208:209], s[62:63], 0, v[198:199]
	s_add_u32 s62, s62, s34
	s_addc_u32 s63, s63, s35
	s_add_i32 s25, s56, s6
	global_load_lds_dwordx4 v[208:209], off
	v_lshl_add_u64 v[210:211], s[62:63], 0, v[194:195]
	s_mov_b32 m0, s25
	v_lshl_add_u64 v[212:213], s[62:63], 0, v[198:199]
	global_load_lds_dwordx4 v[210:211], off
	s_add_i32 m0, s25, 0x2000
	v_lshl_add_u64 v[214:215], s[50:51], 0, v[192:193]
	global_load_lds_dwordx4 v[212:213], off
	s_mov_b32 m0, s7
	v_lshl_add_u64 v[216:217], s[50:51], 0, v[196:197]
	global_load_lds_dwordx4 v[214:215], off
	s_mov_b32 m0, s18
	s_nop 0
	global_load_lds_dwordx4 v[216:217], off
	s_waitcnt vmcnt(8)
	s_waitcnt lgkmcnt(0)
	s_barrier
; #define PG8_STAGE(bufoff, gbase, voff) do { _Pragma("unroll") for (int _i = 0; _i < 2; ++_i) \
;         __builtin_amdgcn_global_load_lds((const unsigned*)((const char*)(gbase) + (voff)[_i]), (PG8_LAS unsigned*)(lds + (bufoff) + ldsw + _i * 8192), 16, 0, 0); } while (0)
; #define PG8_LDA(dst, b, h) do { _Pragma("unroll") for (int m = 0; m < 4; ++m) _Pragma("unroll") for (int k = 0; k < 2; ++k) dst[m][k] = *(const PG8_LAS bf16x8*)(lds + PG8_SA(b, h) + aoff + m * 2048 + k * 1024); } while (0)
; #define PG8_LDB(dst, b, h) do { _Pragma("unroll") for (int n = 0; n < 2; ++n) _Pragma("unroll") for (int k = 0; k < 2; ++k) dst[n][k] = *(const PG8_LAS bf16x8*)(lds + PG8_SB(b, h) + boff + n * 2048 + k * 1024); } while (0)
; #define PG8_MMA(ai, bj, At, Bt) do { __builtin_amdgcn_s_setprio(1); _Pragma("unroll") for (int m = 0; m < 4; ++m) _Pragma("unroll") for (int n = 0; n < 2; ++n) _Pragma("unroll") for (int k = 0; k < 2; ++k) \
;         acc[ai][bj][m][n] = __builtin_amdgcn_mfma_f32_16x16x32_bf16(Bt[n][k], At[m][k], acc[ai][bj][m][n], 0, 0, 0); __builtin_amdgcn_s_setprio(0); } while (0)
; #define PG8_WAIT_V(n) asm volatile("s_waitcnt vmcnt(" #n ")" ::: "memory")
; #define PG8_WAIT_L(n) asm volatile("s_waitcnt lgkmcnt(" #n ")" ::: "memory")
; #define PG8_BAR __builtin_amdgcn_s_barrier()
; #define PG8_SCHED __builtin_amdgcn_sched_barrier(0)
; template <class Epi, class Sched, bool ALIGN_EPI = false, bool SP2 = false>
; __device__ __forceinline__ void gemm_phase(PG8_LAS unsigned char* lds, const Gemm g, const Sched& S, const Epi& E) {
;     ...
;             PG8_WAIT_V(8); PG8_WAIT_L(0); PG8_BAR; PG8_MMA(1, 0, At, B0); PG8_MMA(1, 1, At, B1); PG8_BAR; PG8_SCHED;
;             PG8_LDB(B0, 1, 0); PG8_LDB(B1, 1, 1); PG8_SCHED; PG8_LDA(At, 1, 0); PG8_STAGE(PG8_SA(0, 1), a2 + hstep, voffA);
;             PG8_WAIT_V(8); PG8_WAIT_L(0); PG8_BAR; PG8_MMA(0, 0, At, B0); PG8_MMA(0, 1, At, B1); PG8_BAR; PG8_SCHED;
	s_setprio 1
	s_waitcnt lgkmcnt(0)
	v_mfma_f32_16x16x32_bf16 v[60:63], v[120:123], v[160:163], 0
	v_mfma_f32_16x16x32_bf16 v[56:59], v[136:139], v[160:163], 0
	v_mfma_f32_16x16x32_bf16 v[44:47], v[120:123], v[168:171], 0
	v_mfma_f32_16x16x32_bf16 v[40:43], v[136:139], v[168:171], 0
	v_mfma_f32_16x16x32_bf16 v[28:31], v[120:123], v[176:179], 0
	v_mfma_f32_16x16x32_bf16 v[24:27], v[136:139], v[176:179], 0
	v_mfma_f32_16x16x32_bf16 v[12:15], v[120:123], v[184:187], 0
	v_mfma_f32_16x16x32_bf16 v[8:11], v[136:139], v[184:187], 0
	v_mfma_f32_16x16x32_bf16 v[60:63], v[132:135], v[164:167], v[60:63]
	v_mfma_f32_16x16x32_bf16 v[56:59], v[140:143], v[164:167], v[56:59]
	v_mfma_f32_16x16x32_bf16 v[44:47], v[132:135], v[172:175], v[44:47]
	v_mfma_f32_16x16x32_bf16 v[40:43], v[140:143], v[172:175], v[40:43]
	v_mfma_f32_16x16x32_bf16 v[28:31], v[132:135], v[180:183], v[28:31]
	v_mfma_f32_16x16x32_bf16 v[24:27], v[140:143], v[180:183], v[24:27]
	v_mfma_f32_16x16x32_bf16 v[12:15], v[132:135], v[188:191], v[12:15]
	v_mfma_f32_16x16x32_bf16 v[8:11], v[140:143], v[188:191], v[8:11]
	s_setprio 0
	s_setprio 1
	v_mfma_f32_16x16x32_bf16 v[52:55], v[144:147], v[160:163], 0
	v_mfma_f32_16x16x32_bf16 v[48:51], v[152:155], v[160:163], 0
	v_mfma_f32_16x16x32_bf16 v[36:39], v[144:147], v[168:171], 0
	v_mfma_f32_16x16x32_bf16 v[32:35], v[152:155], v[168:171], 0
	v_mfma_f32_16x16x32_bf16 v[20:23], v[144:147], v[176:179], 0
	v_mfma_f32_16x16x32_bf16 v[16:19], v[152:155], v[176:179], 0
	v_mfma_f32_16x16x32_bf16 v[4:7], v[144:147], v[184:187], 0
	v_mfma_f32_16x16x32_bf16 v[0:3], v[152:155], v[184:187], 0
	v_mfma_f32_16x16x32_bf16 v[52:55], v[148:151], v[164:167], v[52:55]
	v_mfma_f32_16x16x32_bf16 v[48:51], v[156:159], v[164:167], v[48:51]
	v_mfma_f32_16x16x32_bf16 v[36:39], v[148:151], v[172:175], v[36:39]
	v_mfma_f32_16x16x32_bf16 v[32:35], v[156:159], v[172:175], v[32:35]
	v_mfma_f32_16x16x32_bf16 v[20:23], v[148:151], v[180:183], v[20:23]
	v_mfma_f32_16x16x32_bf16 v[16:19], v[156:159], v[180:183], v[16:19]
	v_mfma_f32_16x16x32_bf16 v[4:7], v[148:151], v[188:191], v[4:7]
	v_mfma_f32_16x16x32_bf16 v[0:3], v[156:159], v[188:191], v[0:3]
	s_setprio 0
	s_barrier
	s_add_i32 s25, 0, 0x18000
	s_add_i32 s61, 0, 0x1c000
	v_add_u32_e32 v140, s25, v244
	v_add_u32_e32 v156, s61, v244
	ds_read_b128 v[120:123], v140
	ds_read_b128 v[132:135], v140 offset:1024
	ds_read_b128 v[136:139], v140 offset:2048
	ds_read_b128 v[140:143], v140 offset:3072
	ds_read_b128 v[144:147], v156
	ds_read_b128 v[148:151], v156 offset:1024
	ds_read_b128 v[152:155], v156 offset:2048
	ds_read_b128 v[156:159], v156 offset:3072
	s_add_u32 s50, s50, s34
	s_addc_u32 s51, s51, s35
	s_mov_b32 m0, s19
	v_lshl_add_u64 v[218:219], s[50:51], 0, v[192:193]
	ds_read_b128 v[160:163], v248 offset:32768
	ds_read_b128 v[164:167], v248 offset:33792
	ds_read_b128 v[168:171], v248 offset:34816
	ds_read_b128 v[172:175], v248 offset:35840
	ds_read_b128 v[176:179], v248 offset:36864
	ds_read_b128 v[180:183], v248 offset:37888
	ds_read_b128 v[184:187], v248 offset:38912
	ds_read_b128 v[188:191], v248 offset:39936
	global_load_lds_dwordx4 v[218:219], off
	v_lshl_add_u64 v[218:219], s[50:51], 0, v[196:197]
	s_mov_b32 m0, s26
	s_nop 0
	global_load_lds_dwordx4 v[218:219], off
	s_waitcnt vmcnt(8)
	s_waitcnt lgkmcnt(0)
	s_barrier
	s_setprio 1
	s_waitcnt lgkmcnt(0)
	v_mfma_f32_16x16x32_bf16 v[128:131], v[120:123], v[160:163], v[128:131]
	v_mfma_f32_16x16x32_bf16 v[124:127], v[136:139], v[160:163], v[124:127]
	v_mfma_f32_16x16x32_bf16 v[108:111], v[120:123], v[168:171], v[108:111]
	v_mfma_f32_16x16x32_bf16 v[104:107], v[136:139], v[168:171], v[104:107]
	v_mfma_f32_16x16x32_bf16 v[92:95], v[120:123], v[176:179], v[92:95]
	v_mfma_f32_16x16x32_bf16 v[88:91], v[136:139], v[176:179], v[88:91]
	v_mfma_f32_16x16x32_bf16 v[76:79], v[120:123], v[184:187], v[76:79]
	v_mfma_f32_16x16x32_bf16 v[72:75], v[136:139], v[184:187], v[72:75]
	v_mfma_f32_16x16x32_bf16 v[128:131], v[132:135], v[164:167], v[128:131]
	v_mfma_f32_16x16x32_bf16 v[124:127], v[140:143], v[164:167], v[124:127]
	v_mfma_f32_16x16x32_bf16 v[108:111], v[132:135], v[172:175], v[108:111]
	v_mfma_f32_16x16x32_bf16 v[104:107], v[140:143], v[172:175], v[104:107]
	v_mfma_f32_16x16x32_bf16 v[92:95], v[132:135], v[180:183], v[92:95]
	v_mfma_f32_16x16x32_bf16 v[88:91], v[140:143], v[180:183], v[88:91]
	v_mfma_f32_16x16x32_bf16 v[76:79], v[132:135], v[188:191], v[76:79]
	v_mfma_f32_16x16x32_bf16 v[72:75], v[140:143], v[188:191], v[72:75]
	s_setprio 0
	s_setprio 1
	v_mfma_f32_16x16x32_bf16 v[116:119], v[144:147], v[160:163], v[116:119]
	v_mfma_f32_16x16x32_bf16 v[112:115], v[152:155], v[160:163], v[112:115]
	v_mfma_f32_16x16x32_bf16 v[100:103], v[144:147], v[168:171], v[100:103]
	v_mfma_f32_16x16x32_bf16 v[96:99], v[152:155], v[168:171], v[96:99]
	v_mfma_f32_16x16x32_bf16 v[84:87], v[144:147], v[176:179], v[84:87]
	v_mfma_f32_16x16x32_bf16 v[80:83], v[152:155], v[176:179], v[80:83]
	v_mfma_f32_16x16x32_bf16 v[68:71], v[144:147], v[184:187], v[68:71]
	v_mfma_f32_16x16x32_bf16 v[64:67], v[152:155], v[184:187], v[64:67]
	v_mfma_f32_16x16x32_bf16 v[116:119], v[148:151], v[164:167], v[116:119]
	v_mfma_f32_16x16x32_bf16 v[112:115], v[156:159], v[164:167], v[112:115]
	v_mfma_f32_16x16x32_bf16 v[100:103], v[148:151], v[172:175], v[100:103]
	v_mfma_f32_16x16x32_bf16 v[96:99], v[156:159], v[172:175], v[96:99]
	v_mfma_f32_16x16x32_bf16 v[84:87], v[148:151], v[180:183], v[84:87]
	v_mfma_f32_16x16x32_bf16 v[80:83], v[156:159], v[180:183], v[80:83]
	v_mfma_f32_16x16x32_bf16 v[68:71], v[148:151], v[188:191], v[68:71]
	v_mfma_f32_16x16x32_bf16 v[64:67], v[156:159], v[188:191], v[64:67]
	s_setprio 0
	s_barrier
; #define PG8_STAGE(bufoff, gbase, voff) do { _Pragma("unroll") for (int _i = 0; _i < 2; ++_i) \
;         __builtin_amdgcn_global_load_lds((const unsigned*)((const char*)(gbase) + (voff)[_i]), (PG8_LAS unsigned*)(lds + (bufoff) + ldsw + _i * 8192), 16, 0, 0); } while (0)
; #define PG8_LDA(dst, b, h) do { _Pragma("unroll") for (int m = 0; m < 4; ++m) _Pragma("unroll") for (int k = 0; k < 2; ++k) dst[m][k] = *(const PG8_LAS bf16x8*)(lds + PG8_SA(b, h) + aoff + m * 2048 + k * 1024); } while (0)
; #define PG8_MMA(ai, bj, At, Bt) do { __builtin_amdgcn_s_setprio(1); _Pragma("unroll") for (int m = 0; m < 4; ++m) _Pragma("unroll") for (int n = 0; n < 2; ++n) _Pragma("unroll") for (int k = 0; k < 2; ++k) \
;         acc[ai][bj][m][n] = __builtin_amdgcn_mfma_f32_16x16x32_bf16(Bt[n][k], At[m][k], acc[ai][bj][m][n], 0, 0, 0); __builtin_amdgcn_s_setprio(0); } while (0)
; #define PG8_WAIT_V(n) asm volatile("s_waitcnt vmcnt(" #n ")" ::: "memory")
; #define PG8_WAIT_L(n) asm volatile("s_waitcnt lgkmcnt(" #n ")" ::: "memory")
; #define PG8_BAR __builtin_amdgcn_s_barrier()
; #define PG8_SCHED __builtin_amdgcn_sched_barrier(0)
; template <class Epi, class Sched, bool ALIGN_EPI = false, bool SP2 = false>
; __device__ __forceinline__ void gemm_phase(PG8_LAS unsigned char* lds, const Gemm g, const Sched& S, const Epi& E) {
;     ...
;         for (int t = 0; t < nt; t += 2) {
;             const bool last = (t == nt - 2);
;             const char* a1 = cA + (size_t)(t + 1) * kstep;
;             const char* a2 = last ? nA : cA + (size_t)(t + 2) * kstep; const char* b2 = last ? nB : cB + (size_t)(t + 2) * kstep;
;     ...
;             PG8_LDA(At, 1, 1); PG8_STAGE(PG8_SB(1, 0), b3, voffB); PG8_STAGE(PG8_SB(1, 1), b3 + hstep, voffB); PG8_STAGE(PG8_SA(1, 0), a3, voffA);
;             PG8_WAIT_V(8); PG8_WAIT_L(0); PG8_BAR; PG8_MMA(1, 0, At, B0); PG8_MMA(1, 1, At, B1); PG8_BAR; PG8_SCHED;
	s_add_i32 s25, s25, s6
	v_lshl_add_u64 v[206:207], v[206:207], 0, s[42:43]
	s_mov_b32 m0, s25
	ds_read_b128 v[160:163], v248 offset:49152
	ds_read_b128 v[164:167], v248 offset:50176
	ds_read_b128 v[168:171], v248 offset:51200
	ds_read_b128 v[172:175], v248 offset:52224
	ds_read_b128 v[176:179], v248 offset:53248
	ds_read_b128 v[180:183], v248 offset:54272
	ds_read_b128 v[184:187], v248 offset:55296
	ds_read_b128 v[188:191], v248 offset:56320
	global_load_lds_dwordx4 v[206:207], off
	v_lshl_add_u64 v[206:207], v[208:209], 0, s[42:43]
	s_add_i32 m0, s25, 0x2000
	s_add_i32 s25, s61, s6
	global_load_lds_dwordx4 v[206:207], off
	v_lshl_add_u64 v[206:207], v[210:211], 0, s[42:43]
	s_mov_b32 m0, s25
	s_nop 0
	global_load_lds_dwordx4 v[206:207], off
	v_lshl_add_u64 v[206:207], v[212:213], 0, s[42:43]
	s_add_i32 m0, s25, 0x2000
	s_nop 0
	global_load_lds_dwordx4 v[206:207], off
	v_lshl_add_u64 v[206:207], v[214:215], 0, s[42:43]
	s_mov_b32 m0, s27
	s_nop 0
	global_load_lds_dwordx4 v[206:207], off
	v_lshl_add_u64 v[206:207], v[216:217], 0, s[42:43]
	s_mov_b32 m0, s33
	s_nop 0
	global_load_lds_dwordx4 v[206:207], off
	s_waitcnt vmcnt(8)
	s_waitcnt lgkmcnt(0)
	s_barrier
	s_setprio 1
	s_waitcnt lgkmcnt(0)
	v_mfma_f32_16x16x32_bf16 v[60:63], v[120:123], v[160:163], v[60:63]
	v_mfma_f32_16x16x32_bf16 v[56:59], v[136:139], v[160:163], v[56:59]
	v_mfma_f32_16x16x32_bf16 v[44:47], v[120:123], v[168:171], v[44:47]
	v_mfma_f32_16x16x32_bf16 v[40:43], v[136:139], v[168:171], v[40:43]
	v_mfma_f32_16x16x32_bf16 v[28:31], v[120:123], v[176:179], v[28:31]
	v_mfma_f32_16x16x32_bf16 v[24:27], v[136:139], v[176:179], v[24:27]
	v_mfma_f32_16x16x32_bf16 v[12:15], v[120:123], v[184:187], v[12:15]
	v_mfma_f32_16x16x32_bf16 v[8:11], v[136:139], v[184:187], v[8:11]
	v_mfma_f32_16x16x32_bf16 v[60:63], v[132:135], v[164:167], v[60:63]
	v_mfma_f32_16x16x32_bf16 v[56:59], v[140:143], v[164:167], v[56:59]
	v_mfma_f32_16x16x32_bf16 v[44:47], v[132:135], v[172:175], v[44:47]
	v_mfma_f32_16x16x32_bf16 v[40:43], v[140:143], v[172:175], v[40:43]
	v_mfma_f32_16x16x32_bf16 v[28:31], v[132:135], v[180:183], v[28:31]
	v_mfma_f32_16x16x32_bf16 v[24:27], v[140:143], v[180:183], v[24:27]
	v_mfma_f32_16x16x32_bf16 v[12:15], v[132:135], v[188:191], v[12:15]
	v_mfma_f32_16x16x32_bf16 v[8:11], v[140:143], v[188:191], v[8:11]
	s_setprio 0
	s_setprio 1
	v_mfma_f32_16x16x32_bf16 v[52:55], v[144:147], v[160:163], v[52:55]
	v_mfma_f32_16x16x32_bf16 v[48:51], v[152:155], v[160:163], v[48:51]
	v_mfma_f32_16x16x32_bf16 v[36:39], v[144:147], v[168:171], v[36:39]
	v_mfma_f32_16x16x32_bf16 v[32:35], v[152:155], v[168:171], v[32:35]
	v_mfma_f32_16x16x32_bf16 v[20:23], v[144:147], v[176:179], v[20:23]
	v_mfma_f32_16x16x32_bf16 v[16:19], v[152:155], v[176:179], v[16:19]
	v_mfma_f32_16x16x32_bf16 v[4:7], v[144:147], v[184:187], v[4:7]
	v_mfma_f32_16x16x32_bf16 v[0:3], v[152:155], v[184:187], v[0:3]
	v_mfma_f32_16x16x32_bf16 v[52:55], v[148:151], v[164:167], v[52:55]
	v_mfma_f32_16x16x32_bf16 v[48:51], v[156:159], v[164:167], v[48:51]
	v_mfma_f32_16x16x32_bf16 v[36:39], v[148:151], v[172:175], v[36:39]
	v_mfma_f32_16x16x32_bf16 v[32:35], v[156:159], v[172:175], v[32:35]
	v_mfma_f32_16x16x32_bf16 v[20:23], v[148:151], v[180:183], v[20:23]
	v_mfma_f32_16x16x32_bf16 v[16:19], v[156:159], v[180:183], v[16:19]
	v_mfma_f32_16x16x32_bf16 v[4:7], v[148:151], v[188:191], v[4:7]
	v_mfma_f32_16x16x32_bf16 v[0:3], v[156:159], v[188:191], v[0:3]
	s_setprio 0
	s_barrier
	s_add_u32 s48, s48, 0x100
	s_addc_u32 s49, s49, 0
	s_add_u32 s2, s2, 0x100
	s_addc_u32 s24, s24, 0
	s_cmp_ge_i32 s60, s53
	s_mov_b32 s25, s60
	s_cbranch_scc1 .Lpeelx_10

; #define PG8_BAR __builtin_amdgcn_s_barrier()
; template <class Epi, class Sched, bool ALIGN_EPI = false, bool SP2 = false>
; __device__ __forceinline__ void gemm_phase(PG8_LAS unsigned char* lds, const Gemm g, const Sched& S, const Epi& E) {
;     ...
;         if constexpr (ALIGN_EPI) { if (wr == 0) PG8_BAR; }
;         if constexpr (!Epi::AFTER_DRAIN) { E(acc, cur, wr, wc, fr, fq); S.done(cur); }
.Lpeelx_10:
.LBB0_2286:
	s_and_b64 vcc, exec, s[44:45]
	s_cbranch_vccz .LBB0_2288
	s_barrier

; #define PG8_STAGE(bufoff, gbase, voff) do { _Pragma("unroll") for (int _i = 0; _i < 2; ++_i) \
;         __builtin_amdgcn_global_load_lds((const unsigned*)((const char*)(gbase) + (voff)[_i]), (PG8_LAS unsigned*)(lds + (bufoff) + ldsw + _i * 8192), 16, 0, 0); } while (0)
; #define PG8_LDA(dst, b, h) do { _Pragma("unroll") for (int m = 0; m < 4; ++m) _Pragma("unroll") for (int k = 0; k < 2; ++k) dst[m][k] = *(const PG8_LAS bf16x8*)(lds + PG8_SA(b, h) + aoff + m * 2048 + k * 1024); } while (0)
; #define PG8_LDB(dst, b, h) do { _Pragma("unroll") for (int n = 0; n < 2; ++n) _Pragma("unroll") for (int k = 0; k < 2; ++k) dst[n][k] = *(const PG8_LAS bf16x8*)(lds + PG8_SB(b, h) + boff + n * 2048 + k * 1024); } while (0)
; #define PG8_WAIT_V(n) asm volatile("s_waitcnt vmcnt(" #n ")" ::: "memory")
; #define PG8_WAIT_L(n) asm volatile("s_waitcnt lgkmcnt(" #n ")" ::: "memory")
; #define PG8_BAR __builtin_amdgcn_s_barrier()
; #define PG8_SCHED __builtin_amdgcn_sched_barrier(0)
; template <class Epi, class Sched, bool ALIGN_EPI = false, bool SP2 = false>
; __device__ __forceinline__ void gemm_phase(PG8_LAS unsigned char* lds, const Gemm g, const Sched& S, const Epi& E) {
;     ...
;     f32x4 acc[2][2][4][2];
; #pragma unroll
;     for (int a = 0; a < 2; ++a)
; #pragma unroll
;         for (int b = 0; b < 2; ++b)
; #pragma unroll
;             for (int m = 0; m < 4; ++m)
; #pragma unroll
;                 for (int n = 0; n < 2; ++n) acc[a][b][m][n] = (f32x4){0.f, 0.f, 0.f, 0.f};
;     ...
;         for (int t = 0; t < nt; t += 2) {
;             const bool last = (t == nt - 2);
;             const char* a1 = cA + (size_t)(t + 1) * kstep;
;             const char* a2 = last ? nA : cA + (size_t)(t + 2) * kstep; const char* b2 = last ? nB : cB + (size_t)(t + 2) * kstep;
;             const char* a3 = a2 + kstep; const char* b3 = b2 + kstep;
;             if (last && has_next) S.a_ready(nxt);
;             if constexpr (SP2) {
;             PG8_LDB(B0, 0, 0); PG8_LDB(B1, 0, 1); PG8_SCHED; PG8_LDA(At, 0, 0); PG8_STAGE(PG8_SA(1, 1), a1 + hstep, voffA);
;             PG8_WAIT_V(8); PG8_WAIT_L(0); PG8_BAR; PG8_MMA(0, 0, At, B0); PG8_MMA(0, 1, At, B1); PG8_BAR; PG8_SCHED;
;             PG8_LDA(At, 0, 1); PG8_STAGE(PG8_SB(0, 0), b2, voffB); PG8_STAGE(PG8_SB(0, 1), b2 + hstep, voffB); PG8_STAGE(PG8_SA(0, 0), a2, voffA);
.LBB0_2385:
	s_and_b64 vcc, exec, s[10:11]
	s_cbranch_vccnz .Lcoldz_11
	s_add_u32 s42, s42, 0x80
	s_addc_u32 s43, s43, 0
	s_add_u32 s24, s44, 0x100
	s_addc_u32 s25, s45, 0
	s_mov_b32 s44, 0
	ds_read_b128 v[152:155], v148
	ds_read_b128 v[156:159], v148 offset:1024
	ds_read_b128 v[160:163], v148 offset:2048
	ds_read_b128 v[164:167], v148 offset:3072
	ds_read_b128 v[168:171], v149
	ds_read_b128 v[172:175], v149 offset:1024
	ds_read_b128 v[176:179], v149 offset:2048
	ds_read_b128 v[180:183], v149 offset:3072
	s_add_i32 s58, s44, 2
	s_add_u32 s59, s42, 0x80
	s_addc_u32 s45, s43, 0
	s_cmp_eq_u32 s47, s44
	s_cselect_b32 s44, s14, s59
	s_cselect_b32 s45, s15, s45
	s_cselect_b32 s61, s41, s25
	s_cselect_b32 s60, s40, s24
	s_mov_b32 m0, s51
	v_lshl_add_u64 v[216:217], s[42:43], 0, v[136:137]
	ds_read_b128 v[184:187], v150
	ds_read_b128 v[188:191], v150 offset:1024
	ds_read_b128 v[192:195], v150 offset:2048
	ds_read_b128 v[196:199], v150 offset:3072
	ds_read_b128 v[200:203], v150 offset:4096
	ds_read_b128 v[204:207], v150 offset:5120
	ds_read_b128 v[208:211], v150 offset:6144
	ds_read_b128 v[212:215], v150 offset:7168
	global_load_lds_dwordx4 v[216:217], off
	v_lshl_add_u64 v[216:217], s[42:43], 0, v[138:139]
	s_mov_b32 m0, s52
	s_nop 0
	global_load_lds_dwordx4 v[216:217], off
	s_waitcnt vmcnt(8)
	s_waitcnt lgkmcnt(0)
	s_barrier
	s_setprio 1
	s_waitcnt lgkmcnt(0)
	v_mfma_f32_16x16x32_bf16 v[120:123], v[152:155], v[184:187], 0
	v_mfma_f32_16x16x32_bf16 v[116:119], v[160:163], v[184:187], 0
	v_mfma_f32_16x16x32_bf16 v[108:111], v[152:155], v[192:195], 0
	v_mfma_f32_16x16x32_bf16 v[100:103], v[160:163], v[192:195], 0
	v_mfma_f32_16x16x32_bf16 v[92:95], v[152:155], v[200:203], 0
	v_mfma_f32_16x16x32_bf16 v[84:87], v[160:163], v[200:203], 0
	v_mfma_f32_16x16x32_bf16 v[76:79], v[152:155], v[208:211], 0
	v_mfma_f32_16x16x32_bf16 v[68:71], v[160:163], v[208:211], 0
	v_mfma_f32_16x16x32_bf16 v[120:123], v[156:159], v[188:191], v[120:123]
	v_mfma_f32_16x16x32_bf16 v[116:119], v[164:167], v[188:191], v[116:119]
	v_mfma_f32_16x16x32_bf16 v[108:111], v[156:159], v[196:199], v[108:111]
	v_mfma_f32_16x16x32_bf16 v[100:103], v[164:167], v[196:199], v[100:103]
	v_mfma_f32_16x16x32_bf16 v[92:95], v[156:159], v[204:207], v[92:95]
	v_mfma_f32_16x16x32_bf16 v[84:87], v[164:167], v[204:207], v[84:87]
	v_mfma_f32_16x16x32_bf16 v[76:79], v[156:159], v[212:215], v[76:79]
	v_mfma_f32_16x16x32_bf16 v[68:71], v[164:167], v[212:215], v[68:71]
	s_setprio 0
	s_setprio 1
	v_mfma_f32_16x16x32_bf16 v[124:127], v[168:171], v[184:187], 0
	v_mfma_f32_16x16x32_bf16 v[112:115], v[176:179], v[184:187], 0
	v_mfma_f32_16x16x32_bf16 v[104:107], v[168:171], v[192:195], 0
	v_mfma_f32_16x16x32_bf16 v[96:99], v[176:179], v[192:195], 0
	v_mfma_f32_16x16x32_bf16 v[88:91], v[168:171], v[200:203], 0
	v_mfma_f32_16x16x32_bf16 v[80:83], v[176:179], v[200:203], 0
	v_mfma_f32_16x16x32_bf16 v[72:75], v[168:171], v[208:211], 0
	v_mfma_f32_16x16x32_bf16 v[64:67], v[176:179], v[208:211], 0
	v_mfma_f32_16x16x32_bf16 v[124:127], v[172:175], v[188:191], v[124:127]
	v_mfma_f32_16x16x32_bf16 v[112:115], v[180:183], v[188:191], v[112:115]
	v_mfma_f32_16x16x32_bf16 v[104:107], v[172:175], v[196:199], v[104:107]
	v_mfma_f32_16x16x32_bf16 v[96:99], v[180:183], v[196:199], v[96:99]
	v_mfma_f32_16x16x32_bf16 v[88:91], v[172:175], v[204:207], v[88:91]
	v_mfma_f32_16x16x32_bf16 v[80:83], v[180:183], v[204:207], v[80:83]
	v_mfma_f32_16x16x32_bf16 v[72:75], v[172:175], v[212:215], v[72:75]
	v_mfma_f32_16x16x32_bf16 v[64:67], v[180:183], v[212:215], v[64:67]
	s_setprio 0
	s_barrier
	s_add_i32 s59, s48, s3
	v_lshl_add_u64 v[216:217], s[60:61], 0, v[132:133]
	s_mov_b32 m0, s59
	ds_read_b128 v[184:187], v150 offset:16384
	ds_read_b128 v[188:191], v150 offset:17408
	ds_read_b128 v[192:195], v150 offset:18432
	ds_read_b128 v[196:199], v150 offset:19456
	ds_read_b128 v[200:203], v150 offset:20480
	ds_read_b128 v[204:207], v150 offset:21504
	ds_read_b128 v[208:211], v150 offset:22528
	ds_read_b128 v[212:215], v150 offset:23552
	global_load_lds_dwordx4 v[216:217], off
	s_add_i32 m0, s59, 0x2000
	v_lshl_add_u64 v[218:219], s[60:61], 0, v[128:129]
	s_add_u32 s60, s60, s16
	s_addc_u32 s61, s61, s17
	s_add_i32 s59, s49, s3
	global_load_lds_dwordx4 v[218:219], off
	v_lshl_add_u64 v[220:221], s[60:61], 0, v[132:133]
	s_mov_b32 m0, s59
	v_lshl_add_u64 v[222:223], s[60:61], 0, v[128:129]
	global_load_lds_dwordx4 v[220:221], off
	s_add_i32 m0, s59, 0x2000
	v_lshl_add_u64 v[224:225], s[44:45], 0, v[134:135]
	global_load_lds_dwordx4 v[222:223], off
	s_mov_b32 m0, s7
	v_lshl_add_u64 v[226:227], s[44:45], 0, v[130:131]
	global_load_lds_dwordx4 v[224:225], off
	s_mov_b32 m0, s18
	s_nop 0
	global_load_lds_dwordx4 v[226:227], off
	s_waitcnt vmcnt(8)
	s_waitcnt lgkmcnt(0)
	s_barrier
; #define PG8_STAGE(bufoff, gbase, voff) do { _Pragma("unroll") for (int _i = 0; _i < 2; ++_i) \
;         __builtin_amdgcn_global_load_lds((const unsigned*)((const char*)(gbase) + (voff)[_i]), (PG8_LAS unsigned*)(lds + (bufoff) + ldsw + _i * 8192), 16, 0, 0); } while (0)
; #define PG8_LDA(dst, b, h) do { _Pragma("unroll") for (int m = 0; m < 4; ++m) _Pragma("unroll") for (int k = 0; k < 2; ++k) dst[m][k] = *(const PG8_LAS bf16x8*)(lds + PG8_SA(b, h) + aoff + m * 2048 + k * 1024); } while (0)
; #define PG8_LDB(dst, b, h) do { _Pragma("unroll") for (int n = 0; n < 2; ++n) _Pragma("unroll") for (int k = 0; k < 2; ++k) dst[n][k] = *(const PG8_LAS bf16x8*)(lds + PG8_SB(b, h) + boff + n * 2048 + k * 1024); } while (0)
; #define PG8_MMA(ai, bj, At, Bt) do { __builtin_amdgcn_s_setprio(1); _Pragma("unroll") for (int m = 0; m < 4; ++m) _Pragma("unroll") for (int n = 0; n < 2; ++n) _Pragma("unroll") for (int k = 0; k < 2; ++k) \
;         acc[ai][bj][m][n] = __builtin_amdgcn_mfma_f32_16x16x32_bf16(Bt[n][k], At[m][k], acc[ai][bj][m][n], 0, 0, 0); __builtin_amdgcn_s_setprio(0); } while (0)
; #define PG8_WAIT_V(n) asm volatile("s_waitcnt vmcnt(" #n ")" ::: "memory")
; #define PG8_WAIT_L(n) asm volatile("s_waitcnt lgkmcnt(" #n ")" ::: "memory")
; #define PG8_BAR __builtin_amdgcn_s_barrier()
; #define PG8_SCHED __builtin_amdgcn_sched_barrier(0)
; template <class Epi, class Sched, bool ALIGN_EPI = false, bool SP2 = false>
; __device__ __forceinline__ void gemm_phase(PG8_LAS unsigned char* lds, const Gemm g, const Sched& S, const Epi& E) {
;     ...
;             PG8_WAIT_V(8); PG8_WAIT_L(0); PG8_BAR; PG8_MMA(1, 0, At, B0); PG8_MMA(1, 1, At, B1); PG8_BAR; PG8_SCHED;
;             PG8_LDB(B0, 1, 0); PG8_LDB(B1, 1, 1); PG8_SCHED; PG8_LDA(At, 1, 0); PG8_STAGE(PG8_SA(0, 1), a2 + hstep, voffA);
;             PG8_WAIT_V(8); PG8_WAIT_L(0); PG8_BAR; PG8_MMA(0, 0, At, B0); PG8_MMA(0, 1, At, B1); PG8_BAR; PG8_SCHED;
	s_setprio 1
	s_waitcnt lgkmcnt(0)
	v_mfma_f32_16x16x32_bf16 v[60:63], v[152:155], v[184:187], 0
	v_mfma_f32_16x16x32_bf16 v[52:55], v[160:163], v[184:187], 0
	v_mfma_f32_16x16x32_bf16 v[44:47], v[152:155], v[192:195], 0
	v_mfma_f32_16x16x32_bf16 v[36:39], v[160:163], v[192:195], 0
	v_mfma_f32_16x16x32_bf16 v[28:31], v[152:155], v[200:203], 0
	v_mfma_f32_16x16x32_bf16 v[20:23], v[160:163], v[200:203], 0
	v_mfma_f32_16x16x32_bf16 v[12:15], v[152:155], v[208:211], 0
	v_mfma_f32_16x16x32_bf16 v[4:7], v[160:163], v[208:211], 0
	v_mfma_f32_16x16x32_bf16 v[60:63], v[156:159], v[188:191], v[60:63]
	v_mfma_f32_16x16x32_bf16 v[52:55], v[164:167], v[188:191], v[52:55]
	v_mfma_f32_16x16x32_bf16 v[44:47], v[156:159], v[196:199], v[44:47]
	v_mfma_f32_16x16x32_bf16 v[36:39], v[164:167], v[196:199], v[36:39]
	v_mfma_f32_16x16x32_bf16 v[28:31], v[156:159], v[204:207], v[28:31]
	v_mfma_f32_16x16x32_bf16 v[20:23], v[164:167], v[204:207], v[20:23]
	v_mfma_f32_16x16x32_bf16 v[12:15], v[156:159], v[212:215], v[12:15]
	v_mfma_f32_16x16x32_bf16 v[4:7], v[164:167], v[212:215], v[4:7]
	s_setprio 0
	s_setprio 1
	v_mfma_f32_16x16x32_bf16 v[56:59], v[168:171], v[184:187], 0
	v_mfma_f32_16x16x32_bf16 v[48:51], v[176:179], v[184:187], 0
	v_mfma_f32_16x16x32_bf16 v[40:43], v[168:171], v[192:195], 0
	v_mfma_f32_16x16x32_bf16 v[32:35], v[176:179], v[192:195], 0
	v_mfma_f32_16x16x32_bf16 v[24:27], v[168:171], v[200:203], 0
	v_mfma_f32_16x16x32_bf16 v[16:19], v[176:179], v[200:203], 0
	v_mfma_f32_16x16x32_bf16 v[8:11], v[168:171], v[208:211], 0
	v_mfma_f32_16x16x32_bf16 v[0:3], v[176:179], v[208:211], 0
	v_mfma_f32_16x16x32_bf16 v[56:59], v[172:175], v[188:191], v[56:59]
	v_mfma_f32_16x16x32_bf16 v[48:51], v[180:183], v[188:191], v[48:51]
	v_mfma_f32_16x16x32_bf16 v[40:43], v[172:175], v[196:199], v[40:43]
	v_mfma_f32_16x16x32_bf16 v[32:35], v[180:183], v[196:199], v[32:35]
	v_mfma_f32_16x16x32_bf16 v[24:27], v[172:175], v[204:207], v[24:27]
	v_mfma_f32_16x16x32_bf16 v[16:19], v[180:183], v[204:207], v[16:19]
	v_mfma_f32_16x16x32_bf16 v[8:11], v[172:175], v[212:215], v[8:11]
	v_mfma_f32_16x16x32_bf16 v[0:3], v[180:183], v[212:215], v[0:3]
	s_setprio 0
	s_barrier
	s_add_i32 s59, 0, 0x18000
	v_add_u32_e32 v151, s59, v145
	s_add_i32 s60, 0, 0x1c000
	ds_read_b128 v[152:155], v151
	ds_read_b128 v[156:159], v151 offset:1024
	ds_read_b128 v[160:163], v151 offset:2048
	ds_read_b128 v[164:167], v151 offset:3072
	v_add_u32_e32 v151, s60, v145
	ds_read_b128 v[168:171], v151
	ds_read_b128 v[172:175], v151 offset:1024
	ds_read_b128 v[176:179], v151 offset:2048
	ds_read_b128 v[180:183], v151 offset:3072
	s_add_u32 s44, s44, s16
	s_addc_u32 s45, s45, s17
	s_mov_b32 m0, s19
	v_lshl_add_u64 v[228:229], s[44:45], 0, v[134:135]
	ds_read_b128 v[184:187], v150 offset:32768
	ds_read_b128 v[188:191], v150 offset:33792
	ds_read_b128 v[192:195], v150 offset:34816
	ds_read_b128 v[196:199], v150 offset:35840
	ds_read_b128 v[200:203], v150 offset:36864
	ds_read_b128 v[204:207], v150 offset:37888
	ds_read_b128 v[208:211], v150 offset:38912
	ds_read_b128 v[212:215], v150 offset:39936
	global_load_lds_dwordx4 v[228:229], off
	v_lshl_add_u64 v[228:229], s[44:45], 0, v[130:131]
	s_mov_b32 m0, s26
	s_nop 0
	global_load_lds_dwordx4 v[228:229], off
	s_waitcnt vmcnt(8)
	s_waitcnt lgkmcnt(0)
	s_barrier
	s_setprio 1
	s_waitcnt lgkmcnt(0)
	v_mfma_f32_16x16x32_bf16 v[120:123], v[152:155], v[184:187], v[120:123]
	v_mfma_f32_16x16x32_bf16 v[116:119], v[160:163], v[184:187], v[116:119]
	v_mfma_f32_16x16x32_bf16 v[108:111], v[152:155], v[192:195], v[108:111]
	v_mfma_f32_16x16x32_bf16 v[100:103], v[160:163], v[192:195], v[100:103]
	v_mfma_f32_16x16x32_bf16 v[92:95], v[152:155], v[200:203], v[92:95]
	v_mfma_f32_16x16x32_bf16 v[84:87], v[160:163], v[200:203], v[84:87]
	v_mfma_f32_16x16x32_bf16 v[76:79], v[152:155], v[208:211], v[76:79]
	v_mfma_f32_16x16x32_bf16 v[68:71], v[160:163], v[208:211], v[68:71]
	v_mfma_f32_16x16x32_bf16 v[120:123], v[156:159], v[188:191], v[120:123]
	v_mfma_f32_16x16x32_bf16 v[116:119], v[164:167], v[188:191], v[116:119]
	v_mfma_f32_16x16x32_bf16 v[108:111], v[156:159], v[196:199], v[108:111]
	v_mfma_f32_16x16x32_bf16 v[100:103], v[164:167], v[196:199], v[100:103]
	v_mfma_f32_16x16x32_bf16 v[92:95], v[156:159], v[204:207], v[92:95]
	v_mfma_f32_16x16x32_bf16 v[84:87], v[164:167], v[204:207], v[84:87]
	v_mfma_f32_16x16x32_bf16 v[76:79], v[156:159], v[212:215], v[76:79]
	v_mfma_f32_16x16x32_bf16 v[68:71], v[164:167], v[212:215], v[68:71]
	s_setprio 0
	s_setprio 1
	v_mfma_f32_16x16x32_bf16 v[124:127], v[168:171], v[184:187], v[124:127]
	v_mfma_f32_16x16x32_bf16 v[112:115], v[176:179], v[184:187], v[112:115]
	v_mfma_f32_16x16x32_bf16 v[104:107], v[168:171], v[192:195], v[104:107]
	v_mfma_f32_16x16x32_bf16 v[96:99], v[176:179], v[192:195], v[96:99]
	v_mfma_f32_16x16x32_bf16 v[88:91], v[168:171], v[200:203], v[88:91]
	v_mfma_f32_16x16x32_bf16 v[80:83], v[176:179], v[200:203], v[80:83]
	v_mfma_f32_16x16x32_bf16 v[72:75], v[168:171], v[208:211], v[72:75]
	v_mfma_f32_16x16x32_bf16 v[64:67], v[176:179], v[208:211], v[64:67]
	v_mfma_f32_16x16x32_bf16 v[124:127], v[172:175], v[188:191], v[124:127]
	v_mfma_f32_16x16x32_bf16 v[112:115], v[180:183], v[188:191], v[112:115]
	v_mfma_f32_16x16x32_bf16 v[104:107], v[172:175], v[196:199], v[104:107]
	v_mfma_f32_16x16x32_bf16 v[96:99], v[180:183], v[196:199], v[96:99]
	v_mfma_f32_16x16x32_bf16 v[88:91], v[172:175], v[204:207], v[88:91]
	v_mfma_f32_16x16x32_bf16 v[80:83], v[180:183], v[204:207], v[80:83]
	v_mfma_f32_16x16x32_bf16 v[72:75], v[172:175], v[212:215], v[72:75]
	v_mfma_f32_16x16x32_bf16 v[64:67], v[180:183], v[212:215], v[64:67]
	s_setprio 0
	s_barrier
; #define PG8_STAGE(bufoff, gbase, voff) do { _Pragma("unroll") for (int _i = 0; _i < 2; ++_i) \
;         __builtin_amdgcn_global_load_lds((const unsigned*)((const char*)(gbase) + (voff)[_i]), (PG8_LAS unsigned*)(lds + (bufoff) + ldsw + _i * 8192), 16, 0, 0); } while (0)
; #define PG8_LDA(dst, b, h) do { _Pragma("unroll") for (int m = 0; m < 4; ++m) _Pragma("unroll") for (int k = 0; k < 2; ++k) dst[m][k] = *(const PG8_LAS bf16x8*)(lds + PG8_SA(b, h) + aoff + m * 2048 + k * 1024); } while (0)
; #define PG8_MMA(ai, bj, At, Bt) do { __builtin_amdgcn_s_setprio(1); _Pragma("unroll") for (int m = 0; m < 4; ++m) _Pragma("unroll") for (int n = 0; n < 2; ++n) _Pragma("unroll") for (int k = 0; k < 2; ++k) \
;         acc[ai][bj][m][n] = __builtin_amdgcn_mfma_f32_16x16x32_bf16(Bt[n][k], At[m][k], acc[ai][bj][m][n], 0, 0, 0); __builtin_amdgcn_s_setprio(0); } while (0)
; #define PG8_WAIT_V(n) asm volatile("s_waitcnt vmcnt(" #n ")" ::: "memory")
; #define PG8_WAIT_L(n) asm volatile("s_waitcnt lgkmcnt(" #n ")" ::: "memory")
; #define PG8_BAR __builtin_amdgcn_s_barrier()
; #define PG8_SCHED __builtin_amdgcn_sched_barrier(0)
; template <class Epi, class Sched, bool ALIGN_EPI = false, bool SP2 = false>
; __device__ __forceinline__ void gemm_phase(PG8_LAS unsigned char* lds, const Gemm g, const Sched& S, const Epi& E) {
;     ...
;         for (int t = 0; t < nt; t += 2) {
;             const bool last = (t == nt - 2);
;             const char* a1 = cA + (size_t)(t + 1) * kstep;
;             const char* a2 = last ? nA : cA + (size_t)(t + 2) * kstep; const char* b2 = last ? nB : cB + (size_t)(t + 2) * kstep;
;     ...
;             PG8_LDA(At, 1, 1); PG8_STAGE(PG8_SB(1, 0), b3, voffB); PG8_STAGE(PG8_SB(1, 1), b3 + hstep, voffB); PG8_STAGE(PG8_SA(1, 0), a3, voffA);
;             PG8_WAIT_V(8); PG8_WAIT_L(0); PG8_BAR; PG8_MMA(1, 0, At, B0); PG8_MMA(1, 1, At, B1); PG8_BAR; PG8_SCHED;
	s_add_i32 s44, s59, s3
	v_lshl_add_u64 v[216:217], v[216:217], 0, s[36:37]
	s_mov_b32 m0, s44
	ds_read_b128 v[184:187], v150 offset:49152
	ds_read_b128 v[188:191], v150 offset:50176
	ds_read_b128 v[192:195], v150 offset:51200
	ds_read_b128 v[196:199], v150 offset:52224
	ds_read_b128 v[200:203], v150 offset:53248
	ds_read_b128 v[204:207], v150 offset:54272
	ds_read_b128 v[208:211], v150 offset:55296
	ds_read_b128 v[212:215], v150 offset:56320
	global_load_lds_dwordx4 v[216:217], off
	v_lshl_add_u64 v[216:217], v[218:219], 0, s[36:37]
	s_add_i32 m0, s44, 0x2000
	s_add_i32 s44, s60, s3
	global_load_lds_dwordx4 v[216:217], off
	v_lshl_add_u64 v[216:217], v[220:221], 0, s[36:37]
	s_mov_b32 m0, s44
	s_nop 0
	global_load_lds_dwordx4 v[216:217], off
	v_lshl_add_u64 v[216:217], v[222:223], 0, s[36:37]
	s_add_i32 m0, s44, 0x2000
	s_nop 0
	global_load_lds_dwordx4 v[216:217], off
	v_lshl_add_u64 v[216:217], v[224:225], 0, s[36:37]
	s_mov_b32 m0, s27
	s_nop 0
	global_load_lds_dwordx4 v[216:217], off
	v_lshl_add_u64 v[216:217], v[226:227], 0, s[36:37]
	s_mov_b32 m0, s33
	s_nop 0
	global_load_lds_dwordx4 v[216:217], off
	s_waitcnt vmcnt(8)
	s_waitcnt lgkmcnt(0)
	s_barrier
	s_setprio 1
	s_waitcnt lgkmcnt(0)
	v_mfma_f32_16x16x32_bf16 v[60:63], v[152:155], v[184:187], v[60:63]
	v_mfma_f32_16x16x32_bf16 v[52:55], v[160:163], v[184:187], v[52:55]
	v_mfma_f32_16x16x32_bf16 v[44:47], v[152:155], v[192:195], v[44:47]
	v_mfma_f32_16x16x32_bf16 v[36:39], v[160:163], v[192:195], v[36:39]
	v_mfma_f32_16x16x32_bf16 v[28:31], v[152:155], v[200:203], v[28:31]
	v_mfma_f32_16x16x32_bf16 v[20:23], v[160:163], v[200:203], v[20:23]
	v_mfma_f32_16x16x32_bf16 v[12:15], v[152:155], v[208:211], v[12:15]
	v_mfma_f32_16x16x32_bf16 v[4:7], v[160:163], v[208:211], v[4:7]
	v_mfma_f32_16x16x32_bf16 v[60:63], v[156:159], v[188:191], v[60:63]
	v_mfma_f32_16x16x32_bf16 v[52:55], v[164:167], v[188:191], v[52:55]
	v_mfma_f32_16x16x32_bf16 v[44:47], v[156:159], v[196:199], v[44:47]
	v_mfma_f32_16x16x32_bf16 v[36:39], v[164:167], v[196:199], v[36:39]
	v_mfma_f32_16x16x32_bf16 v[28:31], v[156:159], v[204:207], v[28:31]
	v_mfma_f32_16x16x32_bf16 v[20:23], v[164:167], v[204:207], v[20:23]
	v_mfma_f32_16x16x32_bf16 v[12:15], v[156:159], v[212:215], v[12:15]
	v_mfma_f32_16x16x32_bf16 v[4:7], v[164:167], v[212:215], v[4:7]
	s_setprio 0
	s_setprio 1
	v_mfma_f32_16x16x32_bf16 v[56:59], v[168:171], v[184:187], v[56:59]
	v_mfma_f32_16x16x32_bf16 v[48:51], v[176:179], v[184:187], v[48:51]
	v_mfma_f32_16x16x32_bf16 v[40:43], v[168:171], v[192:195], v[40:43]
	v_mfma_f32_16x16x32_bf16 v[32:35], v[176:179], v[192:195], v[32:35]
	v_mfma_f32_16x16x32_bf16 v[24:27], v[168:171], v[200:203], v[24:27]
	v_mfma_f32_16x16x32_bf16 v[16:19], v[176:179], v[200:203], v[16:19]
	v_mfma_f32_16x16x32_bf16 v[8:11], v[168:171], v[208:211], v[8:11]
	v_mfma_f32_16x16x32_bf16 v[0:3], v[176:179], v[208:211], v[0:3]
	v_mfma_f32_16x16x32_bf16 v[56:59], v[172:175], v[188:191], v[56:59]
	v_mfma_f32_16x16x32_bf16 v[48:51], v[180:183], v[188:191], v[48:51]
	v_mfma_f32_16x16x32_bf16 v[40:43], v[172:175], v[196:199], v[40:43]
	v_mfma_f32_16x16x32_bf16 v[32:35], v[180:183], v[196:199], v[32:35]
	v_mfma_f32_16x16x32_bf16 v[24:27], v[172:175], v[204:207], v[24:27]
	v_mfma_f32_16x16x32_bf16 v[16:19], v[180:183], v[204:207], v[16:19]
	v_mfma_f32_16x16x32_bf16 v[8:11], v[172:175], v[212:215], v[8:11]
	v_mfma_f32_16x16x32_bf16 v[0:3], v[180:183], v[212:215], v[0:3]
	s_setprio 0
	s_barrier
	s_add_u32 s42, s42, 0x100
	s_addc_u32 s43, s43, 0
	s_add_u32 s24, s24, 0x100
	s_addc_u32 s25, s25, 0
	s_cmp_ge_i32 s58, s46
	s_mov_b32 s44, s58
	s_cbranch_scc1 .Lpeelx_11

; #define PG8_BAR __builtin_amdgcn_s_barrier()
; template <class Epi, class Sched, bool ALIGN_EPI = false, bool SP2 = false>
; __device__ __forceinline__ void gemm_phase(PG8_LAS unsigned char* lds, const Gemm g, const Sched& S, const Epi& E) {
;     ...
;         if constexpr (ALIGN_EPI) { if (wr == 0) PG8_BAR; }
;         if constexpr (!Epi::AFTER_DRAIN) { E(acc, cur, wr, wc, fr, fq); S.done(cur); }
.Lpeelx_11:
.LBB0_2388:
	s_and_b64 vcc, exec, s[38:39]
	s_cbranch_vccz .LBB0_2390
	s_barrier

; #define PG8_STAGE(bufoff, gbase, voff) do { _Pragma("unroll") for (int _i = 0; _i < 2; ++_i) \
;         __builtin_amdgcn_global_load_lds((const unsigned*)((const char*)(gbase) + (voff)[_i]), (PG8_LAS unsigned*)(lds + (bufoff) + ldsw + _i * 8192), 16, 0, 0); } while (0)
; #define PG8_LDA(dst, b, h) do { _Pragma("unroll") for (int m = 0; m < 4; ++m) _Pragma("unroll") for (int k = 0; k < 2; ++k) dst[m][k] = *(const PG8_LAS bf16x8*)(lds + PG8_SA(b, h) + aoff + m * 2048 + k * 1024); } while (0)
; #define PG8_LDB(dst, b, h) do { _Pragma("unroll") for (int n = 0; n < 2; ++n) _Pragma("unroll") for (int k = 0; k < 2; ++k) dst[n][k] = *(const PG8_LAS bf16x8*)(lds + PG8_SB(b, h) + boff + n * 2048 + k * 1024); } while (0)
; #define PG8_WAIT_V(n) asm volatile("s_waitcnt vmcnt(" #n ")" ::: "memory")
; #define PG8_WAIT_L(n) asm volatile("s_waitcnt lgkmcnt(" #n ")" ::: "memory")
; #define PG8_BAR __builtin_amdgcn_s_barrier()
; #define PG8_SCHED __builtin_amdgcn_sched_barrier(0)
; template <class Epi, class Sched, bool ALIGN_EPI = false, bool SP2 = false>
; __device__ __forceinline__ void gemm_phase(PG8_LAS unsigned char* lds, const Gemm g, const Sched& S, const Epi& E) {
;     ...
;     f32x4 acc[2][2][4][2];
; #pragma unroll
;     for (int a = 0; a < 2; ++a)
; #pragma unroll
;         for (int b = 0; b < 2; ++b)
; #pragma unroll
;             for (int m = 0; m < 4; ++m)
; #pragma unroll
;                 for (int n = 0; n < 2; ++n) acc[a][b][m][n] = (f32x4){0.f, 0.f, 0.f, 0.f};
;     ...
;         for (int t = 0; t < nt; t += 2) {
;             const bool last = (t == nt - 2);
;             const char* a1 = cA + (size_t)(t + 1) * kstep;
;             const char* a2 = last ? nA : cA + (size_t)(t + 2) * kstep; const char* b2 = last ? nB : cB + (size_t)(t + 2) * kstep;
;             const char* a3 = a2 + kstep; const char* b3 = b2 + kstep;
;             if (last && has_next) S.a_ready(nxt);
;             if constexpr (SP2) {
;             PG8_LDB(B0, 0, 0); PG8_LDB(B1, 0, 1); PG8_SCHED; PG8_LDA(At, 0, 0); PG8_STAGE(PG8_SA(1, 1), a1 + hstep, voffA);
;             PG8_WAIT_V(8); PG8_WAIT_L(0); PG8_BAR; PG8_MMA(0, 0, At, B0); PG8_MMA(0, 1, At, B1); PG8_BAR; PG8_SCHED;
;             PG8_LDA(At, 0, 1); PG8_STAGE(PG8_SB(0, 0), b2, voffB); PG8_STAGE(PG8_SB(0, 1), b2 + hstep, voffB); PG8_STAGE(PG8_SA(0, 0), a2, voffA);
.LBB0_2468:
	s_and_b64 vcc, exec, s[12:13]
	s_cbranch_vccnz .Lcoldz_12
	s_add_u32 s48, s48, 0x80
	s_addc_u32 s49, s49, 0
	s_add_u32 s2, s50, 0x100
	s_addc_u32 s24, s51, 0
	s_mov_b32 s25, 0
	ds_read_b128 v[142:145], v246
	ds_read_b128 v[146:149], v246 offset:1024
	ds_read_b128 v[150:153], v246 offset:2048
	ds_read_b128 v[154:157], v246 offset:3072
	ds_read_b128 v[158:161], v247
	ds_read_b128 v[162:165], v247 offset:1024
	ds_read_b128 v[166:169], v247 offset:2048
	ds_read_b128 v[170:173], v247 offset:3072
	s_add_i32 s62, s25, 2
	s_add_u32 s50, s48, 0x80
	s_addc_u32 s51, s49, 0
	s_cmp_eq_u32 s56, s25
	s_cselect_b32 s51, s17, s51
	s_cselect_b32 s50, s16, s50
	s_cselect_b32 s65, s47, s24
	s_cselect_b32 s64, s46, s2
	v_lshl_add_u64 v[206:207], s[48:49], 0, v[136:137]
	s_add_i32 m0, s19, 0xc000
	ds_read_b128 v[174:177], v248
	ds_read_b128 v[178:181], v248 offset:1024
	ds_read_b128 v[182:185], v248 offset:2048
	ds_read_b128 v[186:189], v248 offset:3072
	ds_read_b128 v[190:193], v248 offset:4096
	ds_read_b128 v[194:197], v248 offset:5120
	ds_read_b128 v[198:201], v248 offset:6144
	ds_read_b128 v[202:205], v248 offset:7168
	global_load_lds_dwordx4 v[206:207], off
	v_lshl_add_u64 v[206:207], s[48:49], 0, v[138:139]
	s_add_i32 m0, s19, 0xe000
	s_nop 0
	global_load_lds_dwordx4 v[206:207], off
	s_waitcnt vmcnt(8)
	s_waitcnt lgkmcnt(0)
	s_barrier
	s_setprio 1
	s_waitcnt lgkmcnt(0)
	v_mfma_f32_16x16x32_bf16 v[124:127], v[142:145], v[174:177], 0
	v_mfma_f32_16x16x32_bf16 v[120:123], v[150:153], v[174:177], 0
	v_mfma_f32_16x16x32_bf16 v[116:119], v[142:145], v[182:185], 0
	v_mfma_f32_16x16x32_bf16 v[112:115], v[150:153], v[182:185], 0
	v_mfma_f32_16x16x32_bf16 v[104:107], v[142:145], v[190:193], 0
	v_mfma_f32_16x16x32_bf16 v[96:99], v[150:153], v[190:193], 0
	v_mfma_f32_16x16x32_bf16 v[88:91], v[142:145], v[198:201], 0
	v_mfma_f32_16x16x32_bf16 v[80:83], v[150:153], v[198:201], 0
	v_mfma_f32_16x16x32_bf16 v[124:127], v[146:149], v[178:181], v[124:127]
	v_mfma_f32_16x16x32_bf16 v[120:123], v[154:157], v[178:181], v[120:123]
	v_mfma_f32_16x16x32_bf16 v[116:119], v[146:149], v[186:189], v[116:119]
	v_mfma_f32_16x16x32_bf16 v[112:115], v[154:157], v[186:189], v[112:115]
	v_mfma_f32_16x16x32_bf16 v[104:107], v[146:149], v[194:197], v[104:107]
	v_mfma_f32_16x16x32_bf16 v[96:99], v[154:157], v[194:197], v[96:99]
	v_mfma_f32_16x16x32_bf16 v[88:91], v[146:149], v[202:205], v[88:91]
	v_mfma_f32_16x16x32_bf16 v[80:83], v[154:157], v[202:205], v[80:83]
	s_setprio 0
	s_setprio 1
	v_mfma_f32_16x16x32_bf16 v[108:111], v[158:161], v[174:177], 0
	v_mfma_f32_16x16x32_bf16 v[100:103], v[166:169], v[174:177], 0
	v_mfma_f32_16x16x32_bf16 v[92:95], v[158:161], v[182:185], 0
	v_mfma_f32_16x16x32_bf16 v[84:87], v[166:169], v[182:185], 0
	v_mfma_f32_16x16x32_bf16 v[76:79], v[158:161], v[190:193], 0
	v_mfma_f32_16x16x32_bf16 v[72:75], v[166:169], v[190:193], 0
	v_mfma_f32_16x16x32_bf16 v[68:71], v[158:161], v[198:201], 0
	v_mfma_f32_16x16x32_bf16 v[64:67], v[166:169], v[198:201], 0
	v_mfma_f32_16x16x32_bf16 v[108:111], v[162:165], v[178:181], v[108:111]
	v_mfma_f32_16x16x32_bf16 v[100:103], v[170:173], v[178:181], v[100:103]
	v_mfma_f32_16x16x32_bf16 v[92:95], v[162:165], v[186:189], v[92:95]
	v_mfma_f32_16x16x32_bf16 v[84:87], v[170:173], v[186:189], v[84:87]
	v_mfma_f32_16x16x32_bf16 v[76:79], v[162:165], v[194:197], v[76:79]
	v_mfma_f32_16x16x32_bf16 v[72:75], v[170:173], v[194:197], v[72:75]
	v_mfma_f32_16x16x32_bf16 v[68:71], v[162:165], v[202:205], v[68:71]
	v_mfma_f32_16x16x32_bf16 v[64:67], v[170:173], v[202:205], v[64:67]
	s_setprio 0
	s_barrier
	s_add_i32 s25, s57, s18
	v_lshl_add_u64 v[206:207], s[64:65], 0, v[130:131]
	s_mov_b32 m0, s25
	ds_read_b128 v[174:177], v248 offset:16384
	ds_read_b128 v[178:181], v248 offset:17408
	ds_read_b128 v[182:185], v248 offset:18432
	ds_read_b128 v[186:189], v248 offset:19456
	ds_read_b128 v[190:193], v248 offset:20480
	ds_read_b128 v[194:197], v248 offset:21504
	ds_read_b128 v[198:201], v248 offset:22528
	ds_read_b128 v[202:205], v248 offset:23552
	global_load_lds_dwordx4 v[206:207], off
	s_add_i32 m0, s25, 0x2000
	v_lshl_add_u64 v[208:209], s[64:65], 0, v[134:135]
	s_add_u32 s64, s64, s34
	s_addc_u32 s65, s65, s35
	s_add_i32 s25, s58, s18
	global_load_lds_dwordx4 v[208:209], off
	v_lshl_add_u64 v[210:211], s[64:65], 0, v[130:131]
	s_mov_b32 m0, s25
	v_lshl_add_u64 v[212:213], s[64:65], 0, v[134:135]
	global_load_lds_dwordx4 v[210:211], off
	s_add_i32 m0, s25, 0x2000
	v_lshl_add_u64 v[214:215], s[50:51], 0, v[128:129]
	global_load_lds_dwordx4 v[212:213], off
	s_mov_b32 m0, s19
	v_lshl_add_u64 v[216:217], s[50:51], 0, v[132:133]
	global_load_lds_dwordx4 v[214:215], off
	s_mov_b32 m0, s26
	s_nop 0
	global_load_lds_dwordx4 v[216:217], off
	s_waitcnt vmcnt(8)
	s_waitcnt lgkmcnt(0)
	s_barrier
; #define PG8_STAGE(bufoff, gbase, voff) do { _Pragma("unroll") for (int _i = 0; _i < 2; ++_i) \
;         __builtin_amdgcn_global_load_lds((const unsigned*)((const char*)(gbase) + (voff)[_i]), (PG8_LAS unsigned*)(lds + (bufoff) + ldsw + _i * 8192), 16, 0, 0); } while (0)
; #define PG8_LDA(dst, b, h) do { _Pragma("unroll") for (int m = 0; m < 4; ++m) _Pragma("unroll") for (int k = 0; k < 2; ++k) dst[m][k] = *(const PG8_LAS bf16x8*)(lds + PG8_SA(b, h) + aoff + m * 2048 + k * 1024); } while (0)
; #define PG8_LDB(dst, b, h) do { _Pragma("unroll") for (int n = 0; n < 2; ++n) _Pragma("unroll") for (int k = 0; k < 2; ++k) dst[n][k] = *(const PG8_LAS bf16x8*)(lds + PG8_SB(b, h) + boff + n * 2048 + k * 1024); } while (0)
; #define PG8_MMA(ai, bj, At, Bt) do { __builtin_amdgcn_s_setprio(1); _Pragma("unroll") for (int m = 0; m < 4; ++m) _Pragma("unroll") for (int n = 0; n < 2; ++n) _Pragma("unroll") for (int k = 0; k < 2; ++k) \
;         acc[ai][bj][m][n] = __builtin_amdgcn_mfma_f32_16x16x32_bf16(Bt[n][k], At[m][k], acc[ai][bj][m][n], 0, 0, 0); __builtin_amdgcn_s_setprio(0); } while (0)
; #define PG8_WAIT_V(n) asm volatile("s_waitcnt vmcnt(" #n ")" ::: "memory")
; #define PG8_WAIT_L(n) asm volatile("s_waitcnt lgkmcnt(" #n ")" ::: "memory")
; #define PG8_BAR __builtin_amdgcn_s_barrier()
; #define PG8_SCHED __builtin_amdgcn_sched_barrier(0)
; template <class Epi, class Sched, bool ALIGN_EPI = false, bool SP2 = false>
; __device__ __forceinline__ void gemm_phase(PG8_LAS unsigned char* lds, const Gemm g, const Sched& S, const Epi& E) {
;     ...
;             PG8_WAIT_V(8); PG8_WAIT_L(0); PG8_BAR; PG8_MMA(1, 0, At, B0); PG8_MMA(1, 1, At, B1); PG8_BAR; PG8_SCHED;
;             PG8_LDB(B0, 1, 0); PG8_LDB(B1, 1, 1); PG8_SCHED; PG8_LDA(At, 1, 0); PG8_STAGE(PG8_SA(0, 1), a2 + hstep, voffA);
;             PG8_WAIT_V(8); PG8_WAIT_L(0); PG8_BAR; PG8_MMA(0, 0, At, B0); PG8_MMA(0, 1, At, B1); PG8_BAR; PG8_SCHED;
	s_setprio 1
	s_waitcnt lgkmcnt(0)
	v_mfma_f32_16x16x32_bf16 v[60:63], v[142:145], v[174:177], 0
	v_mfma_f32_16x16x32_bf16 v[56:59], v[150:153], v[174:177], 0
	v_mfma_f32_16x16x32_bf16 v[52:55], v[142:145], v[182:185], 0
	v_mfma_f32_16x16x32_bf16 v[48:51], v[150:153], v[182:185], 0
	v_mfma_f32_16x16x32_bf16 v[40:43], v[142:145], v[190:193], 0
	v_mfma_f32_16x16x32_bf16 v[32:35], v[150:153], v[190:193], 0
	v_mfma_f32_16x16x32_bf16 v[24:27], v[142:145], v[198:201], 0
	v_mfma_f32_16x16x32_bf16 v[16:19], v[150:153], v[198:201], 0
	v_mfma_f32_16x16x32_bf16 v[60:63], v[146:149], v[178:181], v[60:63]
	v_mfma_f32_16x16x32_bf16 v[56:59], v[154:157], v[178:181], v[56:59]
	v_mfma_f32_16x16x32_bf16 v[52:55], v[146:149], v[186:189], v[52:55]
	v_mfma_f32_16x16x32_bf16 v[48:51], v[154:157], v[186:189], v[48:51]
	v_mfma_f32_16x16x32_bf16 v[40:43], v[146:149], v[194:197], v[40:43]
	v_mfma_f32_16x16x32_bf16 v[32:35], v[154:157], v[194:197], v[32:35]
	v_mfma_f32_16x16x32_bf16 v[24:27], v[146:149], v[202:205], v[24:27]
	v_mfma_f32_16x16x32_bf16 v[16:19], v[154:157], v[202:205], v[16:19]
	s_setprio 0
	s_setprio 1
	v_mfma_f32_16x16x32_bf16 v[44:47], v[158:161], v[174:177], 0
	v_mfma_f32_16x16x32_bf16 v[36:39], v[166:169], v[174:177], 0
	v_mfma_f32_16x16x32_bf16 v[28:31], v[158:161], v[182:185], 0
	v_mfma_f32_16x16x32_bf16 v[20:23], v[166:169], v[182:185], 0
	v_mfma_f32_16x16x32_bf16 v[12:15], v[158:161], v[190:193], 0
	v_mfma_f32_16x16x32_bf16 v[8:11], v[166:169], v[190:193], 0
	v_mfma_f32_16x16x32_bf16 v[4:7], v[158:161], v[198:201], 0
	v_mfma_f32_16x16x32_bf16 v[0:3], v[166:169], v[198:201], 0
	v_mfma_f32_16x16x32_bf16 v[44:47], v[162:165], v[178:181], v[44:47]
	v_mfma_f32_16x16x32_bf16 v[36:39], v[170:173], v[178:181], v[36:39]
	v_mfma_f32_16x16x32_bf16 v[28:31], v[162:165], v[186:189], v[28:31]
	v_mfma_f32_16x16x32_bf16 v[20:23], v[170:173], v[186:189], v[20:23]
	v_mfma_f32_16x16x32_bf16 v[12:15], v[162:165], v[194:197], v[12:15]
	v_mfma_f32_16x16x32_bf16 v[8:11], v[170:173], v[194:197], v[8:11]
	v_mfma_f32_16x16x32_bf16 v[4:7], v[162:165], v[202:205], v[4:7]
	v_mfma_f32_16x16x32_bf16 v[0:3], v[170:173], v[202:205], v[0:3]
	s_setprio 0
	s_barrier
	s_add_i32 s25, 0, 0x18000
	s_add_i32 s63, 0, 0x1c000
	v_add_u32_e32 v154, s25, v244
	v_add_u32_e32 v170, s63, v244
	ds_read_b128 v[142:145], v154
	ds_read_b128 v[146:149], v154 offset:1024
	ds_read_b128 v[150:153], v154 offset:2048
	ds_read_b128 v[154:157], v154 offset:3072
	ds_read_b128 v[158:161], v170
	ds_read_b128 v[162:165], v170 offset:1024
	ds_read_b128 v[166:169], v170 offset:2048
	ds_read_b128 v[170:173], v170 offset:3072
	s_add_u32 s50, s50, s34
	s_addc_u32 s51, s51, s35
	s_mov_b32 m0, s27
	v_lshl_add_u64 v[218:219], s[50:51], 0, v[128:129]
	ds_read_b128 v[174:177], v248 offset:32768
	ds_read_b128 v[178:181], v248 offset:33792
	ds_read_b128 v[182:185], v248 offset:34816
	ds_read_b128 v[186:189], v248 offset:35840
	ds_read_b128 v[190:193], v248 offset:36864
	ds_read_b128 v[194:197], v248 offset:37888
	ds_read_b128 v[198:201], v248 offset:38912
	ds_read_b128 v[202:205], v248 offset:39936
	global_load_lds_dwordx4 v[218:219], off
	v_lshl_add_u64 v[218:219], s[50:51], 0, v[132:133]
	s_mov_b32 m0, s33
	s_nop 0
	global_load_lds_dwordx4 v[218:219], off
	s_waitcnt vmcnt(8)
	s_waitcnt lgkmcnt(0)
	s_barrier
	s_setprio 1
	s_waitcnt lgkmcnt(0)
	v_mfma_f32_16x16x32_bf16 v[124:127], v[142:145], v[174:177], v[124:127]
	v_mfma_f32_16x16x32_bf16 v[120:123], v[150:153], v[174:177], v[120:123]
	v_mfma_f32_16x16x32_bf16 v[116:119], v[142:145], v[182:185], v[116:119]
	v_mfma_f32_16x16x32_bf16 v[112:115], v[150:153], v[182:185], v[112:115]
	v_mfma_f32_16x16x32_bf16 v[104:107], v[142:145], v[190:193], v[104:107]
	v_mfma_f32_16x16x32_bf16 v[96:99], v[150:153], v[190:193], v[96:99]
	v_mfma_f32_16x16x32_bf16 v[88:91], v[142:145], v[198:201], v[88:91]
	v_mfma_f32_16x16x32_bf16 v[80:83], v[150:153], v[198:201], v[80:83]
	v_mfma_f32_16x16x32_bf16 v[124:127], v[146:149], v[178:181], v[124:127]
	v_mfma_f32_16x16x32_bf16 v[120:123], v[154:157], v[178:181], v[120:123]
	v_mfma_f32_16x16x32_bf16 v[116:119], v[146:149], v[186:189], v[116:119]
	v_mfma_f32_16x16x32_bf16 v[112:115], v[154:157], v[186:189], v[112:115]
	v_mfma_f32_16x16x32_bf16 v[104:107], v[146:149], v[194:197], v[104:107]
	v_mfma_f32_16x16x32_bf16 v[96:99], v[154:157], v[194:197], v[96:99]
	v_mfma_f32_16x16x32_bf16 v[88:91], v[146:149], v[202:205], v[88:91]
	v_mfma_f32_16x16x32_bf16 v[80:83], v[154:157], v[202:205], v[80:83]
	s_setprio 0
	s_setprio 1
	v_mfma_f32_16x16x32_bf16 v[108:111], v[158:161], v[174:177], v[108:111]
	v_mfma_f32_16x16x32_bf16 v[100:103], v[166:169], v[174:177], v[100:103]
	v_mfma_f32_16x16x32_bf16 v[92:95], v[158:161], v[182:185], v[92:95]
	v_mfma_f32_16x16x32_bf16 v[84:87], v[166:169], v[182:185], v[84:87]
	v_mfma_f32_16x16x32_bf16 v[76:79], v[158:161], v[190:193], v[76:79]
	v_mfma_f32_16x16x32_bf16 v[72:75], v[166:169], v[190:193], v[72:75]
	v_mfma_f32_16x16x32_bf16 v[68:71], v[158:161], v[198:201], v[68:71]
	v_mfma_f32_16x16x32_bf16 v[64:67], v[166:169], v[198:201], v[64:67]
	v_mfma_f32_16x16x32_bf16 v[108:111], v[162:165], v[178:181], v[108:111]
	v_mfma_f32_16x16x32_bf16 v[100:103], v[170:173], v[178:181], v[100:103]
	v_mfma_f32_16x16x32_bf16 v[92:95], v[162:165], v[186:189], v[92:95]
	v_mfma_f32_16x16x32_bf16 v[84:87], v[170:173], v[186:189], v[84:87]
	v_mfma_f32_16x16x32_bf16 v[76:79], v[162:165], v[194:197], v[76:79]
	v_mfma_f32_16x16x32_bf16 v[72:75], v[170:173], v[194:197], v[72:75]
	v_mfma_f32_16x16x32_bf16 v[68:71], v[162:165], v[202:205], v[68:71]
	v_mfma_f32_16x16x32_bf16 v[64:67], v[170:173], v[202:205], v[64:67]
	s_setprio 0
	s_barrier
; #define PG8_STAGE(bufoff, gbase, voff) do { _Pragma("unroll") for (int _i = 0; _i < 2; ++_i) \
;         __builtin_amdgcn_global_load_lds((const unsigned*)((const char*)(gbase) + (voff)[_i]), (PG8_LAS unsigned*)(lds + (bufoff) + ldsw + _i * 8192), 16, 0, 0); } while (0)
; #define PG8_LDA(dst, b, h) do { _Pragma("unroll") for (int m = 0; m < 4; ++m) _Pragma("unroll") for (int k = 0; k < 2; ++k) dst[m][k] = *(const PG8_LAS bf16x8*)(lds + PG8_SA(b, h) + aoff + m * 2048 + k * 1024); } while (0)
; #define PG8_MMA(ai, bj, At, Bt) do { __builtin_amdgcn_s_setprio(1); _Pragma("unroll") for (int m = 0; m < 4; ++m) _Pragma("unroll") for (int n = 0; n < 2; ++n) _Pragma("unroll") for (int k = 0; k < 2; ++k) \
;         acc[ai][bj][m][n] = __builtin_amdgcn_mfma_f32_16x16x32_bf16(Bt[n][k], At[m][k], acc[ai][bj][m][n], 0, 0, 0); __builtin_amdgcn_s_setprio(0); } while (0)
; #define PG8_WAIT_V(n) asm volatile("s_waitcnt vmcnt(" #n ")" ::: "memory")
; #define PG8_WAIT_L(n) asm volatile("s_waitcnt lgkmcnt(" #n ")" ::: "memory")
; #define PG8_BAR __builtin_amdgcn_s_barrier()
; #define PG8_SCHED __builtin_amdgcn_sched_barrier(0)
; template <class Epi, class Sched, bool ALIGN_EPI = false, bool SP2 = false>
; __device__ __forceinline__ void gemm_phase(PG8_LAS unsigned char* lds, const Gemm g, const Sched& S, const Epi& E) {
;     ...
;         for (int t = 0; t < nt; t += 2) {
;             const bool last = (t == nt - 2);
;             const char* a1 = cA + (size_t)(t + 1) * kstep;
;             const char* a2 = last ? nA : cA + (size_t)(t + 2) * kstep; const char* b2 = last ? nB : cB + (size_t)(t + 2) * kstep;
;     ...
;             PG8_LDA(At, 1, 1); PG8_STAGE(PG8_SB(1, 0), b3, voffB); PG8_STAGE(PG8_SB(1, 1), b3 + hstep, voffB); PG8_STAGE(PG8_SA(1, 0), a3, voffA);
;             PG8_WAIT_V(8); PG8_WAIT_L(0); PG8_BAR; PG8_MMA(1, 0, At, B0); PG8_MMA(1, 1, At, B1); PG8_BAR; PG8_SCHED;
	s_add_i32 s25, s25, s18
	v_lshl_add_u64 v[206:207], v[206:207], 0, s[42:43]
	s_mov_b32 m0, s25
	ds_read_b128 v[174:177], v248 offset:49152
	ds_read_b128 v[178:181], v248 offset:50176
	ds_read_b128 v[182:185], v248 offset:51200
	ds_read_b128 v[186:189], v248 offset:52224
	ds_read_b128 v[190:193], v248 offset:53248
	ds_read_b128 v[194:197], v248 offset:54272
	ds_read_b128 v[198:201], v248 offset:55296
	ds_read_b128 v[202:205], v248 offset:56320
	global_load_lds_dwordx4 v[206:207], off
	v_lshl_add_u64 v[206:207], v[208:209], 0, s[42:43]
	s_add_i32 m0, s25, 0x2000
	s_add_i32 s25, s63, s18
	global_load_lds_dwordx4 v[206:207], off
	v_lshl_add_u64 v[206:207], v[210:211], 0, s[42:43]
	s_mov_b32 m0, s25
	s_nop 0
	global_load_lds_dwordx4 v[206:207], off
	v_lshl_add_u64 v[206:207], v[212:213], 0, s[42:43]
	s_add_i32 m0, s25, 0x2000
	s_nop 0
	global_load_lds_dwordx4 v[206:207], off
	v_lshl_add_u64 v[206:207], v[214:215], 0, s[42:43]
	s_mov_b32 m0, s52
	s_nop 0
	global_load_lds_dwordx4 v[206:207], off
	v_lshl_add_u64 v[206:207], v[216:217], 0, s[42:43]
	s_mov_b32 m0, s53
	s_nop 0
	global_load_lds_dwordx4 v[206:207], off
	s_waitcnt vmcnt(8)
	s_waitcnt lgkmcnt(0)
	s_barrier
	s_setprio 1
	s_waitcnt lgkmcnt(0)
	v_mfma_f32_16x16x32_bf16 v[60:63], v[142:145], v[174:177], v[60:63]
	v_mfma_f32_16x16x32_bf16 v[56:59], v[150:153], v[174:177], v[56:59]
	v_mfma_f32_16x16x32_bf16 v[52:55], v[142:145], v[182:185], v[52:55]
	v_mfma_f32_16x16x32_bf16 v[48:51], v[150:153], v[182:185], v[48:51]
	v_mfma_f32_16x16x32_bf16 v[40:43], v[142:145], v[190:193], v[40:43]
	v_mfma_f32_16x16x32_bf16 v[32:35], v[150:153], v[190:193], v[32:35]
	v_mfma_f32_16x16x32_bf16 v[24:27], v[142:145], v[198:201], v[24:27]
	v_mfma_f32_16x16x32_bf16 v[16:19], v[150:153], v[198:201], v[16:19]
	v_mfma_f32_16x16x32_bf16 v[60:63], v[146:149], v[178:181], v[60:63]
	v_mfma_f32_16x16x32_bf16 v[56:59], v[154:157], v[178:181], v[56:59]
	v_mfma_f32_16x16x32_bf16 v[52:55], v[146:149], v[186:189], v[52:55]
	v_mfma_f32_16x16x32_bf16 v[48:51], v[154:157], v[186:189], v[48:51]
	v_mfma_f32_16x16x32_bf16 v[40:43], v[146:149], v[194:197], v[40:43]
	v_mfma_f32_16x16x32_bf16 v[32:35], v[154:157], v[194:197], v[32:35]
	v_mfma_f32_16x16x32_bf16 v[24:27], v[146:149], v[202:205], v[24:27]
	v_mfma_f32_16x16x32_bf16 v[16:19], v[154:157], v[202:205], v[16:19]
	s_setprio 0
	s_setprio 1
	v_mfma_f32_16x16x32_bf16 v[44:47], v[158:161], v[174:177], v[44:47]
	v_mfma_f32_16x16x32_bf16 v[36:39], v[166:169], v[174:177], v[36:39]
	v_mfma_f32_16x16x32_bf16 v[28:31], v[158:161], v[182:185], v[28:31]
	v_mfma_f32_16x16x32_bf16 v[20:23], v[166:169], v[182:185], v[20:23]
	v_mfma_f32_16x16x32_bf16 v[12:15], v[158:161], v[190:193], v[12:15]
	v_mfma_f32_16x16x32_bf16 v[8:11], v[166:169], v[190:193], v[8:11]
	v_mfma_f32_16x16x32_bf16 v[4:7], v[158:161], v[198:201], v[4:7]
	v_mfma_f32_16x16x32_bf16 v[0:3], v[166:169], v[198:201], v[0:3]
	v_mfma_f32_16x16x32_bf16 v[44:47], v[162:165], v[178:181], v[44:47]
	v_mfma_f32_16x16x32_bf16 v[36:39], v[170:173], v[178:181], v[36:39]
	v_mfma_f32_16x16x32_bf16 v[28:31], v[162:165], v[186:189], v[28:31]
	v_mfma_f32_16x16x32_bf16 v[20:23], v[170:173], v[186:189], v[20:23]
	v_mfma_f32_16x16x32_bf16 v[12:15], v[162:165], v[194:197], v[12:15]
	v_mfma_f32_16x16x32_bf16 v[8:11], v[170:173], v[194:197], v[8:11]
	v_mfma_f32_16x16x32_bf16 v[4:7], v[162:165], v[202:205], v[4:7]
	v_mfma_f32_16x16x32_bf16 v[0:3], v[170:173], v[202:205], v[0:3]
	s_setprio 0
	s_barrier
	s_add_u32 s48, s48, 0x100
	s_addc_u32 s49, s49, 0
	s_add_u32 s2, s2, 0x100
	s_addc_u32 s24, s24, 0
	s_cmp_ge_i32 s62, s55
	s_mov_b32 s25, s62
	s_cbranch_scc1 .Lpeelx_12

; __device__ __forceinline__ u32x4 pack8(const f32x4 a, const f32x4 b) { u32x4 w; w.x = cvt2(a[0], a[1]); w.y = cvt2(a[2], a[3]); w.z = cvt2(b[0], b[1]); w.w = cvt2(b[2], b[3]); return w; }
;     __device__ __forceinline__ void operator()(const f32x4 (&acc)[2][2][4][2], const Unit& u, int wr, int wc, int fr, int fq) const {
;     ...
;                 for (int bj = 0; bj < 2; ++bj) { const u32x4 x4 = xw[ai][m][bj]; f32x4 v0, v1;
;                     v0[0] = __uint_as_float(x4.x << 16); v0[1] = __uint_as_float(x4.x & 0xffff0000u); v0[2] = __uint_as_float(x4.y << 16); v0[3] = __uint_as_float(x4.y & 0xffff0000u);
;                     v1[0] = __uint_as_float(x4.z << 16); v1[1] = __uint_as_float(x4.z & 0xffff0000u); v1[2] = __uint_as_float(x4.w << 16); v1[3] = __uint_as_float(x4.w & 0xffff0000u);
;                     v0 = v0 + acc[ai][bj][m][0] * scale; v1 = v1 + acc[ai][bj][m][1] * scale;
;                     const u32x4 w = pack8(v0, v1); *(u32x4*)(p + bj * HALF) = w;
.Lpeelx_12:
	v_readlane_b32 s64, v255, 16
	v_pk_mul_f32 v[222:223], v[126:127], 0.5 op_sel_hi:[1,0]
	v_pk_mul_f32 v[220:221], v[124:125], 0.5 op_sel_hi:[1,0]
	v_pk_mul_f32 v[218:219], v[122:123], 0.5 op_sel_hi:[1,0]
	v_pk_mul_f32 v[216:217], v[120:121], 0.5 op_sel_hi:[1,0]
	v_pk_mul_f32 v[214:215], v[110:111], 0.5 op_sel_hi:[1,0]
	v_pk_mul_f32 v[212:213], v[108:109], 0.5 op_sel_hi:[1,0]
	v_pk_mul_f32 v[210:211], v[102:103], 0.5 op_sel_hi:[1,0]
	v_pk_mul_f32 v[208:209], v[100:101], 0.5 op_sel_hi:[1,0]
	v_pk_mul_f32 v[202:203], v[118:119], 0.5 op_sel_hi:[1,0]
	v_pk_mul_f32 v[200:201], v[116:117], 0.5 op_sel_hi:[1,0]
	v_pk_mul_f32 v[198:199], v[114:115], 0.5 op_sel_hi:[1,0]
	v_pk_mul_f32 v[196:197], v[112:113], 0.5 op_sel_hi:[1,0]
	v_pk_mul_f32 v[194:195], v[94:95], 0.5 op_sel_hi:[1,0]
	v_pk_mul_f32 v[192:193], v[92:93], 0.5 op_sel_hi:[1,0]
	v_pk_mul_f32 v[190:191], v[86:87], 0.5 op_sel_hi:[1,0]
	v_pk_mul_f32 v[188:189], v[84:85], 0.5 op_sel_hi:[1,0]
	v_pk_mul_f32 v[182:183], v[106:107], 0.5 op_sel_hi:[1,0]
	v_pk_mul_f32 v[180:181], v[104:105], 0.5 op_sel_hi:[1,0]
	v_pk_mul_f32 v[178:179], v[98:99], 0.5 op_sel_hi:[1,0]
	v_pk_mul_f32 v[176:177], v[96:97], 0.5 op_sel_hi:[1,0]
	v_pk_mul_f32 v[174:175], v[78:79], 0.5 op_sel_hi:[1,0]
	v_pk_mul_f32 v[172:173], v[76:77], 0.5 op_sel_hi:[1,0]
	v_pk_mul_f32 v[170:171], v[74:75], 0.5 op_sel_hi:[1,0]
	v_pk_mul_f32 v[168:169], v[72:73], 0.5 op_sel_hi:[1,0]
	v_pk_mul_f32 v[162:163], v[90:91], 0.5 op_sel_hi:[1,0]
	v_pk_mul_f32 v[160:161], v[88:89], 0.5 op_sel_hi:[1,0]
	v_pk_mul_f32 v[158:159], v[82:83], 0.5 op_sel_hi:[1,0]
	v_pk_mul_f32 v[156:157], v[80:81], 0.5 op_sel_hi:[1,0]
	v_pk_mul_f32 v[154:155], v[70:71], 0.5 op_sel_hi:[1,0]
	v_pk_mul_f32 v[152:153], v[68:69], 0.5 op_sel_hi:[1,0]
	v_pk_mul_f32 v[150:151], v[66:67], 0.5 op_sel_hi:[1,0]
	v_pk_mul_f32 v[148:149], v[64:65], 0.5 op_sel_hi:[1,0]
	v_pk_mul_f32 v[142:143], v[62:63], 0.5 op_sel_hi:[1,0]
	v_pk_mul_f32 v[126:127], v[60:61], 0.5 op_sel_hi:[1,0]
	v_pk_mul_f32 v[124:125], v[58:59], 0.5 op_sel_hi:[1,0]
	v_pk_mul_f32 v[122:123], v[56:57], 0.5 op_sel_hi:[1,0]
	v_pk_mul_f32 v[120:121], v[46:47], 0.5 op_sel_hi:[1,0]
	v_pk_mul_f32 v[118:119], v[44:45], 0.5 op_sel_hi:[1,0]
	v_pk_mul_f32 v[116:117], v[38:39], 0.5 op_sel_hi:[1,0]
	v_pk_mul_f32 v[114:115], v[36:37], 0.5 op_sel_hi:[1,0]
	v_pk_mul_f32 v[110:111], v[54:55], 0.5 op_sel_hi:[1,0]
	v_pk_mul_f32 v[108:109], v[52:53], 0.5 op_sel_hi:[1,0]
	v_pk_mul_f32 v[106:107], v[50:51], 0.5 op_sel_hi:[1,0]
	v_pk_mul_f32 v[104:105], v[48:49], 0.5 op_sel_hi:[1,0]
	v_pk_mul_f32 v[102:103], v[30:31], 0.5 op_sel_hi:[1,0]
	v_pk_mul_f32 v[100:101], v[28:29], 0.5 op_sel_hi:[1,0]
	v_pk_mul_f32 v[98:99], v[22:23], 0.5 op_sel_hi:[1,0]
	v_pk_mul_f32 v[96:97], v[20:21], 0.5 op_sel_hi:[1,0]
	v_pk_mul_f32 v[94:95], v[42:43], 0.5 op_sel_hi:[1,0]
	v_pk_mul_f32 v[92:93], v[40:41], 0.5 op_sel_hi:[1,0]
	v_pk_mul_f32 v[90:91], v[34:35], 0.5 op_sel_hi:[1,0]
	v_pk_mul_f32 v[88:89], v[32:33], 0.5 op_sel_hi:[1,0]
	v_pk_mul_f32 v[86:87], v[14:15], 0.5 op_sel_hi:[1,0]
	v_pk_mul_f32 v[84:85], v[12:13], 0.5 op_sel_hi:[1,0]
	v_pk_mul_f32 v[82:83], v[10:11], 0.5 op_sel_hi:[1,0]
	v_pk_mul_f32 v[80:81], v[8:9], 0.5 op_sel_hi:[1,0]
	v_pk_mul_f32 v[78:79], v[26:27], 0.5 op_sel_hi:[1,0]
	v_pk_mul_f32 v[76:77], v[24:25], 0.5 op_sel_hi:[1,0]
	v_pk_mul_f32 v[74:75], v[18:19], 0.5 op_sel_hi:[1,0]
	v_pk_mul_f32 v[72:73], v[16:17], 0.5 op_sel_hi:[1,0]
	v_pk_mul_f32 v[70:71], v[6:7], 0.5 op_sel_hi:[1,0]
	v_pk_mul_f32 v[68:69], v[4:5], 0.5 op_sel_hi:[1,0]
	v_pk_mul_f32 v[66:67], v[2:3], 0.5 op_sel_hi:[1,0]
	v_pk_mul_f32 v[64:65], v[0:1], 0.5 op_sel_hi:[1,0]
	v_readlane_b32 s65, v255, 17

; #define PG8_STAGE(bufoff, gbase, voff) do { _Pragma("unroll") for (int _i = 0; _i < 2; ++_i) \
;         __builtin_amdgcn_global_load_lds((const unsigned*)((const char*)(gbase) + (voff)[_i]), (PG8_LAS unsigned*)(lds + (bufoff) + ldsw + _i * 8192), 16, 0, 0); } while (0)
; #define PG8_LDA(dst, b, h) do { _Pragma("unroll") for (int m = 0; m < 4; ++m) _Pragma("unroll") for (int k = 0; k < 2; ++k) dst[m][k] = *(const PG8_LAS bf16x8*)(lds + PG8_SA(b, h) + aoff + m * 2048 + k * 1024); } while (0)
; #define PG8_LDB(dst, b, h) do { _Pragma("unroll") for (int n = 0; n < 2; ++n) _Pragma("unroll") for (int k = 0; k < 2; ++k) dst[n][k] = *(const PG8_LAS bf16x8*)(lds + PG8_SB(b, h) + boff + n * 2048 + k * 1024); } while (0)
; #define PG8_WAIT_V(n) asm volatile("s_waitcnt vmcnt(" #n ")" ::: "memory")
; #define PG8_WAIT_L(n) asm volatile("s_waitcnt lgkmcnt(" #n ")" ::: "memory")
; #define PG8_BAR __builtin_amdgcn_s_barrier()
; #define PG8_SCHED __builtin_amdgcn_sched_barrier(0)
; template <class Epi, class Sched, bool ALIGN_EPI = false, bool SP2 = false>
; __device__ __forceinline__ void gemm_phase(PG8_LAS unsigned char* lds, const Gemm g, const Sched& S, const Epi& E) {
;     ...
;     f32x4 acc[2][2][4][2];
; #pragma unroll
;     for (int a = 0; a < 2; ++a)
; #pragma unroll
;         for (int b = 0; b < 2; ++b)
; #pragma unroll
;             for (int m = 0; m < 4; ++m)
; #pragma unroll
;                 for (int n = 0; n < 2; ++n) acc[a][b][m][n] = (f32x4){0.f, 0.f, 0.f, 0.f};
;     ...
;         for (int t = 0; t < nt; t += 2) {
;             const bool last = (t == nt - 2);
;             const char* a1 = cA + (size_t)(t + 1) * kstep;
;             const char* a2 = last ? nA : cA + (size_t)(t + 2) * kstep; const char* b2 = last ? nB : cB + (size_t)(t + 2) * kstep;
;             const char* a3 = a2 + kstep; const char* b3 = b2 + kstep;
;             if (last && has_next) S.a_ready(nxt);
;             if constexpr (SP2) {
;             PG8_LDB(B0, 0, 0); PG8_LDB(B1, 0, 1); PG8_SCHED; PG8_LDA(At, 0, 0); PG8_STAGE(PG8_SA(1, 1), a1 + hstep, voffA);
;             PG8_WAIT_V(8); PG8_WAIT_L(0); PG8_BAR; PG8_MMA(0, 0, At, B0); PG8_MMA(0, 1, At, B1); PG8_BAR; PG8_SCHED;
;             PG8_LDA(At, 0, 1); PG8_STAGE(PG8_SB(0, 0), b2, voffB); PG8_STAGE(PG8_SB(0, 1), b2 + hstep, voffB); PG8_STAGE(PG8_SA(0, 0), a2, voffA);
.LBB0_2577:
	s_and_b64 vcc, exec, s[8:9]
	s_cbranch_vccnz .Lcoldz_13
	s_add_u32 s40, s40, 0x80
	s_addc_u32 s41, s41, 0
	s_add_u32 s24, s42, 0x100
	s_addc_u32 s25, s43, 0
	s_mov_b32 s42, 0
	ds_read_b128 v[152:155], v147
	ds_read_b128 v[156:159], v147 offset:1024
	ds_read_b128 v[160:163], v147 offset:2048
	ds_read_b128 v[164:167], v147 offset:3072
	ds_read_b128 v[168:171], v148
	ds_read_b128 v[172:175], v148 offset:1024
	ds_read_b128 v[176:179], v148 offset:2048
	ds_read_b128 v[180:183], v148 offset:3072
	s_add_i32 s59, s42, 2
	s_add_u32 s60, s40, 0x80
	s_addc_u32 s43, s41, 0
	s_cmp_eq_u32 s44, s42
	s_cselect_b32 s42, s12, s60
	s_cselect_b32 s43, s13, s43
	s_cselect_b32 s61, s39, s25
	s_cselect_b32 s60, s38, s24
	s_mov_b32 m0, s46
	v_lshl_add_u64 v[216:217], s[40:41], 0, v[136:137]
	ds_read_b128 v[184:187], v149
	ds_read_b128 v[188:191], v149 offset:1024
	ds_read_b128 v[192:195], v149 offset:2048
	ds_read_b128 v[196:199], v149 offset:3072
	ds_read_b128 v[200:203], v149 offset:4096
	ds_read_b128 v[204:207], v149 offset:5120
	ds_read_b128 v[208:211], v149 offset:6144
	ds_read_b128 v[212:215], v149 offset:7168
	global_load_lds_dwordx4 v[216:217], off
	v_lshl_add_u64 v[216:217], s[40:41], 0, v[138:139]
	s_mov_b32 m0, s47
	s_nop 0
	global_load_lds_dwordx4 v[216:217], off
	s_waitcnt vmcnt(8)
	s_waitcnt lgkmcnt(0)
	s_barrier
	s_setprio 1
	s_waitcnt lgkmcnt(0)
	v_mfma_f32_16x16x32_bf16 v[120:123], v[152:155], v[184:187], 0
	v_mfma_f32_16x16x32_bf16 v[116:119], v[160:163], v[184:187], 0
	v_mfma_f32_16x16x32_bf16 v[108:111], v[152:155], v[192:195], 0
	v_mfma_f32_16x16x32_bf16 v[100:103], v[160:163], v[192:195], 0
	v_mfma_f32_16x16x32_bf16 v[92:95], v[152:155], v[200:203], 0
	v_mfma_f32_16x16x32_bf16 v[84:87], v[160:163], v[200:203], 0
	v_mfma_f32_16x16x32_bf16 v[76:79], v[152:155], v[208:211], 0
	v_mfma_f32_16x16x32_bf16 v[68:71], v[160:163], v[208:211], 0
	v_mfma_f32_16x16x32_bf16 v[120:123], v[156:159], v[188:191], v[120:123]
	v_mfma_f32_16x16x32_bf16 v[116:119], v[164:167], v[188:191], v[116:119]
	v_mfma_f32_16x16x32_bf16 v[108:111], v[156:159], v[196:199], v[108:111]
	v_mfma_f32_16x16x32_bf16 v[100:103], v[164:167], v[196:199], v[100:103]
	v_mfma_f32_16x16x32_bf16 v[92:95], v[156:159], v[204:207], v[92:95]
	v_mfma_f32_16x16x32_bf16 v[84:87], v[164:167], v[204:207], v[84:87]
	v_mfma_f32_16x16x32_bf16 v[76:79], v[156:159], v[212:215], v[76:79]
	v_mfma_f32_16x16x32_bf16 v[68:71], v[164:167], v[212:215], v[68:71]
	s_setprio 0
	s_setprio 1
	v_mfma_f32_16x16x32_bf16 v[124:127], v[168:171], v[184:187], 0
	v_mfma_f32_16x16x32_bf16 v[112:115], v[176:179], v[184:187], 0
	v_mfma_f32_16x16x32_bf16 v[104:107], v[168:171], v[192:195], 0
	v_mfma_f32_16x16x32_bf16 v[96:99], v[176:179], v[192:195], 0
	v_mfma_f32_16x16x32_bf16 v[88:91], v[168:171], v[200:203], 0
	v_mfma_f32_16x16x32_bf16 v[80:83], v[176:179], v[200:203], 0
	v_mfma_f32_16x16x32_bf16 v[72:75], v[168:171], v[208:211], 0
	v_mfma_f32_16x16x32_bf16 v[64:67], v[176:179], v[208:211], 0
	v_mfma_f32_16x16x32_bf16 v[124:127], v[172:175], v[188:191], v[124:127]
	v_mfma_f32_16x16x32_bf16 v[112:115], v[180:183], v[188:191], v[112:115]
	v_mfma_f32_16x16x32_bf16 v[104:107], v[172:175], v[196:199], v[104:107]
	v_mfma_f32_16x16x32_bf16 v[96:99], v[180:183], v[196:199], v[96:99]
	v_mfma_f32_16x16x32_bf16 v[88:91], v[172:175], v[204:207], v[88:91]
	v_mfma_f32_16x16x32_bf16 v[80:83], v[180:183], v[204:207], v[80:83]
	v_mfma_f32_16x16x32_bf16 v[72:75], v[172:175], v[212:215], v[72:75]
	v_mfma_f32_16x16x32_bf16 v[64:67], v[180:183], v[212:215], v[64:67]
	s_setprio 0
	s_barrier
	s_mov_b32 m0, s48
	v_lshl_add_u64 v[216:217], s[60:61], 0, v[132:133]
	v_lshl_add_u64 v[218:219], s[60:61], 0, v[128:129]
	s_add_u32 s60, s60, s14
	ds_read_b128 v[184:187], v149 offset:16384
	ds_read_b128 v[188:191], v149 offset:17408
	ds_read_b128 v[192:195], v149 offset:18432
	ds_read_b128 v[196:199], v149 offset:19456
	ds_read_b128 v[200:203], v149 offset:20480
	ds_read_b128 v[204:207], v149 offset:21504
	ds_read_b128 v[208:211], v149 offset:22528
	ds_read_b128 v[212:215], v149 offset:23552
	global_load_lds_dwordx4 v[216:217], off
	s_mov_b32 m0, s49
	s_addc_u32 s61, s61, s15
	global_load_lds_dwordx4 v[218:219], off
	v_lshl_add_u64 v[220:221], s[60:61], 0, v[132:133]
	s_mov_b32 m0, s50
	v_lshl_add_u64 v[222:223], s[60:61], 0, v[128:129]
	global_load_lds_dwordx4 v[220:221], off
	s_mov_b32 m0, s51
	v_lshl_add_u64 v[224:225], s[42:43], 0, v[134:135]
	global_load_lds_dwordx4 v[222:223], off
	s_mov_b32 m0, s6
	v_lshl_add_u64 v[226:227], s[42:43], 0, v[130:131]
	global_load_lds_dwordx4 v[224:225], off
	s_mov_b32 m0, s7
	s_nop 0
	global_load_lds_dwordx4 v[226:227], off
	s_waitcnt vmcnt(8)
	s_waitcnt lgkmcnt(0)
	s_barrier
; #define PG8_STAGE(bufoff, gbase, voff) do { _Pragma("unroll") for (int _i = 0; _i < 2; ++_i) \
;         __builtin_amdgcn_global_load_lds((const unsigned*)((const char*)(gbase) + (voff)[_i]), (PG8_LAS unsigned*)(lds + (bufoff) + ldsw + _i * 8192), 16, 0, 0); } while (0)
; #define PG8_LDA(dst, b, h) do { _Pragma("unroll") for (int m = 0; m < 4; ++m) _Pragma("unroll") for (int k = 0; k < 2; ++k) dst[m][k] = *(const PG8_LAS bf16x8*)(lds + PG8_SA(b, h) + aoff + m * 2048 + k * 1024); } while (0)
; #define PG8_LDB(dst, b, h) do { _Pragma("unroll") for (int n = 0; n < 2; ++n) _Pragma("unroll") for (int k = 0; k < 2; ++k) dst[n][k] = *(const PG8_LAS bf16x8*)(lds + PG8_SB(b, h) + boff + n * 2048 + k * 1024); } while (0)
; #define PG8_MMA(ai, bj, At, Bt) do { __builtin_amdgcn_s_setprio(1); _Pragma("unroll") for (int m = 0; m < 4; ++m) _Pragma("unroll") for (int n = 0; n < 2; ++n) _Pragma("unroll") for (int k = 0; k < 2; ++k) \
;         acc[ai][bj][m][n] = __builtin_amdgcn_mfma_f32_16x16x32_bf16(Bt[n][k], At[m][k], acc[ai][bj][m][n], 0, 0, 0); __builtin_amdgcn_s_setprio(0); } while (0)
; #define PG8_WAIT_V(n) asm volatile("s_waitcnt vmcnt(" #n ")" ::: "memory")
; #define PG8_WAIT_L(n) asm volatile("s_waitcnt lgkmcnt(" #n ")" ::: "memory")
; #define PG8_BAR __builtin_amdgcn_s_barrier()
; #define PG8_SCHED __builtin_amdgcn_sched_barrier(0)
; template <class Epi, class Sched, bool ALIGN_EPI = false, bool SP2 = false>
; __device__ __forceinline__ void gemm_phase(PG8_LAS unsigned char* lds, const Gemm g, const Sched& S, const Epi& E) {
;     ...
;             PG8_WAIT_V(8); PG8_WAIT_L(0); PG8_BAR; PG8_MMA(1, 0, At, B0); PG8_MMA(1, 1, At, B1); PG8_BAR; PG8_SCHED;
;             PG8_LDB(B0, 1, 0); PG8_LDB(B1, 1, 1); PG8_SCHED; PG8_LDA(At, 1, 0); PG8_STAGE(PG8_SA(0, 1), a2 + hstep, voffA);
;             PG8_WAIT_V(8); PG8_WAIT_L(0); PG8_BAR; PG8_MMA(0, 0, At, B0); PG8_MMA(0, 1, At, B1); PG8_BAR; PG8_SCHED;
	s_setprio 1
	s_waitcnt lgkmcnt(0)
	v_mfma_f32_16x16x32_bf16 v[60:63], v[152:155], v[184:187], 0
	v_mfma_f32_16x16x32_bf16 v[52:55], v[160:163], v[184:187], 0
	v_mfma_f32_16x16x32_bf16 v[44:47], v[152:155], v[192:195], 0
	v_mfma_f32_16x16x32_bf16 v[36:39], v[160:163], v[192:195], 0
	v_mfma_f32_16x16x32_bf16 v[28:31], v[152:155], v[200:203], 0
	v_mfma_f32_16x16x32_bf16 v[20:23], v[160:163], v[200:203], 0
	v_mfma_f32_16x16x32_bf16 v[12:15], v[152:155], v[208:211], 0
	v_mfma_f32_16x16x32_bf16 v[4:7], v[160:163], v[208:211], 0
	v_mfma_f32_16x16x32_bf16 v[60:63], v[156:159], v[188:191], v[60:63]
	v_mfma_f32_16x16x32_bf16 v[52:55], v[164:167], v[188:191], v[52:55]
	v_mfma_f32_16x16x32_bf16 v[44:47], v[156:159], v[196:199], v[44:47]
	v_mfma_f32_16x16x32_bf16 v[36:39], v[164:167], v[196:199], v[36:39]
	v_mfma_f32_16x16x32_bf16 v[28:31], v[156:159], v[204:207], v[28:31]
	v_mfma_f32_16x16x32_bf16 v[20:23], v[164:167], v[204:207], v[20:23]
	v_mfma_f32_16x16x32_bf16 v[12:15], v[156:159], v[212:215], v[12:15]
	v_mfma_f32_16x16x32_bf16 v[4:7], v[164:167], v[212:215], v[4:7]
	s_setprio 0
	s_setprio 1
	v_mfma_f32_16x16x32_bf16 v[56:59], v[168:171], v[184:187], 0
	v_mfma_f32_16x16x32_bf16 v[48:51], v[176:179], v[184:187], 0
	v_mfma_f32_16x16x32_bf16 v[40:43], v[168:171], v[192:195], 0
	v_mfma_f32_16x16x32_bf16 v[32:35], v[176:179], v[192:195], 0
	v_mfma_f32_16x16x32_bf16 v[24:27], v[168:171], v[200:203], 0
	v_mfma_f32_16x16x32_bf16 v[16:19], v[176:179], v[200:203], 0
	v_mfma_f32_16x16x32_bf16 v[8:11], v[168:171], v[208:211], 0
	v_mfma_f32_16x16x32_bf16 v[0:3], v[176:179], v[208:211], 0
	v_mfma_f32_16x16x32_bf16 v[56:59], v[172:175], v[188:191], v[56:59]
	v_mfma_f32_16x16x32_bf16 v[48:51], v[180:183], v[188:191], v[48:51]
	v_mfma_f32_16x16x32_bf16 v[40:43], v[172:175], v[196:199], v[40:43]
	v_mfma_f32_16x16x32_bf16 v[32:35], v[180:183], v[196:199], v[32:35]
	v_mfma_f32_16x16x32_bf16 v[24:27], v[172:175], v[204:207], v[24:27]
	v_mfma_f32_16x16x32_bf16 v[16:19], v[180:183], v[204:207], v[16:19]
	v_mfma_f32_16x16x32_bf16 v[8:11], v[172:175], v[212:215], v[8:11]
	v_mfma_f32_16x16x32_bf16 v[0:3], v[180:183], v[212:215], v[0:3]
	s_setprio 0
	s_barrier
	ds_read_b128 v[152:155], v150
	ds_read_b128 v[156:159], v150 offset:1024
	ds_read_b128 v[160:163], v150 offset:2048
	ds_read_b128 v[164:167], v150 offset:3072
	ds_read_b128 v[168:171], v151
	ds_read_b128 v[172:175], v151 offset:1024
	ds_read_b128 v[176:179], v151 offset:2048
	ds_read_b128 v[180:183], v151 offset:3072
	s_add_u32 s42, s42, s14
	s_addc_u32 s43, s43, s15
	s_mov_b32 m0, s18
	v_lshl_add_u64 v[228:229], s[42:43], 0, v[134:135]
	ds_read_b128 v[184:187], v149 offset:32768
	ds_read_b128 v[188:191], v149 offset:33792
	ds_read_b128 v[192:195], v149 offset:34816
	ds_read_b128 v[196:199], v149 offset:35840
	ds_read_b128 v[200:203], v149 offset:36864
	ds_read_b128 v[204:207], v149 offset:37888
	ds_read_b128 v[208:211], v149 offset:38912
	ds_read_b128 v[212:215], v149 offset:39936
	global_load_lds_dwordx4 v[228:229], off
	v_lshl_add_u64 v[228:229], s[42:43], 0, v[130:131]
	s_mov_b32 m0, s19
	s_nop 0
	global_load_lds_dwordx4 v[228:229], off
	s_waitcnt vmcnt(8)
	s_waitcnt lgkmcnt(0)
	s_barrier
	s_setprio 1
	s_waitcnt lgkmcnt(0)
	v_mfma_f32_16x16x32_bf16 v[120:123], v[152:155], v[184:187], v[120:123]
	v_mfma_f32_16x16x32_bf16 v[116:119], v[160:163], v[184:187], v[116:119]
	v_mfma_f32_16x16x32_bf16 v[108:111], v[152:155], v[192:195], v[108:111]
	v_mfma_f32_16x16x32_bf16 v[100:103], v[160:163], v[192:195], v[100:103]
	v_mfma_f32_16x16x32_bf16 v[92:95], v[152:155], v[200:203], v[92:95]
	v_mfma_f32_16x16x32_bf16 v[84:87], v[160:163], v[200:203], v[84:87]
	v_mfma_f32_16x16x32_bf16 v[76:79], v[152:155], v[208:211], v[76:79]
	v_mfma_f32_16x16x32_bf16 v[68:71], v[160:163], v[208:211], v[68:71]
	v_mfma_f32_16x16x32_bf16 v[120:123], v[156:159], v[188:191], v[120:123]
	v_mfma_f32_16x16x32_bf16 v[116:119], v[164:167], v[188:191], v[116:119]
	v_mfma_f32_16x16x32_bf16 v[108:111], v[156:159], v[196:199], v[108:111]
	v_mfma_f32_16x16x32_bf16 v[100:103], v[164:167], v[196:199], v[100:103]
	v_mfma_f32_16x16x32_bf16 v[92:95], v[156:159], v[204:207], v[92:95]
	v_mfma_f32_16x16x32_bf16 v[84:87], v[164:167], v[204:207], v[84:87]
	v_mfma_f32_16x16x32_bf16 v[76:79], v[156:159], v[212:215], v[76:79]
	v_mfma_f32_16x16x32_bf16 v[68:71], v[164:167], v[212:215], v[68:71]
	s_setprio 0
	s_setprio 1
	v_mfma_f32_16x16x32_bf16 v[124:127], v[168:171], v[184:187], v[124:127]
	v_mfma_f32_16x16x32_bf16 v[112:115], v[176:179], v[184:187], v[112:115]
	v_mfma_f32_16x16x32_bf16 v[104:107], v[168:171], v[192:195], v[104:107]
	v_mfma_f32_16x16x32_bf16 v[96:99], v[176:179], v[192:195], v[96:99]
	v_mfma_f32_16x16x32_bf16 v[88:91], v[168:171], v[200:203], v[88:91]
	v_mfma_f32_16x16x32_bf16 v[80:83], v[176:179], v[200:203], v[80:83]
	v_mfma_f32_16x16x32_bf16 v[72:75], v[168:171], v[208:211], v[72:75]
	v_mfma_f32_16x16x32_bf16 v[64:67], v[176:179], v[208:211], v[64:67]
	v_mfma_f32_16x16x32_bf16 v[124:127], v[172:175], v[188:191], v[124:127]
	v_mfma_f32_16x16x32_bf16 v[112:115], v[180:183], v[188:191], v[112:115]
	v_mfma_f32_16x16x32_bf16 v[104:107], v[172:175], v[196:199], v[104:107]
	v_mfma_f32_16x16x32_bf16 v[96:99], v[180:183], v[196:199], v[96:99]
	v_mfma_f32_16x16x32_bf16 v[88:91], v[172:175], v[204:207], v[88:91]
	v_mfma_f32_16x16x32_bf16 v[80:83], v[180:183], v[204:207], v[80:83]
	v_mfma_f32_16x16x32_bf16 v[72:75], v[172:175], v[212:215], v[72:75]
	v_mfma_f32_16x16x32_bf16 v[64:67], v[180:183], v[212:215], v[64:67]
	s_setprio 0
	s_barrier
; #define PG8_STAGE(bufoff, gbase, voff) do { _Pragma("unroll") for (int _i = 0; _i < 2; ++_i) \
;         __builtin_amdgcn_global_load_lds((const unsigned*)((const char*)(gbase) + (voff)[_i]), (PG8_LAS unsigned*)(lds + (bufoff) + ldsw + _i * 8192), 16, 0, 0); } while (0)
; #define PG8_LDA(dst, b, h) do { _Pragma("unroll") for (int m = 0; m < 4; ++m) _Pragma("unroll") for (int k = 0; k < 2; ++k) dst[m][k] = *(const PG8_LAS bf16x8*)(lds + PG8_SA(b, h) + aoff + m * 2048 + k * 1024); } while (0)
; #define PG8_MMA(ai, bj, At, Bt) do { __builtin_amdgcn_s_setprio(1); _Pragma("unroll") for (int m = 0; m < 4; ++m) _Pragma("unroll") for (int n = 0; n < 2; ++n) _Pragma("unroll") for (int k = 0; k < 2; ++k) \
;         acc[ai][bj][m][n] = __builtin_amdgcn_mfma_f32_16x16x32_bf16(Bt[n][k], At[m][k], acc[ai][bj][m][n], 0, 0, 0); __builtin_amdgcn_s_setprio(0); } while (0)
; #define PG8_WAIT_V(n) asm volatile("s_waitcnt vmcnt(" #n ")" ::: "memory")
; #define PG8_WAIT_L(n) asm volatile("s_waitcnt lgkmcnt(" #n ")" ::: "memory")
; #define PG8_BAR __builtin_amdgcn_s_barrier()
; #define PG8_SCHED __builtin_amdgcn_sched_barrier(0)
; template <class Epi, class Sched, bool ALIGN_EPI = false, bool SP2 = false>
; __device__ __forceinline__ void gemm_phase(PG8_LAS unsigned char* lds, const Gemm g, const Sched& S, const Epi& E) {
;     ...
;         for (int t = 0; t < nt; t += 2) {
;             const bool last = (t == nt - 2);
;             const char* a1 = cA + (size_t)(t + 1) * kstep;
;             const char* a2 = last ? nA : cA + (size_t)(t + 2) * kstep; const char* b2 = last ? nB : cB + (size_t)(t + 2) * kstep;
;     ...
;             PG8_LDA(At, 1, 1); PG8_STAGE(PG8_SB(1, 0), b3, voffB); PG8_STAGE(PG8_SB(1, 1), b3 + hstep, voffB); PG8_STAGE(PG8_SA(1, 0), a3, voffA);
;             PG8_WAIT_V(8); PG8_WAIT_L(0); PG8_BAR; PG8_MMA(1, 0, At, B0); PG8_MMA(1, 1, At, B1); PG8_BAR; PG8_SCHED;
	s_mov_b32 m0, s53
	v_lshl_add_u64 v[216:217], v[216:217], 0, s[34:35]
	ds_read_b128 v[184:187], v149 offset:49152
	ds_read_b128 v[188:191], v149 offset:50176
	ds_read_b128 v[192:195], v149 offset:51200
	ds_read_b128 v[196:199], v149 offset:52224
	ds_read_b128 v[200:203], v149 offset:53248
	ds_read_b128 v[204:207], v149 offset:54272
	ds_read_b128 v[208:211], v149 offset:55296
	ds_read_b128 v[212:215], v149 offset:56320
	global_load_lds_dwordx4 v[216:217], off
	v_lshl_add_u64 v[216:217], v[218:219], 0, s[34:35]
	s_add_i32 m0, s53, 0x2000
	s_add_i32 s42, s52, s2
	global_load_lds_dwordx4 v[216:217], off
	v_lshl_add_u64 v[216:217], v[220:221], 0, s[34:35]
	s_mov_b32 m0, s42
	s_nop 0
	global_load_lds_dwordx4 v[216:217], off
	v_lshl_add_u64 v[216:217], v[222:223], 0, s[34:35]
	s_add_i32 m0, s42, 0x2000
	s_nop 0
	global_load_lds_dwordx4 v[216:217], off
	v_lshl_add_u64 v[216:217], v[224:225], 0, s[34:35]
	s_mov_b32 m0, s26
	s_nop 0
	global_load_lds_dwordx4 v[216:217], off
	v_lshl_add_u64 v[216:217], v[226:227], 0, s[34:35]
	s_mov_b32 m0, s27
	s_nop 0
	global_load_lds_dwordx4 v[216:217], off
	s_waitcnt vmcnt(8)
	s_waitcnt lgkmcnt(0)
	s_barrier
	s_setprio 1
	s_waitcnt lgkmcnt(0)
	v_mfma_f32_16x16x32_bf16 v[60:63], v[152:155], v[184:187], v[60:63]
	v_mfma_f32_16x16x32_bf16 v[52:55], v[160:163], v[184:187], v[52:55]
	v_mfma_f32_16x16x32_bf16 v[44:47], v[152:155], v[192:195], v[44:47]
	v_mfma_f32_16x16x32_bf16 v[36:39], v[160:163], v[192:195], v[36:39]
	v_mfma_f32_16x16x32_bf16 v[28:31], v[152:155], v[200:203], v[28:31]
	v_mfma_f32_16x16x32_bf16 v[20:23], v[160:163], v[200:203], v[20:23]
	v_mfma_f32_16x16x32_bf16 v[12:15], v[152:155], v[208:211], v[12:15]
	v_mfma_f32_16x16x32_bf16 v[4:7], v[160:163], v[208:211], v[4:7]
	v_mfma_f32_16x16x32_bf16 v[60:63], v[156:159], v[188:191], v[60:63]
	v_mfma_f32_16x16x32_bf16 v[52:55], v[164:167], v[188:191], v[52:55]
	v_mfma_f32_16x16x32_bf16 v[44:47], v[156:159], v[196:199], v[44:47]
	v_mfma_f32_16x16x32_bf16 v[36:39], v[164:167], v[196:199], v[36:39]
	v_mfma_f32_16x16x32_bf16 v[28:31], v[156:159], v[204:207], v[28:31]
	v_mfma_f32_16x16x32_bf16 v[20:23], v[164:167], v[204:207], v[20:23]
	v_mfma_f32_16x16x32_bf16 v[12:15], v[156:159], v[212:215], v[12:15]
	v_mfma_f32_16x16x32_bf16 v[4:7], v[164:167], v[212:215], v[4:7]
	s_setprio 0
	s_setprio 1
	v_mfma_f32_16x16x32_bf16 v[56:59], v[168:171], v[184:187], v[56:59]
	v_mfma_f32_16x16x32_bf16 v[48:51], v[176:179], v[184:187], v[48:51]
	v_mfma_f32_16x16x32_bf16 v[40:43], v[168:171], v[192:195], v[40:43]
	v_mfma_f32_16x16x32_bf16 v[32:35], v[176:179], v[192:195], v[32:35]
	v_mfma_f32_16x16x32_bf16 v[24:27], v[168:171], v[200:203], v[24:27]
	v_mfma_f32_16x16x32_bf16 v[16:19], v[176:179], v[200:203], v[16:19]
	v_mfma_f32_16x16x32_bf16 v[8:11], v[168:171], v[208:211], v[8:11]
	v_mfma_f32_16x16x32_bf16 v[0:3], v[176:179], v[208:211], v[0:3]
	v_mfma_f32_16x16x32_bf16 v[56:59], v[172:175], v[188:191], v[56:59]
	v_mfma_f32_16x16x32_bf16 v[48:51], v[180:183], v[188:191], v[48:51]
	v_mfma_f32_16x16x32_bf16 v[40:43], v[172:175], v[196:199], v[40:43]
	v_mfma_f32_16x16x32_bf16 v[32:35], v[180:183], v[196:199], v[32:35]
	v_mfma_f32_16x16x32_bf16 v[24:27], v[172:175], v[204:207], v[24:27]
	v_mfma_f32_16x16x32_bf16 v[16:19], v[180:183], v[204:207], v[16:19]
	v_mfma_f32_16x16x32_bf16 v[8:11], v[172:175], v[212:215], v[8:11]
	v_mfma_f32_16x16x32_bf16 v[0:3], v[180:183], v[212:215], v[0:3]
	s_setprio 0
	s_barrier
	s_add_u32 s40, s40, 0x100
	s_addc_u32 s41, s41, 0
	s_add_u32 s24, s24, 0x100
	s_addc_u32 s25, s25, 0
	s_cmp_ge_i32 s59, s33
	s_mov_b32 s42, s59
	s_cbranch_scc1 .Lpeelx_13

; #define PG8_BAR __builtin_amdgcn_s_barrier()
; template <class Epi, class Sched, bool ALIGN_EPI = false, bool SP2 = false>
; __device__ __forceinline__ void gemm_phase(PG8_LAS unsigned char* lds, const Gemm g, const Sched& S, const Epi& E) {
;     ...
;         if constexpr (ALIGN_EPI) { if (wr == 0) PG8_BAR; }
;         if constexpr (!Epi::AFTER_DRAIN) { E(acc, cur, wr, wc, fr, fq); S.done(cur); }
.Lpeelx_13:
.LBB0_2580:
	s_and_b64 vcc, exec, s[36:37]
	s_cbranch_vccz .LBB0_2582
	s_barrier
